# v33 with the back-to-back s_setprio 0 / s_setprio 1 pair in the middle of each 32-MFMA segment removed (priority stays raised across the segment)
# speedup vs baseline: 1.0050x; 1.0050x over previous
; #define PG8_STAGE(bufoff, gbase, voff) do { _Pragma("unroll") for (int _i = 0; _i < 2; ++_i) \
;         __builtin_amdgcn_global_load_lds((const unsigned*)((const char*)(gbase) + (voff)[_i]), (LAS unsigned*)(lds + (bufoff) + ldsw + _i * 8192), 16, 0, 0); } while (0)
; #define PG8_LDA(dst, b, h) do { _Pragma("unroll") for (int m = 0; m < 4; ++m) _Pragma("unroll") for (int k = 0; k < 2; ++k) dst[m][k] = *(const LAS bf16x8*)(lds + PG8_SA(b, h) + aoff + m * 2048 + k * 1024); } while (0)
; #define PG8_LDB(dst, b, h) do { _Pragma("unroll") for (int n = 0; n < 2; ++n) _Pragma("unroll") for (int k = 0; k < 2; ++k) dst[n][k] = *(const LAS bf16x8*)(lds + PG8_SB(b, h) + boff + n * 2048 + k * 1024); } while (0)
; #define PG8_MMA(ai, bj, At, Bt) do { __builtin_amdgcn_s_setprio(1); _Pragma("unroll") for (int m = 0; m < 4; ++m) _Pragma("unroll") for (int n = 0; n < 2; ++n) _Pragma("unroll") for (int k = 0; k < 2; ++k) \
;         acc[ai][bj][m][n] = __builtin_amdgcn_mfma_f32_16x16x32_bf16(Bt[n][k], At[m][k], acc[ai][bj][m][n], 0, 0, 0); __builtin_amdgcn_s_setprio(0); } while (0)
; #define PG8_WAIT_V(n) asm volatile("s_waitcnt vmcnt(" #n ")" ::: "memory")
; #define PG8_WAIT_L(n) asm volatile("s_waitcnt lgkmcnt(" #n ")" ::: "memory")
; #define PG8_BAR __builtin_amdgcn_s_barrier()
; #define PG8_SCHED __builtin_amdgcn_sched_barrier(0)
; template <class Epi>
; __device__ __forceinline__ void gemm_phase(LAS unsigned char* lds, const Gemm g, const StaticOrder& S, const Epi& E) {
;     ...
;             const bool last = (t == nt - 2);
;             const char* a1 = cA + (size_t)(t + 1) * kstep;
;             const char* a2 = last ? nA : cA + (size_t)(t + 2) * kstep; const char* b2 = last ? nB : cB + (size_t)(t + 2) * kstep;
;             const char* a3 = a2 + kstep; const char* b3 = b2 + kstep;
;             PG8_LDB(B0, 0, 0); PG8_LDB(B1, 0, 1); PG8_SCHED; PG8_LDA(At, 0, 0); PG8_STAGE(PG8_SA(1, 1), a1 + hstepA, voffA);
;             PG8_WAIT_V(8); PG8_WAIT_L(0); PG8_BAR; PG8_MMA(0, 0, At, B0); PG8_MMA(0, 1, At, B1); PG8_BAR; PG8_SCHED;
;             PG8_LDA(At, 0, 1); PG8_STAGE(PG8_SB(0, 0), b2, voffB); PG8_STAGE(PG8_SB(0, 1), b2 + hstepB, voffB); PG8_STAGE(PG8_SA(0, 0), a2, voffA);
;             PG8_WAIT_V(8); PG8_WAIT_L(0); PG8_BAR; PG8_MMA(1, 0, At, B0); PG8_MMA(1, 1, At, B1); PG8_BAR; PG8_SCHED;
.LBB0_414:
	s_add_u32 s14, s26, 0xfff80080
	s_addc_u32 s15, s27, -1
	s_add_i32 s33, 0, 0x10000
	s_cmp_eq_u32 s21, 28
	s_cselect_b32 s29, s0, s15
	s_cselect_b32 s28, s1, s14
	s_cselect_b32 s15, s3, s19
	s_cselect_b32 s14, s7, s9
	s_add_i32 s52, 0, 0x14000
	v_add_u32_e32 v150, s33, v1
	v_add_u32_e32 v159, s52, v1
	ds_read_b128 v[138:141], v150
	ds_read_b128 v[142:145], v150 offset:1024
	ds_read_b128 v[146:149], v150 offset:2048
	ds_read_b128 v[150:153], v150 offset:3072
	ds_read_b128 v[154:157], v159
	ds_read_b128 v[160:163], v159 offset:1024
	ds_read_b128 v[164:167], v159 offset:2048
	ds_read_b128 v[168:171], v159 offset:3072
	v_lshl_add_u64 v[184:185], s[26:27], 0, v[134:135]
	s_add_i32 m0, s35, 0xc000
	ds_read_b128 v[172:175], v158
	ds_read_b128 v[176:179], v158 offset:1024
	ds_read_b128 v[188:191], v158 offset:2048
	ds_read_b128 v[192:195], v158 offset:3072
	ds_read_b128 v[196:199], v158 offset:4096
	ds_read_b128 v[200:203], v158 offset:5120
	ds_read_b128 v[204:207], v158 offset:6144
	ds_read_b128 v[208:211], v158 offset:7168
	global_load_lds_dwordx4 v[184:185], off
	v_lshl_add_u64 v[184:185], s[26:27], 0, v[136:137]
	s_add_i32 m0, s35, 0xe000
	s_nop 0
	global_load_lds_dwordx4 v[184:185], off
	s_waitcnt vmcnt(8)
	s_waitcnt lgkmcnt(0)
	s_barrier
	s_setprio 1
	s_waitcnt lgkmcnt(0)
	v_mfma_f32_16x16x32_bf16 v[126:129], v[138:141], v[172:175], v[126:129]
	v_mfma_f32_16x16x32_bf16 v[122:125], v[146:149], v[172:175], v[122:125]
	v_mfma_f32_16x16x32_bf16 v[110:113], v[138:141], v[188:191], v[110:113]
	v_mfma_f32_16x16x32_bf16 v[106:109], v[146:149], v[188:191], v[106:109]
	v_mfma_f32_16x16x32_bf16 v[94:97], v[138:141], v[196:199], v[94:97]
	v_mfma_f32_16x16x32_bf16 v[90:93], v[146:149], v[196:199], v[90:93]
	v_mfma_f32_16x16x32_bf16 v[78:81], v[138:141], v[204:207], v[78:81]
	v_mfma_f32_16x16x32_bf16 v[74:77], v[146:149], v[204:207], v[74:77]
	v_mfma_f32_16x16x32_bf16 v[126:129], v[142:145], v[176:179], v[126:129]
	v_mfma_f32_16x16x32_bf16 v[122:125], v[150:153], v[176:179], v[122:125]
	v_mfma_f32_16x16x32_bf16 v[110:113], v[142:145], v[192:195], v[110:113]
	v_mfma_f32_16x16x32_bf16 v[106:109], v[150:153], v[192:195], v[106:109]
	v_mfma_f32_16x16x32_bf16 v[94:97], v[142:145], v[200:203], v[94:97]
	v_mfma_f32_16x16x32_bf16 v[90:93], v[150:153], v[200:203], v[90:93]
	v_mfma_f32_16x16x32_bf16 v[78:81], v[142:145], v[208:211], v[78:81]
	v_mfma_f32_16x16x32_bf16 v[74:77], v[150:153], v[208:211], v[74:77]
	v_mfma_f32_16x16x32_bf16 v[118:121], v[154:157], v[172:175], v[118:121]
	v_mfma_f32_16x16x32_bf16 v[114:117], v[164:167], v[172:175], v[114:117]
	v_mfma_f32_16x16x32_bf16 v[102:105], v[154:157], v[188:191], v[102:105]
	v_mfma_f32_16x16x32_bf16 v[98:101], v[164:167], v[188:191], v[98:101]
	v_mfma_f32_16x16x32_bf16 v[86:89], v[154:157], v[196:199], v[86:89]
	v_mfma_f32_16x16x32_bf16 v[82:85], v[164:167], v[196:199], v[82:85]
	v_mfma_f32_16x16x32_bf16 v[70:73], v[154:157], v[204:207], v[70:73]
	v_mfma_f32_16x16x32_bf16 v[66:69], v[164:167], v[204:207], v[66:69]
	v_mfma_f32_16x16x32_bf16 v[118:121], v[160:163], v[176:179], v[118:121]
	v_mfma_f32_16x16x32_bf16 v[114:117], v[168:171], v[176:179], v[114:117]
	v_mfma_f32_16x16x32_bf16 v[102:105], v[160:163], v[192:195], v[102:105]
	v_mfma_f32_16x16x32_bf16 v[98:101], v[168:171], v[192:195], v[98:101]
	v_mfma_f32_16x16x32_bf16 v[86:89], v[160:163], v[200:203], v[86:89]
	v_mfma_f32_16x16x32_bf16 v[82:85], v[168:171], v[200:203], v[82:85]
	v_mfma_f32_16x16x32_bf16 v[70:73], v[160:163], v[208:211], v[70:73]
	v_mfma_f32_16x16x32_bf16 v[66:69], v[168:171], v[208:211], v[66:69]
	s_setprio 0
	s_barrier
	s_add_i32 s33, s33, s34
	v_lshl_add_u64 v[184:185], s[14:15], 0, v[130:131]
	s_mov_b32 m0, s33
	ds_read_b128 v[172:175], v158 offset:16384
	ds_read_b128 v[176:179], v158 offset:17408
	ds_read_b128 v[188:191], v158 offset:18432
	ds_read_b128 v[192:195], v158 offset:19456
	ds_read_b128 v[196:199], v158 offset:20480
	ds_read_b128 v[200:203], v158 offset:21504
	ds_read_b128 v[204:207], v158 offset:22528
	ds_read_b128 v[208:211], v158 offset:23552
	global_load_lds_dwordx4 v[184:185], off
	s_add_i32 m0, s33, 0x2000
	s_add_u32 s40, s14, 0x80000
	v_lshl_add_u64 v[212:213], s[14:15], 0, v[132:133]
	s_addc_u32 s41, s15, 0
	s_add_i32 s33, s52, s34
	global_load_lds_dwordx4 v[212:213], off
	v_lshl_add_u64 v[214:215], s[40:41], 0, v[130:131]
	s_mov_b32 m0, s33
	v_lshl_add_u64 v[216:217], s[28:29], 0, v[132:133]
	global_load_lds_dwordx4 v[214:215], off
	v_lshl_add_u64 v[214:215], s[40:41], 0, v[132:133]
	s_add_i32 m0, s33, 0x2000
	s_nop 0
	global_load_lds_dwordx4 v[214:215], off
	v_lshl_add_u64 v[214:215], s[28:29], 0, v[130:131]
	s_mov_b32 m0, s35
	s_nop 0
	global_load_lds_dwordx4 v[214:215], off
	s_mov_b32 m0, s42
	s_nop 0
	global_load_lds_dwordx4 v[216:217], off
	s_waitcnt vmcnt(8)
	s_waitcnt lgkmcnt(0)
	s_barrier
; #define PG8_STAGE(bufoff, gbase, voff) do { _Pragma("unroll") for (int _i = 0; _i < 2; ++_i) \
;         __builtin_amdgcn_global_load_lds((const unsigned*)((const char*)(gbase) + (voff)[_i]), (LAS unsigned*)(lds + (bufoff) + ldsw + _i * 8192), 16, 0, 0); } while (0)
; #define PG8_LDA(dst, b, h) do { _Pragma("unroll") for (int m = 0; m < 4; ++m) _Pragma("unroll") for (int k = 0; k < 2; ++k) dst[m][k] = *(const LAS bf16x8*)(lds + PG8_SA(b, h) + aoff + m * 2048 + k * 1024); } while (0)
; #define PG8_LDB(dst, b, h) do { _Pragma("unroll") for (int n = 0; n < 2; ++n) _Pragma("unroll") for (int k = 0; k < 2; ++k) dst[n][k] = *(const LAS bf16x8*)(lds + PG8_SB(b, h) + boff + n * 2048 + k * 1024); } while (0)
; #define PG8_MMA(ai, bj, At, Bt) do { __builtin_amdgcn_s_setprio(1); _Pragma("unroll") for (int m = 0; m < 4; ++m) _Pragma("unroll") for (int n = 0; n < 2; ++n) _Pragma("unroll") for (int k = 0; k < 2; ++k) \
;         acc[ai][bj][m][n] = __builtin_amdgcn_mfma_f32_16x16x32_bf16(Bt[n][k], At[m][k], acc[ai][bj][m][n], 0, 0, 0); __builtin_amdgcn_s_setprio(0); } while (0)
; #define PG8_WAIT_V(n) asm volatile("s_waitcnt vmcnt(" #n ")" ::: "memory")
; #define PG8_WAIT_L(n) asm volatile("s_waitcnt lgkmcnt(" #n ")" ::: "memory")
; #define PG8_BAR __builtin_amdgcn_s_barrier()
; #define PG8_SCHED __builtin_amdgcn_sched_barrier(0)
; template <class Epi>
; __device__ __forceinline__ void gemm_phase(LAS unsigned char* lds, const Gemm g, const StaticOrder& S, const Epi& E) {
;     ...
;             PG8_WAIT_V(8); PG8_WAIT_L(0); PG8_BAR; PG8_MMA(1, 0, At, B0); PG8_MMA(1, 1, At, B1); PG8_BAR; PG8_SCHED;
;             PG8_LDB(B0, 1, 0); PG8_LDB(B1, 1, 1); PG8_SCHED; PG8_LDA(At, 1, 0); PG8_STAGE(PG8_SA(0, 1), a2 + hstepA, voffA);
;             PG8_WAIT_V(8); PG8_WAIT_L(0); PG8_BAR; PG8_MMA(0, 0, At, B0); PG8_MMA(0, 1, At, B1); PG8_BAR; PG8_SCHED;
	s_setprio 1
	s_waitcnt lgkmcnt(0)
	v_mfma_f32_16x16x32_bf16 v[62:65], v[138:141], v[172:175], v[62:65]
	v_mfma_f32_16x16x32_bf16 v[58:61], v[146:149], v[172:175], v[58:61]
	v_mfma_f32_16x16x32_bf16 v[46:49], v[138:141], v[188:191], v[46:49]
	v_mfma_f32_16x16x32_bf16 v[42:45], v[146:149], v[188:191], v[42:45]
	v_mfma_f32_16x16x32_bf16 v[30:33], v[138:141], v[196:199], v[30:33]
	v_mfma_f32_16x16x32_bf16 v[26:29], v[146:149], v[196:199], v[26:29]
	v_mfma_f32_16x16x32_bf16 v[14:17], v[138:141], v[204:207], v[14:17]
	v_mfma_f32_16x16x32_bf16 v[10:13], v[146:149], v[204:207], v[10:13]
	v_mfma_f32_16x16x32_bf16 v[62:65], v[142:145], v[176:179], v[62:65]
	v_mfma_f32_16x16x32_bf16 v[58:61], v[150:153], v[176:179], v[58:61]
	v_mfma_f32_16x16x32_bf16 v[46:49], v[142:145], v[192:195], v[46:49]
	v_mfma_f32_16x16x32_bf16 v[42:45], v[150:153], v[192:195], v[42:45]
	v_mfma_f32_16x16x32_bf16 v[30:33], v[142:145], v[200:203], v[30:33]
	v_mfma_f32_16x16x32_bf16 v[26:29], v[150:153], v[200:203], v[26:29]
	v_mfma_f32_16x16x32_bf16 v[14:17], v[142:145], v[208:211], v[14:17]
	v_mfma_f32_16x16x32_bf16 v[10:13], v[150:153], v[208:211], v[10:13]
	v_mfma_f32_16x16x32_bf16 v[54:57], v[154:157], v[172:175], v[54:57]
	v_mfma_f32_16x16x32_bf16 v[50:53], v[164:167], v[172:175], v[50:53]
	v_mfma_f32_16x16x32_bf16 v[38:41], v[154:157], v[188:191], v[38:41]
	v_mfma_f32_16x16x32_bf16 v[34:37], v[164:167], v[188:191], v[34:37]
	v_mfma_f32_16x16x32_bf16 v[22:25], v[154:157], v[196:199], v[22:25]
	v_mfma_f32_16x16x32_bf16 v[18:21], v[164:167], v[196:199], v[18:21]
	v_mfma_f32_16x16x32_bf16 v[6:9], v[154:157], v[204:207], v[6:9]
	v_mfma_f32_16x16x32_bf16 v[2:5], v[164:167], v[204:207], v[2:5]
	v_mfma_f32_16x16x32_bf16 v[54:57], v[160:163], v[176:179], v[54:57]
	v_mfma_f32_16x16x32_bf16 v[50:53], v[168:171], v[176:179], v[50:53]
	v_mfma_f32_16x16x32_bf16 v[38:41], v[160:163], v[192:195], v[38:41]
	v_mfma_f32_16x16x32_bf16 v[34:37], v[168:171], v[192:195], v[34:37]
	v_mfma_f32_16x16x32_bf16 v[22:25], v[160:163], v[200:203], v[22:25]
	v_mfma_f32_16x16x32_bf16 v[18:21], v[168:171], v[200:203], v[18:21]
	v_mfma_f32_16x16x32_bf16 v[6:9], v[160:163], v[208:211], v[6:9]
	v_mfma_f32_16x16x32_bf16 v[2:5], v[168:171], v[208:211], v[2:5]
	s_setprio 0
	s_barrier
	s_add_i32 s33, 0, 0x18000
	s_add_i32 s40, 0, 0x1c000
	v_add_u32_e32 v150, s33, v1
	v_add_u32_e32 v159, s40, v1
	ds_read_b128 v[138:141], v150
	ds_read_b128 v[142:145], v150 offset:1024
	ds_read_b128 v[146:149], v150 offset:2048
	ds_read_b128 v[150:153], v150 offset:3072
	ds_read_b128 v[154:157], v159
	ds_read_b128 v[160:163], v159 offset:1024
	ds_read_b128 v[164:167], v159 offset:2048
	ds_read_b128 v[168:171], v159 offset:3072
	s_add_u32 s28, s28, 0x80000
	s_addc_u32 s29, s29, 0
	s_mov_b32 m0, s45
	v_lshl_add_u64 v[218:219], s[28:29], 0, v[130:131]
	ds_read_b128 v[172:175], v158 offset:32768
	ds_read_b128 v[176:179], v158 offset:33792
	ds_read_b128 v[188:191], v158 offset:34816
	ds_read_b128 v[192:195], v158 offset:35840
	ds_read_b128 v[196:199], v158 offset:36864
	ds_read_b128 v[200:203], v158 offset:37888
	ds_read_b128 v[204:207], v158 offset:38912
	ds_read_b128 v[208:211], v158 offset:39936
	global_load_lds_dwordx4 v[218:219], off
	v_lshl_add_u64 v[218:219], s[28:29], 0, v[132:133]
	s_mov_b32 m0, s68
	s_nop 0
	global_load_lds_dwordx4 v[218:219], off
	s_waitcnt vmcnt(8)
	s_waitcnt lgkmcnt(0)
	s_barrier
	s_setprio 1
	s_waitcnt lgkmcnt(0)
	v_mfma_f32_16x16x32_bf16 v[126:129], v[138:141], v[172:175], v[126:129]
	v_mfma_f32_16x16x32_bf16 v[122:125], v[146:149], v[172:175], v[122:125]
	v_mfma_f32_16x16x32_bf16 v[110:113], v[138:141], v[188:191], v[110:113]
	v_mfma_f32_16x16x32_bf16 v[106:109], v[146:149], v[188:191], v[106:109]
	v_mfma_f32_16x16x32_bf16 v[94:97], v[138:141], v[196:199], v[94:97]
	v_mfma_f32_16x16x32_bf16 v[90:93], v[146:149], v[196:199], v[90:93]
	v_mfma_f32_16x16x32_bf16 v[78:81], v[138:141], v[204:207], v[78:81]
	v_mfma_f32_16x16x32_bf16 v[74:77], v[146:149], v[204:207], v[74:77]
	v_mfma_f32_16x16x32_bf16 v[126:129], v[142:145], v[176:179], v[126:129]
	v_mfma_f32_16x16x32_bf16 v[122:125], v[150:153], v[176:179], v[122:125]
	v_mfma_f32_16x16x32_bf16 v[110:113], v[142:145], v[192:195], v[110:113]
	v_mfma_f32_16x16x32_bf16 v[106:109], v[150:153], v[192:195], v[106:109]
	v_mfma_f32_16x16x32_bf16 v[94:97], v[142:145], v[200:203], v[94:97]
	v_mfma_f32_16x16x32_bf16 v[90:93], v[150:153], v[200:203], v[90:93]
	v_mfma_f32_16x16x32_bf16 v[78:81], v[142:145], v[208:211], v[78:81]
	v_mfma_f32_16x16x32_bf16 v[74:77], v[150:153], v[208:211], v[74:77]
	v_mfma_f32_16x16x32_bf16 v[118:121], v[154:157], v[172:175], v[118:121]
	v_mfma_f32_16x16x32_bf16 v[114:117], v[164:167], v[172:175], v[114:117]
	v_mfma_f32_16x16x32_bf16 v[102:105], v[154:157], v[188:191], v[102:105]
	v_mfma_f32_16x16x32_bf16 v[98:101], v[164:167], v[188:191], v[98:101]
	v_mfma_f32_16x16x32_bf16 v[86:89], v[154:157], v[196:199], v[86:89]
	v_mfma_f32_16x16x32_bf16 v[82:85], v[164:167], v[196:199], v[82:85]
	v_mfma_f32_16x16x32_bf16 v[70:73], v[154:157], v[204:207], v[70:73]
	v_mfma_f32_16x16x32_bf16 v[66:69], v[164:167], v[204:207], v[66:69]
	v_mfma_f32_16x16x32_bf16 v[118:121], v[160:163], v[176:179], v[118:121]
	v_mfma_f32_16x16x32_bf16 v[114:117], v[168:171], v[176:179], v[114:117]
	v_mfma_f32_16x16x32_bf16 v[102:105], v[160:163], v[192:195], v[102:105]
	v_mfma_f32_16x16x32_bf16 v[98:101], v[168:171], v[192:195], v[98:101]
	v_mfma_f32_16x16x32_bf16 v[86:89], v[160:163], v[200:203], v[86:89]
	v_mfma_f32_16x16x32_bf16 v[82:85], v[168:171], v[200:203], v[82:85]
	v_mfma_f32_16x16x32_bf16 v[70:73], v[160:163], v[208:211], v[70:73]
	v_mfma_f32_16x16x32_bf16 v[66:69], v[168:171], v[208:211], v[66:69]
	s_setprio 0
	s_barrier
; #define PG8_STAGE(bufoff, gbase, voff) do { _Pragma("unroll") for (int _i = 0; _i < 2; ++_i) \
;         __builtin_amdgcn_global_load_lds((const unsigned*)((const char*)(gbase) + (voff)[_i]), (LAS unsigned*)(lds + (bufoff) + ldsw + _i * 8192), 16, 0, 0); } while (0)
; #define PG8_LDA(dst, b, h) do { _Pragma("unroll") for (int m = 0; m < 4; ++m) _Pragma("unroll") for (int k = 0; k < 2; ++k) dst[m][k] = *(const LAS bf16x8*)(lds + PG8_SA(b, h) + aoff + m * 2048 + k * 1024); } while (0)
; #define PG8_MMA(ai, bj, At, Bt) do { __builtin_amdgcn_s_setprio(1); _Pragma("unroll") for (int m = 0; m < 4; ++m) _Pragma("unroll") for (int n = 0; n < 2; ++n) _Pragma("unroll") for (int k = 0; k < 2; ++k) \
;         acc[ai][bj][m][n] = __builtin_amdgcn_mfma_f32_16x16x32_bf16(Bt[n][k], At[m][k], acc[ai][bj][m][n], 0, 0, 0); __builtin_amdgcn_s_setprio(0); } while (0)
; #define PG8_WAIT_V(n) asm volatile("s_waitcnt vmcnt(" #n ")" ::: "memory")
; #define PG8_WAIT_L(n) asm volatile("s_waitcnt lgkmcnt(" #n ")" ::: "memory")
; #define PG8_BAR __builtin_amdgcn_s_barrier()
; #define PG8_SCHED __builtin_amdgcn_sched_barrier(0)
; template <class Epi>
; __device__ __forceinline__ void gemm_phase(LAS unsigned char* lds, const Gemm g, const StaticOrder& S, const Epi& E) {
;     ...
;             PG8_LDA(At, 1, 1); PG8_STAGE(PG8_SB(1, 0), b3, voffB); PG8_STAGE(PG8_SB(1, 1), b3 + hstepB, voffB); PG8_STAGE(PG8_SA(1, 0), a3, voffA);
;             PG8_WAIT_V(8); PG8_WAIT_L(0); PG8_BAR; PG8_MMA(1, 0, At, B0); PG8_MMA(1, 1, At, B1); PG8_BAR; PG8_SCHED;
;         }
;         if (wr == 0) PG8_BAR;
	s_add_i32 s28, s33, s34
	v_lshl_add_u64 v[184:185], v[184:185], 0, s[84:85]
	s_mov_b32 m0, s28
	ds_read_b128 v[172:175], v158 offset:49152
	ds_read_b128 v[176:179], v158 offset:50176
	ds_read_b128 v[188:191], v158 offset:51200
	ds_read_b128 v[192:195], v158 offset:52224
	ds_read_b128 v[196:199], v158 offset:53248
	ds_read_b128 v[200:203], v158 offset:54272
	ds_read_b128 v[204:207], v158 offset:55296
	ds_read_b128 v[208:211], v158 offset:56320
	global_load_lds_dwordx4 v[184:185], off
	s_add_i32 m0, s28, 0x2000
	s_add_u32 s14, s14, 0x80080
	v_lshl_add_u64 v[184:185], v[212:213], 0, s[84:85]
	s_addc_u32 s15, s15, 0
	s_add_i32 s28, s40, s34
	global_load_lds_dwordx4 v[184:185], off
	v_lshl_add_u64 v[184:185], s[14:15], 0, v[130:131]
	s_mov_b32 m0, s28
	s_nop 0
	global_load_lds_dwordx4 v[184:185], off
	v_lshl_add_u64 v[184:185], s[14:15], 0, v[132:133]
	s_add_i32 m0, s28, 0x2000
	s_nop 0
	global_load_lds_dwordx4 v[184:185], off
	v_lshl_add_u64 v[184:185], v[214:215], 0, s[84:85]
	s_mov_b32 m0, s87
	s_nop 0
	global_load_lds_dwordx4 v[184:185], off
	v_lshl_add_u64 v[184:185], v[216:217], 0, s[84:85]
	s_mov_b32 m0, s91
	s_nop 0
	global_load_lds_dwordx4 v[184:185], off
	s_waitcnt vmcnt(8)
	s_waitcnt lgkmcnt(0)
	s_barrier
	s_setprio 1
	s_waitcnt lgkmcnt(0)
	v_mfma_f32_16x16x32_bf16 v[62:65], v[138:141], v[172:175], v[62:65]
	v_mfma_f32_16x16x32_bf16 v[58:61], v[146:149], v[172:175], v[58:61]
	v_mfma_f32_16x16x32_bf16 v[46:49], v[138:141], v[188:191], v[46:49]
	v_mfma_f32_16x16x32_bf16 v[42:45], v[146:149], v[188:191], v[42:45]
	v_mfma_f32_16x16x32_bf16 v[30:33], v[138:141], v[196:199], v[30:33]
	v_mfma_f32_16x16x32_bf16 v[26:29], v[146:149], v[196:199], v[26:29]
	v_mfma_f32_16x16x32_bf16 v[14:17], v[138:141], v[204:207], v[14:17]
	v_mfma_f32_16x16x32_bf16 v[10:13], v[146:149], v[204:207], v[10:13]
	v_mfma_f32_16x16x32_bf16 v[62:65], v[142:145], v[176:179], v[62:65]
	v_mfma_f32_16x16x32_bf16 v[58:61], v[150:153], v[176:179], v[58:61]
	v_mfma_f32_16x16x32_bf16 v[46:49], v[142:145], v[192:195], v[46:49]
	v_mfma_f32_16x16x32_bf16 v[42:45], v[150:153], v[192:195], v[42:45]
	v_mfma_f32_16x16x32_bf16 v[30:33], v[142:145], v[200:203], v[30:33]
	v_mfma_f32_16x16x32_bf16 v[26:29], v[150:153], v[200:203], v[26:29]
	v_mfma_f32_16x16x32_bf16 v[14:17], v[142:145], v[208:211], v[14:17]
	v_mfma_f32_16x16x32_bf16 v[10:13], v[150:153], v[208:211], v[10:13]
	v_mfma_f32_16x16x32_bf16 v[54:57], v[154:157], v[172:175], v[54:57]
	v_mfma_f32_16x16x32_bf16 v[50:53], v[164:167], v[172:175], v[50:53]
	v_mfma_f32_16x16x32_bf16 v[38:41], v[154:157], v[188:191], v[38:41]
	v_mfma_f32_16x16x32_bf16 v[34:37], v[164:167], v[188:191], v[34:37]
	v_mfma_f32_16x16x32_bf16 v[22:25], v[154:157], v[196:199], v[22:25]
	v_mfma_f32_16x16x32_bf16 v[18:21], v[164:167], v[196:199], v[18:21]
	v_mfma_f32_16x16x32_bf16 v[6:9], v[154:157], v[204:207], v[6:9]
	v_mfma_f32_16x16x32_bf16 v[2:5], v[164:167], v[204:207], v[2:5]
	v_mfma_f32_16x16x32_bf16 v[54:57], v[160:163], v[176:179], v[54:57]
	v_mfma_f32_16x16x32_bf16 v[50:53], v[168:171], v[176:179], v[50:53]
	v_mfma_f32_16x16x32_bf16 v[38:41], v[160:163], v[192:195], v[38:41]
	v_mfma_f32_16x16x32_bf16 v[34:37], v[168:171], v[192:195], v[34:37]
	v_mfma_f32_16x16x32_bf16 v[22:25], v[160:163], v[200:203], v[22:25]
	v_mfma_f32_16x16x32_bf16 v[18:21], v[168:171], v[200:203], v[18:21]
	v_mfma_f32_16x16x32_bf16 v[6:9], v[160:163], v[208:211], v[6:9]
	v_mfma_f32_16x16x32_bf16 v[2:5], v[168:171], v[208:211], v[2:5]
	s_setprio 0
	s_barrier
	s_add_i32 s21, s21, 2
	s_add_u32 s26, s26, 0x100
	s_addc_u32 s27, s27, 0
	s_add_u32 s9, s9, 0x100
	s_addc_u32 s19, s19, 0
	s_cmp_gt_u32 s21, 29
	s_cbranch_scc0 .LBB0_414
	s_and_b64 vcc, exec, s[16:17]
	s_cbranch_vccz .LBB0_417
	s_barrier

; #define PG8_STAGE(bufoff, gbase, voff) do { _Pragma("unroll") for (int _i = 0; _i < 2; ++_i) \
;         __builtin_amdgcn_global_load_lds((const unsigned*)((const char*)(gbase) + (voff)[_i]), (LAS unsigned*)(lds + (bufoff) + ldsw + _i * 8192), 16, 0, 0); } while (0)
; #define PG8_LDA(dst, b, h) do { _Pragma("unroll") for (int m = 0; m < 4; ++m) _Pragma("unroll") for (int k = 0; k < 2; ++k) dst[m][k] = *(const LAS bf16x8*)(lds + PG8_SA(b, h) + aoff + m * 2048 + k * 1024); } while (0)
; #define PG8_LDB(dst, b, h) do { _Pragma("unroll") for (int n = 0; n < 2; ++n) _Pragma("unroll") for (int k = 0; k < 2; ++k) dst[n][k] = *(const LAS bf16x8*)(lds + PG8_SB(b, h) + boff + n * 2048 + k * 1024); } while (0)
; #define PG8_MMA(ai, bj, At, Bt) do { __builtin_amdgcn_s_setprio(1); _Pragma("unroll") for (int m = 0; m < 4; ++m) _Pragma("unroll") for (int n = 0; n < 2; ++n) _Pragma("unroll") for (int k = 0; k < 2; ++k) \
;         acc[ai][bj][m][n] = __builtin_amdgcn_mfma_f32_16x16x32_bf16(Bt[n][k], At[m][k], acc[ai][bj][m][n], 0, 0, 0); __builtin_amdgcn_s_setprio(0); } while (0)
; #define PG8_WAIT_V(n) asm volatile("s_waitcnt vmcnt(" #n ")" ::: "memory")
; #define PG8_BAR __builtin_amdgcn_s_barrier()
; template <class Epi>
; __device__ __forceinline__ void gemm_phase(LAS unsigned char* lds, const Gemm g, const StaticOrder& S, const Epi& E) {
;     ...
;         const bool has_next = S.next(ui + 1, nxt);
;         const char* nA = has_next ? PG8_UA(nxt) : cA; const char* nB = has_next ? PG8_UB(nxt) : cB;
;         for (int t = 0; t < nt; t += 2) {
;             const bool last = (t == nt - 2);
;             const char* a1 = cA + (size_t)(t + 1) * kstep;
;             const char* a2 = last ? nA : cA + (size_t)(t + 2) * kstep; const char* b2 = last ? nB : cB + (size_t)(t + 2) * kstep;
;             const char* a3 = a2 + kstep; const char* b3 = b2 + kstep;
;             PG8_LDB(B0, 0, 0); PG8_LDB(B1, 0, 1); PG8_SCHED; PG8_LDA(At, 0, 0); PG8_STAGE(PG8_SA(1, 1), a1 + hstepA, voffA);
;             PG8_WAIT_V(8); PG8_WAIT_L(0); PG8_BAR; PG8_MMA(0, 0, At, B0); PG8_MMA(0, 1, At, B1); PG8_BAR; PG8_SCHED;
;             PG8_LDA(At, 0, 1); PG8_STAGE(PG8_SB(0, 0), b2, voffB); PG8_STAGE(PG8_SB(0, 1), b2 + hstepB, voffB); PG8_STAGE(PG8_SA(0, 0), a2, voffA);
;             PG8_WAIT_V(8); PG8_WAIT_L(0); PG8_BAR; PG8_MMA(1, 0, At, B0); PG8_MMA(1, 1, At, B1); PG8_BAR; PG8_SCHED;
.LBB0_682:
	s_ashr_i32 s21, s20, 31
	s_lshl_b64 s[26:27], s[20:21], 17
	v_readlane_b32 s40, v254, 33
	v_readlane_b32 s41, v254, 34
	s_add_u32 s26, s40, s26
	s_addc_u32 s27, s41, s27
	s_and_b64 s[6:7], s[6:7], exec
	s_cselect_b32 s7, s27, s35
	s_cselect_b32 s6, s26, s34
	s_add_i32 s33, 0, 0x10000
	s_add_i32 s21, 0, 0x14000
	v_add_u32_e32 v147, s33, v1
	v_add_u32_e32 v181, s21, v1
	ds_read_b128 v[2:5], v147
	ds_read_b128 v[6:9], v147 offset:1024
	ds_read_b128 v[10:13], v147 offset:2048
	ds_read_b128 v[14:17], v147 offset:3072
	ds_read_b128 v[18:21], v181
	ds_read_b128 v[22:25], v181 offset:1024
	ds_read_b128 v[26:29], v181 offset:2048
	ds_read_b128 v[30:33], v181 offset:3072
	s_add_u32 s52, s30, 0x80080
	s_addc_u32 s53, s31, 0
	s_add_i32 s41, s14, 0xc000
	v_lshl_add_u64 v[66:67], s[52:53], 0, v[130:131]
	s_mov_b32 m0, s41
	s_add_i32 s1, s14, 0xe000
	ds_read_b128 v[34:37], v146
	ds_read_b128 v[38:41], v146 offset:1024
	ds_read_b128 v[42:45], v146 offset:2048
	ds_read_b128 v[46:49], v146 offset:3072
	ds_read_b128 v[50:53], v146 offset:4096
	ds_read_b128 v[54:57], v146 offset:5120
	ds_read_b128 v[58:61], v146 offset:6144
	ds_read_b128 v[62:65], v146 offset:7168
	global_load_lds_dwordx4 v[66:67], off
	v_lshl_add_u64 v[66:67], s[52:53], 0, v[134:135]
	s_mov_b32 m0, s1
	s_nop 0
	global_load_lds_dwordx4 v[66:67], off
	s_waitcnt vmcnt(8)
	s_waitcnt lgkmcnt(0)
	s_barrier
	s_setprio 1
	s_waitcnt lgkmcnt(0)
	v_mfma_f32_16x16x32_bf16 v[66:69], v[2:5], v[34:37], 0
	v_mfma_f32_16x16x32_bf16 v[70:73], v[10:13], v[34:37], 0
	v_mfma_f32_16x16x32_bf16 v[74:77], v[2:5], v[42:45], 0
	v_mfma_f32_16x16x32_bf16 v[78:81], v[10:13], v[42:45], 0
	v_mfma_f32_16x16x32_bf16 v[82:85], v[2:5], v[50:53], 0
	v_mfma_f32_16x16x32_bf16 v[86:89], v[10:13], v[50:53], 0
	v_mfma_f32_16x16x32_bf16 v[90:93], v[2:5], v[58:61], 0
	v_mfma_f32_16x16x32_bf16 v[94:97], v[10:13], v[58:61], 0
	v_mfma_f32_16x16x32_bf16 v[66:69], v[6:9], v[38:41], v[66:69]
	v_mfma_f32_16x16x32_bf16 v[70:73], v[14:17], v[38:41], v[70:73]
	v_mfma_f32_16x16x32_bf16 v[74:77], v[6:9], v[46:49], v[74:77]
	v_mfma_f32_16x16x32_bf16 v[78:81], v[14:17], v[46:49], v[78:81]
	v_mfma_f32_16x16x32_bf16 v[82:85], v[6:9], v[54:57], v[82:85]
	v_mfma_f32_16x16x32_bf16 v[86:89], v[14:17], v[54:57], v[86:89]
	v_mfma_f32_16x16x32_bf16 v[90:93], v[6:9], v[62:65], v[90:93]
	v_mfma_f32_16x16x32_bf16 v[94:97], v[14:17], v[62:65], v[94:97]
	v_mfma_f32_16x16x32_bf16 v[98:101], v[18:21], v[34:37], 0
	v_mfma_f32_16x16x32_bf16 v[34:37], v[26:29], v[34:37], 0
	v_mfma_f32_16x16x32_bf16 v[98:101], v[22:25], v[38:41], v[98:101]
	v_mfma_f32_16x16x32_bf16 v[34:37], v[30:33], v[38:41], v[34:37]
	v_mfma_f32_16x16x32_bf16 v[38:41], v[18:21], v[42:45], 0
	v_mfma_f32_16x16x32_bf16 v[42:45], v[26:29], v[42:45], 0
	v_mfma_f32_16x16x32_bf16 v[38:41], v[22:25], v[46:49], v[38:41]
	v_mfma_f32_16x16x32_bf16 v[42:45], v[30:33], v[46:49], v[42:45]
	v_mfma_f32_16x16x32_bf16 v[46:49], v[18:21], v[50:53], 0
	v_mfma_f32_16x16x32_bf16 v[50:53], v[26:29], v[50:53], 0
	v_mfma_f32_16x16x32_bf16 v[46:49], v[22:25], v[54:57], v[46:49]
	v_mfma_f32_16x16x32_bf16 v[50:53], v[30:33], v[54:57], v[50:53]
	v_mfma_f32_16x16x32_bf16 v[54:57], v[18:21], v[58:61], 0
	v_mfma_f32_16x16x32_bf16 v[58:61], v[26:29], v[58:61], 0
	v_mfma_f32_16x16x32_bf16 v[54:57], v[22:25], v[62:65], v[54:57]
	v_mfma_f32_16x16x32_bf16 v[58:61], v[30:33], v[62:65], v[58:61]
	s_setprio 0
	s_barrier
	s_add_i32 s33, s33, s11
	v_lshl_add_u64 v[184:185], s[34:35], 0, v[132:133]
	s_mov_b64 s[62:63], 0x100
	s_add_i32 s3, s33, 0x2000
	v_lshl_add_u64 v[138:139], v[184:185], 0, s[62:63]
	s_mov_b32 m0, s33
	v_lshl_add_u64 v[212:213], s[34:35], 0, v[136:137]
	s_add_u32 s52, s34, 0x10100
	ds_read_b128 v[62:65], v146 offset:16384
	ds_read_b128 v[102:105], v146 offset:17408
	ds_read_b128 v[106:109], v146 offset:18432
	ds_read_b128 v[110:113], v146 offset:19456
	ds_read_b128 v[114:117], v146 offset:20480
	ds_read_b128 v[118:121], v146 offset:21504
	ds_read_b128 v[122:125], v146 offset:22528
	ds_read_b128 v[126:129], v146 offset:23552
	global_load_lds_dwordx4 v[138:139], off
	v_lshl_add_u64 v[138:139], v[212:213], 0, s[62:63]
	s_mov_b32 m0, s3
	s_addc_u32 s53, s35, 0
	s_add_i32 s21, s21, s11
	global_load_lds_dwordx4 v[138:139], off
	v_lshl_add_u64 v[138:139], s[52:53], 0, v[132:133]
	s_mov_b32 m0, s21
	s_add_i32 s23, s21, 0x2000
	global_load_lds_dwordx4 v[138:139], off
	v_lshl_add_u64 v[138:139], s[52:53], 0, v[136:137]
	s_mov_b32 m0, s23
	v_lshl_add_u64 v[214:215], s[30:31], 0, v[130:131]
	global_load_lds_dwordx4 v[138:139], off
	v_lshl_add_u64 v[138:139], v[214:215], 0, s[62:63]
	s_mov_b32 m0, s14
	v_lshl_add_u64 v[216:217], s[30:31], 0, v[134:135]
	global_load_lds_dwordx4 v[138:139], off
	v_lshl_add_u64 v[138:139], v[216:217], 0, s[62:63]
	s_mov_b32 m0, s15
	s_nop 0
	global_load_lds_dwordx4 v[138:139], off
	s_waitcnt vmcnt(8)
	s_waitcnt lgkmcnt(0)
	s_barrier
; #define PG8_STAGE(bufoff, gbase, voff) do { _Pragma("unroll") for (int _i = 0; _i < 2; ++_i) \
;         __builtin_amdgcn_global_load_lds((const unsigned*)((const char*)(gbase) + (voff)[_i]), (LAS unsigned*)(lds + (bufoff) + ldsw + _i * 8192), 16, 0, 0); } while (0)
; #define PG8_LDA(dst, b, h) do { _Pragma("unroll") for (int m = 0; m < 4; ++m) _Pragma("unroll") for (int k = 0; k < 2; ++k) dst[m][k] = *(const LAS bf16x8*)(lds + PG8_SA(b, h) + aoff + m * 2048 + k * 1024); } while (0)
; #define PG8_LDB(dst, b, h) do { _Pragma("unroll") for (int n = 0; n < 2; ++n) _Pragma("unroll") for (int k = 0; k < 2; ++k) dst[n][k] = *(const LAS bf16x8*)(lds + PG8_SB(b, h) + boff + n * 2048 + k * 1024); } while (0)
; #define PG8_MMA(ai, bj, At, Bt) do { __builtin_amdgcn_s_setprio(1); _Pragma("unroll") for (int m = 0; m < 4; ++m) _Pragma("unroll") for (int n = 0; n < 2; ++n) _Pragma("unroll") for (int k = 0; k < 2; ++k) \
;         acc[ai][bj][m][n] = __builtin_amdgcn_mfma_f32_16x16x32_bf16(Bt[n][k], At[m][k], acc[ai][bj][m][n], 0, 0, 0); __builtin_amdgcn_s_setprio(0); } while (0)
; #define PG8_WAIT_V(n) asm volatile("s_waitcnt vmcnt(" #n ")" ::: "memory")
; #define PG8_WAIT_L(n) asm volatile("s_waitcnt lgkmcnt(" #n ")" ::: "memory")
; #define PG8_BAR __builtin_amdgcn_s_barrier()
; #define PG8_SCHED __builtin_amdgcn_sched_barrier(0)
; template <class Epi>
; __device__ __forceinline__ void gemm_phase(LAS unsigned char* lds, const Gemm g, const StaticOrder& S, const Epi& E) {
;     ...
;             PG8_WAIT_V(8); PG8_WAIT_L(0); PG8_BAR; PG8_MMA(1, 0, At, B0); PG8_MMA(1, 1, At, B1); PG8_BAR; PG8_SCHED;
;             PG8_LDB(B0, 1, 0); PG8_LDB(B1, 1, 1); PG8_SCHED; PG8_LDA(At, 1, 0); PG8_STAGE(PG8_SA(0, 1), a2 + hstepA, voffA);
;             PG8_WAIT_V(8); PG8_WAIT_L(0); PG8_BAR; PG8_MMA(0, 0, At, B0); PG8_MMA(0, 1, At, B1); PG8_BAR; PG8_SCHED;
	s_setprio 1
	s_waitcnt lgkmcnt(0)
	v_mfma_f32_16x16x32_bf16 v[138:141], v[2:5], v[62:65], 0
	v_mfma_f32_16x16x32_bf16 v[148:151], v[2:5], v[106:109], 0
	v_mfma_f32_16x16x32_bf16 v[156:159], v[2:5], v[114:117], 0
	v_mfma_f32_16x16x32_bf16 v[2:5], v[2:5], v[122:125], 0
	v_mfma_f32_16x16x32_bf16 v[138:141], v[6:9], v[102:105], v[138:141]
	v_mfma_f32_16x16x32_bf16 v[148:151], v[6:9], v[110:113], v[148:151]
	v_mfma_f32_16x16x32_bf16 v[156:159], v[6:9], v[118:121], v[156:159]
	v_mfma_f32_16x16x32_bf16 v[2:5], v[6:9], v[126:129], v[2:5]
	v_mfma_f32_16x16x32_bf16 v[6:9], v[10:13], v[122:125], 0
	v_mfma_f32_16x16x32_bf16 v[142:145], v[10:13], v[62:65], 0
	v_mfma_f32_16x16x32_bf16 v[152:155], v[10:13], v[106:109], 0
	v_mfma_f32_16x16x32_bf16 v[160:163], v[10:13], v[114:117], 0
	v_mfma_f32_16x16x32_bf16 v[6:9], v[14:17], v[126:129], v[6:9]
	v_mfma_f32_16x16x32_bf16 v[142:145], v[14:17], v[102:105], v[142:145]
	v_mfma_f32_16x16x32_bf16 v[152:155], v[14:17], v[110:113], v[152:155]
	v_mfma_f32_16x16x32_bf16 v[160:163], v[14:17], v[118:121], v[160:163]
	v_mfma_f32_16x16x32_bf16 v[10:13], v[18:21], v[62:65], 0
	v_mfma_f32_16x16x32_bf16 v[14:17], v[26:29], v[62:65], 0
	v_mfma_f32_16x16x32_bf16 v[10:13], v[22:25], v[102:105], v[10:13]
	v_mfma_f32_16x16x32_bf16 v[14:17], v[30:33], v[102:105], v[14:17]
	v_mfma_f32_16x16x32_bf16 v[62:65], v[18:21], v[106:109], 0
	v_mfma_f32_16x16x32_bf16 v[102:105], v[26:29], v[106:109], 0
	v_mfma_f32_16x16x32_bf16 v[106:109], v[18:21], v[114:117], 0
	v_mfma_f32_16x16x32_bf16 v[18:21], v[18:21], v[122:125], 0
	v_mfma_f32_16x16x32_bf16 v[62:65], v[22:25], v[110:113], v[62:65]
	v_mfma_f32_16x16x32_bf16 v[102:105], v[30:33], v[110:113], v[102:105]
	v_mfma_f32_16x16x32_bf16 v[106:109], v[22:25], v[118:121], v[106:109]
	v_mfma_f32_16x16x32_bf16 v[110:113], v[26:29], v[114:117], 0
	v_mfma_f32_16x16x32_bf16 v[18:21], v[22:25], v[126:129], v[18:21]
	v_mfma_f32_16x16x32_bf16 v[22:25], v[26:29], v[122:125], 0
	v_mfma_f32_16x16x32_bf16 v[110:113], v[30:33], v[118:121], v[110:113]
	v_mfma_f32_16x16x32_bf16 v[22:25], v[30:33], v[126:129], v[22:25]
	s_setprio 0
	s_barrier
	s_add_i32 s40, 0, 0x18000
	s_add_i32 s64, 0, 0x1c000
	v_add_u32_e32 v183, s40, v1
	v_add_u32_e32 v186, s64, v1
	ds_read_b128 v[26:29], v183
	ds_read_b128 v[30:33], v183 offset:1024
	ds_read_b128 v[114:117], v183 offset:2048
	ds_read_b128 v[118:121], v183 offset:3072
	ds_read_b128 v[122:125], v186
	ds_read_b128 v[126:129], v186 offset:1024
	ds_read_b128 v[164:167], v186 offset:2048
	ds_read_b128 v[168:171], v186 offset:3072
	s_add_u32 s52, s30, 0x80100
	s_addc_u32 s53, s31, 0
	s_mov_b32 m0, s29
	v_lshl_add_u64 v[218:219], s[52:53], 0, v[130:131]
	ds_read_b128 v[172:175], v146 offset:32768
	ds_read_b128 v[176:179], v146 offset:33792
	ds_read_b128 v[188:191], v146 offset:34816
	ds_read_b128 v[192:195], v146 offset:35840
	ds_read_b128 v[196:199], v146 offset:36864
	ds_read_b128 v[200:203], v146 offset:37888
	ds_read_b128 v[204:207], v146 offset:38912
	ds_read_b128 v[208:211], v146 offset:39936
	global_load_lds_dwordx4 v[218:219], off
	v_lshl_add_u64 v[218:219], s[52:53], 0, v[134:135]
	s_mov_b32 m0, s42
	s_nop 0
	global_load_lds_dwordx4 v[218:219], off
	s_waitcnt vmcnt(8)
	s_waitcnt lgkmcnt(0)
	s_barrier
	s_setprio 1
	s_waitcnt lgkmcnt(0)
	v_mfma_f32_16x16x32_bf16 v[66:69], v[26:29], v[172:175], v[66:69]
	v_mfma_f32_16x16x32_bf16 v[70:73], v[114:117], v[172:175], v[70:73]
	v_mfma_f32_16x16x32_bf16 v[74:77], v[26:29], v[188:191], v[74:77]
	v_mfma_f32_16x16x32_bf16 v[78:81], v[114:117], v[188:191], v[78:81]
	v_mfma_f32_16x16x32_bf16 v[82:85], v[26:29], v[196:199], v[82:85]
	v_mfma_f32_16x16x32_bf16 v[86:89], v[114:117], v[196:199], v[86:89]
	v_mfma_f32_16x16x32_bf16 v[90:93], v[26:29], v[204:207], v[90:93]
	v_mfma_f32_16x16x32_bf16 v[94:97], v[114:117], v[204:207], v[94:97]
	v_mfma_f32_16x16x32_bf16 v[66:69], v[30:33], v[176:179], v[66:69]
	v_mfma_f32_16x16x32_bf16 v[70:73], v[118:121], v[176:179], v[70:73]
	v_mfma_f32_16x16x32_bf16 v[74:77], v[30:33], v[192:195], v[74:77]
	v_mfma_f32_16x16x32_bf16 v[78:81], v[118:121], v[192:195], v[78:81]
	v_mfma_f32_16x16x32_bf16 v[82:85], v[30:33], v[200:203], v[82:85]
	v_mfma_f32_16x16x32_bf16 v[86:89], v[118:121], v[200:203], v[86:89]
	v_mfma_f32_16x16x32_bf16 v[90:93], v[30:33], v[208:211], v[90:93]
	v_mfma_f32_16x16x32_bf16 v[94:97], v[118:121], v[208:211], v[94:97]
	v_mfma_f32_16x16x32_bf16 v[98:101], v[122:125], v[172:175], v[98:101]
	v_mfma_f32_16x16x32_bf16 v[34:37], v[164:167], v[172:175], v[34:37]
	v_mfma_f32_16x16x32_bf16 v[38:41], v[122:125], v[188:191], v[38:41]
	v_mfma_f32_16x16x32_bf16 v[42:45], v[164:167], v[188:191], v[42:45]
	v_mfma_f32_16x16x32_bf16 v[46:49], v[122:125], v[196:199], v[46:49]
	v_mfma_f32_16x16x32_bf16 v[50:53], v[164:167], v[196:199], v[50:53]
	v_mfma_f32_16x16x32_bf16 v[54:57], v[122:125], v[204:207], v[54:57]
	v_mfma_f32_16x16x32_bf16 v[58:61], v[164:167], v[204:207], v[58:61]
	v_mfma_f32_16x16x32_bf16 v[98:101], v[126:129], v[176:179], v[98:101]
	v_mfma_f32_16x16x32_bf16 v[34:37], v[168:171], v[176:179], v[34:37]
	v_mfma_f32_16x16x32_bf16 v[38:41], v[126:129], v[192:195], v[38:41]
	v_mfma_f32_16x16x32_bf16 v[42:45], v[168:171], v[192:195], v[42:45]
	v_mfma_f32_16x16x32_bf16 v[46:49], v[126:129], v[200:203], v[46:49]
	v_mfma_f32_16x16x32_bf16 v[50:53], v[168:171], v[200:203], v[50:53]
	v_mfma_f32_16x16x32_bf16 v[54:57], v[126:129], v[208:211], v[54:57]
	v_mfma_f32_16x16x32_bf16 v[58:61], v[168:171], v[208:211], v[58:61]
	s_setprio 0
	s_barrier
; #define PG8_STAGE(bufoff, gbase, voff) do { _Pragma("unroll") for (int _i = 0; _i < 2; ++_i) \
;         __builtin_amdgcn_global_load_lds((const unsigned*)((const char*)(gbase) + (voff)[_i]), (LAS unsigned*)(lds + (bufoff) + ldsw + _i * 8192), 16, 0, 0); } while (0)
; #define PG8_LDA(dst, b, h) do { _Pragma("unroll") for (int m = 0; m < 4; ++m) _Pragma("unroll") for (int k = 0; k < 2; ++k) dst[m][k] = *(const LAS bf16x8*)(lds + PG8_SA(b, h) + aoff + m * 2048 + k * 1024); } while (0)
; #define PG8_LDB(dst, b, h) do { _Pragma("unroll") for (int n = 0; n < 2; ++n) _Pragma("unroll") for (int k = 0; k < 2; ++k) dst[n][k] = *(const LAS bf16x8*)(lds + PG8_SB(b, h) + boff + n * 2048 + k * 1024); } while (0)
; #define PG8_MMA(ai, bj, At, Bt) do { __builtin_amdgcn_s_setprio(1); _Pragma("unroll") for (int m = 0; m < 4; ++m) _Pragma("unroll") for (int n = 0; n < 2; ++n) _Pragma("unroll") for (int k = 0; k < 2; ++k) \
;         acc[ai][bj][m][n] = __builtin_amdgcn_mfma_f32_16x16x32_bf16(Bt[n][k], At[m][k], acc[ai][bj][m][n], 0, 0, 0); __builtin_amdgcn_s_setprio(0); } while (0)
; #define PG8_WAIT_V(n) asm volatile("s_waitcnt vmcnt(" #n ")" ::: "memory")
; #define PG8_WAIT_L(n) asm volatile("s_waitcnt lgkmcnt(" #n ")" ::: "memory")
; #define PG8_BAR __builtin_amdgcn_s_barrier()
; #define PG8_SCHED __builtin_amdgcn_sched_barrier(0)
; template <class Epi>
; __device__ __forceinline__ void gemm_phase(LAS unsigned char* lds, const Gemm g, const StaticOrder& S, const Epi& E) {
;     ...
;             PG8_LDB(B0, 0, 0); PG8_LDB(B1, 0, 1); PG8_SCHED; PG8_LDA(At, 0, 0); PG8_STAGE(PG8_SA(1, 1), a1 + hstepA, voffA);
;             PG8_WAIT_V(8); PG8_WAIT_L(0); PG8_BAR; PG8_MMA(0, 0, At, B0); PG8_MMA(0, 1, At, B1); PG8_BAR; PG8_SCHED;
;     ...
;             PG8_LDA(At, 1, 1); PG8_STAGE(PG8_SB(1, 0), b3, voffB); PG8_STAGE(PG8_SB(1, 1), b3 + hstepB, voffB); PG8_STAGE(PG8_SA(1, 0), a3, voffA);
;             PG8_WAIT_V(8); PG8_WAIT_L(0); PG8_BAR; PG8_MMA(1, 0, At, B0); PG8_MMA(1, 1, At, B1); PG8_BAR; PG8_SCHED;
	s_add_i32 s52, s40, s11
	s_mov_b64 vcc, 0x180
	s_add_i32 s40, s52, 0x2000
	v_lshl_add_u64 v[184:185], v[184:185], 0, vcc
	s_mov_b32 m0, s52
	s_add_u32 s62, s34, 0x10180
	ds_read_b128 v[172:175], v146 offset:49152
	ds_read_b128 v[176:179], v146 offset:50176
	ds_read_b128 v[188:191], v146 offset:51200
	ds_read_b128 v[192:195], v146 offset:52224
	ds_read_b128 v[196:199], v146 offset:53248
	ds_read_b128 v[200:203], v146 offset:54272
	ds_read_b128 v[204:207], v146 offset:55296
	ds_read_b128 v[208:211], v146 offset:56320
	global_load_lds_dwordx4 v[184:185], off
	v_lshl_add_u64 v[184:185], v[212:213], 0, vcc
	s_mov_b32 m0, s40
	s_addc_u32 s63, s35, 0
	s_add_i32 s34, s64, s11
	global_load_lds_dwordx4 v[184:185], off
	v_lshl_add_u64 v[184:185], s[62:63], 0, v[132:133]
	s_mov_b32 m0, s34
	s_add_i32 s35, s34, 0x2000
	global_load_lds_dwordx4 v[184:185], off
	v_lshl_add_u64 v[184:185], s[62:63], 0, v[136:137]
	s_mov_b32 m0, s35
	s_nop 0
	global_load_lds_dwordx4 v[184:185], off
	v_lshl_add_u64 v[184:185], v[214:215], 0, vcc
	s_mov_b32 m0, s68
	s_nop 0
	global_load_lds_dwordx4 v[184:185], off
	v_lshl_add_u64 v[184:185], v[216:217], 0, vcc
	s_mov_b32 m0, s69
	s_nop 0
	global_load_lds_dwordx4 v[184:185], off
	s_waitcnt vmcnt(8)
	s_waitcnt lgkmcnt(0)
	s_barrier
	s_setprio 1
	s_waitcnt lgkmcnt(0)
	v_mfma_f32_16x16x32_bf16 v[2:5], v[26:29], v[204:207], v[2:5]
	v_mfma_f32_16x16x32_bf16 v[6:9], v[114:117], v[204:207], v[6:9]
	v_mfma_f32_16x16x32_bf16 v[138:141], v[26:29], v[172:175], v[138:141]
	v_mfma_f32_16x16x32_bf16 v[142:145], v[114:117], v[172:175], v[142:145]
	v_mfma_f32_16x16x32_bf16 v[148:151], v[26:29], v[188:191], v[148:151]
	v_mfma_f32_16x16x32_bf16 v[152:155], v[114:117], v[188:191], v[152:155]
	v_mfma_f32_16x16x32_bf16 v[156:159], v[26:29], v[196:199], v[156:159]
	v_mfma_f32_16x16x32_bf16 v[160:163], v[114:117], v[196:199], v[160:163]
	v_mfma_f32_16x16x32_bf16 v[2:5], v[30:33], v[208:211], v[2:5]
	v_mfma_f32_16x16x32_bf16 v[6:9], v[118:121], v[208:211], v[6:9]
	v_mfma_f32_16x16x32_bf16 v[138:141], v[30:33], v[176:179], v[138:141]
	v_mfma_f32_16x16x32_bf16 v[142:145], v[118:121], v[176:179], v[142:145]
	v_mfma_f32_16x16x32_bf16 v[148:151], v[30:33], v[192:195], v[148:151]
	v_mfma_f32_16x16x32_bf16 v[152:155], v[118:121], v[192:195], v[152:155]
	v_mfma_f32_16x16x32_bf16 v[156:159], v[30:33], v[200:203], v[156:159]
	v_mfma_f32_16x16x32_bf16 v[160:163], v[118:121], v[200:203], v[160:163]
	v_mfma_f32_16x16x32_bf16 v[10:13], v[122:125], v[172:175], v[10:13]
	v_mfma_f32_16x16x32_bf16 v[14:17], v[164:167], v[172:175], v[14:17]
	v_mfma_f32_16x16x32_bf16 v[26:29], v[122:125], v[188:191], v[62:65]
	v_mfma_f32_16x16x32_bf16 v[30:33], v[164:167], v[188:191], v[102:105]
	v_mfma_f32_16x16x32_bf16 v[62:65], v[122:125], v[196:199], v[106:109]
	v_mfma_f32_16x16x32_bf16 v[102:105], v[164:167], v[196:199], v[110:113]
	v_mfma_f32_16x16x32_bf16 v[18:21], v[122:125], v[204:207], v[18:21]
	v_mfma_f32_16x16x32_bf16 v[22:25], v[164:167], v[204:207], v[22:25]
	v_mfma_f32_16x16x32_bf16 v[10:13], v[126:129], v[176:179], v[10:13]
	v_mfma_f32_16x16x32_bf16 v[14:17], v[168:171], v[176:179], v[14:17]
	v_mfma_f32_16x16x32_bf16 v[26:29], v[126:129], v[192:195], v[26:29]
	v_mfma_f32_16x16x32_bf16 v[30:33], v[168:171], v[192:195], v[30:33]
	v_mfma_f32_16x16x32_bf16 v[62:65], v[126:129], v[200:203], v[62:65]
	v_mfma_f32_16x16x32_bf16 v[102:105], v[168:171], v[200:203], v[102:105]
	v_mfma_f32_16x16x32_bf16 v[18:21], v[126:129], v[208:211], v[18:21]
	v_mfma_f32_16x16x32_bf16 v[22:25], v[168:171], v[208:211], v[22:25]
	s_setprio 0
	s_barrier
	ds_read_b128 v[106:109], v147
	ds_read_b128 v[110:113], v147 offset:1024
	ds_read_b128 v[114:117], v147 offset:2048
	ds_read_b128 v[118:121], v147 offset:3072
	ds_read_b128 v[122:125], v181
	ds_read_b128 v[126:129], v181 offset:1024
	ds_read_b128 v[164:167], v181 offset:2048
	ds_read_b128 v[168:171], v181 offset:3072
	s_add_u32 s30, s30, 0x80180
	s_addc_u32 s31, s31, 0
	s_mov_b32 m0, s41
	v_lshl_add_u64 v[184:185], s[30:31], 0, v[130:131]
	ds_read_b128 v[172:175], v146
	ds_read_b128 v[176:179], v146 offset:1024
	ds_read_b128 v[188:191], v146 offset:2048
	ds_read_b128 v[192:195], v146 offset:3072
	ds_read_b128 v[196:199], v146 offset:4096
	ds_read_b128 v[200:203], v146 offset:5120
	ds_read_b128 v[204:207], v146 offset:6144
	ds_read_b128 v[208:211], v146 offset:7168
	global_load_lds_dwordx4 v[184:185], off
	v_lshl_add_u64 v[184:185], s[30:31], 0, v[134:135]
	s_mov_b32 m0, s1
	s_nop 0
	global_load_lds_dwordx4 v[184:185], off
	s_waitcnt vmcnt(8)
	s_waitcnt lgkmcnt(0)
	s_barrier
; #define PG8_STAGE(bufoff, gbase, voff) do { _Pragma("unroll") for (int _i = 0; _i < 2; ++_i) \
;         __builtin_amdgcn_global_load_lds((const unsigned*)((const char*)(gbase) + (voff)[_i]), (LAS unsigned*)(lds + (bufoff) + ldsw + _i * 8192), 16, 0, 0); } while (0)
; #define PG8_LDA(dst, b, h) do { _Pragma("unroll") for (int m = 0; m < 4; ++m) _Pragma("unroll") for (int k = 0; k < 2; ++k) dst[m][k] = *(const LAS bf16x8*)(lds + PG8_SA(b, h) + aoff + m * 2048 + k * 1024); } while (0)
; #define PG8_MMA(ai, bj, At, Bt) do { __builtin_amdgcn_s_setprio(1); _Pragma("unroll") for (int m = 0; m < 4; ++m) _Pragma("unroll") for (int n = 0; n < 2; ++n) _Pragma("unroll") for (int k = 0; k < 2; ++k) \
;         acc[ai][bj][m][n] = __builtin_amdgcn_mfma_f32_16x16x32_bf16(Bt[n][k], At[m][k], acc[ai][bj][m][n], 0, 0, 0); __builtin_amdgcn_s_setprio(0); } while (0)
; #define PG8_WAIT_V(n) asm volatile("s_waitcnt vmcnt(" #n ")" ::: "memory")
; #define PG8_WAIT_L(n) asm volatile("s_waitcnt lgkmcnt(" #n ")" ::: "memory")
; #define PG8_BAR __builtin_amdgcn_s_barrier()
; #define PG8_SCHED __builtin_amdgcn_sched_barrier(0)
; template <class Epi>
; __device__ __forceinline__ void gemm_phase(LAS unsigned char* lds, const Gemm g, const StaticOrder& S, const Epi& E) {
;     ...
;             PG8_WAIT_V(8); PG8_WAIT_L(0); PG8_BAR; PG8_MMA(0, 0, At, B0); PG8_MMA(0, 1, At, B1); PG8_BAR; PG8_SCHED;
;             PG8_LDA(At, 0, 1); PG8_STAGE(PG8_SB(0, 0), b2, voffB); PG8_STAGE(PG8_SB(0, 1), b2 + hstepB, voffB); PG8_STAGE(PG8_SA(0, 0), a2, voffA);
;             PG8_WAIT_V(8); PG8_WAIT_L(0); PG8_BAR; PG8_MMA(1, 0, At, B0); PG8_MMA(1, 1, At, B1); PG8_BAR; PG8_SCHED;
	s_setprio 1
	s_waitcnt lgkmcnt(0)
	v_mfma_f32_16x16x32_bf16 v[90:93], v[106:109], v[204:207], v[90:93]
	v_mfma_f32_16x16x32_bf16 v[66:69], v[106:109], v[172:175], v[66:69]
	v_mfma_f32_16x16x32_bf16 v[70:73], v[114:117], v[172:175], v[70:73]
	v_mfma_f32_16x16x32_bf16 v[74:77], v[106:109], v[188:191], v[74:77]
	v_mfma_f32_16x16x32_bf16 v[78:81], v[114:117], v[188:191], v[78:81]
	v_mfma_f32_16x16x32_bf16 v[82:85], v[106:109], v[196:199], v[82:85]
	v_mfma_f32_16x16x32_bf16 v[86:89], v[114:117], v[196:199], v[86:89]
	v_mfma_f32_16x16x32_bf16 v[212:215], v[110:113], v[208:211], v[90:93]
	v_mfma_f32_16x16x32_bf16 v[90:93], v[114:117], v[204:207], v[94:97]
	v_mfma_f32_16x16x32_bf16 v[66:69], v[110:113], v[176:179], v[66:69]
	v_mfma_f32_16x16x32_bf16 v[70:73], v[118:121], v[176:179], v[70:73]
	v_mfma_f32_16x16x32_bf16 v[74:77], v[110:113], v[192:195], v[74:77]
	v_mfma_f32_16x16x32_bf16 v[78:81], v[118:121], v[192:195], v[78:81]
	v_mfma_f32_16x16x32_bf16 v[82:85], v[110:113], v[200:203], v[82:85]
	v_mfma_f32_16x16x32_bf16 v[86:89], v[118:121], v[200:203], v[86:89]
	v_mfma_f32_16x16x32_bf16 v[94:97], v[118:121], v[208:211], v[90:93]
	v_mfma_f32_16x16x32_bf16 v[90:93], v[122:125], v[172:175], v[98:101]
	v_mfma_f32_16x16x32_bf16 v[34:37], v[164:167], v[172:175], v[34:37]
	v_mfma_f32_16x16x32_bf16 v[38:41], v[122:125], v[188:191], v[38:41]
	v_mfma_f32_16x16x32_bf16 v[42:45], v[164:167], v[188:191], v[42:45]
	v_mfma_f32_16x16x32_bf16 v[46:49], v[122:125], v[196:199], v[46:49]
	v_mfma_f32_16x16x32_bf16 v[50:53], v[164:167], v[196:199], v[50:53]
	v_mfma_f32_16x16x32_bf16 v[54:57], v[122:125], v[204:207], v[54:57]
	v_mfma_f32_16x16x32_bf16 v[58:61], v[164:167], v[204:207], v[58:61]
	v_mfma_f32_16x16x32_bf16 v[98:101], v[126:129], v[176:179], v[90:93]
	v_mfma_f32_16x16x32_bf16 v[34:37], v[168:171], v[176:179], v[34:37]
	v_mfma_f32_16x16x32_bf16 v[38:41], v[126:129], v[192:195], v[38:41]
	v_mfma_f32_16x16x32_bf16 v[42:45], v[168:171], v[192:195], v[42:45]
	v_mfma_f32_16x16x32_bf16 v[46:49], v[126:129], v[200:203], v[46:49]
	v_mfma_f32_16x16x32_bf16 v[50:53], v[168:171], v[200:203], v[50:53]
	v_mfma_f32_16x16x32_bf16 v[54:57], v[126:129], v[208:211], v[54:57]
	v_mfma_f32_16x16x32_bf16 v[58:61], v[168:171], v[208:211], v[58:61]
	s_setprio 0
	s_barrier
	s_mov_b32 m0, s33
	v_lshl_add_u64 v[184:185], s[6:7], 0, v[132:133]
	s_add_u32 s30, s6, 0x10000
	ds_read_b128 v[90:93], v146 offset:16384
	ds_read_b128 v[172:175], v146 offset:17408
	ds_read_b128 v[176:179], v146 offset:18432
	ds_read_b128 v[188:191], v146 offset:19456
	ds_read_b128 v[192:195], v146 offset:20480
	ds_read_b128 v[196:199], v146 offset:21504
	ds_read_b128 v[200:203], v146 offset:22528
	ds_read_b128 v[204:207], v146 offset:23552
	global_load_lds_dwordx4 v[184:185], off
	v_lshl_add_u64 v[244:245], s[6:7], 0, v[136:137]
	s_mov_b32 m0, s3
	s_addc_u32 s31, s7, 0
	global_load_lds_dwordx4 v[244:245], off
	v_lshl_add_u64 v[208:209], s[30:31], 0, v[132:133]
	s_mov_b32 m0, s21
	v_lshl_add_u64 v[246:247], s[24:25], 0, v[130:131]
	global_load_lds_dwordx4 v[208:209], off
	v_lshl_add_u64 v[208:209], s[30:31], 0, v[136:137]
	s_mov_b32 m0, s23
	v_lshl_add_u64 v[248:249], s[24:25], 0, v[134:135]
	global_load_lds_dwordx4 v[208:209], off
	s_mov_b32 m0, s14
	s_nop 0
	global_load_lds_dwordx4 v[246:247], off
	s_mov_b32 m0, s15
	s_nop 0
	global_load_lds_dwordx4 v[248:249], off
	s_waitcnt vmcnt(8)
	s_waitcnt lgkmcnt(0)
	s_barrier
	s_setprio 1
	s_waitcnt lgkmcnt(0)
	v_mfma_f32_16x16x32_bf16 v[2:5], v[106:109], v[200:203], v[2:5]
	v_mfma_f32_16x16x32_bf16 v[6:9], v[114:117], v[200:203], v[6:9]
	v_mfma_f32_16x16x32_bf16 v[138:141], v[106:109], v[90:93], v[138:141]
	v_mfma_f32_16x16x32_bf16 v[142:145], v[114:117], v[90:93], v[142:145]
	v_mfma_f32_16x16x32_bf16 v[148:151], v[106:109], v[176:179], v[148:151]
	v_mfma_f32_16x16x32_bf16 v[152:155], v[114:117], v[176:179], v[152:155]
	v_mfma_f32_16x16x32_bf16 v[156:159], v[106:109], v[192:195], v[156:159]
	v_mfma_f32_16x16x32_bf16 v[160:163], v[114:117], v[192:195], v[160:163]
	v_mfma_f32_16x16x32_bf16 v[2:5], v[110:113], v[204:207], v[2:5]
	v_mfma_f32_16x16x32_bf16 v[6:9], v[118:121], v[204:207], v[6:9]
	v_mfma_f32_16x16x32_bf16 v[138:141], v[110:113], v[172:175], v[138:141]
	v_mfma_f32_16x16x32_bf16 v[142:145], v[118:121], v[172:175], v[142:145]
	v_mfma_f32_16x16x32_bf16 v[148:151], v[110:113], v[188:191], v[148:151]
	v_mfma_f32_16x16x32_bf16 v[152:155], v[118:121], v[188:191], v[152:155]
	v_mfma_f32_16x16x32_bf16 v[156:159], v[110:113], v[196:199], v[156:159]
	v_mfma_f32_16x16x32_bf16 v[160:163], v[118:121], v[196:199], v[160:163]
	v_mfma_f32_16x16x32_bf16 v[10:13], v[122:125], v[90:93], v[10:13]
	v_mfma_f32_16x16x32_bf16 v[208:211], v[126:129], v[172:175], v[10:13]
	v_mfma_f32_16x16x32_bf16 v[10:13], v[164:167], v[90:93], v[14:17]
	v_mfma_f32_16x16x32_bf16 v[14:17], v[168:171], v[172:175], v[10:13]
	v_mfma_f32_16x16x32_bf16 v[10:13], v[122:125], v[176:179], v[26:29]
	v_mfma_f32_16x16x32_bf16 v[172:175], v[126:129], v[188:191], v[10:13]
	v_mfma_f32_16x16x32_bf16 v[10:13], v[164:167], v[176:179], v[30:33]
	v_mfma_f32_16x16x32_bf16 v[30:33], v[168:171], v[188:191], v[10:13]
	v_mfma_f32_16x16x32_bf16 v[10:13], v[122:125], v[192:195], v[62:65]
	v_mfma_f32_16x16x32_bf16 v[176:179], v[126:129], v[196:199], v[10:13]
	v_mfma_f32_16x16x32_bf16 v[10:13], v[164:167], v[192:195], v[102:105]
	v_mfma_f32_16x16x32_bf16 v[188:191], v[168:171], v[196:199], v[10:13]
	v_mfma_f32_16x16x32_bf16 v[10:13], v[122:125], v[200:203], v[18:21]
	v_mfma_f32_16x16x32_bf16 v[192:195], v[126:129], v[204:207], v[10:13]
	v_mfma_f32_16x16x32_bf16 v[10:13], v[164:167], v[200:203], v[22:25]
	v_mfma_f32_16x16x32_bf16 v[164:167], v[168:171], v[204:207], v[10:13]
	s_setprio 0
	s_barrier
; #define PG8_STAGE(bufoff, gbase, voff) do { _Pragma("unroll") for (int _i = 0; _i < 2; ++_i) \
;         __builtin_amdgcn_global_load_lds((const unsigned*)((const char*)(gbase) + (voff)[_i]), (LAS unsigned*)(lds + (bufoff) + ldsw + _i * 8192), 16, 0, 0); } while (0)
; #define PG8_LDA(dst, b, h) do { _Pragma("unroll") for (int m = 0; m < 4; ++m) _Pragma("unroll") for (int k = 0; k < 2; ++k) dst[m][k] = *(const LAS bf16x8*)(lds + PG8_SA(b, h) + aoff + m * 2048 + k * 1024); } while (0)
; #define PG8_LDB(dst, b, h) do { _Pragma("unroll") for (int n = 0; n < 2; ++n) _Pragma("unroll") for (int k = 0; k < 2; ++k) dst[n][k] = *(const LAS bf16x8*)(lds + PG8_SB(b, h) + boff + n * 2048 + k * 1024); } while (0)
; #define PG8_MMA(ai, bj, At, Bt) do { __builtin_amdgcn_s_setprio(1); _Pragma("unroll") for (int m = 0; m < 4; ++m) _Pragma("unroll") for (int n = 0; n < 2; ++n) _Pragma("unroll") for (int k = 0; k < 2; ++k) \
;         acc[ai][bj][m][n] = __builtin_amdgcn_mfma_f32_16x16x32_bf16(Bt[n][k], At[m][k], acc[ai][bj][m][n], 0, 0, 0); __builtin_amdgcn_s_setprio(0); } while (0)
; #define PG8_WAIT_V(n) asm volatile("s_waitcnt vmcnt(" #n ")" ::: "memory")
; #define PG8_WAIT_L(n) asm volatile("s_waitcnt lgkmcnt(" #n ")" ::: "memory")
; #define PG8_BAR __builtin_amdgcn_s_barrier()
; #define PG8_SCHED __builtin_amdgcn_sched_barrier(0)
; template <class Epi>
; __device__ __forceinline__ void gemm_phase(LAS unsigned char* lds, const Gemm g, const StaticOrder& S, const Epi& E) {
;     ...
;             PG8_LDB(B0, 1, 0); PG8_LDB(B1, 1, 1); PG8_SCHED; PG8_LDA(At, 1, 0); PG8_STAGE(PG8_SA(0, 1), a2 + hstepA, voffA);
;             PG8_WAIT_V(8); PG8_WAIT_L(0); PG8_BAR; PG8_MMA(0, 0, At, B0); PG8_MMA(0, 1, At, B1); PG8_BAR; PG8_SCHED;
;             PG8_LDA(At, 1, 1); PG8_STAGE(PG8_SB(1, 0), b3, voffB); PG8_STAGE(PG8_SB(1, 1), b3 + hstepB, voffB); PG8_STAGE(PG8_SA(1, 0), a3, voffA);
;             PG8_WAIT_V(8); PG8_WAIT_L(0); PG8_BAR; PG8_MMA(1, 0, At, B0); PG8_MMA(1, 1, At, B1); PG8_BAR; PG8_SCHED;
;         }
;         if (wr == 0) PG8_BAR;
	s_nop 4
	ds_read_b128 v[10:13], v183
	ds_read_b128 v[18:21], v183 offset:1024
	ds_read_b128 v[62:65], v183 offset:2048
	ds_read_b128 v[168:171], v183 offset:3072
	ds_read_b128 v[196:199], v186
	ds_read_b128 v[200:203], v186 offset:1024
	ds_read_b128 v[204:207], v186 offset:2048
	ds_read_b128 v[216:219], v186 offset:3072
	s_add_u32 s30, s24, 0x80000
	s_addc_u32 s31, s25, 0
	s_mov_b32 m0, s29
	v_lshl_add_u64 v[90:91], s[30:31], 0, v[130:131]
	ds_read_b128 v[22:25], v146 offset:32768
	ds_read_b128 v[26:29], v146 offset:33792
	ds_read_b128 v[220:223], v146 offset:34816
	ds_read_b128 v[224:227], v146 offset:35840
	ds_read_b128 v[228:231], v146 offset:36864
	ds_read_b128 v[232:235], v146 offset:37888
	ds_read_b128 v[236:239], v146 offset:38912
	ds_read_b128 v[240:243], v146 offset:39936
	global_load_lds_dwordx4 v[90:91], off
	v_lshl_add_u64 v[90:91], s[30:31], 0, v[134:135]
	s_mov_b32 m0, s42
	s_nop 0
	global_load_lds_dwordx4 v[90:91], off
	s_waitcnt vmcnt(8)
	s_waitcnt lgkmcnt(0)
	s_barrier
	s_setprio 1
	s_waitcnt lgkmcnt(0)
	v_mfma_f32_16x16x32_bf16 v[66:69], v[10:13], v[22:25], v[66:69]
	v_mfma_f32_16x16x32_bf16 v[126:129], v[18:21], v[26:29], v[66:69]
	v_mfma_f32_16x16x32_bf16 v[66:69], v[62:65], v[22:25], v[70:73]
	v_mfma_f32_16x16x32_bf16 v[118:121], v[168:171], v[26:29], v[66:69]
	v_mfma_f32_16x16x32_bf16 v[66:69], v[10:13], v[220:223], v[74:77]
	v_mfma_f32_16x16x32_bf16 v[106:109], v[18:21], v[224:227], v[66:69]
	v_mfma_f32_16x16x32_bf16 v[66:69], v[62:65], v[220:223], v[78:81]
	v_mfma_f32_16x16x32_bf16 v[102:105], v[168:171], v[224:227], v[66:69]
	v_mfma_f32_16x16x32_bf16 v[66:69], v[10:13], v[228:231], v[82:85]
	v_mfma_f32_16x16x32_bf16 v[90:93], v[18:21], v[232:235], v[66:69]
	v_mfma_f32_16x16x32_bf16 v[66:69], v[62:65], v[228:231], v[86:89]
	v_mfma_f32_16x16x32_bf16 v[86:89], v[168:171], v[232:235], v[66:69]
	v_mfma_f32_16x16x32_bf16 v[66:69], v[10:13], v[236:239], v[212:215]
	v_mfma_f32_16x16x32_bf16 v[74:77], v[18:21], v[240:243], v[66:69]
	v_mfma_f32_16x16x32_bf16 v[66:69], v[62:65], v[236:239], v[94:97]
	v_mfma_f32_16x16x32_bf16 v[70:73], v[168:171], v[240:243], v[66:69]
	v_mfma_f32_16x16x32_bf16 v[66:69], v[196:199], v[22:25], v[98:101]
	v_mfma_f32_16x16x32_bf16 v[22:25], v[204:207], v[22:25], v[34:37]
	v_mfma_f32_16x16x32_bf16 v[114:117], v[216:219], v[26:29], v[22:25]
	v_mfma_f32_16x16x32_bf16 v[22:25], v[196:199], v[220:223], v[38:41]
	v_mfma_f32_16x16x32_bf16 v[110:113], v[200:203], v[224:227], v[22:25]
	v_mfma_f32_16x16x32_bf16 v[22:25], v[204:207], v[220:223], v[42:45]
	v_mfma_f32_16x16x32_bf16 v[98:101], v[216:219], v[224:227], v[22:25]
	v_mfma_f32_16x16x32_bf16 v[22:25], v[196:199], v[228:231], v[46:49]
	v_mfma_f32_16x16x32_bf16 v[94:97], v[200:203], v[232:235], v[22:25]
	v_mfma_f32_16x16x32_bf16 v[22:25], v[204:207], v[228:231], v[50:53]
	v_mfma_f32_16x16x32_bf16 v[82:85], v[216:219], v[232:235], v[22:25]
	v_mfma_f32_16x16x32_bf16 v[22:25], v[196:199], v[236:239], v[54:57]
	v_mfma_f32_16x16x32_bf16 v[78:81], v[200:203], v[240:243], v[22:25]
	v_mfma_f32_16x16x32_bf16 v[22:25], v[204:207], v[236:239], v[58:61]
	v_mfma_f32_16x16x32_bf16 v[122:125], v[200:203], v[26:29], v[66:69]
	v_mfma_f32_16x16x32_bf16 v[66:69], v[216:219], v[240:243], v[22:25]
	s_setprio 0
	s_barrier
	s_mov_b32 m0, s52
	s_nop 2
	v_lshl_add_u64 v[22:23], v[184:185], 0, s[84:85]
	s_add_u32 s6, s6, 0x10080
	ds_read_b128 v[34:37], v146 offset:49152
	ds_read_b128 v[46:49], v146 offset:50176
	ds_read_b128 v[212:215], v146 offset:51200
	ds_read_b128 v[220:223], v146 offset:52224
	ds_read_b128 v[224:227], v146 offset:53248
	ds_read_b128 v[228:231], v146 offset:54272
	ds_read_b128 v[232:235], v146 offset:55296
	ds_read_b128 v[236:239], v146 offset:56320
	global_load_lds_dwordx4 v[22:23], off
	v_lshl_add_u64 v[22:23], v[244:245], 0, s[84:85]
	s_mov_b32 m0, s40
	s_addc_u32 s7, s7, 0
	global_load_lds_dwordx4 v[22:23], off
	v_lshl_add_u64 v[22:23], s[6:7], 0, v[132:133]
	s_mov_b32 m0, s34
	s_nop 0
	global_load_lds_dwordx4 v[22:23], off
	v_lshl_add_u64 v[22:23], s[6:7], 0, v[136:137]
	s_mov_b32 m0, s35
	s_nop 0
	global_load_lds_dwordx4 v[22:23], off
	v_lshl_add_u64 v[22:23], v[246:247], 0, s[84:85]
	s_mov_b32 m0, s68
	s_nop 0
	global_load_lds_dwordx4 v[22:23], off
	v_lshl_add_u64 v[22:23], v[248:249], 0, s[84:85]
	s_mov_b32 m0, s69
	s_nop 0
	global_load_lds_dwordx4 v[22:23], off
	s_waitcnt vmcnt(8)
	s_waitcnt lgkmcnt(0)
	s_barrier
	s_setprio 1
	s_waitcnt lgkmcnt(0)
	v_mfma_f32_16x16x32_bf16 v[22:25], v[10:13], v[34:37], v[138:141]
	v_mfma_f32_16x16x32_bf16 v[58:61], v[18:21], v[46:49], v[22:25]
	v_mfma_f32_16x16x32_bf16 v[22:25], v[62:65], v[34:37], v[142:145]
	v_mfma_f32_16x16x32_bf16 v[54:57], v[168:171], v[46:49], v[22:25]
	v_mfma_f32_16x16x32_bf16 v[22:25], v[10:13], v[212:215], v[148:151]
	v_mfma_f32_16x16x32_bf16 v[42:45], v[18:21], v[220:223], v[22:25]
	v_mfma_f32_16x16x32_bf16 v[22:25], v[62:65], v[212:215], v[152:155]
	v_mfma_f32_16x16x32_bf16 v[38:41], v[168:171], v[220:223], v[22:25]
	v_mfma_f32_16x16x32_bf16 v[22:25], v[10:13], v[224:227], v[156:159]
	v_mfma_f32_16x16x32_bf16 v[2:5], v[10:13], v[232:235], v[2:5]
	v_mfma_f32_16x16x32_bf16 v[26:29], v[18:21], v[228:231], v[22:25]
	v_mfma_f32_16x16x32_bf16 v[22:25], v[62:65], v[224:227], v[160:163]
	v_mfma_f32_16x16x32_bf16 v[10:13], v[18:21], v[236:239], v[2:5]
	v_mfma_f32_16x16x32_bf16 v[2:5], v[62:65], v[232:235], v[6:9]
	v_mfma_f32_16x16x32_bf16 v[22:25], v[168:171], v[228:231], v[22:25]
	v_mfma_f32_16x16x32_bf16 v[6:9], v[168:171], v[236:239], v[2:5]
	v_mfma_f32_16x16x32_bf16 v[2:5], v[196:199], v[34:37], v[208:211]
	v_mfma_f32_16x16x32_bf16 v[62:65], v[200:203], v[46:49], v[2:5]
	v_mfma_f32_16x16x32_bf16 v[2:5], v[204:207], v[34:37], v[14:17]
	v_mfma_f32_16x16x32_bf16 v[50:53], v[216:219], v[46:49], v[2:5]
	v_mfma_f32_16x16x32_bf16 v[2:5], v[196:199], v[212:215], v[172:175]
	v_mfma_f32_16x16x32_bf16 v[46:49], v[200:203], v[220:223], v[2:5]
	v_mfma_f32_16x16x32_bf16 v[2:5], v[204:207], v[212:215], v[30:33]
	v_mfma_f32_16x16x32_bf16 v[34:37], v[216:219], v[220:223], v[2:5]
	v_mfma_f32_16x16x32_bf16 v[2:5], v[196:199], v[224:227], v[176:179]
	v_mfma_f32_16x16x32_bf16 v[30:33], v[200:203], v[228:231], v[2:5]
	v_mfma_f32_16x16x32_bf16 v[2:5], v[204:207], v[224:227], v[188:191]
	v_mfma_f32_16x16x32_bf16 v[18:21], v[216:219], v[228:231], v[2:5]
	v_mfma_f32_16x16x32_bf16 v[2:5], v[196:199], v[232:235], v[192:195]
	v_mfma_f32_16x16x32_bf16 v[14:17], v[200:203], v[236:239], v[2:5]
	v_mfma_f32_16x16x32_bf16 v[2:5], v[204:207], v[232:235], v[164:167]
	v_mfma_f32_16x16x32_bf16 v[2:5], v[216:219], v[236:239], v[2:5]
	s_setprio 0
	s_barrier
	s_andn2_b64 vcc, exec, s[16:17]
	s_cbranch_vccnz .LBB0_684
	s_barrier

; #define PG8_STAGE(bufoff, gbase, voff) do { _Pragma("unroll") for (int _i = 0; _i < 2; ++_i) \
;         __builtin_amdgcn_global_load_lds((const unsigned*)((const char*)(gbase) + (voff)[_i]), (LAS unsigned*)(lds + (bufoff) + ldsw + _i * 8192), 16, 0, 0); } while (0)
; #define PG8_LDA(dst, b, h) do { _Pragma("unroll") for (int m = 0; m < 4; ++m) _Pragma("unroll") for (int k = 0; k < 2; ++k) dst[m][k] = *(const LAS bf16x8*)(lds + PG8_SA(b, h) + aoff + m * 2048 + k * 1024); } while (0)
; #define PG8_LDB(dst, b, h) do { _Pragma("unroll") for (int n = 0; n < 2; ++n) _Pragma("unroll") for (int k = 0; k < 2; ++k) dst[n][k] = *(const LAS bf16x8*)(lds + PG8_SB(b, h) + boff + n * 2048 + k * 1024); } while (0)
; #define PG8_MMA(ai, bj, At, Bt) do { __builtin_amdgcn_s_setprio(1); _Pragma("unroll") for (int m = 0; m < 4; ++m) _Pragma("unroll") for (int n = 0; n < 2; ++n) _Pragma("unroll") for (int k = 0; k < 2; ++k) \
;         acc[ai][bj][m][n] = __builtin_amdgcn_mfma_f32_16x16x32_bf16(Bt[n][k], At[m][k], acc[ai][bj][m][n], 0, 0, 0); __builtin_amdgcn_s_setprio(0); } while (0)
; #define PG8_WAIT_V(n) asm volatile("s_waitcnt vmcnt(" #n ")" ::: "memory")
; #define PG8_WAIT_L(n) asm volatile("s_waitcnt lgkmcnt(" #n ")" ::: "memory")
; #define PG8_BAR __builtin_amdgcn_s_barrier()
; #define PG8_SCHED __builtin_amdgcn_sched_barrier(0)
; template <class Epi>
; __device__ __forceinline__ void gemm_phase(LAS unsigned char* lds, const Gemm g, const StaticOrder& S, const Epi& E) {
;     ...
;             const bool last = (t == nt - 2);
;             const char* a1 = cA + (size_t)(t + 1) * kstep;
;             const char* a2 = last ? nA : cA + (size_t)(t + 2) * kstep; const char* b2 = last ? nB : cB + (size_t)(t + 2) * kstep;
;             const char* a3 = a2 + kstep; const char* b3 = b2 + kstep;
;             PG8_LDB(B0, 0, 0); PG8_LDB(B1, 0, 1); PG8_SCHED; PG8_LDA(At, 0, 0); PG8_STAGE(PG8_SA(1, 1), a1 + hstepA, voffA);
;             PG8_WAIT_V(8); PG8_WAIT_L(0); PG8_BAR; PG8_MMA(0, 0, At, B0); PG8_MMA(0, 1, At, B1); PG8_BAR; PG8_SCHED;
;             PG8_LDA(At, 0, 1); PG8_STAGE(PG8_SB(0, 0), b2, voffB); PG8_STAGE(PG8_SB(0, 1), b2 + hstepB, voffB); PG8_STAGE(PG8_SA(0, 0), a2, voffA);
;             PG8_WAIT_V(8); PG8_WAIT_L(0); PG8_BAR; PG8_MMA(1, 0, At, B0); PG8_MMA(1, 1, At, B1); PG8_BAR; PG8_SCHED;
.LBB0_1010:
	s_add_u32 s14, s26, 0xfff80080
	s_addc_u32 s15, s27, -1
	s_add_i32 s41, 0, 0x10000
	s_cmp_eq_u32 s52, 28
	s_cselect_b32 s29, s1, s15
	s_cselect_b32 s28, s3, s14
	s_cselect_b32 s15, s7, s40
	s_cselect_b32 s14, s17, s19
	s_add_i32 s53, 0, 0x14000
	v_add_u32_e32 v142, s41, v1
	v_add_u32_e32 v158, s53, v1
	ds_read_b128 v[130:133], v142
	ds_read_b128 v[134:137], v142 offset:1024
	ds_read_b128 v[138:141], v142 offset:2048
	ds_read_b128 v[142:145], v142 offset:3072
	ds_read_b128 v[146:149], v158
	ds_read_b128 v[150:153], v158 offset:1024
	ds_read_b128 v[154:157], v158 offset:2048
	ds_read_b128 v[158:161], v158 offset:3072
	v_lshl_add_u64 v[178:179], s[26:27], 0, v[196:197]
	s_add_i32 m0, s25, 0xc000
	ds_read_b128 v[162:165], v181
	ds_read_b128 v[166:169], v181 offset:1024
	ds_read_b128 v[170:173], v181 offset:2048
	ds_read_b128 v[174:177], v181 offset:3072
	ds_read_b128 v[200:203], v181 offset:4096
	ds_read_b128 v[204:207], v181 offset:5120
	ds_read_b128 v[208:211], v181 offset:6144
	ds_read_b128 v[212:215], v181 offset:7168
	global_load_lds_dwordx4 v[178:179], off
	v_lshl_add_u64 v[178:179], s[26:27], 0, v[198:199]
	s_add_i32 m0, s25, 0xe000
	s_nop 0
	global_load_lds_dwordx4 v[178:179], off
	s_waitcnt vmcnt(8)
	s_waitcnt lgkmcnt(0)
	s_barrier
	s_setprio 1
	s_waitcnt lgkmcnt(0)
	v_mfma_f32_16x16x32_bf16 v[126:129], v[130:133], v[162:165], v[126:129]
	v_mfma_f32_16x16x32_bf16 v[122:125], v[138:141], v[162:165], v[122:125]
	v_mfma_f32_16x16x32_bf16 v[110:113], v[130:133], v[170:173], v[110:113]
	v_mfma_f32_16x16x32_bf16 v[106:109], v[138:141], v[170:173], v[106:109]
	v_mfma_f32_16x16x32_bf16 v[94:97], v[130:133], v[200:203], v[94:97]
	v_mfma_f32_16x16x32_bf16 v[90:93], v[138:141], v[200:203], v[90:93]
	v_mfma_f32_16x16x32_bf16 v[82:85], v[130:133], v[208:211], v[82:85]
	v_mfma_f32_16x16x32_bf16 v[74:77], v[138:141], v[208:211], v[74:77]
	v_mfma_f32_16x16x32_bf16 v[126:129], v[134:137], v[166:169], v[126:129]
	v_mfma_f32_16x16x32_bf16 v[122:125], v[142:145], v[166:169], v[122:125]
	v_mfma_f32_16x16x32_bf16 v[110:113], v[134:137], v[174:177], v[110:113]
	v_mfma_f32_16x16x32_bf16 v[106:109], v[142:145], v[174:177], v[106:109]
	v_mfma_f32_16x16x32_bf16 v[94:97], v[134:137], v[204:207], v[94:97]
	v_mfma_f32_16x16x32_bf16 v[90:93], v[142:145], v[204:207], v[90:93]
	v_mfma_f32_16x16x32_bf16 v[82:85], v[134:137], v[212:215], v[82:85]
	v_mfma_f32_16x16x32_bf16 v[74:77], v[142:145], v[212:215], v[74:77]
	v_mfma_f32_16x16x32_bf16 v[118:121], v[146:149], v[162:165], v[118:121]
	v_mfma_f32_16x16x32_bf16 v[114:117], v[154:157], v[162:165], v[114:117]
	v_mfma_f32_16x16x32_bf16 v[102:105], v[146:149], v[170:173], v[102:105]
	v_mfma_f32_16x16x32_bf16 v[98:101], v[154:157], v[170:173], v[98:101]
	v_mfma_f32_16x16x32_bf16 v[86:89], v[146:149], v[200:203], v[86:89]
	v_mfma_f32_16x16x32_bf16 v[78:81], v[154:157], v[200:203], v[78:81]
	v_mfma_f32_16x16x32_bf16 v[70:73], v[146:149], v[208:211], v[70:73]
	v_mfma_f32_16x16x32_bf16 v[66:69], v[154:157], v[208:211], v[66:69]
	v_mfma_f32_16x16x32_bf16 v[118:121], v[150:153], v[166:169], v[118:121]
	v_mfma_f32_16x16x32_bf16 v[114:117], v[158:161], v[166:169], v[114:117]
	v_mfma_f32_16x16x32_bf16 v[102:105], v[150:153], v[174:177], v[102:105]
	v_mfma_f32_16x16x32_bf16 v[98:101], v[158:161], v[174:177], v[98:101]
	v_mfma_f32_16x16x32_bf16 v[86:89], v[150:153], v[204:207], v[86:89]
	v_mfma_f32_16x16x32_bf16 v[78:81], v[158:161], v[204:207], v[78:81]
	v_mfma_f32_16x16x32_bf16 v[70:73], v[150:153], v[212:215], v[70:73]
	v_mfma_f32_16x16x32_bf16 v[66:69], v[158:161], v[212:215], v[66:69]
	s_setprio 0
	s_barrier
	s_add_i32 s41, s41, s30
	v_lshl_add_u64 v[178:179], s[14:15], 0, v[190:191]
	s_mov_b32 m0, s41
	ds_read_b128 v[162:165], v181 offset:16384
	ds_read_b128 v[166:169], v181 offset:17408
	ds_read_b128 v[170:173], v181 offset:18432
	ds_read_b128 v[174:177], v181 offset:19456
	ds_read_b128 v[200:203], v181 offset:20480
	ds_read_b128 v[204:207], v181 offset:21504
	ds_read_b128 v[208:211], v181 offset:22528
	ds_read_b128 v[212:215], v181 offset:23552
	global_load_lds_dwordx4 v[178:179], off
	s_add_i32 m0, s41, 0x2000
	s_add_u32 s62, s14, 0x80000
	v_lshl_add_u64 v[184:185], s[14:15], 0, v[194:195]
	s_addc_u32 s63, s15, 0
	s_add_i32 s41, s53, s30
	global_load_lds_dwordx4 v[184:185], off
	v_lshl_add_u64 v[216:217], s[62:63], 0, v[190:191]
	s_mov_b32 m0, s41
	v_lshl_add_u64 v[218:219], s[28:29], 0, v[192:193]
	global_load_lds_dwordx4 v[216:217], off
	v_lshl_add_u64 v[216:217], s[62:63], 0, v[194:195]
	s_add_i32 m0, s41, 0x2000
	s_nop 0
	global_load_lds_dwordx4 v[216:217], off
	v_lshl_add_u64 v[216:217], s[28:29], 0, v[188:189]
	s_mov_b32 m0, s25
	s_nop 0
	global_load_lds_dwordx4 v[216:217], off
	s_mov_b32 m0, s31
	s_nop 0
	global_load_lds_dwordx4 v[218:219], off
	s_waitcnt vmcnt(8)
	s_waitcnt lgkmcnt(0)
	s_barrier
; #define PG8_STAGE(bufoff, gbase, voff) do { _Pragma("unroll") for (int _i = 0; _i < 2; ++_i) \
;         __builtin_amdgcn_global_load_lds((const unsigned*)((const char*)(gbase) + (voff)[_i]), (LAS unsigned*)(lds + (bufoff) + ldsw + _i * 8192), 16, 0, 0); } while (0)
; #define PG8_LDA(dst, b, h) do { _Pragma("unroll") for (int m = 0; m < 4; ++m) _Pragma("unroll") for (int k = 0; k < 2; ++k) dst[m][k] = *(const LAS bf16x8*)(lds + PG8_SA(b, h) + aoff + m * 2048 + k * 1024); } while (0)
; #define PG8_LDB(dst, b, h) do { _Pragma("unroll") for (int n = 0; n < 2; ++n) _Pragma("unroll") for (int k = 0; k < 2; ++k) dst[n][k] = *(const LAS bf16x8*)(lds + PG8_SB(b, h) + boff + n * 2048 + k * 1024); } while (0)
; #define PG8_MMA(ai, bj, At, Bt) do { __builtin_amdgcn_s_setprio(1); _Pragma("unroll") for (int m = 0; m < 4; ++m) _Pragma("unroll") for (int n = 0; n < 2; ++n) _Pragma("unroll") for (int k = 0; k < 2; ++k) \
;         acc[ai][bj][m][n] = __builtin_amdgcn_mfma_f32_16x16x32_bf16(Bt[n][k], At[m][k], acc[ai][bj][m][n], 0, 0, 0); __builtin_amdgcn_s_setprio(0); } while (0)
; #define PG8_WAIT_V(n) asm volatile("s_waitcnt vmcnt(" #n ")" ::: "memory")
; #define PG8_WAIT_L(n) asm volatile("s_waitcnt lgkmcnt(" #n ")" ::: "memory")
; #define PG8_BAR __builtin_amdgcn_s_barrier()
; #define PG8_SCHED __builtin_amdgcn_sched_barrier(0)
; template <class Epi>
; __device__ __forceinline__ void gemm_phase(LAS unsigned char* lds, const Gemm g, const StaticOrder& S, const Epi& E) {
;     ...
;             PG8_WAIT_V(8); PG8_WAIT_L(0); PG8_BAR; PG8_MMA(1, 0, At, B0); PG8_MMA(1, 1, At, B1); PG8_BAR; PG8_SCHED;
;             PG8_LDB(B0, 1, 0); PG8_LDB(B1, 1, 1); PG8_SCHED; PG8_LDA(At, 1, 0); PG8_STAGE(PG8_SA(0, 1), a2 + hstepA, voffA);
;             PG8_WAIT_V(8); PG8_WAIT_L(0); PG8_BAR; PG8_MMA(0, 0, At, B0); PG8_MMA(0, 1, At, B1); PG8_BAR; PG8_SCHED;
	s_setprio 1
	s_waitcnt lgkmcnt(0)
	v_mfma_f32_16x16x32_bf16 v[62:65], v[130:133], v[162:165], v[62:65]
	v_mfma_f32_16x16x32_bf16 v[58:61], v[138:141], v[162:165], v[58:61]
	v_mfma_f32_16x16x32_bf16 v[50:53], v[130:133], v[170:173], v[50:53]
	v_mfma_f32_16x16x32_bf16 v[42:45], v[138:141], v[170:173], v[42:45]
	v_mfma_f32_16x16x32_bf16 v[30:33], v[130:133], v[200:203], v[30:33]
	v_mfma_f32_16x16x32_bf16 v[26:29], v[138:141], v[200:203], v[26:29]
	v_mfma_f32_16x16x32_bf16 v[18:21], v[130:133], v[208:211], v[18:21]
	v_mfma_f32_16x16x32_bf16 v[10:13], v[138:141], v[208:211], v[10:13]
	v_mfma_f32_16x16x32_bf16 v[62:65], v[134:137], v[166:169], v[62:65]
	v_mfma_f32_16x16x32_bf16 v[58:61], v[142:145], v[166:169], v[58:61]
	v_mfma_f32_16x16x32_bf16 v[50:53], v[134:137], v[174:177], v[50:53]
	v_mfma_f32_16x16x32_bf16 v[42:45], v[142:145], v[174:177], v[42:45]
	v_mfma_f32_16x16x32_bf16 v[30:33], v[134:137], v[204:207], v[30:33]
	v_mfma_f32_16x16x32_bf16 v[26:29], v[142:145], v[204:207], v[26:29]
	v_mfma_f32_16x16x32_bf16 v[18:21], v[134:137], v[212:215], v[18:21]
	v_mfma_f32_16x16x32_bf16 v[10:13], v[142:145], v[212:215], v[10:13]
	v_mfma_f32_16x16x32_bf16 v[54:57], v[146:149], v[162:165], v[54:57]
	v_mfma_f32_16x16x32_bf16 v[46:49], v[154:157], v[162:165], v[46:49]
	v_mfma_f32_16x16x32_bf16 v[38:41], v[146:149], v[170:173], v[38:41]
	v_mfma_f32_16x16x32_bf16 v[34:37], v[154:157], v[170:173], v[34:37]
	v_mfma_f32_16x16x32_bf16 v[22:25], v[146:149], v[200:203], v[22:25]
	v_mfma_f32_16x16x32_bf16 v[14:17], v[154:157], v[200:203], v[14:17]
	v_mfma_f32_16x16x32_bf16 v[6:9], v[146:149], v[208:211], v[6:9]
	v_mfma_f32_16x16x32_bf16 v[2:5], v[154:157], v[208:211], v[2:5]
	v_mfma_f32_16x16x32_bf16 v[54:57], v[150:153], v[166:169], v[54:57]
	v_mfma_f32_16x16x32_bf16 v[46:49], v[158:161], v[166:169], v[46:49]
	v_mfma_f32_16x16x32_bf16 v[38:41], v[150:153], v[174:177], v[38:41]
	v_mfma_f32_16x16x32_bf16 v[34:37], v[158:161], v[174:177], v[34:37]
	v_mfma_f32_16x16x32_bf16 v[22:25], v[150:153], v[204:207], v[22:25]
	v_mfma_f32_16x16x32_bf16 v[14:17], v[158:161], v[204:207], v[14:17]
	v_mfma_f32_16x16x32_bf16 v[6:9], v[150:153], v[212:215], v[6:9]
	v_mfma_f32_16x16x32_bf16 v[2:5], v[158:161], v[212:215], v[2:5]
	s_setprio 0
	s_barrier
	s_add_i32 s41, 0, 0x18000
	s_add_i32 s53, 0, 0x1c000
	v_add_u32_e32 v142, s41, v1
	v_add_u32_e32 v158, s53, v1
	ds_read_b128 v[130:133], v142
	ds_read_b128 v[134:137], v142 offset:1024
	ds_read_b128 v[138:141], v142 offset:2048
	ds_read_b128 v[142:145], v142 offset:3072
	ds_read_b128 v[146:149], v158
	ds_read_b128 v[150:153], v158 offset:1024
	ds_read_b128 v[154:157], v158 offset:2048
	ds_read_b128 v[158:161], v158 offset:3072
	s_add_u32 s28, s28, 0x80000
	s_addc_u32 s29, s29, 0
	s_mov_b32 m0, s33
	v_lshl_add_u64 v[220:221], s[28:29], 0, v[188:189]
	ds_read_b128 v[162:165], v181 offset:32768
	ds_read_b128 v[166:169], v181 offset:33792
	ds_read_b128 v[170:173], v181 offset:34816
	ds_read_b128 v[174:177], v181 offset:35840
	ds_read_b128 v[200:203], v181 offset:36864
	ds_read_b128 v[204:207], v181 offset:37888
	ds_read_b128 v[208:211], v181 offset:38912
	ds_read_b128 v[212:215], v181 offset:39936
	global_load_lds_dwordx4 v[220:221], off
	v_lshl_add_u64 v[220:221], s[28:29], 0, v[192:193]
	s_mov_b32 m0, s34
	s_nop 0
	global_load_lds_dwordx4 v[220:221], off
	s_waitcnt vmcnt(8)
	s_waitcnt lgkmcnt(0)
	s_barrier
	s_setprio 1
	s_waitcnt lgkmcnt(0)
	v_mfma_f32_16x16x32_bf16 v[126:129], v[130:133], v[162:165], v[126:129]
	v_mfma_f32_16x16x32_bf16 v[122:125], v[138:141], v[162:165], v[122:125]
	v_mfma_f32_16x16x32_bf16 v[110:113], v[130:133], v[170:173], v[110:113]
	v_mfma_f32_16x16x32_bf16 v[106:109], v[138:141], v[170:173], v[106:109]
	v_mfma_f32_16x16x32_bf16 v[94:97], v[130:133], v[200:203], v[94:97]
	v_mfma_f32_16x16x32_bf16 v[90:93], v[138:141], v[200:203], v[90:93]
	v_mfma_f32_16x16x32_bf16 v[82:85], v[130:133], v[208:211], v[82:85]
	v_mfma_f32_16x16x32_bf16 v[74:77], v[138:141], v[208:211], v[74:77]
	v_mfma_f32_16x16x32_bf16 v[126:129], v[134:137], v[166:169], v[126:129]
	v_mfma_f32_16x16x32_bf16 v[122:125], v[142:145], v[166:169], v[122:125]
	v_mfma_f32_16x16x32_bf16 v[110:113], v[134:137], v[174:177], v[110:113]
	v_mfma_f32_16x16x32_bf16 v[106:109], v[142:145], v[174:177], v[106:109]
	v_mfma_f32_16x16x32_bf16 v[94:97], v[134:137], v[204:207], v[94:97]
	v_mfma_f32_16x16x32_bf16 v[90:93], v[142:145], v[204:207], v[90:93]
	v_mfma_f32_16x16x32_bf16 v[82:85], v[134:137], v[212:215], v[82:85]
	v_mfma_f32_16x16x32_bf16 v[74:77], v[142:145], v[212:215], v[74:77]
	v_mfma_f32_16x16x32_bf16 v[118:121], v[146:149], v[162:165], v[118:121]
	v_mfma_f32_16x16x32_bf16 v[114:117], v[154:157], v[162:165], v[114:117]
	v_mfma_f32_16x16x32_bf16 v[102:105], v[146:149], v[170:173], v[102:105]
	v_mfma_f32_16x16x32_bf16 v[98:101], v[154:157], v[170:173], v[98:101]
	v_mfma_f32_16x16x32_bf16 v[86:89], v[146:149], v[200:203], v[86:89]
	v_mfma_f32_16x16x32_bf16 v[78:81], v[154:157], v[200:203], v[78:81]
	v_mfma_f32_16x16x32_bf16 v[70:73], v[146:149], v[208:211], v[70:73]
	v_mfma_f32_16x16x32_bf16 v[66:69], v[154:157], v[208:211], v[66:69]
	v_mfma_f32_16x16x32_bf16 v[118:121], v[150:153], v[166:169], v[118:121]
	v_mfma_f32_16x16x32_bf16 v[114:117], v[158:161], v[166:169], v[114:117]
	v_mfma_f32_16x16x32_bf16 v[102:105], v[150:153], v[174:177], v[102:105]
	v_mfma_f32_16x16x32_bf16 v[98:101], v[158:161], v[174:177], v[98:101]
	v_mfma_f32_16x16x32_bf16 v[86:89], v[150:153], v[204:207], v[86:89]
	v_mfma_f32_16x16x32_bf16 v[78:81], v[158:161], v[204:207], v[78:81]
	v_mfma_f32_16x16x32_bf16 v[70:73], v[150:153], v[212:215], v[70:73]
	v_mfma_f32_16x16x32_bf16 v[66:69], v[158:161], v[212:215], v[66:69]
	s_setprio 0
	s_barrier
; #define PG8_STAGE(bufoff, gbase, voff) do { _Pragma("unroll") for (int _i = 0; _i < 2; ++_i) \
;         __builtin_amdgcn_global_load_lds((const unsigned*)((const char*)(gbase) + (voff)[_i]), (LAS unsigned*)(lds + (bufoff) + ldsw + _i * 8192), 16, 0, 0); } while (0)
; #define PG8_LDA(dst, b, h) do { _Pragma("unroll") for (int m = 0; m < 4; ++m) _Pragma("unroll") for (int k = 0; k < 2; ++k) dst[m][k] = *(const LAS bf16x8*)(lds + PG8_SA(b, h) + aoff + m * 2048 + k * 1024); } while (0)
; #define PG8_MMA(ai, bj, At, Bt) do { __builtin_amdgcn_s_setprio(1); _Pragma("unroll") for (int m = 0; m < 4; ++m) _Pragma("unroll") for (int n = 0; n < 2; ++n) _Pragma("unroll") for (int k = 0; k < 2; ++k) \
;         acc[ai][bj][m][n] = __builtin_amdgcn_mfma_f32_16x16x32_bf16(Bt[n][k], At[m][k], acc[ai][bj][m][n], 0, 0, 0); __builtin_amdgcn_s_setprio(0); } while (0)
; #define PG8_WAIT_V(n) asm volatile("s_waitcnt vmcnt(" #n ")" ::: "memory")
; #define PG8_WAIT_L(n) asm volatile("s_waitcnt lgkmcnt(" #n ")" ::: "memory")
; #define PG8_BAR __builtin_amdgcn_s_barrier()
; #define PG8_SCHED __builtin_amdgcn_sched_barrier(0)
; template <class Epi>
; __device__ __forceinline__ void gemm_phase(LAS unsigned char* lds, const Gemm g, const StaticOrder& S, const Epi& E) {
;     ...
;             PG8_LDA(At, 1, 1); PG8_STAGE(PG8_SB(1, 0), b3, voffB); PG8_STAGE(PG8_SB(1, 1), b3 + hstepB, voffB); PG8_STAGE(PG8_SA(1, 0), a3, voffA);
;             PG8_WAIT_V(8); PG8_WAIT_L(0); PG8_BAR; PG8_MMA(1, 0, At, B0); PG8_MMA(1, 1, At, B1); PG8_BAR; PG8_SCHED;
	s_add_i32 s28, s41, s30
	v_lshl_add_u64 v[178:179], v[178:179], 0, s[84:85]
	s_mov_b32 m0, s28
	ds_read_b128 v[162:165], v181 offset:49152
	ds_read_b128 v[166:169], v181 offset:50176
	ds_read_b128 v[170:173], v181 offset:51200
	ds_read_b128 v[174:177], v181 offset:52224
	ds_read_b128 v[200:203], v181 offset:53248
	ds_read_b128 v[204:207], v181 offset:54272
	ds_read_b128 v[208:211], v181 offset:55296
	ds_read_b128 v[212:215], v181 offset:56320
	global_load_lds_dwordx4 v[178:179], off
	s_add_i32 m0, s28, 0x2000
	s_add_u32 s14, s14, 0x80080
	v_lshl_add_u64 v[178:179], v[184:185], 0, s[84:85]
	s_addc_u32 s15, s15, 0
	s_add_i32 s28, s53, s30
	global_load_lds_dwordx4 v[178:179], off
	v_lshl_add_u64 v[178:179], s[14:15], 0, v[190:191]
	s_mov_b32 m0, s28
	s_nop 0
	global_load_lds_dwordx4 v[178:179], off
	v_lshl_add_u64 v[178:179], s[14:15], 0, v[194:195]
	s_add_i32 m0, s28, 0x2000
	s_nop 0
	global_load_lds_dwordx4 v[178:179], off
	v_lshl_add_u64 v[178:179], v[216:217], 0, s[84:85]
	s_mov_b32 m0, s44
	s_nop 0
	global_load_lds_dwordx4 v[178:179], off
	v_lshl_add_u64 v[178:179], v[218:219], 0, s[84:85]
	s_mov_b32 m0, s45
	s_nop 0
	global_load_lds_dwordx4 v[178:179], off
	s_waitcnt vmcnt(8)
	s_waitcnt lgkmcnt(0)
	s_barrier
	s_setprio 1
	s_waitcnt lgkmcnt(0)
	v_mfma_f32_16x16x32_bf16 v[62:65], v[130:133], v[162:165], v[62:65]
	v_mfma_f32_16x16x32_bf16 v[58:61], v[138:141], v[162:165], v[58:61]
	v_mfma_f32_16x16x32_bf16 v[50:53], v[130:133], v[170:173], v[50:53]
	v_mfma_f32_16x16x32_bf16 v[42:45], v[138:141], v[170:173], v[42:45]
	v_mfma_f32_16x16x32_bf16 v[30:33], v[130:133], v[200:203], v[30:33]
	v_mfma_f32_16x16x32_bf16 v[26:29], v[138:141], v[200:203], v[26:29]
	v_mfma_f32_16x16x32_bf16 v[18:21], v[130:133], v[208:211], v[18:21]
	v_mfma_f32_16x16x32_bf16 v[10:13], v[138:141], v[208:211], v[10:13]
	v_mfma_f32_16x16x32_bf16 v[62:65], v[134:137], v[166:169], v[62:65]
	v_mfma_f32_16x16x32_bf16 v[58:61], v[142:145], v[166:169], v[58:61]
	v_mfma_f32_16x16x32_bf16 v[50:53], v[134:137], v[174:177], v[50:53]
	v_mfma_f32_16x16x32_bf16 v[42:45], v[142:145], v[174:177], v[42:45]
	v_mfma_f32_16x16x32_bf16 v[30:33], v[134:137], v[204:207], v[30:33]
	v_mfma_f32_16x16x32_bf16 v[26:29], v[142:145], v[204:207], v[26:29]
	v_mfma_f32_16x16x32_bf16 v[18:21], v[134:137], v[212:215], v[18:21]
	v_mfma_f32_16x16x32_bf16 v[10:13], v[142:145], v[212:215], v[10:13]
	v_mfma_f32_16x16x32_bf16 v[54:57], v[146:149], v[162:165], v[54:57]
	v_mfma_f32_16x16x32_bf16 v[46:49], v[154:157], v[162:165], v[46:49]
	v_mfma_f32_16x16x32_bf16 v[38:41], v[146:149], v[170:173], v[38:41]
	v_mfma_f32_16x16x32_bf16 v[34:37], v[154:157], v[170:173], v[34:37]
	v_mfma_f32_16x16x32_bf16 v[22:25], v[146:149], v[200:203], v[22:25]
	v_mfma_f32_16x16x32_bf16 v[14:17], v[154:157], v[200:203], v[14:17]
	v_mfma_f32_16x16x32_bf16 v[6:9], v[146:149], v[208:211], v[6:9]
	v_mfma_f32_16x16x32_bf16 v[2:5], v[154:157], v[208:211], v[2:5]
	v_mfma_f32_16x16x32_bf16 v[54:57], v[150:153], v[166:169], v[54:57]
	v_mfma_f32_16x16x32_bf16 v[46:49], v[158:161], v[166:169], v[46:49]
	v_mfma_f32_16x16x32_bf16 v[38:41], v[150:153], v[174:177], v[38:41]
	v_mfma_f32_16x16x32_bf16 v[34:37], v[158:161], v[174:177], v[34:37]
	v_mfma_f32_16x16x32_bf16 v[22:25], v[150:153], v[204:207], v[22:25]
	v_mfma_f32_16x16x32_bf16 v[14:17], v[158:161], v[204:207], v[14:17]
	v_mfma_f32_16x16x32_bf16 v[6:9], v[150:153], v[212:215], v[6:9]
	v_mfma_f32_16x16x32_bf16 v[2:5], v[158:161], v[212:215], v[2:5]
	s_setprio 0
	s_barrier
	s_add_i32 s52, s52, 2
	s_add_u32 s26, s26, 0x100
	s_addc_u32 s27, s27, 0
	s_add_u32 s19, s19, 0x100
	s_addc_u32 s40, s40, 0
	s_cmp_gt_u32 s52, 29
	s_cbranch_scc0 .LBB0_1010
	s_cmp_ge_u32 s74, 16
	s_cbranch_scc1 .Lwpf_a
	s_lshl_b32 s100, s74, 9
	v_add_u32_e32 v130, s100, v246
	v_lshrrev_b32_e32 v131, 2, v130
	v_and_b32_e32 v130, 3, v130
	v_lshlrev_b32_e32 v130, 7, v130
	v_lshl_add_u32 v130, v131, 12, v130
	s_add_u32 s100, s88, 0x1800000
	s_addc_u32 s101, s89, 0
	s_mov_b32 m0, 0x21000
	s_nop 0
	global_load_lds_dword v130, s[100:101]

; #define PG8_STAGE(bufoff, gbase, voff) do { _Pragma("unroll") for (int _i = 0; _i < 2; ++_i) \
;         __builtin_amdgcn_global_load_lds((const unsigned*)((const char*)(gbase) + (voff)[_i]), (LAS unsigned*)(lds + (bufoff) + ldsw + _i * 8192), 16, 0, 0); } while (0)
; #define PG8_LDA(dst, b, h) do { _Pragma("unroll") for (int m = 0; m < 4; ++m) _Pragma("unroll") for (int k = 0; k < 2; ++k) dst[m][k] = *(const LAS bf16x8*)(lds + PG8_SA(b, h) + aoff + m * 2048 + k * 1024); } while (0)
; #define PG8_LDB(dst, b, h) do { _Pragma("unroll") for (int n = 0; n < 2; ++n) _Pragma("unroll") for (int k = 0; k < 2; ++k) dst[n][k] = *(const LAS bf16x8*)(lds + PG8_SB(b, h) + boff + n * 2048 + k * 1024); } while (0)
; #define PG8_MMA(ai, bj, At, Bt) do { __builtin_amdgcn_s_setprio(1); _Pragma("unroll") for (int m = 0; m < 4; ++m) _Pragma("unroll") for (int n = 0; n < 2; ++n) _Pragma("unroll") for (int k = 0; k < 2; ++k) \
;         acc[ai][bj][m][n] = __builtin_amdgcn_mfma_f32_16x16x32_bf16(Bt[n][k], At[m][k], acc[ai][bj][m][n], 0, 0, 0); __builtin_amdgcn_s_setprio(0); } while (0)
; #define PG8_WAIT_V(n) asm volatile("s_waitcnt vmcnt(" #n ")" ::: "memory")
; #define PG8_WAIT_L(n) asm volatile("s_waitcnt lgkmcnt(" #n ")" ::: "memory")
; #define PG8_BAR __builtin_amdgcn_s_barrier()
; #define PG8_SCHED __builtin_amdgcn_sched_barrier(0)
; template <class Epi>
; __device__ __forceinline__ void gemm_phase(LAS unsigned char* lds, const Gemm g, const StaticOrder& S, const Epi& E) {
;     ...
;             const bool last = (t == nt - 2);
;             const char* a1 = cA + (size_t)(t + 1) * kstep;
;             const char* a2 = last ? nA : cA + (size_t)(t + 2) * kstep; const char* b2 = last ? nB : cB + (size_t)(t + 2) * kstep;
;             const char* a3 = a2 + kstep; const char* b3 = b2 + kstep;
;             PG8_LDB(B0, 0, 0); PG8_LDB(B1, 0, 1); PG8_SCHED; PG8_LDA(At, 0, 0); PG8_STAGE(PG8_SA(1, 1), a1 + hstepA, voffA);
;             PG8_WAIT_V(8); PG8_WAIT_L(0); PG8_BAR; PG8_MMA(0, 0, At, B0); PG8_MMA(0, 1, At, B1); PG8_BAR; PG8_SCHED;
;             PG8_LDA(At, 0, 1); PG8_STAGE(PG8_SB(0, 0), b2, voffB); PG8_STAGE(PG8_SB(0, 1), b2 + hstepB, voffB); PG8_STAGE(PG8_SA(0, 0), a2, voffA);
;             PG8_WAIT_V(8); PG8_WAIT_L(0); PG8_BAR; PG8_MMA(1, 0, At, B0); PG8_MMA(1, 1, At, B1); PG8_BAR; PG8_SCHED;
.LBB0_1107:
	s_add_u32 s34, vcc_lo, 0xfff80080
	s_addc_u32 s35, vcc_hi, -1
	s_add_i32 s76, 0, 0x10000
	s_cmp_eq_u32 s41, 28
	s_cselect_b32 s69, s3, s35
	s_cselect_b32 s68, s7, s34
	s_cselect_b32 s35, s13, s87
	s_cselect_b32 s34, s40, s65
	s_add_i32 s78, 0, 0x14000
	v_add_u32_e32 v142, s76, v1
	v_add_u32_e32 v163, s78, v1
	ds_read_b128 v[130:133], v142
	ds_read_b128 v[134:137], v142 offset:1024
	ds_read_b128 v[138:141], v142 offset:2048
	ds_read_b128 v[142:145], v142 offset:3072
	ds_read_b128 v[158:161], v163
	ds_read_b128 v[164:167], v163 offset:1024
	ds_read_b128 v[168:171], v163 offset:2048
	ds_read_b128 v[172:175], v163 offset:3072
	v_lshl_add_u64 v[184:185], vcc, 0, v[154:155]
	s_add_i32 m0, s70, 0xc000
	ds_read_b128 v[176:179], v162
	ds_read_b128 v[188:191], v162 offset:1024
	ds_read_b128 v[192:195], v162 offset:2048
	ds_read_b128 v[196:199], v162 offset:3072
	ds_read_b128 v[200:203], v162 offset:4096
	ds_read_b128 v[204:207], v162 offset:5120
	ds_read_b128 v[208:211], v162 offset:6144
	ds_read_b128 v[212:215], v162 offset:7168
	global_load_lds_dwordx4 v[184:185], off
	v_lshl_add_u64 v[184:185], vcc, 0, v[156:157]
	s_add_i32 m0, s70, 0xe000
	s_nop 0
	global_load_lds_dwordx4 v[184:185], off
	s_waitcnt vmcnt(8)
	s_waitcnt lgkmcnt(0)
	s_barrier
	s_setprio 1
	s_waitcnt lgkmcnt(0)
	v_mfma_f32_16x16x32_bf16 v[126:129], v[130:133], v[176:179], v[126:129]
	v_mfma_f32_16x16x32_bf16 v[122:125], v[138:141], v[176:179], v[122:125]
	v_mfma_f32_16x16x32_bf16 v[114:117], v[130:133], v[192:195], v[114:117]
	v_mfma_f32_16x16x32_bf16 v[106:109], v[138:141], v[192:195], v[106:109]
	v_mfma_f32_16x16x32_bf16 v[98:101], v[130:133], v[200:203], v[98:101]
	v_mfma_f32_16x16x32_bf16 v[90:93], v[138:141], v[200:203], v[90:93]
	v_mfma_f32_16x16x32_bf16 v[82:85], v[130:133], v[208:211], v[82:85]
	v_mfma_f32_16x16x32_bf16 v[74:77], v[138:141], v[208:211], v[74:77]
	v_mfma_f32_16x16x32_bf16 v[126:129], v[134:137], v[188:191], v[126:129]
	v_mfma_f32_16x16x32_bf16 v[122:125], v[142:145], v[188:191], v[122:125]
	v_mfma_f32_16x16x32_bf16 v[114:117], v[134:137], v[196:199], v[114:117]
	v_mfma_f32_16x16x32_bf16 v[106:109], v[142:145], v[196:199], v[106:109]
	v_mfma_f32_16x16x32_bf16 v[98:101], v[134:137], v[204:207], v[98:101]
	v_mfma_f32_16x16x32_bf16 v[90:93], v[142:145], v[204:207], v[90:93]
	v_mfma_f32_16x16x32_bf16 v[82:85], v[134:137], v[212:215], v[82:85]
	v_mfma_f32_16x16x32_bf16 v[74:77], v[142:145], v[212:215], v[74:77]
	v_mfma_f32_16x16x32_bf16 v[118:121], v[158:161], v[176:179], v[118:121]
	v_mfma_f32_16x16x32_bf16 v[110:113], v[168:171], v[176:179], v[110:113]
	v_mfma_f32_16x16x32_bf16 v[102:105], v[158:161], v[192:195], v[102:105]
	v_mfma_f32_16x16x32_bf16 v[94:97], v[168:171], v[192:195], v[94:97]
	v_mfma_f32_16x16x32_bf16 v[86:89], v[158:161], v[200:203], v[86:89]
	v_mfma_f32_16x16x32_bf16 v[78:81], v[168:171], v[200:203], v[78:81]
	v_mfma_f32_16x16x32_bf16 v[70:73], v[158:161], v[208:211], v[70:73]
	v_mfma_f32_16x16x32_bf16 v[66:69], v[168:171], v[208:211], v[66:69]
	v_mfma_f32_16x16x32_bf16 v[118:121], v[164:167], v[188:191], v[118:121]
	v_mfma_f32_16x16x32_bf16 v[110:113], v[172:175], v[188:191], v[110:113]
	v_mfma_f32_16x16x32_bf16 v[102:105], v[164:167], v[196:199], v[102:105]
	v_mfma_f32_16x16x32_bf16 v[94:97], v[172:175], v[196:199], v[94:97]
	v_mfma_f32_16x16x32_bf16 v[86:89], v[164:167], v[204:207], v[86:89]
	v_mfma_f32_16x16x32_bf16 v[78:81], v[172:175], v[204:207], v[78:81]
	v_mfma_f32_16x16x32_bf16 v[70:73], v[164:167], v[212:215], v[70:73]
	v_mfma_f32_16x16x32_bf16 v[66:69], v[172:175], v[212:215], v[66:69]
	s_setprio 0
	s_barrier
	s_add_i32 s76, s76, s42
	v_lshl_add_u64 v[184:185], s[34:35], 0, v[148:149]
	s_mov_b32 m0, s76
	ds_read_b128 v[176:179], v162 offset:16384
	ds_read_b128 v[188:191], v162 offset:17408
	ds_read_b128 v[192:195], v162 offset:18432
	ds_read_b128 v[196:199], v162 offset:19456
	ds_read_b128 v[200:203], v162 offset:20480
	ds_read_b128 v[204:207], v162 offset:21504
	ds_read_b128 v[208:211], v162 offset:22528
	ds_read_b128 v[212:215], v162 offset:23552
	global_load_lds_dwordx4 v[184:185], off
	s_add_i32 m0, s76, 0x2000
	s_add_u32 s76, s34, 0x80000
	v_lshl_add_u64 v[216:217], s[34:35], 0, v[152:153]
	s_addc_u32 s77, s35, 0
	s_add_i32 s78, s78, s42
	global_load_lds_dwordx4 v[216:217], off
	v_lshl_add_u64 v[218:219], s[76:77], 0, v[148:149]
	s_mov_b32 m0, s78
	v_lshl_add_u64 v[220:221], s[68:69], 0, v[150:151]
	global_load_lds_dwordx4 v[218:219], off
	v_lshl_add_u64 v[218:219], s[76:77], 0, v[152:153]
	s_add_i32 m0, s78, 0x2000
	s_nop 0
	global_load_lds_dwordx4 v[218:219], off
	v_lshl_add_u64 v[218:219], s[68:69], 0, v[146:147]
	s_mov_b32 m0, s70
	s_nop 0
	global_load_lds_dwordx4 v[218:219], off
	s_mov_b32 m0, s91
	s_nop 0
	global_load_lds_dwordx4 v[220:221], off
	s_waitcnt vmcnt(8)
	s_waitcnt lgkmcnt(0)
	s_barrier
; #define PG8_STAGE(bufoff, gbase, voff) do { _Pragma("unroll") for (int _i = 0; _i < 2; ++_i) \
;         __builtin_amdgcn_global_load_lds((const unsigned*)((const char*)(gbase) + (voff)[_i]), (LAS unsigned*)(lds + (bufoff) + ldsw + _i * 8192), 16, 0, 0); } while (0)
; #define PG8_LDA(dst, b, h) do { _Pragma("unroll") for (int m = 0; m < 4; ++m) _Pragma("unroll") for (int k = 0; k < 2; ++k) dst[m][k] = *(const LAS bf16x8*)(lds + PG8_SA(b, h) + aoff + m * 2048 + k * 1024); } while (0)
; #define PG8_LDB(dst, b, h) do { _Pragma("unroll") for (int n = 0; n < 2; ++n) _Pragma("unroll") for (int k = 0; k < 2; ++k) dst[n][k] = *(const LAS bf16x8*)(lds + PG8_SB(b, h) + boff + n * 2048 + k * 1024); } while (0)
; #define PG8_MMA(ai, bj, At, Bt) do { __builtin_amdgcn_s_setprio(1); _Pragma("unroll") for (int m = 0; m < 4; ++m) _Pragma("unroll") for (int n = 0; n < 2; ++n) _Pragma("unroll") for (int k = 0; k < 2; ++k) \
;         acc[ai][bj][m][n] = __builtin_amdgcn_mfma_f32_16x16x32_bf16(Bt[n][k], At[m][k], acc[ai][bj][m][n], 0, 0, 0); __builtin_amdgcn_s_setprio(0); } while (0)
; #define PG8_WAIT_V(n) asm volatile("s_waitcnt vmcnt(" #n ")" ::: "memory")
; #define PG8_WAIT_L(n) asm volatile("s_waitcnt lgkmcnt(" #n ")" ::: "memory")
; #define PG8_BAR __builtin_amdgcn_s_barrier()
; #define PG8_SCHED __builtin_amdgcn_sched_barrier(0)
; template <class Epi>
; __device__ __forceinline__ void gemm_phase(LAS unsigned char* lds, const Gemm g, const StaticOrder& S, const Epi& E) {
;     ...
;             PG8_WAIT_V(8); PG8_WAIT_L(0); PG8_BAR; PG8_MMA(1, 0, At, B0); PG8_MMA(1, 1, At, B1); PG8_BAR; PG8_SCHED;
;             PG8_LDB(B0, 1, 0); PG8_LDB(B1, 1, 1); PG8_SCHED; PG8_LDA(At, 1, 0); PG8_STAGE(PG8_SA(0, 1), a2 + hstepA, voffA);
;             PG8_WAIT_V(8); PG8_WAIT_L(0); PG8_BAR; PG8_MMA(0, 0, At, B0); PG8_MMA(0, 1, At, B1); PG8_BAR; PG8_SCHED;
	s_setprio 1
	s_waitcnt lgkmcnt(0)
	v_mfma_f32_16x16x32_bf16 v[62:65], v[130:133], v[176:179], v[62:65]
	v_mfma_f32_16x16x32_bf16 v[58:61], v[138:141], v[176:179], v[58:61]
	v_mfma_f32_16x16x32_bf16 v[54:57], v[130:133], v[192:195], v[54:57]
	v_mfma_f32_16x16x32_bf16 v[46:49], v[138:141], v[192:195], v[46:49]
	v_mfma_f32_16x16x32_bf16 v[38:41], v[130:133], v[200:203], v[38:41]
	v_mfma_f32_16x16x32_bf16 v[30:33], v[138:141], v[200:203], v[30:33]
	v_mfma_f32_16x16x32_bf16 v[22:25], v[130:133], v[208:211], v[22:25]
	v_mfma_f32_16x16x32_bf16 v[14:17], v[138:141], v[208:211], v[14:17]
	v_mfma_f32_16x16x32_bf16 v[62:65], v[134:137], v[188:191], v[62:65]
	v_mfma_f32_16x16x32_bf16 v[58:61], v[142:145], v[188:191], v[58:61]
	v_mfma_f32_16x16x32_bf16 v[54:57], v[134:137], v[196:199], v[54:57]
	v_mfma_f32_16x16x32_bf16 v[46:49], v[142:145], v[196:199], v[46:49]
	v_mfma_f32_16x16x32_bf16 v[38:41], v[134:137], v[204:207], v[38:41]
	v_mfma_f32_16x16x32_bf16 v[30:33], v[142:145], v[204:207], v[30:33]
	v_mfma_f32_16x16x32_bf16 v[22:25], v[134:137], v[212:215], v[22:25]
	v_mfma_f32_16x16x32_bf16 v[14:17], v[142:145], v[212:215], v[14:17]
	v_mfma_f32_16x16x32_bf16 v[50:53], v[158:161], v[176:179], v[50:53]
	v_mfma_f32_16x16x32_bf16 v[42:45], v[168:171], v[176:179], v[42:45]
	v_mfma_f32_16x16x32_bf16 v[34:37], v[158:161], v[192:195], v[34:37]
	v_mfma_f32_16x16x32_bf16 v[26:29], v[168:171], v[192:195], v[26:29]
	v_mfma_f32_16x16x32_bf16 v[18:21], v[158:161], v[200:203], v[18:21]
	v_mfma_f32_16x16x32_bf16 v[10:13], v[168:171], v[200:203], v[10:13]
	v_mfma_f32_16x16x32_bf16 v[6:9], v[158:161], v[208:211], v[6:9]
	v_mfma_f32_16x16x32_bf16 v[2:5], v[168:171], v[208:211], v[2:5]
	v_mfma_f32_16x16x32_bf16 v[50:53], v[164:167], v[188:191], v[50:53]
	v_mfma_f32_16x16x32_bf16 v[42:45], v[172:175], v[188:191], v[42:45]
	v_mfma_f32_16x16x32_bf16 v[34:37], v[164:167], v[196:199], v[34:37]
	v_mfma_f32_16x16x32_bf16 v[26:29], v[172:175], v[196:199], v[26:29]
	v_mfma_f32_16x16x32_bf16 v[18:21], v[164:167], v[204:207], v[18:21]
	v_mfma_f32_16x16x32_bf16 v[10:13], v[172:175], v[204:207], v[10:13]
	v_mfma_f32_16x16x32_bf16 v[6:9], v[164:167], v[212:215], v[6:9]
	v_mfma_f32_16x16x32_bf16 v[2:5], v[172:175], v[212:215], v[2:5]
	s_setprio 0
	s_barrier
	s_add_i32 s76, 0, 0x18000
	s_add_i32 s77, 0, 0x1c000
	v_add_u32_e32 v142, s76, v1
	v_add_u32_e32 v163, s77, v1
	ds_read_b128 v[130:133], v142
	ds_read_b128 v[134:137], v142 offset:1024
	ds_read_b128 v[138:141], v142 offset:2048
	ds_read_b128 v[142:145], v142 offset:3072
	ds_read_b128 v[158:161], v163
	ds_read_b128 v[164:167], v163 offset:1024
	ds_read_b128 v[168:171], v163 offset:2048
	ds_read_b128 v[172:175], v163 offset:3072
	s_add_u32 s68, s68, 0x80000
	s_addc_u32 s69, s69, 0
	s_mov_b32 m0, s62
	v_lshl_add_u64 v[222:223], s[68:69], 0, v[146:147]
	ds_read_b128 v[176:179], v162 offset:32768
	ds_read_b128 v[188:191], v162 offset:33792
	ds_read_b128 v[192:195], v162 offset:34816
	ds_read_b128 v[196:199], v162 offset:35840
	ds_read_b128 v[200:203], v162 offset:36864
	ds_read_b128 v[204:207], v162 offset:37888
	ds_read_b128 v[208:211], v162 offset:38912
	ds_read_b128 v[212:215], v162 offset:39936
	global_load_lds_dwordx4 v[222:223], off
	v_lshl_add_u64 v[222:223], s[68:69], 0, v[150:151]
	s_mov_b32 m0, s63
	s_nop 0
	global_load_lds_dwordx4 v[222:223], off
	s_waitcnt vmcnt(8)
	s_waitcnt lgkmcnt(0)
	s_barrier
	s_setprio 1
	s_waitcnt lgkmcnt(0)
	v_mfma_f32_16x16x32_bf16 v[126:129], v[130:133], v[176:179], v[126:129]
	v_mfma_f32_16x16x32_bf16 v[122:125], v[138:141], v[176:179], v[122:125]
	v_mfma_f32_16x16x32_bf16 v[114:117], v[130:133], v[192:195], v[114:117]
	v_mfma_f32_16x16x32_bf16 v[106:109], v[138:141], v[192:195], v[106:109]
	v_mfma_f32_16x16x32_bf16 v[98:101], v[130:133], v[200:203], v[98:101]
	v_mfma_f32_16x16x32_bf16 v[90:93], v[138:141], v[200:203], v[90:93]
	v_mfma_f32_16x16x32_bf16 v[82:85], v[130:133], v[208:211], v[82:85]
	v_mfma_f32_16x16x32_bf16 v[74:77], v[138:141], v[208:211], v[74:77]
	v_mfma_f32_16x16x32_bf16 v[126:129], v[134:137], v[188:191], v[126:129]
	v_mfma_f32_16x16x32_bf16 v[122:125], v[142:145], v[188:191], v[122:125]
	v_mfma_f32_16x16x32_bf16 v[114:117], v[134:137], v[196:199], v[114:117]
	v_mfma_f32_16x16x32_bf16 v[106:109], v[142:145], v[196:199], v[106:109]
	v_mfma_f32_16x16x32_bf16 v[98:101], v[134:137], v[204:207], v[98:101]
	v_mfma_f32_16x16x32_bf16 v[90:93], v[142:145], v[204:207], v[90:93]
	v_mfma_f32_16x16x32_bf16 v[82:85], v[134:137], v[212:215], v[82:85]
	v_mfma_f32_16x16x32_bf16 v[74:77], v[142:145], v[212:215], v[74:77]
	v_mfma_f32_16x16x32_bf16 v[118:121], v[158:161], v[176:179], v[118:121]
	v_mfma_f32_16x16x32_bf16 v[110:113], v[168:171], v[176:179], v[110:113]
	v_mfma_f32_16x16x32_bf16 v[102:105], v[158:161], v[192:195], v[102:105]
	v_mfma_f32_16x16x32_bf16 v[94:97], v[168:171], v[192:195], v[94:97]
	v_mfma_f32_16x16x32_bf16 v[86:89], v[158:161], v[200:203], v[86:89]
	v_mfma_f32_16x16x32_bf16 v[78:81], v[168:171], v[200:203], v[78:81]
	v_mfma_f32_16x16x32_bf16 v[70:73], v[158:161], v[208:211], v[70:73]
	v_mfma_f32_16x16x32_bf16 v[66:69], v[168:171], v[208:211], v[66:69]
	v_mfma_f32_16x16x32_bf16 v[118:121], v[164:167], v[188:191], v[118:121]
	v_mfma_f32_16x16x32_bf16 v[110:113], v[172:175], v[188:191], v[110:113]
	v_mfma_f32_16x16x32_bf16 v[102:105], v[164:167], v[196:199], v[102:105]
	v_mfma_f32_16x16x32_bf16 v[94:97], v[172:175], v[196:199], v[94:97]
	v_mfma_f32_16x16x32_bf16 v[86:89], v[164:167], v[204:207], v[86:89]
	v_mfma_f32_16x16x32_bf16 v[78:81], v[172:175], v[204:207], v[78:81]
	v_mfma_f32_16x16x32_bf16 v[70:73], v[164:167], v[212:215], v[70:73]
	v_mfma_f32_16x16x32_bf16 v[66:69], v[172:175], v[212:215], v[66:69]
	s_setprio 0
	s_barrier
; #define PG8_STAGE(bufoff, gbase, voff) do { _Pragma("unroll") for (int _i = 0; _i < 2; ++_i) \
;         __builtin_amdgcn_global_load_lds((const unsigned*)((const char*)(gbase) + (voff)[_i]), (LAS unsigned*)(lds + (bufoff) + ldsw + _i * 8192), 16, 0, 0); } while (0)
; #define PG8_LDA(dst, b, h) do { _Pragma("unroll") for (int m = 0; m < 4; ++m) _Pragma("unroll") for (int k = 0; k < 2; ++k) dst[m][k] = *(const LAS bf16x8*)(lds + PG8_SA(b, h) + aoff + m * 2048 + k * 1024); } while (0)
; #define PG8_MMA(ai, bj, At, Bt) do { __builtin_amdgcn_s_setprio(1); _Pragma("unroll") for (int m = 0; m < 4; ++m) _Pragma("unroll") for (int n = 0; n < 2; ++n) _Pragma("unroll") for (int k = 0; k < 2; ++k) \
;         acc[ai][bj][m][n] = __builtin_amdgcn_mfma_f32_16x16x32_bf16(Bt[n][k], At[m][k], acc[ai][bj][m][n], 0, 0, 0); __builtin_amdgcn_s_setprio(0); } while (0)
; #define PG8_WAIT_V(n) asm volatile("s_waitcnt vmcnt(" #n ")" ::: "memory")
; #define PG8_WAIT_L(n) asm volatile("s_waitcnt lgkmcnt(" #n ")" ::: "memory")
; #define PG8_BAR __builtin_amdgcn_s_barrier()
; #define PG8_SCHED __builtin_amdgcn_sched_barrier(0)
; template <class Epi>
; __device__ __forceinline__ void gemm_phase(LAS unsigned char* lds, const Gemm g, const StaticOrder& S, const Epi& E) {
;     ...
;             PG8_LDA(At, 1, 1); PG8_STAGE(PG8_SB(1, 0), b3, voffB); PG8_STAGE(PG8_SB(1, 1), b3 + hstepB, voffB); PG8_STAGE(PG8_SA(1, 0), a3, voffA);
;             PG8_WAIT_V(8); PG8_WAIT_L(0); PG8_BAR; PG8_MMA(1, 0, At, B0); PG8_MMA(1, 1, At, B1); PG8_BAR; PG8_SCHED;
;         }
;         if (wr == 0) PG8_BAR;
	s_add_i32 s68, s76, s42
	v_lshl_add_u64 v[184:185], v[184:185], 0, s[84:85]
	s_mov_b32 m0, s68
	ds_read_b128 v[176:179], v162 offset:49152
	ds_read_b128 v[188:191], v162 offset:50176
	ds_read_b128 v[192:195], v162 offset:51200
	ds_read_b128 v[196:199], v162 offset:52224
	ds_read_b128 v[200:203], v162 offset:53248
	ds_read_b128 v[204:207], v162 offset:54272
	ds_read_b128 v[208:211], v162 offset:55296
	ds_read_b128 v[212:215], v162 offset:56320
	global_load_lds_dwordx4 v[184:185], off
	s_add_i32 m0, s68, 0x2000
	s_add_u32 s34, s34, 0x80080
	v_lshl_add_u64 v[184:185], v[216:217], 0, s[84:85]
	s_addc_u32 s35, s35, 0
	s_add_i32 s68, s77, s42
	global_load_lds_dwordx4 v[184:185], off
	v_lshl_add_u64 v[184:185], s[34:35], 0, v[148:149]
	s_mov_b32 m0, s68
	s_nop 0
	global_load_lds_dwordx4 v[184:185], off
	v_lshl_add_u64 v[184:185], s[34:35], 0, v[152:153]
	s_add_i32 m0, s68, 0x2000
	s_nop 0
	global_load_lds_dwordx4 v[184:185], off
	v_lshl_add_u64 v[184:185], v[218:219], 0, s[84:85]
	s_mov_b32 m0, s94
	s_nop 0
	global_load_lds_dwordx4 v[184:185], off
	v_lshl_add_u64 v[184:185], v[220:221], 0, s[84:85]
	s_mov_b32 m0, s95
	s_nop 0
	global_load_lds_dwordx4 v[184:185], off
	s_waitcnt vmcnt(8)
	s_waitcnt lgkmcnt(0)
	s_barrier
	s_setprio 1
	s_waitcnt lgkmcnt(0)
	v_mfma_f32_16x16x32_bf16 v[62:65], v[130:133], v[176:179], v[62:65]
	v_mfma_f32_16x16x32_bf16 v[58:61], v[138:141], v[176:179], v[58:61]
	v_mfma_f32_16x16x32_bf16 v[54:57], v[130:133], v[192:195], v[54:57]
	v_mfma_f32_16x16x32_bf16 v[46:49], v[138:141], v[192:195], v[46:49]
	v_mfma_f32_16x16x32_bf16 v[38:41], v[130:133], v[200:203], v[38:41]
	v_mfma_f32_16x16x32_bf16 v[30:33], v[138:141], v[200:203], v[30:33]
	v_mfma_f32_16x16x32_bf16 v[22:25], v[130:133], v[208:211], v[22:25]
	v_mfma_f32_16x16x32_bf16 v[14:17], v[138:141], v[208:211], v[14:17]
	v_mfma_f32_16x16x32_bf16 v[62:65], v[134:137], v[188:191], v[62:65]
	v_mfma_f32_16x16x32_bf16 v[58:61], v[142:145], v[188:191], v[58:61]
	v_mfma_f32_16x16x32_bf16 v[54:57], v[134:137], v[196:199], v[54:57]
	v_mfma_f32_16x16x32_bf16 v[46:49], v[142:145], v[196:199], v[46:49]
	v_mfma_f32_16x16x32_bf16 v[38:41], v[134:137], v[204:207], v[38:41]
	v_mfma_f32_16x16x32_bf16 v[30:33], v[142:145], v[204:207], v[30:33]
	v_mfma_f32_16x16x32_bf16 v[22:25], v[134:137], v[212:215], v[22:25]
	v_mfma_f32_16x16x32_bf16 v[14:17], v[142:145], v[212:215], v[14:17]
	v_mfma_f32_16x16x32_bf16 v[50:53], v[158:161], v[176:179], v[50:53]
	v_mfma_f32_16x16x32_bf16 v[42:45], v[168:171], v[176:179], v[42:45]
	v_mfma_f32_16x16x32_bf16 v[34:37], v[158:161], v[192:195], v[34:37]
	v_mfma_f32_16x16x32_bf16 v[26:29], v[168:171], v[192:195], v[26:29]
	v_mfma_f32_16x16x32_bf16 v[18:21], v[158:161], v[200:203], v[18:21]
	v_mfma_f32_16x16x32_bf16 v[10:13], v[168:171], v[200:203], v[10:13]
	v_mfma_f32_16x16x32_bf16 v[6:9], v[158:161], v[208:211], v[6:9]
	v_mfma_f32_16x16x32_bf16 v[2:5], v[168:171], v[208:211], v[2:5]
	v_mfma_f32_16x16x32_bf16 v[50:53], v[164:167], v[188:191], v[50:53]
	v_mfma_f32_16x16x32_bf16 v[42:45], v[172:175], v[188:191], v[42:45]
	v_mfma_f32_16x16x32_bf16 v[34:37], v[164:167], v[196:199], v[34:37]
	v_mfma_f32_16x16x32_bf16 v[26:29], v[172:175], v[196:199], v[26:29]
	v_mfma_f32_16x16x32_bf16 v[18:21], v[164:167], v[204:207], v[18:21]
	v_mfma_f32_16x16x32_bf16 v[10:13], v[172:175], v[204:207], v[10:13]
	v_mfma_f32_16x16x32_bf16 v[6:9], v[164:167], v[212:215], v[6:9]
	v_mfma_f32_16x16x32_bf16 v[2:5], v[172:175], v[212:215], v[2:5]
	s_setprio 0
	s_barrier
	s_add_i32 s41, s41, 2
	s_add_u32 vcc_lo, vcc_lo, 0x100
	s_addc_u32 vcc_hi, vcc_hi, 0
	s_add_u32 s65, s65, 0x100
	s_addc_u32 s87, s87, 0
	s_cmp_gt_u32 s41, 29
	s_cbranch_scc0 .LBB0_1107
	s_and_b64 vcc, exec, s[10:11]
	s_cbranch_vccz .LBB0_1110
	s_barrier

; #define PG8_STAGE(bufoff, gbase, voff) do { _Pragma("unroll") for (int _i = 0; _i < 2; ++_i) \
;         __builtin_amdgcn_global_load_lds((const unsigned*)((const char*)(gbase) + (voff)[_i]), (LAS unsigned*)(lds + (bufoff) + ldsw + _i * 8192), 16, 0, 0); } while (0)
; #define PG8_LDA(dst, b, h) do { _Pragma("unroll") for (int m = 0; m < 4; ++m) _Pragma("unroll") for (int k = 0; k < 2; ++k) dst[m][k] = *(const LAS bf16x8*)(lds + PG8_SA(b, h) + aoff + m * 2048 + k * 1024); } while (0)
; #define PG8_LDB(dst, b, h) do { _Pragma("unroll") for (int n = 0; n < 2; ++n) _Pragma("unroll") for (int k = 0; k < 2; ++k) dst[n][k] = *(const LAS bf16x8*)(lds + PG8_SB(b, h) + boff + n * 2048 + k * 1024); } while (0)
; #define PG8_MMA(ai, bj, At, Bt) do { __builtin_amdgcn_s_setprio(1); _Pragma("unroll") for (int m = 0; m < 4; ++m) _Pragma("unroll") for (int n = 0; n < 2; ++n) _Pragma("unroll") for (int k = 0; k < 2; ++k) \
;         acc[ai][bj][m][n] = __builtin_amdgcn_mfma_f32_16x16x32_bf16(Bt[n][k], At[m][k], acc[ai][bj][m][n], 0, 0, 0); __builtin_amdgcn_s_setprio(0); } while (0)
; #define PG8_WAIT_V(n) asm volatile("s_waitcnt vmcnt(" #n ")" ::: "memory")
; #define PG8_WAIT_L(n) asm volatile("s_waitcnt lgkmcnt(" #n ")" ::: "memory")
; #define PG8_BAR __builtin_amdgcn_s_barrier()
; #define PG8_SCHED __builtin_amdgcn_sched_barrier(0)
; template <class Epi>
; __device__ __forceinline__ void gemm_phase(LAS unsigned char* lds, const Gemm g, const StaticOrder& S, const Epi& E) {
;     ...
;             const bool last = (t == nt - 2);
;             const char* a1 = cA + (size_t)(t + 1) * kstep;
;             const char* a2 = last ? nA : cA + (size_t)(t + 2) * kstep; const char* b2 = last ? nB : cB + (size_t)(t + 2) * kstep;
;             const char* a3 = a2 + kstep; const char* b3 = b2 + kstep;
;             PG8_LDB(B0, 0, 0); PG8_LDB(B1, 0, 1); PG8_SCHED; PG8_LDA(At, 0, 0); PG8_STAGE(PG8_SA(1, 1), a1 + hstepA, voffA);
;             PG8_WAIT_V(8); PG8_WAIT_L(0); PG8_BAR; PG8_MMA(0, 0, At, B0); PG8_MMA(0, 1, At, B1); PG8_BAR; PG8_SCHED;
;             PG8_LDA(At, 0, 1); PG8_STAGE(PG8_SB(0, 0), b2, voffB); PG8_STAGE(PG8_SB(0, 1), b2 + hstepB, voffB); PG8_STAGE(PG8_SA(0, 0), a2, voffA);
;             PG8_WAIT_V(8); PG8_WAIT_L(0); PG8_BAR; PG8_MMA(1, 0, At, B0); PG8_MMA(1, 1, At, B1); PG8_BAR; PG8_SCHED;
.LBB0_1324:
	s_add_u32 s14, s24, 0xfff80080
	s_addc_u32 s15, s25, -1
	s_add_i32 s53, 0, 0x10000
	s_cmp_eq_u32 s41, 28
	s_cselect_b32 s27, s3, s15
	s_cselect_b32 s26, s7, s14
	s_cselect_b32 s15, s13, s52
	s_cselect_b32 s14, s17, s40
	s_add_i32 s69, 0, 0x14000
	v_add_u32_e32 v142, s53, v1
	v_add_u32_e32 v158, s69, v1
	ds_read_b128 v[130:133], v142
	ds_read_b128 v[134:137], v142 offset:1024
	ds_read_b128 v[138:141], v142 offset:2048
	ds_read_b128 v[142:145], v142 offset:3072
	ds_read_b128 v[146:149], v158
	ds_read_b128 v[150:153], v158 offset:1024
	ds_read_b128 v[154:157], v158 offset:2048
	ds_read_b128 v[158:161], v158 offset:3072
	v_lshl_add_u64 v[178:179], s[24:25], 0, v[170:171]
	s_add_i32 m0, s23, 0xc000
	ds_read_b128 v[162:165], v181
	ds_read_b128 v[174:177], v181 offset:1024
	ds_read_b128 v[188:191], v181 offset:2048
	ds_read_b128 v[192:195], v181 offset:3072
	ds_read_b128 v[196:199], v181 offset:4096
	ds_read_b128 v[200:203], v181 offset:5120
	ds_read_b128 v[204:207], v181 offset:6144
	ds_read_b128 v[208:211], v181 offset:7168
	global_load_lds_dwordx4 v[178:179], off
	v_lshl_add_u64 v[178:179], s[24:25], 0, v[172:173]
	s_add_i32 m0, s23, 0xe000
	s_nop 0
	global_load_lds_dwordx4 v[178:179], off
	s_waitcnt vmcnt(8)
	s_waitcnt lgkmcnt(0)
	s_barrier
	s_setprio 1
	s_waitcnt lgkmcnt(0)
	v_mfma_f32_16x16x32_bf16 v[122:125], v[130:133], v[162:165], v[122:125]
	v_mfma_f32_16x16x32_bf16 v[118:121], v[138:141], v[162:165], v[118:121]
	v_mfma_f32_16x16x32_bf16 v[110:113], v[130:133], v[188:191], v[110:113]
	v_mfma_f32_16x16x32_bf16 v[102:105], v[138:141], v[188:191], v[102:105]
	v_mfma_f32_16x16x32_bf16 v[94:97], v[130:133], v[196:199], v[94:97]
	v_mfma_f32_16x16x32_bf16 v[86:89], v[138:141], v[196:199], v[86:89]
	v_mfma_f32_16x16x32_bf16 v[78:81], v[130:133], v[204:207], v[78:81]
	v_mfma_f32_16x16x32_bf16 v[70:73], v[138:141], v[204:207], v[70:73]
	v_mfma_f32_16x16x32_bf16 v[122:125], v[134:137], v[174:177], v[122:125]
	v_mfma_f32_16x16x32_bf16 v[118:121], v[142:145], v[174:177], v[118:121]
	v_mfma_f32_16x16x32_bf16 v[110:113], v[134:137], v[192:195], v[110:113]
	v_mfma_f32_16x16x32_bf16 v[102:105], v[142:145], v[192:195], v[102:105]
	v_mfma_f32_16x16x32_bf16 v[94:97], v[134:137], v[200:203], v[94:97]
	v_mfma_f32_16x16x32_bf16 v[86:89], v[142:145], v[200:203], v[86:89]
	v_mfma_f32_16x16x32_bf16 v[78:81], v[134:137], v[208:211], v[78:81]
	v_mfma_f32_16x16x32_bf16 v[70:73], v[142:145], v[208:211], v[70:73]
	v_mfma_f32_16x16x32_bf16 v[126:129], v[146:149], v[162:165], v[126:129]
	v_mfma_f32_16x16x32_bf16 v[114:117], v[154:157], v[162:165], v[114:117]
	v_mfma_f32_16x16x32_bf16 v[106:109], v[146:149], v[188:191], v[106:109]
	v_mfma_f32_16x16x32_bf16 v[98:101], v[154:157], v[188:191], v[98:101]
	v_mfma_f32_16x16x32_bf16 v[90:93], v[146:149], v[196:199], v[90:93]
	v_mfma_f32_16x16x32_bf16 v[82:85], v[154:157], v[196:199], v[82:85]
	v_mfma_f32_16x16x32_bf16 v[74:77], v[146:149], v[204:207], v[74:77]
	v_mfma_f32_16x16x32_bf16 v[66:69], v[154:157], v[204:207], v[66:69]
	v_mfma_f32_16x16x32_bf16 v[126:129], v[150:153], v[174:177], v[126:129]
	v_mfma_f32_16x16x32_bf16 v[114:117], v[158:161], v[174:177], v[114:117]
	v_mfma_f32_16x16x32_bf16 v[106:109], v[150:153], v[192:195], v[106:109]
	v_mfma_f32_16x16x32_bf16 v[98:101], v[158:161], v[192:195], v[98:101]
	v_mfma_f32_16x16x32_bf16 v[90:93], v[150:153], v[200:203], v[90:93]
	v_mfma_f32_16x16x32_bf16 v[82:85], v[158:161], v[200:203], v[82:85]
	v_mfma_f32_16x16x32_bf16 v[74:77], v[150:153], v[208:211], v[74:77]
	v_mfma_f32_16x16x32_bf16 v[66:69], v[158:161], v[208:211], v[66:69]
	s_setprio 0
	s_barrier
	s_add_i32 s53, s53, s28
	v_lshl_add_u64 v[178:179], s[14:15], 0, v[166:167]
	s_mov_b32 m0, s53
	ds_read_b128 v[162:165], v181 offset:16384
	ds_read_b128 v[174:177], v181 offset:17408
	ds_read_b128 v[188:191], v181 offset:18432
	ds_read_b128 v[192:195], v181 offset:19456
	ds_read_b128 v[196:199], v181 offset:20480
	ds_read_b128 v[200:203], v181 offset:21504
	ds_read_b128 v[204:207], v181 offset:22528
	ds_read_b128 v[208:211], v181 offset:23552
	global_load_lds_dwordx4 v[178:179], off
	s_add_i32 m0, s53, 0x2000
	s_add_u32 s64, s14, 0x80000
	v_lshl_add_u64 v[184:185], s[14:15], 0, v[168:169]
	s_addc_u32 s65, s15, 0
	s_add_i32 s53, s69, s28
	global_load_lds_dwordx4 v[184:185], off
	v_lshl_add_u64 v[212:213], s[64:65], 0, v[166:167]
	s_mov_b32 m0, s53
	v_lshl_add_u64 v[214:215], s[26:27], 0, v[168:169]
	global_load_lds_dwordx4 v[212:213], off
	v_lshl_add_u64 v[212:213], s[64:65], 0, v[168:169]
	s_add_i32 m0, s53, 0x2000
	s_nop 0
	global_load_lds_dwordx4 v[212:213], off
	v_lshl_add_u64 v[212:213], s[26:27], 0, v[166:167]
	s_mov_b32 m0, s23
	s_nop 0
	global_load_lds_dwordx4 v[212:213], off
	s_mov_b32 m0, s29
	s_nop 0
	global_load_lds_dwordx4 v[214:215], off
	s_waitcnt vmcnt(8)
	s_waitcnt lgkmcnt(0)
	s_barrier
; #define PG8_STAGE(bufoff, gbase, voff) do { _Pragma("unroll") for (int _i = 0; _i < 2; ++_i) \
;         __builtin_amdgcn_global_load_lds((const unsigned*)((const char*)(gbase) + (voff)[_i]), (LAS unsigned*)(lds + (bufoff) + ldsw + _i * 8192), 16, 0, 0); } while (0)
; #define PG8_LDA(dst, b, h) do { _Pragma("unroll") for (int m = 0; m < 4; ++m) _Pragma("unroll") for (int k = 0; k < 2; ++k) dst[m][k] = *(const LAS bf16x8*)(lds + PG8_SA(b, h) + aoff + m * 2048 + k * 1024); } while (0)
; #define PG8_LDB(dst, b, h) do { _Pragma("unroll") for (int n = 0; n < 2; ++n) _Pragma("unroll") for (int k = 0; k < 2; ++k) dst[n][k] = *(const LAS bf16x8*)(lds + PG8_SB(b, h) + boff + n * 2048 + k * 1024); } while (0)
; #define PG8_MMA(ai, bj, At, Bt) do { __builtin_amdgcn_s_setprio(1); _Pragma("unroll") for (int m = 0; m < 4; ++m) _Pragma("unroll") for (int n = 0; n < 2; ++n) _Pragma("unroll") for (int k = 0; k < 2; ++k) \
;         acc[ai][bj][m][n] = __builtin_amdgcn_mfma_f32_16x16x32_bf16(Bt[n][k], At[m][k], acc[ai][bj][m][n], 0, 0, 0); __builtin_amdgcn_s_setprio(0); } while (0)
; #define PG8_WAIT_V(n) asm volatile("s_waitcnt vmcnt(" #n ")" ::: "memory")
; #define PG8_WAIT_L(n) asm volatile("s_waitcnt lgkmcnt(" #n ")" ::: "memory")
; #define PG8_BAR __builtin_amdgcn_s_barrier()
; #define PG8_SCHED __builtin_amdgcn_sched_barrier(0)
; template <class Epi>
; __device__ __forceinline__ void gemm_phase(LAS unsigned char* lds, const Gemm g, const StaticOrder& S, const Epi& E) {
;     ...
;             PG8_WAIT_V(8); PG8_WAIT_L(0); PG8_BAR; PG8_MMA(1, 0, At, B0); PG8_MMA(1, 1, At, B1); PG8_BAR; PG8_SCHED;
;             PG8_LDB(B0, 1, 0); PG8_LDB(B1, 1, 1); PG8_SCHED; PG8_LDA(At, 1, 0); PG8_STAGE(PG8_SA(0, 1), a2 + hstepA, voffA);
;             PG8_WAIT_V(8); PG8_WAIT_L(0); PG8_BAR; PG8_MMA(0, 0, At, B0); PG8_MMA(0, 1, At, B1); PG8_BAR; PG8_SCHED;
	s_setprio 1
	s_waitcnt lgkmcnt(0)
	v_mfma_f32_16x16x32_bf16 v[62:65], v[130:133], v[162:165], v[62:65]
	v_mfma_f32_16x16x32_bf16 v[54:57], v[138:141], v[162:165], v[54:57]
	v_mfma_f32_16x16x32_bf16 v[46:49], v[130:133], v[188:191], v[46:49]
	v_mfma_f32_16x16x32_bf16 v[38:41], v[138:141], v[188:191], v[38:41]
	v_mfma_f32_16x16x32_bf16 v[30:33], v[130:133], v[196:199], v[30:33]
	v_mfma_f32_16x16x32_bf16 v[22:25], v[138:141], v[196:199], v[22:25]
	v_mfma_f32_16x16x32_bf16 v[14:17], v[130:133], v[204:207], v[14:17]
	v_mfma_f32_16x16x32_bf16 v[6:9], v[138:141], v[204:207], v[6:9]
	v_mfma_f32_16x16x32_bf16 v[62:65], v[134:137], v[174:177], v[62:65]
	v_mfma_f32_16x16x32_bf16 v[54:57], v[142:145], v[174:177], v[54:57]
	v_mfma_f32_16x16x32_bf16 v[46:49], v[134:137], v[192:195], v[46:49]
	v_mfma_f32_16x16x32_bf16 v[38:41], v[142:145], v[192:195], v[38:41]
	v_mfma_f32_16x16x32_bf16 v[30:33], v[134:137], v[200:203], v[30:33]
	v_mfma_f32_16x16x32_bf16 v[22:25], v[142:145], v[200:203], v[22:25]
	v_mfma_f32_16x16x32_bf16 v[14:17], v[134:137], v[208:211], v[14:17]
	v_mfma_f32_16x16x32_bf16 v[6:9], v[142:145], v[208:211], v[6:9]
	v_mfma_f32_16x16x32_bf16 v[58:61], v[146:149], v[162:165], v[58:61]
	v_mfma_f32_16x16x32_bf16 v[50:53], v[154:157], v[162:165], v[50:53]
	v_mfma_f32_16x16x32_bf16 v[42:45], v[146:149], v[188:191], v[42:45]
	v_mfma_f32_16x16x32_bf16 v[34:37], v[154:157], v[188:191], v[34:37]
	v_mfma_f32_16x16x32_bf16 v[26:29], v[146:149], v[196:199], v[26:29]
	v_mfma_f32_16x16x32_bf16 v[18:21], v[154:157], v[196:199], v[18:21]
	v_mfma_f32_16x16x32_bf16 v[10:13], v[146:149], v[204:207], v[10:13]
	v_mfma_f32_16x16x32_bf16 v[2:5], v[154:157], v[204:207], v[2:5]
	v_mfma_f32_16x16x32_bf16 v[58:61], v[150:153], v[174:177], v[58:61]
	v_mfma_f32_16x16x32_bf16 v[50:53], v[158:161], v[174:177], v[50:53]
	v_mfma_f32_16x16x32_bf16 v[42:45], v[150:153], v[192:195], v[42:45]
	v_mfma_f32_16x16x32_bf16 v[34:37], v[158:161], v[192:195], v[34:37]
	v_mfma_f32_16x16x32_bf16 v[26:29], v[150:153], v[200:203], v[26:29]
	v_mfma_f32_16x16x32_bf16 v[18:21], v[158:161], v[200:203], v[18:21]
	v_mfma_f32_16x16x32_bf16 v[10:13], v[150:153], v[208:211], v[10:13]
	v_mfma_f32_16x16x32_bf16 v[2:5], v[158:161], v[208:211], v[2:5]
	s_setprio 0
	s_barrier
	s_add_i32 s53, 0, 0x18000
	s_add_i32 s64, 0, 0x1c000
	v_add_u32_e32 v142, s53, v1
	v_add_u32_e32 v158, s64, v1
	ds_read_b128 v[130:133], v142
	ds_read_b128 v[134:137], v142 offset:1024
	ds_read_b128 v[138:141], v142 offset:2048
	ds_read_b128 v[142:145], v142 offset:3072
	ds_read_b128 v[146:149], v158
	ds_read_b128 v[150:153], v158 offset:1024
	ds_read_b128 v[154:157], v158 offset:2048
	ds_read_b128 v[158:161], v158 offset:3072
	s_add_u32 s26, s26, 0x80000
	s_addc_u32 s27, s27, 0
	s_mov_b32 m0, s30
	v_lshl_add_u64 v[216:217], s[26:27], 0, v[166:167]
	ds_read_b128 v[162:165], v181 offset:32768
	ds_read_b128 v[174:177], v181 offset:33792
	ds_read_b128 v[188:191], v181 offset:34816
	ds_read_b128 v[192:195], v181 offset:35840
	ds_read_b128 v[196:199], v181 offset:36864
	ds_read_b128 v[200:203], v181 offset:37888
	ds_read_b128 v[204:207], v181 offset:38912
	ds_read_b128 v[208:211], v181 offset:39936
	global_load_lds_dwordx4 v[216:217], off
	v_lshl_add_u64 v[216:217], s[26:27], 0, v[168:169]
	s_mov_b32 m0, s31
	s_nop 0
	global_load_lds_dwordx4 v[216:217], off
	s_waitcnt vmcnt(8)
	s_waitcnt lgkmcnt(0)
	s_barrier
	s_setprio 1
	s_waitcnt lgkmcnt(0)
	v_mfma_f32_16x16x32_bf16 v[122:125], v[130:133], v[162:165], v[122:125]
	v_mfma_f32_16x16x32_bf16 v[118:121], v[138:141], v[162:165], v[118:121]
	v_mfma_f32_16x16x32_bf16 v[110:113], v[130:133], v[188:191], v[110:113]
	v_mfma_f32_16x16x32_bf16 v[102:105], v[138:141], v[188:191], v[102:105]
	v_mfma_f32_16x16x32_bf16 v[94:97], v[130:133], v[196:199], v[94:97]
	v_mfma_f32_16x16x32_bf16 v[86:89], v[138:141], v[196:199], v[86:89]
	v_mfma_f32_16x16x32_bf16 v[78:81], v[130:133], v[204:207], v[78:81]
	v_mfma_f32_16x16x32_bf16 v[70:73], v[138:141], v[204:207], v[70:73]
	v_mfma_f32_16x16x32_bf16 v[122:125], v[134:137], v[174:177], v[122:125]
	v_mfma_f32_16x16x32_bf16 v[118:121], v[142:145], v[174:177], v[118:121]
	v_mfma_f32_16x16x32_bf16 v[110:113], v[134:137], v[192:195], v[110:113]
	v_mfma_f32_16x16x32_bf16 v[102:105], v[142:145], v[192:195], v[102:105]
	v_mfma_f32_16x16x32_bf16 v[94:97], v[134:137], v[200:203], v[94:97]
	v_mfma_f32_16x16x32_bf16 v[86:89], v[142:145], v[200:203], v[86:89]
	v_mfma_f32_16x16x32_bf16 v[78:81], v[134:137], v[208:211], v[78:81]
	v_mfma_f32_16x16x32_bf16 v[70:73], v[142:145], v[208:211], v[70:73]
	v_mfma_f32_16x16x32_bf16 v[126:129], v[146:149], v[162:165], v[126:129]
	v_mfma_f32_16x16x32_bf16 v[114:117], v[154:157], v[162:165], v[114:117]
	v_mfma_f32_16x16x32_bf16 v[106:109], v[146:149], v[188:191], v[106:109]
	v_mfma_f32_16x16x32_bf16 v[98:101], v[154:157], v[188:191], v[98:101]
	v_mfma_f32_16x16x32_bf16 v[90:93], v[146:149], v[196:199], v[90:93]
	v_mfma_f32_16x16x32_bf16 v[82:85], v[154:157], v[196:199], v[82:85]
	v_mfma_f32_16x16x32_bf16 v[74:77], v[146:149], v[204:207], v[74:77]
	v_mfma_f32_16x16x32_bf16 v[66:69], v[154:157], v[204:207], v[66:69]
	v_mfma_f32_16x16x32_bf16 v[126:129], v[150:153], v[174:177], v[126:129]
	v_mfma_f32_16x16x32_bf16 v[114:117], v[158:161], v[174:177], v[114:117]
	v_mfma_f32_16x16x32_bf16 v[106:109], v[150:153], v[192:195], v[106:109]
	v_mfma_f32_16x16x32_bf16 v[98:101], v[158:161], v[192:195], v[98:101]
	v_mfma_f32_16x16x32_bf16 v[90:93], v[150:153], v[200:203], v[90:93]
	v_mfma_f32_16x16x32_bf16 v[82:85], v[158:161], v[200:203], v[82:85]
	v_mfma_f32_16x16x32_bf16 v[74:77], v[150:153], v[208:211], v[74:77]
	v_mfma_f32_16x16x32_bf16 v[66:69], v[158:161], v[208:211], v[66:69]
	s_setprio 0
	s_barrier
; #define PG8_STAGE(bufoff, gbase, voff) do { _Pragma("unroll") for (int _i = 0; _i < 2; ++_i) \
;         __builtin_amdgcn_global_load_lds((const unsigned*)((const char*)(gbase) + (voff)[_i]), (LAS unsigned*)(lds + (bufoff) + ldsw + _i * 8192), 16, 0, 0); } while (0)
; #define PG8_LDA(dst, b, h) do { _Pragma("unroll") for (int m = 0; m < 4; ++m) _Pragma("unroll") for (int k = 0; k < 2; ++k) dst[m][k] = *(const LAS bf16x8*)(lds + PG8_SA(b, h) + aoff + m * 2048 + k * 1024); } while (0)
; #define PG8_MMA(ai, bj, At, Bt) do { __builtin_amdgcn_s_setprio(1); _Pragma("unroll") for (int m = 0; m < 4; ++m) _Pragma("unroll") for (int n = 0; n < 2; ++n) _Pragma("unroll") for (int k = 0; k < 2; ++k) \
;         acc[ai][bj][m][n] = __builtin_amdgcn_mfma_f32_16x16x32_bf16(Bt[n][k], At[m][k], acc[ai][bj][m][n], 0, 0, 0); __builtin_amdgcn_s_setprio(0); } while (0)
; #define PG8_WAIT_V(n) asm volatile("s_waitcnt vmcnt(" #n ")" ::: "memory")
; #define PG8_WAIT_L(n) asm volatile("s_waitcnt lgkmcnt(" #n ")" ::: "memory")
; #define PG8_BAR __builtin_amdgcn_s_barrier()
; #define PG8_SCHED __builtin_amdgcn_sched_barrier(0)
; template <class Epi>
; __device__ __forceinline__ void gemm_phase(LAS unsigned char* lds, const Gemm g, const StaticOrder& S, const Epi& E) {
;     ...
;             PG8_LDA(At, 1, 1); PG8_STAGE(PG8_SB(1, 0), b3, voffB); PG8_STAGE(PG8_SB(1, 1), b3 + hstepB, voffB); PG8_STAGE(PG8_SA(1, 0), a3, voffA);
;             PG8_WAIT_V(8); PG8_WAIT_L(0); PG8_BAR; PG8_MMA(1, 0, At, B0); PG8_MMA(1, 1, At, B1); PG8_BAR; PG8_SCHED;
	s_add_i32 s26, s53, s28
	v_lshl_add_u64 v[178:179], v[178:179], 0, s[84:85]
	s_mov_b32 m0, s26
	ds_read_b128 v[162:165], v181 offset:49152
	ds_read_b128 v[174:177], v181 offset:50176
	ds_read_b128 v[188:191], v181 offset:51200
	ds_read_b128 v[192:195], v181 offset:52224
	ds_read_b128 v[196:199], v181 offset:53248
	ds_read_b128 v[200:203], v181 offset:54272
	ds_read_b128 v[204:207], v181 offset:55296
	ds_read_b128 v[208:211], v181 offset:56320
	global_load_lds_dwordx4 v[178:179], off
	s_add_i32 m0, s26, 0x2000
	s_add_u32 s14, s14, 0x80080
	v_lshl_add_u64 v[178:179], v[184:185], 0, s[84:85]
	s_addc_u32 s15, s15, 0
	s_add_i32 s26, s64, s28
	global_load_lds_dwordx4 v[178:179], off
	v_lshl_add_u64 v[178:179], s[14:15], 0, v[166:167]
	s_mov_b32 m0, s26
	s_nop 0
	global_load_lds_dwordx4 v[178:179], off
	v_lshl_add_u64 v[178:179], s[14:15], 0, v[168:169]
	s_add_i32 m0, s26, 0x2000
	s_nop 0
	global_load_lds_dwordx4 v[178:179], off
	v_lshl_add_u64 v[178:179], v[212:213], 0, s[84:85]
	s_mov_b32 m0, s35
	s_nop 0
	global_load_lds_dwordx4 v[178:179], off
	v_lshl_add_u64 v[178:179], v[214:215], 0, s[84:85]
	s_mov_b32 m0, s42
	s_nop 0
	global_load_lds_dwordx4 v[178:179], off
	s_waitcnt vmcnt(8)
	s_waitcnt lgkmcnt(0)
	s_barrier
	s_setprio 1
	s_waitcnt lgkmcnt(0)
	v_mfma_f32_16x16x32_bf16 v[62:65], v[130:133], v[162:165], v[62:65]
	v_mfma_f32_16x16x32_bf16 v[54:57], v[138:141], v[162:165], v[54:57]
	v_mfma_f32_16x16x32_bf16 v[46:49], v[130:133], v[188:191], v[46:49]
	v_mfma_f32_16x16x32_bf16 v[38:41], v[138:141], v[188:191], v[38:41]
	v_mfma_f32_16x16x32_bf16 v[30:33], v[130:133], v[196:199], v[30:33]
	v_mfma_f32_16x16x32_bf16 v[22:25], v[138:141], v[196:199], v[22:25]
	v_mfma_f32_16x16x32_bf16 v[14:17], v[130:133], v[204:207], v[14:17]
	v_mfma_f32_16x16x32_bf16 v[6:9], v[138:141], v[204:207], v[6:9]
	v_mfma_f32_16x16x32_bf16 v[62:65], v[134:137], v[174:177], v[62:65]
	v_mfma_f32_16x16x32_bf16 v[54:57], v[142:145], v[174:177], v[54:57]
	v_mfma_f32_16x16x32_bf16 v[46:49], v[134:137], v[192:195], v[46:49]
	v_mfma_f32_16x16x32_bf16 v[38:41], v[142:145], v[192:195], v[38:41]
	v_mfma_f32_16x16x32_bf16 v[30:33], v[134:137], v[200:203], v[30:33]
	v_mfma_f32_16x16x32_bf16 v[22:25], v[142:145], v[200:203], v[22:25]
	v_mfma_f32_16x16x32_bf16 v[14:17], v[134:137], v[208:211], v[14:17]
	v_mfma_f32_16x16x32_bf16 v[6:9], v[142:145], v[208:211], v[6:9]
	v_mfma_f32_16x16x32_bf16 v[58:61], v[146:149], v[162:165], v[58:61]
	v_mfma_f32_16x16x32_bf16 v[50:53], v[154:157], v[162:165], v[50:53]
	v_mfma_f32_16x16x32_bf16 v[42:45], v[146:149], v[188:191], v[42:45]
	v_mfma_f32_16x16x32_bf16 v[34:37], v[154:157], v[188:191], v[34:37]
	v_mfma_f32_16x16x32_bf16 v[26:29], v[146:149], v[196:199], v[26:29]
	v_mfma_f32_16x16x32_bf16 v[18:21], v[154:157], v[196:199], v[18:21]
	v_mfma_f32_16x16x32_bf16 v[10:13], v[146:149], v[204:207], v[10:13]
	v_mfma_f32_16x16x32_bf16 v[2:5], v[154:157], v[204:207], v[2:5]
	v_mfma_f32_16x16x32_bf16 v[58:61], v[150:153], v[174:177], v[58:61]
	v_mfma_f32_16x16x32_bf16 v[50:53], v[158:161], v[174:177], v[50:53]
	v_mfma_f32_16x16x32_bf16 v[42:45], v[150:153], v[192:195], v[42:45]
	v_mfma_f32_16x16x32_bf16 v[34:37], v[158:161], v[192:195], v[34:37]
	v_mfma_f32_16x16x32_bf16 v[26:29], v[150:153], v[200:203], v[26:29]
	v_mfma_f32_16x16x32_bf16 v[18:21], v[158:161], v[200:203], v[18:21]
	v_mfma_f32_16x16x32_bf16 v[10:13], v[150:153], v[208:211], v[10:13]
	v_mfma_f32_16x16x32_bf16 v[2:5], v[158:161], v[208:211], v[2:5]
	s_setprio 0
	s_barrier
	s_add_i32 s41, s41, 2
	s_add_u32 s24, s24, 0x100
	s_addc_u32 s25, s25, 0
	s_add_u32 s40, s40, 0x100
	s_addc_u32 s52, s52, 0
	s_cmp_gt_u32 s41, 29
	s_cbranch_scc0 .LBB0_1324
	s_cmp_ge_u32 s74, 16
	s_cbranch_scc1 .Lwpf_b
	s_lshl_b32 s100, s74, 9
	v_add_u32_e32 v130, s100, v246
	v_lshrrev_b32_e32 v131, 2, v130
	v_and_b32_e32 v130, 3, v130
	v_lshlrev_b32_e32 v130, 7, v130
	v_lshl_add_u32 v130, v131, 12, v130
	s_add_u32 s100, s88, 0x1800000
	s_addc_u32 s101, s89, 0
	s_mov_b32 m0, 0x21000
	s_nop 0
	global_load_lds_dword v130, s[100:101]

; #define PG8_STAGE(bufoff, gbase, voff) do { _Pragma("unroll") for (int _i = 0; _i < 2; ++_i) \
;         __builtin_amdgcn_global_load_lds((const unsigned*)((const char*)(gbase) + (voff)[_i]), (LAS unsigned*)(lds + (bufoff) + ldsw + _i * 8192), 16, 0, 0); } while (0)
; #define PG8_LDA(dst, b, h) do { _Pragma("unroll") for (int m = 0; m < 4; ++m) _Pragma("unroll") for (int k = 0; k < 2; ++k) dst[m][k] = *(const LAS bf16x8*)(lds + PG8_SA(b, h) + aoff + m * 2048 + k * 1024); } while (0)
; #define PG8_LDB(dst, b, h) do { _Pragma("unroll") for (int n = 0; n < 2; ++n) _Pragma("unroll") for (int k = 0; k < 2; ++k) dst[n][k] = *(const LAS bf16x8*)(lds + PG8_SB(b, h) + boff + n * 2048 + k * 1024); } while (0)
; #define PG8_MMA(ai, bj, At, Bt) do { __builtin_amdgcn_s_setprio(1); _Pragma("unroll") for (int m = 0; m < 4; ++m) _Pragma("unroll") for (int n = 0; n < 2; ++n) _Pragma("unroll") for (int k = 0; k < 2; ++k) \
;         acc[ai][bj][m][n] = __builtin_amdgcn_mfma_f32_16x16x32_bf16(Bt[n][k], At[m][k], acc[ai][bj][m][n], 0, 0, 0); __builtin_amdgcn_s_setprio(0); } while (0)
; #define PG8_WAIT_V(n) asm volatile("s_waitcnt vmcnt(" #n ")" ::: "memory")
; #define PG8_WAIT_L(n) asm volatile("s_waitcnt lgkmcnt(" #n ")" ::: "memory")
; #define PG8_BAR __builtin_amdgcn_s_barrier()
; #define PG8_SCHED __builtin_amdgcn_sched_barrier(0)
; template <class Epi>
; __device__ __forceinline__ void gemm_phase(LAS unsigned char* lds, const Gemm g, const StaticOrder& S, const Epi& E) {
;     ...
;             const bool last = (t == nt - 2);
;             const char* a1 = cA + (size_t)(t + 1) * kstep;
;             const char* a2 = last ? nA : cA + (size_t)(t + 2) * kstep; const char* b2 = last ? nB : cB + (size_t)(t + 2) * kstep;
;             const char* a3 = a2 + kstep; const char* b3 = b2 + kstep;
;             PG8_LDB(B0, 0, 0); PG8_LDB(B1, 0, 1); PG8_SCHED; PG8_LDA(At, 0, 0); PG8_STAGE(PG8_SA(1, 1), a1 + hstepA, voffA);
;             PG8_WAIT_V(8); PG8_WAIT_L(0); PG8_BAR; PG8_MMA(0, 0, At, B0); PG8_MMA(0, 1, At, B1); PG8_BAR; PG8_SCHED;
;             PG8_LDA(At, 0, 1); PG8_STAGE(PG8_SB(0, 0), b2, voffB); PG8_STAGE(PG8_SB(0, 1), b2 + hstepB, voffB); PG8_STAGE(PG8_SA(0, 0), a2, voffA);
;             PG8_WAIT_V(8); PG8_WAIT_L(0); PG8_BAR; PG8_MMA(1, 0, At, B0); PG8_MMA(1, 1, At, B1); PG8_BAR; PG8_SCHED;
.LBB0_1412:
	s_add_u32 s14, s22, 0xfff80080
	s_addc_u32 s15, s23, -1
	s_add_i32 s41, 0, 0x10000
	s_cmp_eq_u32 s64, 28
	s_cselect_b32 s25, s3, s15
	s_cselect_b32 s24, s7, s14
	s_cselect_b32 s15, s13, s63
	s_cselect_b32 s14, s17, s40
	s_add_i32 s65, 0, 0x14000
	v_add_u32_e32 v142, s41, v1
	v_add_u32_e32 v163, s65, v1
	ds_read_b128 v[130:133], v142
	ds_read_b128 v[134:137], v142 offset:1024
	ds_read_b128 v[138:141], v142 offset:2048
	ds_read_b128 v[142:145], v142 offset:3072
	ds_read_b128 v[158:161], v163
	ds_read_b128 v[164:167], v163 offset:1024
	ds_read_b128 v[168:171], v163 offset:2048
	ds_read_b128 v[172:175], v163 offset:3072
	v_lshl_add_u64 v[184:185], s[22:23], 0, v[154:155]
	s_add_i32 m0, s30, 0xc000
	ds_read_b128 v[176:179], v162
	ds_read_b128 v[188:191], v162 offset:1024
	ds_read_b128 v[192:195], v162 offset:2048
	ds_read_b128 v[196:199], v162 offset:3072
	ds_read_b128 v[200:203], v162 offset:4096
	ds_read_b128 v[204:207], v162 offset:5120
	ds_read_b128 v[208:211], v162 offset:6144
	ds_read_b128 v[212:215], v162 offset:7168
	global_load_lds_dwordx4 v[184:185], off
	v_lshl_add_u64 v[184:185], s[22:23], 0, v[156:157]
	s_add_i32 m0, s30, 0xe000
	s_nop 0
	global_load_lds_dwordx4 v[184:185], off
	s_waitcnt vmcnt(8)
	s_waitcnt lgkmcnt(0)
	s_barrier
	s_setprio 1
	s_waitcnt lgkmcnt(0)
	v_mfma_f32_16x16x32_bf16 v[126:129], v[130:133], v[176:179], v[126:129]
	v_mfma_f32_16x16x32_bf16 v[122:125], v[138:141], v[176:179], v[122:125]
	v_mfma_f32_16x16x32_bf16 v[118:121], v[130:133], v[192:195], v[118:121]
	v_mfma_f32_16x16x32_bf16 v[110:113], v[138:141], v[192:195], v[110:113]
	v_mfma_f32_16x16x32_bf16 v[102:105], v[130:133], v[200:203], v[102:105]
	v_mfma_f32_16x16x32_bf16 v[94:97], v[138:141], v[200:203], v[94:97]
	v_mfma_f32_16x16x32_bf16 v[86:89], v[130:133], v[208:211], v[86:89]
	v_mfma_f32_16x16x32_bf16 v[78:81], v[138:141], v[208:211], v[78:81]
	v_mfma_f32_16x16x32_bf16 v[126:129], v[134:137], v[188:191], v[126:129]
	v_mfma_f32_16x16x32_bf16 v[122:125], v[142:145], v[188:191], v[122:125]
	v_mfma_f32_16x16x32_bf16 v[118:121], v[134:137], v[196:199], v[118:121]
	v_mfma_f32_16x16x32_bf16 v[110:113], v[142:145], v[196:199], v[110:113]
	v_mfma_f32_16x16x32_bf16 v[102:105], v[134:137], v[204:207], v[102:105]
	v_mfma_f32_16x16x32_bf16 v[94:97], v[142:145], v[204:207], v[94:97]
	v_mfma_f32_16x16x32_bf16 v[86:89], v[134:137], v[212:215], v[86:89]
	v_mfma_f32_16x16x32_bf16 v[78:81], v[142:145], v[212:215], v[78:81]
	v_mfma_f32_16x16x32_bf16 v[114:117], v[158:161], v[176:179], v[114:117]
	v_mfma_f32_16x16x32_bf16 v[106:109], v[168:171], v[176:179], v[106:109]
	v_mfma_f32_16x16x32_bf16 v[98:101], v[158:161], v[192:195], v[98:101]
	v_mfma_f32_16x16x32_bf16 v[90:93], v[168:171], v[192:195], v[90:93]
	v_mfma_f32_16x16x32_bf16 v[82:85], v[158:161], v[200:203], v[82:85]
	v_mfma_f32_16x16x32_bf16 v[74:77], v[168:171], v[200:203], v[74:77]
	v_mfma_f32_16x16x32_bf16 v[70:73], v[158:161], v[208:211], v[70:73]
	v_mfma_f32_16x16x32_bf16 v[66:69], v[168:171], v[208:211], v[66:69]
	v_mfma_f32_16x16x32_bf16 v[114:117], v[164:167], v[188:191], v[114:117]
	v_mfma_f32_16x16x32_bf16 v[106:109], v[172:175], v[188:191], v[106:109]
	v_mfma_f32_16x16x32_bf16 v[98:101], v[164:167], v[196:199], v[98:101]
	v_mfma_f32_16x16x32_bf16 v[90:93], v[172:175], v[196:199], v[90:93]
	v_mfma_f32_16x16x32_bf16 v[82:85], v[164:167], v[204:207], v[82:85]
	v_mfma_f32_16x16x32_bf16 v[74:77], v[172:175], v[204:207], v[74:77]
	v_mfma_f32_16x16x32_bf16 v[70:73], v[164:167], v[212:215], v[70:73]
	v_mfma_f32_16x16x32_bf16 v[66:69], v[172:175], v[212:215], v[66:69]
	s_setprio 0
	s_barrier
	s_add_i32 s41, s41, s28
	v_lshl_add_u64 v[184:185], s[14:15], 0, v[150:151]
	s_mov_b32 m0, s41
	ds_read_b128 v[176:179], v162 offset:16384
	ds_read_b128 v[188:191], v162 offset:17408
	ds_read_b128 v[192:195], v162 offset:18432
	ds_read_b128 v[196:199], v162 offset:19456
	ds_read_b128 v[200:203], v162 offset:20480
	ds_read_b128 v[204:207], v162 offset:21504
	ds_read_b128 v[208:211], v162 offset:22528
	ds_read_b128 v[212:215], v162 offset:23552
	global_load_lds_dwordx4 v[184:185], off
	s_add_i32 m0, s41, 0x2000
	s_add_u32 s68, s14, 0x80000
	v_lshl_add_u64 v[216:217], s[14:15], 0, v[146:147]
	s_addc_u32 s69, s15, 0
	s_add_i32 s41, s65, s28
	global_load_lds_dwordx4 v[216:217], off
	v_lshl_add_u64 v[218:219], s[68:69], 0, v[150:151]
	s_mov_b32 m0, s41
	v_lshl_add_u64 v[220:221], s[24:25], 0, v[148:149]
	global_load_lds_dwordx4 v[218:219], off
	v_lshl_add_u64 v[218:219], s[68:69], 0, v[146:147]
	s_add_i32 m0, s41, 0x2000
	s_nop 0
	global_load_lds_dwordx4 v[218:219], off
	v_lshl_add_u64 v[218:219], s[24:25], 0, v[152:153]
	s_mov_b32 m0, s30
	s_nop 0
	global_load_lds_dwordx4 v[218:219], off
	s_mov_b32 m0, s31
	s_nop 0
	global_load_lds_dwordx4 v[220:221], off
	s_waitcnt vmcnt(8)
	s_waitcnt lgkmcnt(0)
	s_barrier
; #define PG8_STAGE(bufoff, gbase, voff) do { _Pragma("unroll") for (int _i = 0; _i < 2; ++_i) \
;         __builtin_amdgcn_global_load_lds((const unsigned*)((const char*)(gbase) + (voff)[_i]), (LAS unsigned*)(lds + (bufoff) + ldsw + _i * 8192), 16, 0, 0); } while (0)
; #define PG8_LDA(dst, b, h) do { _Pragma("unroll") for (int m = 0; m < 4; ++m) _Pragma("unroll") for (int k = 0; k < 2; ++k) dst[m][k] = *(const LAS bf16x8*)(lds + PG8_SA(b, h) + aoff + m * 2048 + k * 1024); } while (0)
; #define PG8_LDB(dst, b, h) do { _Pragma("unroll") for (int n = 0; n < 2; ++n) _Pragma("unroll") for (int k = 0; k < 2; ++k) dst[n][k] = *(const LAS bf16x8*)(lds + PG8_SB(b, h) + boff + n * 2048 + k * 1024); } while (0)
; #define PG8_MMA(ai, bj, At, Bt) do { __builtin_amdgcn_s_setprio(1); _Pragma("unroll") for (int m = 0; m < 4; ++m) _Pragma("unroll") for (int n = 0; n < 2; ++n) _Pragma("unroll") for (int k = 0; k < 2; ++k) \
;         acc[ai][bj][m][n] = __builtin_amdgcn_mfma_f32_16x16x32_bf16(Bt[n][k], At[m][k], acc[ai][bj][m][n], 0, 0, 0); __builtin_amdgcn_s_setprio(0); } while (0)
; #define PG8_WAIT_V(n) asm volatile("s_waitcnt vmcnt(" #n ")" ::: "memory")
; #define PG8_WAIT_L(n) asm volatile("s_waitcnt lgkmcnt(" #n ")" ::: "memory")
; #define PG8_BAR __builtin_amdgcn_s_barrier()
; #define PG8_SCHED __builtin_amdgcn_sched_barrier(0)
; template <class Epi>
; __device__ __forceinline__ void gemm_phase(LAS unsigned char* lds, const Gemm g, const StaticOrder& S, const Epi& E) {
;     ...
;             PG8_WAIT_V(8); PG8_WAIT_L(0); PG8_BAR; PG8_MMA(1, 0, At, B0); PG8_MMA(1, 1, At, B1); PG8_BAR; PG8_SCHED;
;             PG8_LDB(B0, 1, 0); PG8_LDB(B1, 1, 1); PG8_SCHED; PG8_LDA(At, 1, 0); PG8_STAGE(PG8_SA(0, 1), a2 + hstepA, voffA);
;             PG8_WAIT_V(8); PG8_WAIT_L(0); PG8_BAR; PG8_MMA(0, 0, At, B0); PG8_MMA(0, 1, At, B1); PG8_BAR; PG8_SCHED;
	s_setprio 1
	s_waitcnt lgkmcnt(0)
	v_mfma_f32_16x16x32_bf16 v[62:65], v[130:133], v[176:179], v[62:65]
	v_mfma_f32_16x16x32_bf16 v[58:61], v[138:141], v[176:179], v[58:61]
	v_mfma_f32_16x16x32_bf16 v[54:57], v[130:133], v[192:195], v[54:57]
	v_mfma_f32_16x16x32_bf16 v[46:49], v[138:141], v[192:195], v[46:49]
	v_mfma_f32_16x16x32_bf16 v[38:41], v[130:133], v[200:203], v[38:41]
	v_mfma_f32_16x16x32_bf16 v[30:33], v[138:141], v[200:203], v[30:33]
	v_mfma_f32_16x16x32_bf16 v[22:25], v[130:133], v[208:211], v[22:25]
	v_mfma_f32_16x16x32_bf16 v[14:17], v[138:141], v[208:211], v[14:17]
	v_mfma_f32_16x16x32_bf16 v[62:65], v[134:137], v[188:191], v[62:65]
	v_mfma_f32_16x16x32_bf16 v[58:61], v[142:145], v[188:191], v[58:61]
	v_mfma_f32_16x16x32_bf16 v[54:57], v[134:137], v[196:199], v[54:57]
	v_mfma_f32_16x16x32_bf16 v[46:49], v[142:145], v[196:199], v[46:49]
	v_mfma_f32_16x16x32_bf16 v[38:41], v[134:137], v[204:207], v[38:41]
	v_mfma_f32_16x16x32_bf16 v[30:33], v[142:145], v[204:207], v[30:33]
	v_mfma_f32_16x16x32_bf16 v[22:25], v[134:137], v[212:215], v[22:25]
	v_mfma_f32_16x16x32_bf16 v[14:17], v[142:145], v[212:215], v[14:17]
	v_mfma_f32_16x16x32_bf16 v[50:53], v[158:161], v[176:179], v[50:53]
	v_mfma_f32_16x16x32_bf16 v[42:45], v[168:171], v[176:179], v[42:45]
	v_mfma_f32_16x16x32_bf16 v[34:37], v[158:161], v[192:195], v[34:37]
	v_mfma_f32_16x16x32_bf16 v[26:29], v[168:171], v[192:195], v[26:29]
	v_mfma_f32_16x16x32_bf16 v[18:21], v[158:161], v[200:203], v[18:21]
	v_mfma_f32_16x16x32_bf16 v[10:13], v[168:171], v[200:203], v[10:13]
	v_mfma_f32_16x16x32_bf16 v[6:9], v[158:161], v[208:211], v[6:9]
	v_mfma_f32_16x16x32_bf16 v[2:5], v[168:171], v[208:211], v[2:5]
	v_mfma_f32_16x16x32_bf16 v[50:53], v[164:167], v[188:191], v[50:53]
	v_mfma_f32_16x16x32_bf16 v[42:45], v[172:175], v[188:191], v[42:45]
	v_mfma_f32_16x16x32_bf16 v[34:37], v[164:167], v[196:199], v[34:37]
	v_mfma_f32_16x16x32_bf16 v[26:29], v[172:175], v[196:199], v[26:29]
	v_mfma_f32_16x16x32_bf16 v[18:21], v[164:167], v[204:207], v[18:21]
	v_mfma_f32_16x16x32_bf16 v[10:13], v[172:175], v[204:207], v[10:13]
	v_mfma_f32_16x16x32_bf16 v[6:9], v[164:167], v[212:215], v[6:9]
	v_mfma_f32_16x16x32_bf16 v[2:5], v[172:175], v[212:215], v[2:5]
	s_setprio 0
	s_barrier
	s_add_i32 s41, 0, 0x18000
	s_add_i32 s65, 0, 0x1c000
	v_add_u32_e32 v142, s41, v1
	v_add_u32_e32 v163, s65, v1
	ds_read_b128 v[130:133], v142
	ds_read_b128 v[134:137], v142 offset:1024
	ds_read_b128 v[138:141], v142 offset:2048
	ds_read_b128 v[142:145], v142 offset:3072
	ds_read_b128 v[158:161], v163
	ds_read_b128 v[164:167], v163 offset:1024
	ds_read_b128 v[168:171], v163 offset:2048
	ds_read_b128 v[172:175], v163 offset:3072
	s_add_u32 s24, s24, 0x80000
	s_addc_u32 s25, s25, 0
	s_mov_b32 m0, s33
	v_lshl_add_u64 v[222:223], s[24:25], 0, v[152:153]
	ds_read_b128 v[176:179], v162 offset:32768
	ds_read_b128 v[188:191], v162 offset:33792
	ds_read_b128 v[192:195], v162 offset:34816
	ds_read_b128 v[196:199], v162 offset:35840
	ds_read_b128 v[200:203], v162 offset:36864
	ds_read_b128 v[204:207], v162 offset:37888
	ds_read_b128 v[208:211], v162 offset:38912
	ds_read_b128 v[212:215], v162 offset:39936
	global_load_lds_dwordx4 v[222:223], off
	v_lshl_add_u64 v[222:223], s[24:25], 0, v[148:149]
	s_mov_b32 m0, s34
	s_nop 0
	global_load_lds_dwordx4 v[222:223], off
	s_waitcnt vmcnt(8)
	s_waitcnt lgkmcnt(0)
	s_barrier
	s_setprio 1
	s_waitcnt lgkmcnt(0)
	v_mfma_f32_16x16x32_bf16 v[126:129], v[130:133], v[176:179], v[126:129]
	v_mfma_f32_16x16x32_bf16 v[122:125], v[138:141], v[176:179], v[122:125]
	v_mfma_f32_16x16x32_bf16 v[118:121], v[130:133], v[192:195], v[118:121]
	v_mfma_f32_16x16x32_bf16 v[110:113], v[138:141], v[192:195], v[110:113]
	v_mfma_f32_16x16x32_bf16 v[102:105], v[130:133], v[200:203], v[102:105]
	v_mfma_f32_16x16x32_bf16 v[94:97], v[138:141], v[200:203], v[94:97]
	v_mfma_f32_16x16x32_bf16 v[86:89], v[130:133], v[208:211], v[86:89]
	v_mfma_f32_16x16x32_bf16 v[78:81], v[138:141], v[208:211], v[78:81]
	v_mfma_f32_16x16x32_bf16 v[126:129], v[134:137], v[188:191], v[126:129]
	v_mfma_f32_16x16x32_bf16 v[122:125], v[142:145], v[188:191], v[122:125]
	v_mfma_f32_16x16x32_bf16 v[118:121], v[134:137], v[196:199], v[118:121]
	v_mfma_f32_16x16x32_bf16 v[110:113], v[142:145], v[196:199], v[110:113]
	v_mfma_f32_16x16x32_bf16 v[102:105], v[134:137], v[204:207], v[102:105]
	v_mfma_f32_16x16x32_bf16 v[94:97], v[142:145], v[204:207], v[94:97]
	v_mfma_f32_16x16x32_bf16 v[86:89], v[134:137], v[212:215], v[86:89]
	v_mfma_f32_16x16x32_bf16 v[78:81], v[142:145], v[212:215], v[78:81]
	v_mfma_f32_16x16x32_bf16 v[114:117], v[158:161], v[176:179], v[114:117]
	v_mfma_f32_16x16x32_bf16 v[106:109], v[168:171], v[176:179], v[106:109]
	v_mfma_f32_16x16x32_bf16 v[98:101], v[158:161], v[192:195], v[98:101]
	v_mfma_f32_16x16x32_bf16 v[90:93], v[168:171], v[192:195], v[90:93]
	v_mfma_f32_16x16x32_bf16 v[82:85], v[158:161], v[200:203], v[82:85]
	v_mfma_f32_16x16x32_bf16 v[74:77], v[168:171], v[200:203], v[74:77]
	v_mfma_f32_16x16x32_bf16 v[70:73], v[158:161], v[208:211], v[70:73]
	v_mfma_f32_16x16x32_bf16 v[66:69], v[168:171], v[208:211], v[66:69]
	v_mfma_f32_16x16x32_bf16 v[114:117], v[164:167], v[188:191], v[114:117]
	v_mfma_f32_16x16x32_bf16 v[106:109], v[172:175], v[188:191], v[106:109]
	v_mfma_f32_16x16x32_bf16 v[98:101], v[164:167], v[196:199], v[98:101]
	v_mfma_f32_16x16x32_bf16 v[90:93], v[172:175], v[196:199], v[90:93]
	v_mfma_f32_16x16x32_bf16 v[82:85], v[164:167], v[204:207], v[82:85]
	v_mfma_f32_16x16x32_bf16 v[74:77], v[172:175], v[204:207], v[74:77]
	v_mfma_f32_16x16x32_bf16 v[70:73], v[164:167], v[212:215], v[70:73]
	v_mfma_f32_16x16x32_bf16 v[66:69], v[172:175], v[212:215], v[66:69]
	s_setprio 0
	s_barrier
; #define PG8_STAGE(bufoff, gbase, voff) do { _Pragma("unroll") for (int _i = 0; _i < 2; ++_i) \
;         __builtin_amdgcn_global_load_lds((const unsigned*)((const char*)(gbase) + (voff)[_i]), (LAS unsigned*)(lds + (bufoff) + ldsw + _i * 8192), 16, 0, 0); } while (0)
; #define PG8_LDA(dst, b, h) do { _Pragma("unroll") for (int m = 0; m < 4; ++m) _Pragma("unroll") for (int k = 0; k < 2; ++k) dst[m][k] = *(const LAS bf16x8*)(lds + PG8_SA(b, h) + aoff + m * 2048 + k * 1024); } while (0)
; #define PG8_MMA(ai, bj, At, Bt) do { __builtin_amdgcn_s_setprio(1); _Pragma("unroll") for (int m = 0; m < 4; ++m) _Pragma("unroll") for (int n = 0; n < 2; ++n) _Pragma("unroll") for (int k = 0; k < 2; ++k) \
;         acc[ai][bj][m][n] = __builtin_amdgcn_mfma_f32_16x16x32_bf16(Bt[n][k], At[m][k], acc[ai][bj][m][n], 0, 0, 0); __builtin_amdgcn_s_setprio(0); } while (0)
; #define PG8_WAIT_V(n) asm volatile("s_waitcnt vmcnt(" #n ")" ::: "memory")
; #define PG8_WAIT_L(n) asm volatile("s_waitcnt lgkmcnt(" #n ")" ::: "memory")
; #define PG8_BAR __builtin_amdgcn_s_barrier()
; #define PG8_SCHED __builtin_amdgcn_sched_barrier(0)
; template <class Epi>
; __device__ __forceinline__ void gemm_phase(LAS unsigned char* lds, const Gemm g, const StaticOrder& S, const Epi& E) {
;     ...
;             PG8_LDA(At, 1, 1); PG8_STAGE(PG8_SB(1, 0), b3, voffB); PG8_STAGE(PG8_SB(1, 1), b3 + hstepB, voffB); PG8_STAGE(PG8_SA(1, 0), a3, voffA);
;             PG8_WAIT_V(8); PG8_WAIT_L(0); PG8_BAR; PG8_MMA(1, 0, At, B0); PG8_MMA(1, 1, At, B1); PG8_BAR; PG8_SCHED;
;         }
;         if (wr == 0) PG8_BAR;
	s_add_i32 s24, s41, s28
	v_lshl_add_u64 v[184:185], v[184:185], 0, s[84:85]
	s_mov_b32 m0, s24
	ds_read_b128 v[176:179], v162 offset:49152
	ds_read_b128 v[188:191], v162 offset:50176
	ds_read_b128 v[192:195], v162 offset:51200
	ds_read_b128 v[196:199], v162 offset:52224
	ds_read_b128 v[200:203], v162 offset:53248
	ds_read_b128 v[204:207], v162 offset:54272
	ds_read_b128 v[208:211], v162 offset:55296
	ds_read_b128 v[212:215], v162 offset:56320
	global_load_lds_dwordx4 v[184:185], off
	s_add_i32 m0, s24, 0x2000
	s_add_u32 s14, s14, 0x80080
	v_lshl_add_u64 v[184:185], v[216:217], 0, s[84:85]
	s_addc_u32 s15, s15, 0
	s_add_i32 s24, s65, s28
	global_load_lds_dwordx4 v[184:185], off
	v_lshl_add_u64 v[184:185], s[14:15], 0, v[150:151]
	s_mov_b32 m0, s24
	s_nop 0
	global_load_lds_dwordx4 v[184:185], off
	v_lshl_add_u64 v[184:185], s[14:15], 0, v[146:147]
	s_add_i32 m0, s24, 0x2000
	s_nop 0
	global_load_lds_dwordx4 v[184:185], off
	v_lshl_add_u64 v[184:185], v[218:219], 0, s[84:85]
	s_mov_b32 m0, s44
	s_nop 0
	global_load_lds_dwordx4 v[184:185], off
	v_lshl_add_u64 v[184:185], v[220:221], 0, s[84:85]
	s_mov_b32 m0, s45
	s_nop 0
	global_load_lds_dwordx4 v[184:185], off
	s_waitcnt vmcnt(8)
	s_waitcnt lgkmcnt(0)
	s_barrier
	s_setprio 1
	s_waitcnt lgkmcnt(0)
	v_mfma_f32_16x16x32_bf16 v[62:65], v[130:133], v[176:179], v[62:65]
	v_mfma_f32_16x16x32_bf16 v[58:61], v[138:141], v[176:179], v[58:61]
	v_mfma_f32_16x16x32_bf16 v[54:57], v[130:133], v[192:195], v[54:57]
	v_mfma_f32_16x16x32_bf16 v[46:49], v[138:141], v[192:195], v[46:49]
	v_mfma_f32_16x16x32_bf16 v[38:41], v[130:133], v[200:203], v[38:41]
	v_mfma_f32_16x16x32_bf16 v[30:33], v[138:141], v[200:203], v[30:33]
	v_mfma_f32_16x16x32_bf16 v[22:25], v[130:133], v[208:211], v[22:25]
	v_mfma_f32_16x16x32_bf16 v[14:17], v[138:141], v[208:211], v[14:17]
	v_mfma_f32_16x16x32_bf16 v[62:65], v[134:137], v[188:191], v[62:65]
	v_mfma_f32_16x16x32_bf16 v[58:61], v[142:145], v[188:191], v[58:61]
	v_mfma_f32_16x16x32_bf16 v[54:57], v[134:137], v[196:199], v[54:57]
	v_mfma_f32_16x16x32_bf16 v[46:49], v[142:145], v[196:199], v[46:49]
	v_mfma_f32_16x16x32_bf16 v[38:41], v[134:137], v[204:207], v[38:41]
	v_mfma_f32_16x16x32_bf16 v[30:33], v[142:145], v[204:207], v[30:33]
	v_mfma_f32_16x16x32_bf16 v[22:25], v[134:137], v[212:215], v[22:25]
	v_mfma_f32_16x16x32_bf16 v[14:17], v[142:145], v[212:215], v[14:17]
	v_mfma_f32_16x16x32_bf16 v[50:53], v[158:161], v[176:179], v[50:53]
	v_mfma_f32_16x16x32_bf16 v[42:45], v[168:171], v[176:179], v[42:45]
	v_mfma_f32_16x16x32_bf16 v[34:37], v[158:161], v[192:195], v[34:37]
	v_mfma_f32_16x16x32_bf16 v[26:29], v[168:171], v[192:195], v[26:29]
	v_mfma_f32_16x16x32_bf16 v[18:21], v[158:161], v[200:203], v[18:21]
	v_mfma_f32_16x16x32_bf16 v[10:13], v[168:171], v[200:203], v[10:13]
	v_mfma_f32_16x16x32_bf16 v[6:9], v[158:161], v[208:211], v[6:9]
	v_mfma_f32_16x16x32_bf16 v[2:5], v[168:171], v[208:211], v[2:5]
	v_mfma_f32_16x16x32_bf16 v[50:53], v[164:167], v[188:191], v[50:53]
	v_mfma_f32_16x16x32_bf16 v[42:45], v[172:175], v[188:191], v[42:45]
	v_mfma_f32_16x16x32_bf16 v[34:37], v[164:167], v[196:199], v[34:37]
	v_mfma_f32_16x16x32_bf16 v[26:29], v[172:175], v[196:199], v[26:29]
	v_mfma_f32_16x16x32_bf16 v[18:21], v[164:167], v[204:207], v[18:21]
	v_mfma_f32_16x16x32_bf16 v[10:13], v[172:175], v[204:207], v[10:13]
	v_mfma_f32_16x16x32_bf16 v[6:9], v[164:167], v[212:215], v[6:9]
	v_mfma_f32_16x16x32_bf16 v[2:5], v[172:175], v[212:215], v[2:5]
	s_setprio 0
	s_barrier
	s_add_i32 s64, s64, 2
	s_add_u32 s22, s22, 0x100
	s_addc_u32 s23, s23, 0
	s_add_u32 s40, s40, 0x100
	s_addc_u32 s63, s63, 0
	s_cmp_gt_u32 s64, 29
	s_cbranch_scc0 .LBB0_1412
	s_and_b64 vcc, exec, s[10:11]
	s_cbranch_vccz .LBB0_1415
	s_barrier

; #define PG8_STAGE(bufoff, gbase, voff) do { _Pragma("unroll") for (int _i = 0; _i < 2; ++_i) \
;         __builtin_amdgcn_global_load_lds((const unsigned*)((const char*)(gbase) + (voff)[_i]), (LAS unsigned*)(lds + (bufoff) + ldsw + _i * 8192), 16, 0, 0); } while (0)
; #define PG8_LDA(dst, b, h) do { _Pragma("unroll") for (int m = 0; m < 4; ++m) _Pragma("unroll") for (int k = 0; k < 2; ++k) dst[m][k] = *(const LAS bf16x8*)(lds + PG8_SA(b, h) + aoff + m * 2048 + k * 1024); } while (0)
; #define PG8_LDB(dst, b, h) do { _Pragma("unroll") for (int n = 0; n < 2; ++n) _Pragma("unroll") for (int k = 0; k < 2; ++k) dst[n][k] = *(const LAS bf16x8*)(lds + PG8_SB(b, h) + boff + n * 2048 + k * 1024); } while (0)
; #define PG8_MMA(ai, bj, At, Bt) do { __builtin_amdgcn_s_setprio(1); _Pragma("unroll") for (int m = 0; m < 4; ++m) _Pragma("unroll") for (int n = 0; n < 2; ++n) _Pragma("unroll") for (int k = 0; k < 2; ++k) \
;         acc[ai][bj][m][n] = __builtin_amdgcn_mfma_f32_16x16x32_bf16(Bt[n][k], At[m][k], acc[ai][bj][m][n], 0, 0, 0); __builtin_amdgcn_s_setprio(0); } while (0)
; #define PG8_WAIT_V(n) asm volatile("s_waitcnt vmcnt(" #n ")" ::: "memory")
; #define PG8_WAIT_L(n) asm volatile("s_waitcnt lgkmcnt(" #n ")" ::: "memory")
; #define PG8_BAR __builtin_amdgcn_s_barrier()
; #define PG8_SCHED __builtin_amdgcn_sched_barrier(0)
; template <class Epi>
; __device__ __forceinline__ void gemm_phase(LAS unsigned char* lds, const Gemm g, const StaticOrder& S, const Epi& E) {
;     ...
;         const bool has_next = S.next(ui + 1, nxt);
;         const char* nA = has_next ? PG8_UA(nxt) : cA; const char* nB = has_next ? PG8_UB(nxt) : cB;
;         for (int t = 0; t < nt; t += 2) {
;             const bool last = (t == nt - 2);
;             const char* a1 = cA + (size_t)(t + 1) * kstep;
;             const char* a2 = last ? nA : cA + (size_t)(t + 2) * kstep; const char* b2 = last ? nB : cB + (size_t)(t + 2) * kstep;
;             const char* a3 = a2 + kstep; const char* b3 = b2 + kstep;
;             PG8_LDB(B0, 0, 0); PG8_LDB(B1, 0, 1); PG8_SCHED; PG8_LDA(At, 0, 0); PG8_STAGE(PG8_SA(1, 1), a1 + hstepA, voffA);
;             PG8_WAIT_V(8); PG8_WAIT_L(0); PG8_BAR; PG8_MMA(0, 0, At, B0); PG8_MMA(0, 1, At, B1); PG8_BAR; PG8_SCHED;
;             PG8_LDA(At, 0, 1); PG8_STAGE(PG8_SB(0, 0), b2, voffB); PG8_STAGE(PG8_SB(0, 1), b2 + hstepB, voffB); PG8_STAGE(PG8_SA(0, 0), a2, voffA);
.LBB0_1440:
	s_add_u32 s41, s20, s14
	s_addc_u32 s44, s21, 0
	s_add_u32 s15, s41, 0x100
	s_addc_u32 s34, s44, 0
	s_and_b64 s[30:31], s[28:29], exec
	s_cselect_b32 s31, s19, s34
	s_cselect_b32 s30, s3, s15
	s_add_u32 s14, s12, s14
	s_addc_u32 s15, s13, 0
	s_add_u32 s34, s14, 0x100
	s_addc_u32 s35, s15, 0
	s_add_i32 s81, 0, 0x10000
	s_and_b64 s[14:15], s[28:29], exec
	s_cselect_b32 s35, s17, s35
	s_cselect_b32 s34, s40, s34
	s_add_i32 s29, 0, 0x14000
	s_add_u32 s68, s41, 0x10080
	s_addc_u32 s69, s44, 0
	s_add_i32 s77, s81, s63
	s_add_i32 m0, s11, 0xc000
	s_add_i32 s83, s11, 0xe000
	s_add_i32 s80, s77, 0x2000
	v_add_u32_e32 v139, s81, v1
	s_add_u32 s44, s34, 0x10000
	ds_read_b128 v[140:143], v139
	ds_read_b128 v[144:147], v139 offset:1024
	ds_read_b128 v[148:151], v139 offset:2048
	ds_read_b128 v[152:155], v139 offset:3072
	v_add_u32_e32 v139, s29, v1
	s_addc_u32 s45, s35, 0
	s_add_i32 s79, s29, s63
	ds_read_b128 v[156:159], v139
	ds_read_b128 v[160:163], v139 offset:1024
	ds_read_b128 v[164:167], v139 offset:2048
	ds_read_b128 v[168:171], v139 offset:3072
	s_add_i32 s78, s79, 0x2000
	s_add_i32 vcc_lo, 0, 0x18000
	s_add_i32 vcc_hi, 0, 0x1c000
	s_add_u32 s14, s30, 0x10000
	s_addc_u32 s15, s31, 0
	s_add_i32 s41, vcc_lo, s63
	s_add_i32 s76, s41, 0x2000
	s_add_u32 s28, s34, 0x10080
	s_addc_u32 s29, s35, 0
	s_add_i32 s81, vcc_hi, s63
	s_add_i32 s82, s81, 0x2000
	v_lshl_add_u64 v[184:185], s[68:69], 0, v[130:131]
	ds_read_b128 v[172:175], v138
	ds_read_b128 v[176:179], v138 offset:1024
	ds_read_b128 v[188:191], v138 offset:2048
	ds_read_b128 v[192:195], v138 offset:3072
	ds_read_b128 v[196:199], v138 offset:4096
	ds_read_b128 v[200:203], v138 offset:5120
	ds_read_b128 v[204:207], v138 offset:6144
	ds_read_b128 v[208:211], v138 offset:7168
	global_load_lds_dwordx4 v[184:185], off
	v_lshl_add_u64 v[184:185], s[68:69], 0, v[134:135]
	s_mov_b32 m0, s83
	s_nop 0
	global_load_lds_dwordx4 v[184:185], off
	s_waitcnt vmcnt(8)
	s_waitcnt lgkmcnt(0)
	s_barrier
	s_setprio 1
	s_waitcnt lgkmcnt(0)
	v_mfma_f32_16x16x32_bf16 v[126:129], v[140:143], v[172:175], v[126:129]
	v_mfma_f32_16x16x32_bf16 v[122:125], v[148:151], v[172:175], v[122:125]
	v_mfma_f32_16x16x32_bf16 v[118:121], v[140:143], v[188:191], v[118:121]
	v_mfma_f32_16x16x32_bf16 v[114:117], v[148:151], v[188:191], v[114:117]
	v_mfma_f32_16x16x32_bf16 v[102:105], v[140:143], v[196:199], v[102:105]
	v_mfma_f32_16x16x32_bf16 v[98:101], v[148:151], v[196:199], v[98:101]
	v_mfma_f32_16x16x32_bf16 v[86:89], v[140:143], v[204:207], v[86:89]
	v_mfma_f32_16x16x32_bf16 v[82:85], v[148:151], v[204:207], v[82:85]
	v_mfma_f32_16x16x32_bf16 v[126:129], v[144:147], v[176:179], v[126:129]
	v_mfma_f32_16x16x32_bf16 v[122:125], v[152:155], v[176:179], v[122:125]
	v_mfma_f32_16x16x32_bf16 v[118:121], v[144:147], v[192:195], v[118:121]
	v_mfma_f32_16x16x32_bf16 v[114:117], v[152:155], v[192:195], v[114:117]
	v_mfma_f32_16x16x32_bf16 v[102:105], v[144:147], v[200:203], v[102:105]
	v_mfma_f32_16x16x32_bf16 v[98:101], v[152:155], v[200:203], v[98:101]
	v_mfma_f32_16x16x32_bf16 v[86:89], v[144:147], v[208:211], v[86:89]
	v_mfma_f32_16x16x32_bf16 v[82:85], v[152:155], v[208:211], v[82:85]
	v_mfma_f32_16x16x32_bf16 v[110:113], v[156:159], v[172:175], v[110:113]
	v_mfma_f32_16x16x32_bf16 v[106:109], v[164:167], v[172:175], v[106:109]
	v_mfma_f32_16x16x32_bf16 v[94:97], v[156:159], v[188:191], v[94:97]
	v_mfma_f32_16x16x32_bf16 v[90:93], v[164:167], v[188:191], v[90:93]
	v_mfma_f32_16x16x32_bf16 v[78:81], v[156:159], v[196:199], v[78:81]
	v_mfma_f32_16x16x32_bf16 v[74:77], v[164:167], v[196:199], v[74:77]
	v_mfma_f32_16x16x32_bf16 v[70:73], v[156:159], v[204:207], v[70:73]
	v_mfma_f32_16x16x32_bf16 v[66:69], v[164:167], v[204:207], v[66:69]
	v_mfma_f32_16x16x32_bf16 v[110:113], v[160:163], v[176:179], v[110:113]
	v_mfma_f32_16x16x32_bf16 v[106:109], v[168:171], v[176:179], v[106:109]
	v_mfma_f32_16x16x32_bf16 v[94:97], v[160:163], v[192:195], v[94:97]
	v_mfma_f32_16x16x32_bf16 v[90:93], v[168:171], v[192:195], v[90:93]
	v_mfma_f32_16x16x32_bf16 v[78:81], v[160:163], v[200:203], v[78:81]
	v_mfma_f32_16x16x32_bf16 v[74:77], v[168:171], v[200:203], v[74:77]
	v_mfma_f32_16x16x32_bf16 v[70:73], v[160:163], v[208:211], v[70:73]
	v_mfma_f32_16x16x32_bf16 v[66:69], v[168:171], v[208:211], v[66:69]
	s_setprio 0
	s_barrier
	s_mov_b32 m0, s77
	v_lshl_add_u64 v[184:185], s[34:35], 0, v[132:133]
	ds_read_b128 v[172:175], v138 offset:16384
	ds_read_b128 v[176:179], v138 offset:17408
	ds_read_b128 v[188:191], v138 offset:18432
	ds_read_b128 v[192:195], v138 offset:19456
	ds_read_b128 v[196:199], v138 offset:20480
	ds_read_b128 v[200:203], v138 offset:21504
	ds_read_b128 v[204:207], v138 offset:22528
	ds_read_b128 v[208:211], v138 offset:23552
	global_load_lds_dwordx4 v[184:185], off
	v_lshl_add_u64 v[212:213], s[34:35], 0, v[136:137]
	s_mov_b32 m0, s80
	v_lshl_add_u64 v[214:215], s[44:45], 0, v[132:133]
	global_load_lds_dwordx4 v[212:213], off
	s_mov_b32 m0, s79
	v_lshl_add_u64 v[216:217], s[30:31], 0, v[134:135]
	global_load_lds_dwordx4 v[214:215], off
	v_lshl_add_u64 v[214:215], s[44:45], 0, v[136:137]
	s_mov_b32 m0, s78
	s_nop 0
	global_load_lds_dwordx4 v[214:215], off
	v_lshl_add_u64 v[214:215], s[30:31], 0, v[130:131]
	s_mov_b32 m0, s11
	s_nop 0
	global_load_lds_dwordx4 v[214:215], off
	s_mov_b32 m0, s64
	s_nop 0
	global_load_lds_dwordx4 v[216:217], off
	s_waitcnt vmcnt(8)
	s_waitcnt lgkmcnt(0)
	s_barrier
; #define PG8_STAGE(bufoff, gbase, voff) do { _Pragma("unroll") for (int _i = 0; _i < 2; ++_i) \
;         __builtin_amdgcn_global_load_lds((const unsigned*)((const char*)(gbase) + (voff)[_i]), (LAS unsigned*)(lds + (bufoff) + ldsw + _i * 8192), 16, 0, 0); } while (0)
; #define PG8_LDA(dst, b, h) do { _Pragma("unroll") for (int m = 0; m < 4; ++m) _Pragma("unroll") for (int k = 0; k < 2; ++k) dst[m][k] = *(const LAS bf16x8*)(lds + PG8_SA(b, h) + aoff + m * 2048 + k * 1024); } while (0)
; #define PG8_LDB(dst, b, h) do { _Pragma("unroll") for (int n = 0; n < 2; ++n) _Pragma("unroll") for (int k = 0; k < 2; ++k) dst[n][k] = *(const LAS bf16x8*)(lds + PG8_SB(b, h) + boff + n * 2048 + k * 1024); } while (0)
; #define PG8_MMA(ai, bj, At, Bt) do { __builtin_amdgcn_s_setprio(1); _Pragma("unroll") for (int m = 0; m < 4; ++m) _Pragma("unroll") for (int n = 0; n < 2; ++n) _Pragma("unroll") for (int k = 0; k < 2; ++k) \
;         acc[ai][bj][m][n] = __builtin_amdgcn_mfma_f32_16x16x32_bf16(Bt[n][k], At[m][k], acc[ai][bj][m][n], 0, 0, 0); __builtin_amdgcn_s_setprio(0); } while (0)
; #define PG8_WAIT_V(n) asm volatile("s_waitcnt vmcnt(" #n ")" ::: "memory")
; #define PG8_WAIT_L(n) asm volatile("s_waitcnt lgkmcnt(" #n ")" ::: "memory")
; #define PG8_BAR __builtin_amdgcn_s_barrier()
; #define PG8_SCHED __builtin_amdgcn_sched_barrier(0)
; template <class Epi>
; __device__ __forceinline__ void gemm_phase(LAS unsigned char* lds, const Gemm g, const StaticOrder& S, const Epi& E) {
;     ...
;             PG8_WAIT_V(8); PG8_WAIT_L(0); PG8_BAR; PG8_MMA(0, 0, At, B0); PG8_MMA(0, 1, At, B1); PG8_BAR; PG8_SCHED;
;             PG8_LDA(At, 0, 1); PG8_STAGE(PG8_SB(0, 0), b2, voffB); PG8_STAGE(PG8_SB(0, 1), b2 + hstepB, voffB); PG8_STAGE(PG8_SA(0, 0), a2, voffA);
;             PG8_WAIT_V(8); PG8_WAIT_L(0); PG8_BAR; PG8_MMA(1, 0, At, B0); PG8_MMA(1, 1, At, B1); PG8_BAR; PG8_SCHED;
;             PG8_LDB(B0, 1, 0); PG8_LDB(B1, 1, 1); PG8_SCHED; PG8_LDA(At, 1, 0); PG8_STAGE(PG8_SA(0, 1), a2 + hstepA, voffA);
;             PG8_WAIT_V(8); PG8_WAIT_L(0); PG8_BAR; PG8_MMA(0, 0, At, B0); PG8_MMA(0, 1, At, B1); PG8_BAR; PG8_SCHED;
;             PG8_LDA(At, 1, 1); PG8_STAGE(PG8_SB(1, 0), b3, voffB); PG8_STAGE(PG8_SB(1, 1), b3 + hstepB, voffB); PG8_STAGE(PG8_SA(1, 0), a3, voffA);
	s_setprio 1
	s_waitcnt lgkmcnt(0)
	v_mfma_f32_16x16x32_bf16 v[62:65], v[140:143], v[172:175], v[62:65]
	v_mfma_f32_16x16x32_bf16 v[58:61], v[148:151], v[172:175], v[58:61]
	v_mfma_f32_16x16x32_bf16 v[54:57], v[140:143], v[188:191], v[54:57]
	v_mfma_f32_16x16x32_bf16 v[50:53], v[148:151], v[188:191], v[50:53]
	v_mfma_f32_16x16x32_bf16 v[38:41], v[140:143], v[196:199], v[38:41]
	v_mfma_f32_16x16x32_bf16 v[34:37], v[148:151], v[196:199], v[34:37]
	v_mfma_f32_16x16x32_bf16 v[22:25], v[140:143], v[204:207], v[22:25]
	v_mfma_f32_16x16x32_bf16 v[18:21], v[148:151], v[204:207], v[18:21]
	v_mfma_f32_16x16x32_bf16 v[62:65], v[144:147], v[176:179], v[62:65]
	v_mfma_f32_16x16x32_bf16 v[58:61], v[152:155], v[176:179], v[58:61]
	v_mfma_f32_16x16x32_bf16 v[54:57], v[144:147], v[192:195], v[54:57]
	v_mfma_f32_16x16x32_bf16 v[50:53], v[152:155], v[192:195], v[50:53]
	v_mfma_f32_16x16x32_bf16 v[38:41], v[144:147], v[200:203], v[38:41]
	v_mfma_f32_16x16x32_bf16 v[34:37], v[152:155], v[200:203], v[34:37]
	v_mfma_f32_16x16x32_bf16 v[22:25], v[144:147], v[208:211], v[22:25]
	v_mfma_f32_16x16x32_bf16 v[18:21], v[152:155], v[208:211], v[18:21]
	v_mfma_f32_16x16x32_bf16 v[46:49], v[156:159], v[172:175], v[46:49]
	v_mfma_f32_16x16x32_bf16 v[42:45], v[164:167], v[172:175], v[42:45]
	v_mfma_f32_16x16x32_bf16 v[30:33], v[156:159], v[188:191], v[30:33]
	v_mfma_f32_16x16x32_bf16 v[26:29], v[164:167], v[188:191], v[26:29]
	v_mfma_f32_16x16x32_bf16 v[14:17], v[156:159], v[196:199], v[14:17]
	v_mfma_f32_16x16x32_bf16 v[10:13], v[164:167], v[196:199], v[10:13]
	v_mfma_f32_16x16x32_bf16 v[6:9], v[156:159], v[204:207], v[6:9]
	v_mfma_f32_16x16x32_bf16 v[2:5], v[164:167], v[204:207], v[2:5]
	v_mfma_f32_16x16x32_bf16 v[46:49], v[160:163], v[176:179], v[46:49]
	v_mfma_f32_16x16x32_bf16 v[42:45], v[168:171], v[176:179], v[42:45]
	v_mfma_f32_16x16x32_bf16 v[30:33], v[160:163], v[192:195], v[30:33]
	v_mfma_f32_16x16x32_bf16 v[26:29], v[168:171], v[192:195], v[26:29]
	v_mfma_f32_16x16x32_bf16 v[14:17], v[160:163], v[200:203], v[14:17]
	v_mfma_f32_16x16x32_bf16 v[10:13], v[168:171], v[200:203], v[10:13]
	v_mfma_f32_16x16x32_bf16 v[6:9], v[160:163], v[208:211], v[6:9]
	v_mfma_f32_16x16x32_bf16 v[2:5], v[168:171], v[208:211], v[2:5]
	s_setprio 0
	s_barrier
	v_add_u32_e32 v139, vcc_lo, v1
	ds_read_b128 v[140:143], v139
	ds_read_b128 v[144:147], v139 offset:1024
	ds_read_b128 v[148:151], v139 offset:2048
	ds_read_b128 v[152:155], v139 offset:3072
	v_add_u32_e32 v139, vcc_hi, v1
	ds_read_b128 v[156:159], v139
	ds_read_b128 v[160:163], v139 offset:1024
	ds_read_b128 v[164:167], v139 offset:2048
	ds_read_b128 v[168:171], v139 offset:3072
	s_mov_b32 m0, s65
	v_lshl_add_u64 v[218:219], s[14:15], 0, v[130:131]
	ds_read_b128 v[172:175], v138 offset:32768
	ds_read_b128 v[176:179], v138 offset:33792
	ds_read_b128 v[188:191], v138 offset:34816
	ds_read_b128 v[192:195], v138 offset:35840
	ds_read_b128 v[196:199], v138 offset:36864
	ds_read_b128 v[200:203], v138 offset:37888
	ds_read_b128 v[204:207], v138 offset:38912
	ds_read_b128 v[208:211], v138 offset:39936
	global_load_lds_dwordx4 v[218:219], off
	v_lshl_add_u64 v[218:219], s[14:15], 0, v[134:135]
	s_mov_b32 m0, s70
	s_nop 0
	global_load_lds_dwordx4 v[218:219], off
	s_waitcnt vmcnt(8)
	s_waitcnt lgkmcnt(0)
	s_barrier
	s_setprio 1
	s_waitcnt lgkmcnt(0)
	v_mfma_f32_16x16x32_bf16 v[126:129], v[140:143], v[172:175], v[126:129]
	v_mfma_f32_16x16x32_bf16 v[122:125], v[148:151], v[172:175], v[122:125]
	v_mfma_f32_16x16x32_bf16 v[118:121], v[140:143], v[188:191], v[118:121]
	v_mfma_f32_16x16x32_bf16 v[114:117], v[148:151], v[188:191], v[114:117]
	v_mfma_f32_16x16x32_bf16 v[102:105], v[140:143], v[196:199], v[102:105]
	v_mfma_f32_16x16x32_bf16 v[98:101], v[148:151], v[196:199], v[98:101]
	v_mfma_f32_16x16x32_bf16 v[86:89], v[140:143], v[204:207], v[86:89]
	v_mfma_f32_16x16x32_bf16 v[82:85], v[148:151], v[204:207], v[82:85]
	v_mfma_f32_16x16x32_bf16 v[126:129], v[144:147], v[176:179], v[126:129]
	v_mfma_f32_16x16x32_bf16 v[122:125], v[152:155], v[176:179], v[122:125]
	v_mfma_f32_16x16x32_bf16 v[118:121], v[144:147], v[192:195], v[118:121]
	v_mfma_f32_16x16x32_bf16 v[114:117], v[152:155], v[192:195], v[114:117]
	v_mfma_f32_16x16x32_bf16 v[102:105], v[144:147], v[200:203], v[102:105]
	v_mfma_f32_16x16x32_bf16 v[98:101], v[152:155], v[200:203], v[98:101]
	v_mfma_f32_16x16x32_bf16 v[86:89], v[144:147], v[208:211], v[86:89]
	v_mfma_f32_16x16x32_bf16 v[82:85], v[152:155], v[208:211], v[82:85]
	v_mfma_f32_16x16x32_bf16 v[110:113], v[156:159], v[172:175], v[110:113]
	v_mfma_f32_16x16x32_bf16 v[106:109], v[164:167], v[172:175], v[106:109]
	v_mfma_f32_16x16x32_bf16 v[94:97], v[156:159], v[188:191], v[94:97]
	v_mfma_f32_16x16x32_bf16 v[90:93], v[164:167], v[188:191], v[90:93]
	v_mfma_f32_16x16x32_bf16 v[78:81], v[156:159], v[196:199], v[78:81]
	v_mfma_f32_16x16x32_bf16 v[74:77], v[164:167], v[196:199], v[74:77]
	v_mfma_f32_16x16x32_bf16 v[70:73], v[156:159], v[204:207], v[70:73]
	v_mfma_f32_16x16x32_bf16 v[66:69], v[164:167], v[204:207], v[66:69]
	v_mfma_f32_16x16x32_bf16 v[110:113], v[160:163], v[176:179], v[110:113]
	v_mfma_f32_16x16x32_bf16 v[106:109], v[168:171], v[176:179], v[106:109]
	v_mfma_f32_16x16x32_bf16 v[94:97], v[160:163], v[192:195], v[94:97]
	v_mfma_f32_16x16x32_bf16 v[90:93], v[168:171], v[192:195], v[90:93]
	v_mfma_f32_16x16x32_bf16 v[78:81], v[160:163], v[200:203], v[78:81]
	v_mfma_f32_16x16x32_bf16 v[74:77], v[168:171], v[200:203], v[74:77]
	v_mfma_f32_16x16x32_bf16 v[70:73], v[160:163], v[208:211], v[70:73]
	v_mfma_f32_16x16x32_bf16 v[66:69], v[168:171], v[208:211], v[66:69]
	s_setprio 0
	s_barrier
; __device__ __forceinline__ int launder(int v) { asm volatile("" : "+v"(v)); return v; }
; #define PG8_STAGE(bufoff, gbase, voff) do { _Pragma("unroll") for (int _i = 0; _i < 2; ++_i) \
;         __builtin_amdgcn_global_load_lds((const unsigned*)((const char*)(gbase) + (voff)[_i]), (LAS unsigned*)(lds + (bufoff) + ldsw + _i * 8192), 16, 0, 0); } while (0)
; #define PG8_LDA(dst, b, h) do { _Pragma("unroll") for (int m = 0; m < 4; ++m) _Pragma("unroll") for (int k = 0; k < 2; ++k) dst[m][k] = *(const LAS bf16x8*)(lds + PG8_SA(b, h) + aoff + m * 2048 + k * 1024); } while (0)
; #define PG8_MMA(ai, bj, At, Bt) do { __builtin_amdgcn_s_setprio(1); _Pragma("unroll") for (int m = 0; m < 4; ++m) _Pragma("unroll") for (int n = 0; n < 2; ++n) _Pragma("unroll") for (int k = 0; k < 2; ++k) \
;         acc[ai][bj][m][n] = __builtin_amdgcn_mfma_f32_16x16x32_bf16(Bt[n][k], At[m][k], acc[ai][bj][m][n], 0, 0, 0); __builtin_amdgcn_s_setprio(0); } while (0)
; #define PG8_WAIT_V(n) asm volatile("s_waitcnt vmcnt(" #n ")" ::: "memory")
; #define PG8_WAIT_L(n) asm volatile("s_waitcnt lgkmcnt(" #n ")" ::: "memory")
; #define PG8_BAR __builtin_amdgcn_s_barrier()
; #define PG8_SCHED __builtin_amdgcn_sched_barrier(0)
; template <class Epi>
; __device__ __forceinline__ void gemm_phase(LAS unsigned char* lds, const Gemm g, const StaticOrder& S, const Epi& E) {
;     ...
;             PG8_LDA(At, 1, 1); PG8_STAGE(PG8_SB(1, 0), b3, voffB); PG8_STAGE(PG8_SB(1, 1), b3 + hstepB, voffB); PG8_STAGE(PG8_SA(1, 0), a3, voffA);
;             PG8_WAIT_V(8); PG8_WAIT_L(0); PG8_BAR; PG8_MMA(1, 0, At, B0); PG8_MMA(1, 1, At, B1); PG8_BAR; PG8_SCHED;
;         }
;         if (wr == 0) PG8_BAR;
;         { const int l2 = launder(threadIdx.x) & 63; E(acc, cur, wr, wc, l2 & 15, l2 >> 4); }
;         if (!has_next) break;
	s_mov_b32 m0, s41
	v_lshl_add_u64 v[184:185], v[184:185], 0, s[84:85]
	ds_read_b128 v[172:175], v138 offset:49152
	ds_read_b128 v[176:179], v138 offset:50176
	ds_read_b128 v[188:191], v138 offset:51200
	ds_read_b128 v[192:195], v138 offset:52224
	ds_read_b128 v[196:199], v138 offset:53248
	ds_read_b128 v[200:203], v138 offset:54272
	ds_read_b128 v[204:207], v138 offset:55296
	ds_read_b128 v[208:211], v138 offset:56320
	global_load_lds_dwordx4 v[184:185], off
	v_lshl_add_u64 v[184:185], v[212:213], 0, s[84:85]
	s_mov_b32 m0, s76
	s_nop 0
	global_load_lds_dwordx4 v[184:185], off
	v_lshl_add_u64 v[184:185], s[28:29], 0, v[132:133]
	s_mov_b32 m0, s81
	s_nop 0
	global_load_lds_dwordx4 v[184:185], off
	v_lshl_add_u64 v[184:185], s[28:29], 0, v[136:137]
	s_mov_b32 m0, s82
	s_nop 0
	global_load_lds_dwordx4 v[184:185], off
	v_lshl_add_u64 v[184:185], v[214:215], 0, s[84:85]
	s_mov_b32 m0, s86
	s_nop 0
	global_load_lds_dwordx4 v[184:185], off
	v_lshl_add_u64 v[184:185], v[216:217], 0, s[84:85]
	s_mov_b32 m0, s87
	s_nop 0
	global_load_lds_dwordx4 v[184:185], off
	s_waitcnt vmcnt(8)
	s_waitcnt lgkmcnt(0)
	s_barrier
	s_setprio 1
	s_waitcnt lgkmcnt(0)
	v_mfma_f32_16x16x32_bf16 v[62:65], v[140:143], v[172:175], v[62:65]
	v_mfma_f32_16x16x32_bf16 v[58:61], v[148:151], v[172:175], v[58:61]
	v_mfma_f32_16x16x32_bf16 v[54:57], v[140:143], v[188:191], v[54:57]
	v_mfma_f32_16x16x32_bf16 v[50:53], v[148:151], v[188:191], v[50:53]
	v_mfma_f32_16x16x32_bf16 v[38:41], v[140:143], v[196:199], v[38:41]
	v_mfma_f32_16x16x32_bf16 v[34:37], v[148:151], v[196:199], v[34:37]
	v_mfma_f32_16x16x32_bf16 v[22:25], v[140:143], v[204:207], v[22:25]
	v_mfma_f32_16x16x32_bf16 v[18:21], v[148:151], v[204:207], v[18:21]
	v_mfma_f32_16x16x32_bf16 v[62:65], v[144:147], v[176:179], v[62:65]
	v_mfma_f32_16x16x32_bf16 v[58:61], v[152:155], v[176:179], v[58:61]
	v_mfma_f32_16x16x32_bf16 v[54:57], v[144:147], v[192:195], v[54:57]
	v_mfma_f32_16x16x32_bf16 v[50:53], v[152:155], v[192:195], v[50:53]
	v_mfma_f32_16x16x32_bf16 v[38:41], v[144:147], v[200:203], v[38:41]
	v_mfma_f32_16x16x32_bf16 v[34:37], v[152:155], v[200:203], v[34:37]
	v_mfma_f32_16x16x32_bf16 v[22:25], v[144:147], v[208:211], v[22:25]
	v_mfma_f32_16x16x32_bf16 v[18:21], v[152:155], v[208:211], v[18:21]
	v_mfma_f32_16x16x32_bf16 v[46:49], v[156:159], v[172:175], v[46:49]
	v_mfma_f32_16x16x32_bf16 v[42:45], v[164:167], v[172:175], v[42:45]
	v_mfma_f32_16x16x32_bf16 v[30:33], v[156:159], v[188:191], v[30:33]
	v_mfma_f32_16x16x32_bf16 v[26:29], v[164:167], v[188:191], v[26:29]
	v_mfma_f32_16x16x32_bf16 v[14:17], v[156:159], v[196:199], v[14:17]
	v_mfma_f32_16x16x32_bf16 v[10:13], v[164:167], v[196:199], v[10:13]
	v_mfma_f32_16x16x32_bf16 v[6:9], v[156:159], v[204:207], v[6:9]
	v_mfma_f32_16x16x32_bf16 v[2:5], v[164:167], v[204:207], v[2:5]
	v_mfma_f32_16x16x32_bf16 v[46:49], v[160:163], v[176:179], v[46:49]
	v_mfma_f32_16x16x32_bf16 v[42:45], v[168:171], v[176:179], v[42:45]
	v_mfma_f32_16x16x32_bf16 v[30:33], v[160:163], v[192:195], v[30:33]
	v_mfma_f32_16x16x32_bf16 v[26:29], v[168:171], v[192:195], v[26:29]
	v_mfma_f32_16x16x32_bf16 v[14:17], v[160:163], v[200:203], v[14:17]
	v_mfma_f32_16x16x32_bf16 v[10:13], v[168:171], v[200:203], v[10:13]
	v_mfma_f32_16x16x32_bf16 v[6:9], v[160:163], v[208:211], v[6:9]
	v_mfma_f32_16x16x32_bf16 v[2:5], v[168:171], v[208:211], v[2:5]
	s_setprio 0
	s_barrier
	s_movk_i32 s14, 0x100
	s_andn2_b64 vcc, exec, s[26:27]
	s_mov_b64 s[28:29], -1
	s_mov_b64 s[26:27], 0
	s_cbranch_vccz .LBB0_1440
	v_readlane_b32 s28, v255, 28
	s_and_b64 vcc, exec, s[8:9]
	v_readlane_b32 s29, v255, 29
	s_cbranch_vccz .LBB0_1443
	s_barrier

; #define PG8_STAGE(bufoff, gbase, voff) do { _Pragma("unroll") for (int _i = 0; _i < 2; ++_i) \
;         __builtin_amdgcn_global_load_lds((const unsigned*)((const char*)(gbase) + (voff)[_i]), (LAS unsigned*)(lds + (bufoff) + ldsw + _i * 8192), 16, 0, 0); } while (0)
; #define PG8_LDA(dst, b, h) do { _Pragma("unroll") for (int m = 0; m < 4; ++m) _Pragma("unroll") for (int k = 0; k < 2; ++k) dst[m][k] = *(const LAS bf16x8*)(lds + PG8_SA(b, h) + aoff + m * 2048 + k * 1024); } while (0)
; #define PG8_LDB(dst, b, h) do { _Pragma("unroll") for (int n = 0; n < 2; ++n) _Pragma("unroll") for (int k = 0; k < 2; ++k) dst[n][k] = *(const LAS bf16x8*)(lds + PG8_SB(b, h) + boff + n * 2048 + k * 1024); } while (0)
; #define PG8_MMA(ai, bj, At, Bt) do { __builtin_amdgcn_s_setprio(1); _Pragma("unroll") for (int m = 0; m < 4; ++m) _Pragma("unroll") for (int n = 0; n < 2; ++n) _Pragma("unroll") for (int k = 0; k < 2; ++k) \
;         acc[ai][bj][m][n] = __builtin_amdgcn_mfma_f32_16x16x32_bf16(Bt[n][k], At[m][k], acc[ai][bj][m][n], 0, 0, 0); __builtin_amdgcn_s_setprio(0); } while (0)
; #define PG8_WAIT_V(n) asm volatile("s_waitcnt vmcnt(" #n ")" ::: "memory")
; #define PG8_BAR __builtin_amdgcn_s_barrier()
; template <class Epi>
; __device__ __forceinline__ void gemm_phase(LAS unsigned char* lds, const Gemm g, const StaticOrder& S, const Epi& E) {
;     ...
;         const bool has_next = S.next(ui + 1, nxt);
;         const char* nA = has_next ? PG8_UA(nxt) : cA; const char* nB = has_next ? PG8_UB(nxt) : cB;
;         for (int t = 0; t < nt; t += 2) {
;             const bool last = (t == nt - 2);
;             const char* a1 = cA + (size_t)(t + 1) * kstep;
;             const char* a2 = last ? nA : cA + (size_t)(t + 2) * kstep; const char* b2 = last ? nB : cB + (size_t)(t + 2) * kstep;
;             const char* a3 = a2 + kstep; const char* b3 = b2 + kstep;
;             PG8_LDB(B0, 0, 0); PG8_LDB(B1, 0, 1); PG8_SCHED; PG8_LDA(At, 0, 0); PG8_STAGE(PG8_SA(1, 1), a1 + hstepA, voffA);
;             PG8_WAIT_V(8); PG8_WAIT_L(0); PG8_BAR; PG8_MMA(0, 0, At, B0); PG8_MMA(0, 1, At, B1); PG8_BAR; PG8_SCHED;
;             PG8_LDA(At, 0, 1); PG8_STAGE(PG8_SB(0, 0), b2, voffB); PG8_STAGE(PG8_SB(0, 1), b2 + hstepB, voffB); PG8_STAGE(PG8_SA(0, 0), a2, voffA);
;             PG8_WAIT_V(8); PG8_WAIT_L(0); PG8_BAR; PG8_MMA(1, 0, At, B0); PG8_MMA(1, 1, At, B1); PG8_BAR; PG8_SCHED;
.LBB0_2035:
	s_add_u32 s14, s24, 0xfff80080
	s_addc_u32 s15, s25, -1
	s_add_i32 s41, 0, 0x10000
	s_cmp_eq_u32 s52, 28
	s_cselect_b32 s27, s1, s15
	s_cselect_b32 s26, s3, s14
	s_cselect_b32 s15, s7, s40
	s_cselect_b32 s14, s13, s17
	s_add_i32 s53, 0, 0x14000
	v_add_u32_e32 v142, s41, v1
	v_add_u32_e32 v158, s53, v1
	ds_read_b128 v[130:133], v142
	ds_read_b128 v[134:137], v142 offset:1024
	ds_read_b128 v[138:141], v142 offset:2048
	ds_read_b128 v[142:145], v142 offset:3072
	ds_read_b128 v[146:149], v158
	ds_read_b128 v[150:153], v158 offset:1024
	ds_read_b128 v[154:157], v158 offset:2048
	ds_read_b128 v[158:161], v158 offset:3072
	v_lshl_add_u64 v[178:179], s[24:25], 0, v[196:197]
	s_add_i32 m0, s23, 0xc000
	ds_read_b128 v[162:165], v181
	ds_read_b128 v[166:169], v181 offset:1024
	ds_read_b128 v[170:173], v181 offset:2048
	ds_read_b128 v[174:177], v181 offset:3072
	ds_read_b128 v[200:203], v181 offset:4096
	ds_read_b128 v[204:207], v181 offset:5120
	ds_read_b128 v[208:211], v181 offset:6144
	ds_read_b128 v[212:215], v181 offset:7168
	global_load_lds_dwordx4 v[178:179], off
	v_lshl_add_u64 v[178:179], s[24:25], 0, v[198:199]
	s_add_i32 m0, s23, 0xe000
	s_nop 0
	global_load_lds_dwordx4 v[178:179], off
	s_waitcnt vmcnt(8)
	s_waitcnt lgkmcnt(0)
	s_barrier
	s_setprio 1
	s_waitcnt lgkmcnt(0)
	v_mfma_f32_16x16x32_bf16 v[126:129], v[130:133], v[162:165], v[126:129]
	v_mfma_f32_16x16x32_bf16 v[122:125], v[138:141], v[162:165], v[122:125]
	v_mfma_f32_16x16x32_bf16 v[110:113], v[130:133], v[170:173], v[110:113]
	v_mfma_f32_16x16x32_bf16 v[106:109], v[138:141], v[170:173], v[106:109]
	v_mfma_f32_16x16x32_bf16 v[94:97], v[130:133], v[200:203], v[94:97]
	v_mfma_f32_16x16x32_bf16 v[90:93], v[138:141], v[200:203], v[90:93]
	v_mfma_f32_16x16x32_bf16 v[82:85], v[130:133], v[208:211], v[82:85]
	v_mfma_f32_16x16x32_bf16 v[74:77], v[138:141], v[208:211], v[74:77]
	v_mfma_f32_16x16x32_bf16 v[126:129], v[134:137], v[166:169], v[126:129]
	v_mfma_f32_16x16x32_bf16 v[122:125], v[142:145], v[166:169], v[122:125]
	v_mfma_f32_16x16x32_bf16 v[110:113], v[134:137], v[174:177], v[110:113]
	v_mfma_f32_16x16x32_bf16 v[106:109], v[142:145], v[174:177], v[106:109]
	v_mfma_f32_16x16x32_bf16 v[94:97], v[134:137], v[204:207], v[94:97]
	v_mfma_f32_16x16x32_bf16 v[90:93], v[142:145], v[204:207], v[90:93]
	v_mfma_f32_16x16x32_bf16 v[82:85], v[134:137], v[212:215], v[82:85]
	v_mfma_f32_16x16x32_bf16 v[74:77], v[142:145], v[212:215], v[74:77]
	v_mfma_f32_16x16x32_bf16 v[118:121], v[146:149], v[162:165], v[118:121]
	v_mfma_f32_16x16x32_bf16 v[114:117], v[154:157], v[162:165], v[114:117]
	v_mfma_f32_16x16x32_bf16 v[102:105], v[146:149], v[170:173], v[102:105]
	v_mfma_f32_16x16x32_bf16 v[98:101], v[154:157], v[170:173], v[98:101]
	v_mfma_f32_16x16x32_bf16 v[86:89], v[146:149], v[200:203], v[86:89]
	v_mfma_f32_16x16x32_bf16 v[78:81], v[154:157], v[200:203], v[78:81]
	v_mfma_f32_16x16x32_bf16 v[70:73], v[146:149], v[208:211], v[70:73]
	v_mfma_f32_16x16x32_bf16 v[66:69], v[154:157], v[208:211], v[66:69]
	v_mfma_f32_16x16x32_bf16 v[118:121], v[150:153], v[166:169], v[118:121]
	v_mfma_f32_16x16x32_bf16 v[114:117], v[158:161], v[166:169], v[114:117]
	v_mfma_f32_16x16x32_bf16 v[102:105], v[150:153], v[174:177], v[102:105]
	v_mfma_f32_16x16x32_bf16 v[98:101], v[158:161], v[174:177], v[98:101]
	v_mfma_f32_16x16x32_bf16 v[86:89], v[150:153], v[204:207], v[86:89]
	v_mfma_f32_16x16x32_bf16 v[78:81], v[158:161], v[204:207], v[78:81]
	v_mfma_f32_16x16x32_bf16 v[70:73], v[150:153], v[212:215], v[70:73]
	v_mfma_f32_16x16x32_bf16 v[66:69], v[158:161], v[212:215], v[66:69]
	s_setprio 0
	s_barrier
	s_add_i32 s41, s41, s30
	v_lshl_add_u64 v[178:179], s[14:15], 0, v[190:191]
	s_mov_b32 m0, s41
	ds_read_b128 v[162:165], v181 offset:16384
	ds_read_b128 v[166:169], v181 offset:17408
	ds_read_b128 v[170:173], v181 offset:18432
	ds_read_b128 v[174:177], v181 offset:19456
	ds_read_b128 v[200:203], v181 offset:20480
	ds_read_b128 v[204:207], v181 offset:21504
	ds_read_b128 v[208:211], v181 offset:22528
	ds_read_b128 v[212:215], v181 offset:23552
	global_load_lds_dwordx4 v[178:179], off
	s_add_i32 m0, s41, 0x2000
	s_add_u32 s62, s14, 0x80000
	v_lshl_add_u64 v[184:185], s[14:15], 0, v[194:195]
	s_addc_u32 s63, s15, 0
	s_add_i32 s41, s53, s30
	global_load_lds_dwordx4 v[184:185], off
	v_lshl_add_u64 v[216:217], s[62:63], 0, v[190:191]
	s_mov_b32 m0, s41
	v_lshl_add_u64 v[218:219], s[26:27], 0, v[192:193]
	global_load_lds_dwordx4 v[216:217], off
	v_lshl_add_u64 v[216:217], s[62:63], 0, v[194:195]
	s_add_i32 m0, s41, 0x2000
	s_nop 0
	global_load_lds_dwordx4 v[216:217], off
	v_lshl_add_u64 v[216:217], s[26:27], 0, v[188:189]
	s_mov_b32 m0, s23
	s_nop 0
	global_load_lds_dwordx4 v[216:217], off
	s_mov_b32 m0, s34
	s_nop 0
	global_load_lds_dwordx4 v[218:219], off
	s_waitcnt vmcnt(8)
	s_waitcnt lgkmcnt(0)
	s_barrier
; #define PG8_STAGE(bufoff, gbase, voff) do { _Pragma("unroll") for (int _i = 0; _i < 2; ++_i) \
;         __builtin_amdgcn_global_load_lds((const unsigned*)((const char*)(gbase) + (voff)[_i]), (LAS unsigned*)(lds + (bufoff) + ldsw + _i * 8192), 16, 0, 0); } while (0)
; #define PG8_LDA(dst, b, h) do { _Pragma("unroll") for (int m = 0; m < 4; ++m) _Pragma("unroll") for (int k = 0; k < 2; ++k) dst[m][k] = *(const LAS bf16x8*)(lds + PG8_SA(b, h) + aoff + m * 2048 + k * 1024); } while (0)
; #define PG8_LDB(dst, b, h) do { _Pragma("unroll") for (int n = 0; n < 2; ++n) _Pragma("unroll") for (int k = 0; k < 2; ++k) dst[n][k] = *(const LAS bf16x8*)(lds + PG8_SB(b, h) + boff + n * 2048 + k * 1024); } while (0)
; #define PG8_MMA(ai, bj, At, Bt) do { __builtin_amdgcn_s_setprio(1); _Pragma("unroll") for (int m = 0; m < 4; ++m) _Pragma("unroll") for (int n = 0; n < 2; ++n) _Pragma("unroll") for (int k = 0; k < 2; ++k) \
;         acc[ai][bj][m][n] = __builtin_amdgcn_mfma_f32_16x16x32_bf16(Bt[n][k], At[m][k], acc[ai][bj][m][n], 0, 0, 0); __builtin_amdgcn_s_setprio(0); } while (0)
; #define PG8_WAIT_V(n) asm volatile("s_waitcnt vmcnt(" #n ")" ::: "memory")
; #define PG8_WAIT_L(n) asm volatile("s_waitcnt lgkmcnt(" #n ")" ::: "memory")
; #define PG8_BAR __builtin_amdgcn_s_barrier()
; #define PG8_SCHED __builtin_amdgcn_sched_barrier(0)
; template <class Epi>
; __device__ __forceinline__ void gemm_phase(LAS unsigned char* lds, const Gemm g, const StaticOrder& S, const Epi& E) {
;     ...
;             PG8_LDA(At, 0, 1); PG8_STAGE(PG8_SB(0, 0), b2, voffB); PG8_STAGE(PG8_SB(0, 1), b2 + hstepB, voffB); PG8_STAGE(PG8_SA(0, 0), a2, voffA);
;             PG8_WAIT_V(8); PG8_WAIT_L(0); PG8_BAR; PG8_MMA(1, 0, At, B0); PG8_MMA(1, 1, At, B1); PG8_BAR; PG8_SCHED;
;             PG8_LDB(B0, 1, 0); PG8_LDB(B1, 1, 1); PG8_SCHED; PG8_LDA(At, 1, 0); PG8_STAGE(PG8_SA(0, 1), a2 + hstepA, voffA);
;             PG8_WAIT_V(8); PG8_WAIT_L(0); PG8_BAR; PG8_MMA(0, 0, At, B0); PG8_MMA(0, 1, At, B1); PG8_BAR; PG8_SCHED;
;             PG8_LDA(At, 1, 1); PG8_STAGE(PG8_SB(1, 0), b3, voffB); PG8_STAGE(PG8_SB(1, 1), b3 + hstepB, voffB); PG8_STAGE(PG8_SA(1, 0), a3, voffA);
	s_setprio 1
	s_waitcnt lgkmcnt(0)
	v_mfma_f32_16x16x32_bf16 v[62:65], v[130:133], v[162:165], v[62:65]
	v_mfma_f32_16x16x32_bf16 v[58:61], v[138:141], v[162:165], v[58:61]
	v_mfma_f32_16x16x32_bf16 v[50:53], v[130:133], v[170:173], v[50:53]
	v_mfma_f32_16x16x32_bf16 v[42:45], v[138:141], v[170:173], v[42:45]
	v_mfma_f32_16x16x32_bf16 v[30:33], v[130:133], v[200:203], v[30:33]
	v_mfma_f32_16x16x32_bf16 v[26:29], v[138:141], v[200:203], v[26:29]
	v_mfma_f32_16x16x32_bf16 v[18:21], v[130:133], v[208:211], v[18:21]
	v_mfma_f32_16x16x32_bf16 v[10:13], v[138:141], v[208:211], v[10:13]
	v_mfma_f32_16x16x32_bf16 v[62:65], v[134:137], v[166:169], v[62:65]
	v_mfma_f32_16x16x32_bf16 v[58:61], v[142:145], v[166:169], v[58:61]
	v_mfma_f32_16x16x32_bf16 v[50:53], v[134:137], v[174:177], v[50:53]
	v_mfma_f32_16x16x32_bf16 v[42:45], v[142:145], v[174:177], v[42:45]
	v_mfma_f32_16x16x32_bf16 v[30:33], v[134:137], v[204:207], v[30:33]
	v_mfma_f32_16x16x32_bf16 v[26:29], v[142:145], v[204:207], v[26:29]
	v_mfma_f32_16x16x32_bf16 v[18:21], v[134:137], v[212:215], v[18:21]
	v_mfma_f32_16x16x32_bf16 v[10:13], v[142:145], v[212:215], v[10:13]
	v_mfma_f32_16x16x32_bf16 v[54:57], v[146:149], v[162:165], v[54:57]
	v_mfma_f32_16x16x32_bf16 v[46:49], v[154:157], v[162:165], v[46:49]
	v_mfma_f32_16x16x32_bf16 v[38:41], v[146:149], v[170:173], v[38:41]
	v_mfma_f32_16x16x32_bf16 v[34:37], v[154:157], v[170:173], v[34:37]
	v_mfma_f32_16x16x32_bf16 v[22:25], v[146:149], v[200:203], v[22:25]
	v_mfma_f32_16x16x32_bf16 v[14:17], v[154:157], v[200:203], v[14:17]
	v_mfma_f32_16x16x32_bf16 v[6:9], v[146:149], v[208:211], v[6:9]
	v_mfma_f32_16x16x32_bf16 v[2:5], v[154:157], v[208:211], v[2:5]
	v_mfma_f32_16x16x32_bf16 v[54:57], v[150:153], v[166:169], v[54:57]
	v_mfma_f32_16x16x32_bf16 v[46:49], v[158:161], v[166:169], v[46:49]
	v_mfma_f32_16x16x32_bf16 v[38:41], v[150:153], v[174:177], v[38:41]
	v_mfma_f32_16x16x32_bf16 v[34:37], v[158:161], v[174:177], v[34:37]
	v_mfma_f32_16x16x32_bf16 v[22:25], v[150:153], v[204:207], v[22:25]
	v_mfma_f32_16x16x32_bf16 v[14:17], v[158:161], v[204:207], v[14:17]
	v_mfma_f32_16x16x32_bf16 v[6:9], v[150:153], v[212:215], v[6:9]
	v_mfma_f32_16x16x32_bf16 v[2:5], v[158:161], v[212:215], v[2:5]
	s_setprio 0
	s_barrier
	s_add_i32 s41, 0, 0x18000
	s_add_i32 s53, 0, 0x1c000
	v_add_u32_e32 v142, s41, v1
	v_add_u32_e32 v158, s53, v1
	ds_read_b128 v[130:133], v142
	ds_read_b128 v[134:137], v142 offset:1024
	ds_read_b128 v[138:141], v142 offset:2048
	ds_read_b128 v[142:145], v142 offset:3072
	ds_read_b128 v[146:149], v158
	ds_read_b128 v[150:153], v158 offset:1024
	ds_read_b128 v[154:157], v158 offset:2048
	ds_read_b128 v[158:161], v158 offset:3072
	s_add_u32 s26, s26, 0x80000
	s_addc_u32 s27, s27, 0
	s_mov_b32 m0, s35
	v_lshl_add_u64 v[220:221], s[26:27], 0, v[188:189]
	ds_read_b128 v[162:165], v181 offset:32768
	ds_read_b128 v[166:169], v181 offset:33792
	ds_read_b128 v[170:173], v181 offset:34816
	ds_read_b128 v[174:177], v181 offset:35840
	ds_read_b128 v[200:203], v181 offset:36864
	ds_read_b128 v[204:207], v181 offset:37888
	ds_read_b128 v[208:211], v181 offset:38912
	ds_read_b128 v[212:215], v181 offset:39936
	global_load_lds_dwordx4 v[220:221], off
	v_lshl_add_u64 v[220:221], s[26:27], 0, v[192:193]
	s_mov_b32 m0, s42
	s_nop 0
	global_load_lds_dwordx4 v[220:221], off
	s_waitcnt vmcnt(8)
	s_waitcnt lgkmcnt(0)
	s_barrier
	s_setprio 1
	s_waitcnt lgkmcnt(0)
	v_mfma_f32_16x16x32_bf16 v[126:129], v[130:133], v[162:165], v[126:129]
	v_mfma_f32_16x16x32_bf16 v[122:125], v[138:141], v[162:165], v[122:125]
	v_mfma_f32_16x16x32_bf16 v[110:113], v[130:133], v[170:173], v[110:113]
	v_mfma_f32_16x16x32_bf16 v[106:109], v[138:141], v[170:173], v[106:109]
	v_mfma_f32_16x16x32_bf16 v[94:97], v[130:133], v[200:203], v[94:97]
	v_mfma_f32_16x16x32_bf16 v[90:93], v[138:141], v[200:203], v[90:93]
	v_mfma_f32_16x16x32_bf16 v[82:85], v[130:133], v[208:211], v[82:85]
	v_mfma_f32_16x16x32_bf16 v[74:77], v[138:141], v[208:211], v[74:77]
	v_mfma_f32_16x16x32_bf16 v[126:129], v[134:137], v[166:169], v[126:129]
	v_mfma_f32_16x16x32_bf16 v[122:125], v[142:145], v[166:169], v[122:125]
	v_mfma_f32_16x16x32_bf16 v[110:113], v[134:137], v[174:177], v[110:113]
	v_mfma_f32_16x16x32_bf16 v[106:109], v[142:145], v[174:177], v[106:109]
	v_mfma_f32_16x16x32_bf16 v[94:97], v[134:137], v[204:207], v[94:97]
	v_mfma_f32_16x16x32_bf16 v[90:93], v[142:145], v[204:207], v[90:93]
	v_mfma_f32_16x16x32_bf16 v[82:85], v[134:137], v[212:215], v[82:85]
	v_mfma_f32_16x16x32_bf16 v[74:77], v[142:145], v[212:215], v[74:77]
	v_mfma_f32_16x16x32_bf16 v[118:121], v[146:149], v[162:165], v[118:121]
	v_mfma_f32_16x16x32_bf16 v[114:117], v[154:157], v[162:165], v[114:117]
	v_mfma_f32_16x16x32_bf16 v[102:105], v[146:149], v[170:173], v[102:105]
	v_mfma_f32_16x16x32_bf16 v[98:101], v[154:157], v[170:173], v[98:101]
	v_mfma_f32_16x16x32_bf16 v[86:89], v[146:149], v[200:203], v[86:89]
	v_mfma_f32_16x16x32_bf16 v[78:81], v[154:157], v[200:203], v[78:81]
	v_mfma_f32_16x16x32_bf16 v[70:73], v[146:149], v[208:211], v[70:73]
	v_mfma_f32_16x16x32_bf16 v[66:69], v[154:157], v[208:211], v[66:69]
	v_mfma_f32_16x16x32_bf16 v[118:121], v[150:153], v[166:169], v[118:121]
	v_mfma_f32_16x16x32_bf16 v[114:117], v[158:161], v[166:169], v[114:117]
	v_mfma_f32_16x16x32_bf16 v[102:105], v[150:153], v[174:177], v[102:105]
	v_mfma_f32_16x16x32_bf16 v[98:101], v[158:161], v[174:177], v[98:101]
	v_mfma_f32_16x16x32_bf16 v[86:89], v[150:153], v[204:207], v[86:89]
	v_mfma_f32_16x16x32_bf16 v[78:81], v[158:161], v[204:207], v[78:81]
	v_mfma_f32_16x16x32_bf16 v[70:73], v[150:153], v[212:215], v[70:73]
	v_mfma_f32_16x16x32_bf16 v[66:69], v[158:161], v[212:215], v[66:69]
	s_setprio 0
	s_barrier
; #define PG8_STAGE(bufoff, gbase, voff) do { _Pragma("unroll") for (int _i = 0; _i < 2; ++_i) \
;         __builtin_amdgcn_global_load_lds((const unsigned*)((const char*)(gbase) + (voff)[_i]), (LAS unsigned*)(lds + (bufoff) + ldsw + _i * 8192), 16, 0, 0); } while (0)
; #define PG8_LDA(dst, b, h) do { _Pragma("unroll") for (int m = 0; m < 4; ++m) _Pragma("unroll") for (int k = 0; k < 2; ++k) dst[m][k] = *(const LAS bf16x8*)(lds + PG8_SA(b, h) + aoff + m * 2048 + k * 1024); } while (0)
; #define PG8_MMA(ai, bj, At, Bt) do { __builtin_amdgcn_s_setprio(1); _Pragma("unroll") for (int m = 0; m < 4; ++m) _Pragma("unroll") for (int n = 0; n < 2; ++n) _Pragma("unroll") for (int k = 0; k < 2; ++k) \
;         acc[ai][bj][m][n] = __builtin_amdgcn_mfma_f32_16x16x32_bf16(Bt[n][k], At[m][k], acc[ai][bj][m][n], 0, 0, 0); __builtin_amdgcn_s_setprio(0); } while (0)
; #define PG8_WAIT_V(n) asm volatile("s_waitcnt vmcnt(" #n ")" ::: "memory")
; #define PG8_WAIT_L(n) asm volatile("s_waitcnt lgkmcnt(" #n ")" ::: "memory")
; #define PG8_BAR __builtin_amdgcn_s_barrier()
; #define PG8_SCHED __builtin_amdgcn_sched_barrier(0)
; template <class Epi>
; __device__ __forceinline__ void gemm_phase(LAS unsigned char* lds, const Gemm g, const StaticOrder& S, const Epi& E) {
;     ...
;             PG8_LDA(At, 1, 1); PG8_STAGE(PG8_SB(1, 0), b3, voffB); PG8_STAGE(PG8_SB(1, 1), b3 + hstepB, voffB); PG8_STAGE(PG8_SA(1, 0), a3, voffA);
;             PG8_WAIT_V(8); PG8_WAIT_L(0); PG8_BAR; PG8_MMA(1, 0, At, B0); PG8_MMA(1, 1, At, B1); PG8_BAR; PG8_SCHED;
;         }
	s_add_i32 s26, s41, s30
	v_lshl_add_u64 v[178:179], v[178:179], 0, s[84:85]
	s_mov_b32 m0, s26
	ds_read_b128 v[162:165], v181 offset:49152
	ds_read_b128 v[166:169], v181 offset:50176
	ds_read_b128 v[170:173], v181 offset:51200
	ds_read_b128 v[174:177], v181 offset:52224
	ds_read_b128 v[200:203], v181 offset:53248
	ds_read_b128 v[204:207], v181 offset:54272
	ds_read_b128 v[208:211], v181 offset:55296
	ds_read_b128 v[212:215], v181 offset:56320
	global_load_lds_dwordx4 v[178:179], off
	s_add_i32 m0, s26, 0x2000
	s_add_u32 s14, s14, 0x80080
	v_lshl_add_u64 v[178:179], v[184:185], 0, s[84:85]
	s_addc_u32 s15, s15, 0
	s_add_i32 s26, s53, s30
	global_load_lds_dwordx4 v[178:179], off
	v_lshl_add_u64 v[178:179], s[14:15], 0, v[190:191]
	s_mov_b32 m0, s26
	s_nop 0
	global_load_lds_dwordx4 v[178:179], off
	v_lshl_add_u64 v[178:179], s[14:15], 0, v[194:195]
	s_add_i32 m0, s26, 0x2000
	s_nop 0
	global_load_lds_dwordx4 v[178:179], off
	v_lshl_add_u64 v[178:179], v[216:217], 0, s[84:85]
	s_mov_b32 m0, s68
	s_nop 0
	global_load_lds_dwordx4 v[178:179], off
	v_lshl_add_u64 v[178:179], v[218:219], 0, s[84:85]
	s_mov_b32 m0, s69
	s_nop 0
	global_load_lds_dwordx4 v[178:179], off
	s_waitcnt vmcnt(8)
	s_waitcnt lgkmcnt(0)
	s_barrier
	s_setprio 1
	s_waitcnt lgkmcnt(0)
	v_mfma_f32_16x16x32_bf16 v[62:65], v[130:133], v[162:165], v[62:65]
	v_mfma_f32_16x16x32_bf16 v[58:61], v[138:141], v[162:165], v[58:61]
	v_mfma_f32_16x16x32_bf16 v[50:53], v[130:133], v[170:173], v[50:53]
	v_mfma_f32_16x16x32_bf16 v[42:45], v[138:141], v[170:173], v[42:45]
	v_mfma_f32_16x16x32_bf16 v[30:33], v[130:133], v[200:203], v[30:33]
	v_mfma_f32_16x16x32_bf16 v[26:29], v[138:141], v[200:203], v[26:29]
	v_mfma_f32_16x16x32_bf16 v[18:21], v[130:133], v[208:211], v[18:21]
	v_mfma_f32_16x16x32_bf16 v[10:13], v[138:141], v[208:211], v[10:13]
	v_mfma_f32_16x16x32_bf16 v[62:65], v[134:137], v[166:169], v[62:65]
	v_mfma_f32_16x16x32_bf16 v[58:61], v[142:145], v[166:169], v[58:61]
	v_mfma_f32_16x16x32_bf16 v[50:53], v[134:137], v[174:177], v[50:53]
	v_mfma_f32_16x16x32_bf16 v[42:45], v[142:145], v[174:177], v[42:45]
	v_mfma_f32_16x16x32_bf16 v[30:33], v[134:137], v[204:207], v[30:33]
	v_mfma_f32_16x16x32_bf16 v[26:29], v[142:145], v[204:207], v[26:29]
	v_mfma_f32_16x16x32_bf16 v[18:21], v[134:137], v[212:215], v[18:21]
	v_mfma_f32_16x16x32_bf16 v[10:13], v[142:145], v[212:215], v[10:13]
	v_mfma_f32_16x16x32_bf16 v[54:57], v[146:149], v[162:165], v[54:57]
	v_mfma_f32_16x16x32_bf16 v[46:49], v[154:157], v[162:165], v[46:49]
	v_mfma_f32_16x16x32_bf16 v[38:41], v[146:149], v[170:173], v[38:41]
	v_mfma_f32_16x16x32_bf16 v[34:37], v[154:157], v[170:173], v[34:37]
	v_mfma_f32_16x16x32_bf16 v[22:25], v[146:149], v[200:203], v[22:25]
	v_mfma_f32_16x16x32_bf16 v[14:17], v[154:157], v[200:203], v[14:17]
	v_mfma_f32_16x16x32_bf16 v[6:9], v[146:149], v[208:211], v[6:9]
	v_mfma_f32_16x16x32_bf16 v[2:5], v[154:157], v[208:211], v[2:5]
	v_mfma_f32_16x16x32_bf16 v[54:57], v[150:153], v[166:169], v[54:57]
	v_mfma_f32_16x16x32_bf16 v[46:49], v[158:161], v[166:169], v[46:49]
	v_mfma_f32_16x16x32_bf16 v[38:41], v[150:153], v[174:177], v[38:41]
	v_mfma_f32_16x16x32_bf16 v[34:37], v[158:161], v[174:177], v[34:37]
	v_mfma_f32_16x16x32_bf16 v[22:25], v[150:153], v[204:207], v[22:25]
	v_mfma_f32_16x16x32_bf16 v[14:17], v[158:161], v[204:207], v[14:17]
	v_mfma_f32_16x16x32_bf16 v[6:9], v[150:153], v[212:215], v[6:9]
	v_mfma_f32_16x16x32_bf16 v[2:5], v[158:161], v[212:215], v[2:5]
	s_setprio 0
	s_barrier
	s_add_i32 s52, s52, 2
	s_add_u32 s24, s24, 0x100
	s_addc_u32 s25, s25, 0
	s_add_u32 s17, s17, 0x100
	s_addc_u32 s40, s40, 0
	s_cmp_gt_u32 s52, 29
	s_cbranch_scc0 .LBB0_2035
	s_cmp_ge_u32 s74, 16
	s_cbranch_scc1 .Lwpf_c
	s_lshl_b32 s100, s74, 9
	v_add_u32_e32 v130, s100, v246
	v_lshrrev_b32_e32 v131, 2, v130
	v_and_b32_e32 v130, 3, v130
	v_lshlrev_b32_e32 v130, 7, v130
	v_lshl_add_u32 v130, v131, 12, v130
	s_add_u32 s100, s88, 0x1800000
	s_addc_u32 s101, s89, 0
	s_mov_b32 m0, 0x21000
	s_nop 0
	global_load_lds_dword v130, s[100:101]

; #define PG8_STAGE(bufoff, gbase, voff) do { _Pragma("unroll") for (int _i = 0; _i < 2; ++_i) \
;         __builtin_amdgcn_global_load_lds((const unsigned*)((const char*)(gbase) + (voff)[_i]), (LAS unsigned*)(lds + (bufoff) + ldsw + _i * 8192), 16, 0, 0); } while (0)
; #define PG8_LDA(dst, b, h) do { _Pragma("unroll") for (int m = 0; m < 4; ++m) _Pragma("unroll") for (int k = 0; k < 2; ++k) dst[m][k] = *(const LAS bf16x8*)(lds + PG8_SA(b, h) + aoff + m * 2048 + k * 1024); } while (0)
; #define PG8_LDB(dst, b, h) do { _Pragma("unroll") for (int n = 0; n < 2; ++n) _Pragma("unroll") for (int k = 0; k < 2; ++k) dst[n][k] = *(const LAS bf16x8*)(lds + PG8_SB(b, h) + boff + n * 2048 + k * 1024); } while (0)
; #define PG8_MMA(ai, bj, At, Bt) do { __builtin_amdgcn_s_setprio(1); _Pragma("unroll") for (int m = 0; m < 4; ++m) _Pragma("unroll") for (int n = 0; n < 2; ++n) _Pragma("unroll") for (int k = 0; k < 2; ++k) \
;         acc[ai][bj][m][n] = __builtin_amdgcn_mfma_f32_16x16x32_bf16(Bt[n][k], At[m][k], acc[ai][bj][m][n], 0, 0, 0); __builtin_amdgcn_s_setprio(0); } while (0)
; #define PG8_WAIT_V(n) asm volatile("s_waitcnt vmcnt(" #n ")" ::: "memory")
; #define PG8_BAR __builtin_amdgcn_s_barrier()
; template <class Epi>
; __device__ __forceinline__ void gemm_phase(LAS unsigned char* lds, const Gemm g, const StaticOrder& S, const Epi& E) {
;     ...
;         const bool has_next = S.next(ui + 1, nxt);
;         const char* nA = has_next ? PG8_UA(nxt) : cA; const char* nB = has_next ? PG8_UB(nxt) : cB;
;         for (int t = 0; t < nt; t += 2) {
;             const bool last = (t == nt - 2);
;             const char* a1 = cA + (size_t)(t + 1) * kstep;
;             const char* a2 = last ? nA : cA + (size_t)(t + 2) * kstep; const char* b2 = last ? nB : cB + (size_t)(t + 2) * kstep;
;             const char* a3 = a2 + kstep; const char* b3 = b2 + kstep;
;             PG8_LDB(B0, 0, 0); PG8_LDB(B1, 0, 1); PG8_SCHED; PG8_LDA(At, 0, 0); PG8_STAGE(PG8_SA(1, 1), a1 + hstepA, voffA);
;             PG8_WAIT_V(8); PG8_WAIT_L(0); PG8_BAR; PG8_MMA(0, 0, At, B0); PG8_MMA(0, 1, At, B1); PG8_BAR; PG8_SCHED;
;             PG8_LDA(At, 0, 1); PG8_STAGE(PG8_SB(0, 0), b2, voffB); PG8_STAGE(PG8_SB(0, 1), b2 + hstepB, voffB); PG8_STAGE(PG8_SA(0, 0), a2, voffA);
;             PG8_WAIT_V(8); PG8_WAIT_L(0); PG8_BAR; PG8_MMA(1, 0, At, B0); PG8_MMA(1, 1, At, B1); PG8_BAR; PG8_SCHED;
.LBB0_2130:
	s_add_u32 s14, s20, 0xfff80080
	s_addc_u32 s15, s21, -1
	s_add_i32 s62, 0, 0x10000
	s_cmp_eq_u32 s41, 28
	s_cselect_b32 s23, s3, s15
	s_cselect_b32 s22, s11, s14
	v_add_u32_e32 v142, s62, v1
	s_cselect_b32 s15, s9, s53
	s_cselect_b32 s14, s40, s52
	s_add_i32 s64, 0, 0x14000
	ds_read_b128 v[146:149], v142
	ds_read_b128 v[150:153], v142 offset:1024
	ds_read_b128 v[154:157], v142 offset:2048
	ds_read_b128 v[158:161], v142 offset:3072
	v_add_u32_e32 v142, s64, v1
	ds_read_b128 v[162:165], v142
	ds_read_b128 v[166:169], v142 offset:1024
	ds_read_b128 v[170:173], v142 offset:2048
	ds_read_b128 v[174:177], v142 offset:3072
	v_lshl_add_u64 v[142:143], s[20:21], 0, v[138:139]
	s_add_i32 m0, s19, 0xc000
	ds_read_b128 v[188:191], v144
	ds_read_b128 v[192:195], v144 offset:1024
	ds_read_b128 v[196:199], v144 offset:2048
	ds_read_b128 v[200:203], v144 offset:3072
	ds_read_b128 v[204:207], v144 offset:4096
	ds_read_b128 v[208:211], v144 offset:5120
	ds_read_b128 v[212:215], v144 offset:6144
	ds_read_b128 v[216:219], v144 offset:7168
	global_load_lds_dwordx4 v[142:143], off
	v_lshl_add_u64 v[142:143], s[20:21], 0, v[140:141]
	s_add_i32 m0, s19, 0xe000
	s_nop 0
	global_load_lds_dwordx4 v[142:143], off
	s_waitcnt vmcnt(8)
	s_waitcnt lgkmcnt(0)
	s_barrier
	s_setprio 1
	s_waitcnt lgkmcnt(0)
	v_mfma_f32_16x16x32_bf16 v[126:129], v[146:149], v[188:191], v[126:129]
	v_mfma_f32_16x16x32_bf16 v[122:125], v[154:157], v[188:191], v[122:125]
	v_mfma_f32_16x16x32_bf16 v[110:113], v[146:149], v[196:199], v[110:113]
	v_mfma_f32_16x16x32_bf16 v[106:109], v[154:157], v[196:199], v[106:109]
	v_mfma_f32_16x16x32_bf16 v[94:97], v[146:149], v[204:207], v[94:97]
	v_mfma_f32_16x16x32_bf16 v[90:93], v[154:157], v[204:207], v[90:93]
	v_mfma_f32_16x16x32_bf16 v[78:81], v[146:149], v[212:215], v[78:81]
	v_mfma_f32_16x16x32_bf16 v[74:77], v[154:157], v[212:215], v[74:77]
	v_mfma_f32_16x16x32_bf16 v[126:129], v[150:153], v[192:195], v[126:129]
	v_mfma_f32_16x16x32_bf16 v[122:125], v[158:161], v[192:195], v[122:125]
	v_mfma_f32_16x16x32_bf16 v[110:113], v[150:153], v[200:203], v[110:113]
	v_mfma_f32_16x16x32_bf16 v[106:109], v[158:161], v[200:203], v[106:109]
	v_mfma_f32_16x16x32_bf16 v[94:97], v[150:153], v[208:211], v[94:97]
	v_mfma_f32_16x16x32_bf16 v[90:93], v[158:161], v[208:211], v[90:93]
	v_mfma_f32_16x16x32_bf16 v[78:81], v[150:153], v[216:219], v[78:81]
	v_mfma_f32_16x16x32_bf16 v[74:77], v[158:161], v[216:219], v[74:77]
	v_mfma_f32_16x16x32_bf16 v[118:121], v[162:165], v[188:191], v[118:121]
	v_mfma_f32_16x16x32_bf16 v[114:117], v[170:173], v[188:191], v[114:117]
	v_mfma_f32_16x16x32_bf16 v[102:105], v[162:165], v[196:199], v[102:105]
	v_mfma_f32_16x16x32_bf16 v[98:101], v[170:173], v[196:199], v[98:101]
	v_mfma_f32_16x16x32_bf16 v[86:89], v[162:165], v[204:207], v[86:89]
	v_mfma_f32_16x16x32_bf16 v[82:85], v[170:173], v[204:207], v[82:85]
	v_mfma_f32_16x16x32_bf16 v[70:73], v[162:165], v[212:215], v[70:73]
	v_mfma_f32_16x16x32_bf16 v[66:69], v[170:173], v[212:215], v[66:69]
	v_mfma_f32_16x16x32_bf16 v[118:121], v[166:169], v[192:195], v[118:121]
	v_mfma_f32_16x16x32_bf16 v[114:117], v[174:177], v[192:195], v[114:117]
	v_mfma_f32_16x16x32_bf16 v[102:105], v[166:169], v[200:203], v[102:105]
	v_mfma_f32_16x16x32_bf16 v[98:101], v[174:177], v[200:203], v[98:101]
	v_mfma_f32_16x16x32_bf16 v[86:89], v[166:169], v[208:211], v[86:89]
	v_mfma_f32_16x16x32_bf16 v[82:85], v[174:177], v[208:211], v[82:85]
	v_mfma_f32_16x16x32_bf16 v[70:73], v[166:169], v[216:219], v[70:73]
	v_mfma_f32_16x16x32_bf16 v[66:69], v[174:177], v[216:219], v[66:69]
	s_setprio 0
	s_barrier
	s_add_i32 s62, s62, s27
	v_lshl_add_u64 v[142:143], s[14:15], 0, v[132:133]
	s_mov_b32 m0, s62
	ds_read_b128 v[188:191], v144 offset:16384
	ds_read_b128 v[192:195], v144 offset:17408
	ds_read_b128 v[196:199], v144 offset:18432
	ds_read_b128 v[200:203], v144 offset:19456
	ds_read_b128 v[204:207], v144 offset:20480
	ds_read_b128 v[208:211], v144 offset:21504
	ds_read_b128 v[212:215], v144 offset:22528
	ds_read_b128 v[216:219], v144 offset:23552
	global_load_lds_dwordx4 v[142:143], off
	s_add_i32 m0, s62, 0x2000
	s_add_u32 s62, s14, 0x80000
	v_lshl_add_u64 v[178:179], s[14:15], 0, v[136:137]
	s_addc_u32 s63, s15, 0
	s_add_i32 s64, s64, s27
	global_load_lds_dwordx4 v[178:179], off
	v_lshl_add_u64 v[184:185], s[62:63], 0, v[132:133]
	s_mov_b32 m0, s64
	v_lshl_add_u64 v[220:221], s[22:23], 0, v[134:135]
	global_load_lds_dwordx4 v[184:185], off
	v_lshl_add_u64 v[184:185], s[62:63], 0, v[136:137]
	s_add_i32 m0, s64, 0x2000
	s_nop 0
	global_load_lds_dwordx4 v[184:185], off
	v_lshl_add_u64 v[184:185], s[22:23], 0, v[130:131]
	s_mov_b32 m0, s19
	s_nop 0
	global_load_lds_dwordx4 v[184:185], off
	s_mov_b32 m0, s28
	s_nop 0
	global_load_lds_dwordx4 v[220:221], off
	s_waitcnt vmcnt(8)
	s_waitcnt lgkmcnt(0)
	s_barrier
; #define PG8_STAGE(bufoff, gbase, voff) do { _Pragma("unroll") for (int _i = 0; _i < 2; ++_i) \
;         __builtin_amdgcn_global_load_lds((const unsigned*)((const char*)(gbase) + (voff)[_i]), (LAS unsigned*)(lds + (bufoff) + ldsw + _i * 8192), 16, 0, 0); } while (0)
; #define PG8_LDA(dst, b, h) do { _Pragma("unroll") for (int m = 0; m < 4; ++m) _Pragma("unroll") for (int k = 0; k < 2; ++k) dst[m][k] = *(const LAS bf16x8*)(lds + PG8_SA(b, h) + aoff + m * 2048 + k * 1024); } while (0)
; #define PG8_LDB(dst, b, h) do { _Pragma("unroll") for (int n = 0; n < 2; ++n) _Pragma("unroll") for (int k = 0; k < 2; ++k) dst[n][k] = *(const LAS bf16x8*)(lds + PG8_SB(b, h) + boff + n * 2048 + k * 1024); } while (0)
; #define PG8_MMA(ai, bj, At, Bt) do { __builtin_amdgcn_s_setprio(1); _Pragma("unroll") for (int m = 0; m < 4; ++m) _Pragma("unroll") for (int n = 0; n < 2; ++n) _Pragma("unroll") for (int k = 0; k < 2; ++k) \
;         acc[ai][bj][m][n] = __builtin_amdgcn_mfma_f32_16x16x32_bf16(Bt[n][k], At[m][k], acc[ai][bj][m][n], 0, 0, 0); __builtin_amdgcn_s_setprio(0); } while (0)
; #define PG8_WAIT_V(n) asm volatile("s_waitcnt vmcnt(" #n ")" ::: "memory")
; #define PG8_WAIT_L(n) asm volatile("s_waitcnt lgkmcnt(" #n ")" ::: "memory")
; #define PG8_BAR __builtin_amdgcn_s_barrier()
; #define PG8_SCHED __builtin_amdgcn_sched_barrier(0)
; template <class Epi>
; __device__ __forceinline__ void gemm_phase(LAS unsigned char* lds, const Gemm g, const StaticOrder& S, const Epi& E) {
;     ...
;             PG8_LDA(At, 0, 1); PG8_STAGE(PG8_SB(0, 0), b2, voffB); PG8_STAGE(PG8_SB(0, 1), b2 + hstepB, voffB); PG8_STAGE(PG8_SA(0, 0), a2, voffA);
;             PG8_WAIT_V(8); PG8_WAIT_L(0); PG8_BAR; PG8_MMA(1, 0, At, B0); PG8_MMA(1, 1, At, B1); PG8_BAR; PG8_SCHED;
;             PG8_LDB(B0, 1, 0); PG8_LDB(B1, 1, 1); PG8_SCHED; PG8_LDA(At, 1, 0); PG8_STAGE(PG8_SA(0, 1), a2 + hstepA, voffA);
;             PG8_WAIT_V(8); PG8_WAIT_L(0); PG8_BAR; PG8_MMA(0, 0, At, B0); PG8_MMA(0, 1, At, B1); PG8_BAR; PG8_SCHED;
;             PG8_LDA(At, 1, 1); PG8_STAGE(PG8_SB(1, 0), b3, voffB); PG8_STAGE(PG8_SB(1, 1), b3 + hstepB, voffB); PG8_STAGE(PG8_SA(1, 0), a3, voffA);
	s_setprio 1
	s_waitcnt lgkmcnt(0)
	v_mfma_f32_16x16x32_bf16 v[62:65], v[146:149], v[188:191], v[62:65]
	v_mfma_f32_16x16x32_bf16 v[58:61], v[154:157], v[188:191], v[58:61]
	v_mfma_f32_16x16x32_bf16 v[46:49], v[146:149], v[196:199], v[46:49]
	v_mfma_f32_16x16x32_bf16 v[42:45], v[154:157], v[196:199], v[42:45]
	v_mfma_f32_16x16x32_bf16 v[30:33], v[146:149], v[204:207], v[30:33]
	v_mfma_f32_16x16x32_bf16 v[26:29], v[154:157], v[204:207], v[26:29]
	v_mfma_f32_16x16x32_bf16 v[14:17], v[146:149], v[212:215], v[14:17]
	v_mfma_f32_16x16x32_bf16 v[10:13], v[154:157], v[212:215], v[10:13]
	v_mfma_f32_16x16x32_bf16 v[62:65], v[150:153], v[192:195], v[62:65]
	v_mfma_f32_16x16x32_bf16 v[58:61], v[158:161], v[192:195], v[58:61]
	v_mfma_f32_16x16x32_bf16 v[46:49], v[150:153], v[200:203], v[46:49]
	v_mfma_f32_16x16x32_bf16 v[42:45], v[158:161], v[200:203], v[42:45]
	v_mfma_f32_16x16x32_bf16 v[30:33], v[150:153], v[208:211], v[30:33]
	v_mfma_f32_16x16x32_bf16 v[26:29], v[158:161], v[208:211], v[26:29]
	v_mfma_f32_16x16x32_bf16 v[14:17], v[150:153], v[216:219], v[14:17]
	v_mfma_f32_16x16x32_bf16 v[10:13], v[158:161], v[216:219], v[10:13]
	v_mfma_f32_16x16x32_bf16 v[54:57], v[162:165], v[188:191], v[54:57]
	v_mfma_f32_16x16x32_bf16 v[50:53], v[170:173], v[188:191], v[50:53]
	v_mfma_f32_16x16x32_bf16 v[38:41], v[162:165], v[196:199], v[38:41]
	v_mfma_f32_16x16x32_bf16 v[34:37], v[170:173], v[196:199], v[34:37]
	v_mfma_f32_16x16x32_bf16 v[22:25], v[162:165], v[204:207], v[22:25]
	v_mfma_f32_16x16x32_bf16 v[18:21], v[170:173], v[204:207], v[18:21]
	v_mfma_f32_16x16x32_bf16 v[6:9], v[162:165], v[212:215], v[6:9]
	v_mfma_f32_16x16x32_bf16 v[2:5], v[170:173], v[212:215], v[2:5]
	v_mfma_f32_16x16x32_bf16 v[54:57], v[166:169], v[192:195], v[54:57]
	v_mfma_f32_16x16x32_bf16 v[50:53], v[174:177], v[192:195], v[50:53]
	v_mfma_f32_16x16x32_bf16 v[38:41], v[166:169], v[200:203], v[38:41]
	v_mfma_f32_16x16x32_bf16 v[34:37], v[174:177], v[200:203], v[34:37]
	v_mfma_f32_16x16x32_bf16 v[22:25], v[166:169], v[208:211], v[22:25]
	v_mfma_f32_16x16x32_bf16 v[18:21], v[174:177], v[208:211], v[18:21]
	v_mfma_f32_16x16x32_bf16 v[6:9], v[166:169], v[216:219], v[6:9]
	v_mfma_f32_16x16x32_bf16 v[2:5], v[174:177], v[216:219], v[2:5]
	s_setprio 0
	s_barrier
	s_add_i32 s62, 0, 0x18000
	v_add_u32_e32 v145, s62, v1
	s_add_i32 s63, 0, 0x1c000
	ds_read_b128 v[146:149], v145
	ds_read_b128 v[150:153], v145 offset:1024
	ds_read_b128 v[154:157], v145 offset:2048
	ds_read_b128 v[158:161], v145 offset:3072
	v_add_u32_e32 v145, s63, v1
	ds_read_b128 v[162:165], v145
	ds_read_b128 v[166:169], v145 offset:1024
	ds_read_b128 v[170:173], v145 offset:2048
	ds_read_b128 v[174:177], v145 offset:3072
	s_add_u32 s22, s22, 0x80000
	s_addc_u32 s23, s23, 0
	s_mov_b32 m0, s29
	v_lshl_add_u64 v[222:223], s[22:23], 0, v[130:131]
	ds_read_b128 v[188:191], v144 offset:32768
	ds_read_b128 v[192:195], v144 offset:33792
	ds_read_b128 v[196:199], v144 offset:34816
	ds_read_b128 v[200:203], v144 offset:35840
	ds_read_b128 v[204:207], v144 offset:36864
	ds_read_b128 v[208:211], v144 offset:37888
	ds_read_b128 v[212:215], v144 offset:38912
	ds_read_b128 v[216:219], v144 offset:39936
	global_load_lds_dwordx4 v[222:223], off
	v_lshl_add_u64 v[222:223], s[22:23], 0, v[134:135]
	s_mov_b32 m0, s30
	s_nop 0
	global_load_lds_dwordx4 v[222:223], off
	s_waitcnt vmcnt(8)
	s_waitcnt lgkmcnt(0)
	s_barrier
	s_setprio 1
	s_waitcnt lgkmcnt(0)
	v_mfma_f32_16x16x32_bf16 v[126:129], v[146:149], v[188:191], v[126:129]
	v_mfma_f32_16x16x32_bf16 v[122:125], v[154:157], v[188:191], v[122:125]
	v_mfma_f32_16x16x32_bf16 v[110:113], v[146:149], v[196:199], v[110:113]
	v_mfma_f32_16x16x32_bf16 v[106:109], v[154:157], v[196:199], v[106:109]
	v_mfma_f32_16x16x32_bf16 v[94:97], v[146:149], v[204:207], v[94:97]
	v_mfma_f32_16x16x32_bf16 v[90:93], v[154:157], v[204:207], v[90:93]
	v_mfma_f32_16x16x32_bf16 v[78:81], v[146:149], v[212:215], v[78:81]
	v_mfma_f32_16x16x32_bf16 v[74:77], v[154:157], v[212:215], v[74:77]
	v_mfma_f32_16x16x32_bf16 v[126:129], v[150:153], v[192:195], v[126:129]
	v_mfma_f32_16x16x32_bf16 v[122:125], v[158:161], v[192:195], v[122:125]
	v_mfma_f32_16x16x32_bf16 v[110:113], v[150:153], v[200:203], v[110:113]
	v_mfma_f32_16x16x32_bf16 v[106:109], v[158:161], v[200:203], v[106:109]
	v_mfma_f32_16x16x32_bf16 v[94:97], v[150:153], v[208:211], v[94:97]
	v_mfma_f32_16x16x32_bf16 v[90:93], v[158:161], v[208:211], v[90:93]
	v_mfma_f32_16x16x32_bf16 v[78:81], v[150:153], v[216:219], v[78:81]
	v_mfma_f32_16x16x32_bf16 v[74:77], v[158:161], v[216:219], v[74:77]
	v_mfma_f32_16x16x32_bf16 v[118:121], v[162:165], v[188:191], v[118:121]
	v_mfma_f32_16x16x32_bf16 v[114:117], v[170:173], v[188:191], v[114:117]
	v_mfma_f32_16x16x32_bf16 v[102:105], v[162:165], v[196:199], v[102:105]
	v_mfma_f32_16x16x32_bf16 v[98:101], v[170:173], v[196:199], v[98:101]
	v_mfma_f32_16x16x32_bf16 v[86:89], v[162:165], v[204:207], v[86:89]
	v_mfma_f32_16x16x32_bf16 v[82:85], v[170:173], v[204:207], v[82:85]
	v_mfma_f32_16x16x32_bf16 v[70:73], v[162:165], v[212:215], v[70:73]
	v_mfma_f32_16x16x32_bf16 v[66:69], v[170:173], v[212:215], v[66:69]
	v_mfma_f32_16x16x32_bf16 v[118:121], v[166:169], v[192:195], v[118:121]
	v_mfma_f32_16x16x32_bf16 v[114:117], v[174:177], v[192:195], v[114:117]
	v_mfma_f32_16x16x32_bf16 v[102:105], v[166:169], v[200:203], v[102:105]
	v_mfma_f32_16x16x32_bf16 v[98:101], v[174:177], v[200:203], v[98:101]
	v_mfma_f32_16x16x32_bf16 v[86:89], v[166:169], v[208:211], v[86:89]
	v_mfma_f32_16x16x32_bf16 v[82:85], v[174:177], v[208:211], v[82:85]
	v_mfma_f32_16x16x32_bf16 v[70:73], v[166:169], v[216:219], v[70:73]
	v_mfma_f32_16x16x32_bf16 v[66:69], v[174:177], v[216:219], v[66:69]
	s_setprio 0
	s_barrier
; #define PG8_STAGE(bufoff, gbase, voff) do { _Pragma("unroll") for (int _i = 0; _i < 2; ++_i) \
;         __builtin_amdgcn_global_load_lds((const unsigned*)((const char*)(gbase) + (voff)[_i]), (LAS unsigned*)(lds + (bufoff) + ldsw + _i * 8192), 16, 0, 0); } while (0)
; #define PG8_LDA(dst, b, h) do { _Pragma("unroll") for (int m = 0; m < 4; ++m) _Pragma("unroll") for (int k = 0; k < 2; ++k) dst[m][k] = *(const LAS bf16x8*)(lds + PG8_SA(b, h) + aoff + m * 2048 + k * 1024); } while (0)
; #define PG8_MMA(ai, bj, At, Bt) do { __builtin_amdgcn_s_setprio(1); _Pragma("unroll") for (int m = 0; m < 4; ++m) _Pragma("unroll") for (int n = 0; n < 2; ++n) _Pragma("unroll") for (int k = 0; k < 2; ++k) \
;         acc[ai][bj][m][n] = __builtin_amdgcn_mfma_f32_16x16x32_bf16(Bt[n][k], At[m][k], acc[ai][bj][m][n], 0, 0, 0); __builtin_amdgcn_s_setprio(0); } while (0)
; #define PG8_WAIT_V(n) asm volatile("s_waitcnt vmcnt(" #n ")" ::: "memory")
; #define PG8_WAIT_L(n) asm volatile("s_waitcnt lgkmcnt(" #n ")" ::: "memory")
; #define PG8_BAR __builtin_amdgcn_s_barrier()
; #define PG8_SCHED __builtin_amdgcn_sched_barrier(0)
; template <class Epi>
; __device__ __forceinline__ void gemm_phase(LAS unsigned char* lds, const Gemm g, const StaticOrder& S, const Epi& E) {
;     ...
;             PG8_LDA(At, 1, 1); PG8_STAGE(PG8_SB(1, 0), b3, voffB); PG8_STAGE(PG8_SB(1, 1), b3 + hstepB, voffB); PG8_STAGE(PG8_SA(1, 0), a3, voffA);
;             PG8_WAIT_V(8); PG8_WAIT_L(0); PG8_BAR; PG8_MMA(1, 0, At, B0); PG8_MMA(1, 1, At, B1); PG8_BAR; PG8_SCHED;
;         }
	s_add_i32 s22, s62, s27
	v_lshl_add_u64 v[142:143], v[142:143], 0, s[84:85]
	s_mov_b32 m0, s22
	ds_read_b128 v[188:191], v144 offset:49152
	ds_read_b128 v[192:195], v144 offset:50176
	ds_read_b128 v[196:199], v144 offset:51200
	ds_read_b128 v[200:203], v144 offset:52224
	ds_read_b128 v[204:207], v144 offset:53248
	ds_read_b128 v[208:211], v144 offset:54272
	ds_read_b128 v[212:215], v144 offset:55296
	ds_read_b128 v[216:219], v144 offset:56320
	global_load_lds_dwordx4 v[142:143], off
	s_add_i32 m0, s22, 0x2000
	s_add_u32 s14, s14, 0x80080
	v_lshl_add_u64 v[142:143], v[178:179], 0, s[84:85]
	s_addc_u32 s15, s15, 0
	s_add_i32 s22, s63, s27
	global_load_lds_dwordx4 v[142:143], off
	v_lshl_add_u64 v[142:143], s[14:15], 0, v[132:133]
	s_mov_b32 m0, s22
	s_nop 0
	global_load_lds_dwordx4 v[142:143], off
	v_lshl_add_u64 v[142:143], s[14:15], 0, v[136:137]
	s_add_i32 m0, s22, 0x2000
	s_nop 0
	global_load_lds_dwordx4 v[142:143], off
	v_lshl_add_u64 v[142:143], v[184:185], 0, s[84:85]
	s_mov_b32 m0, s34
	s_nop 0
	global_load_lds_dwordx4 v[142:143], off
	v_lshl_add_u64 v[142:143], v[220:221], 0, s[84:85]
	s_mov_b32 m0, s35
	s_nop 0
	global_load_lds_dwordx4 v[142:143], off
	s_waitcnt vmcnt(8)
	s_waitcnt lgkmcnt(0)
	s_barrier
	s_setprio 1
	s_waitcnt lgkmcnt(0)
	v_mfma_f32_16x16x32_bf16 v[62:65], v[146:149], v[188:191], v[62:65]
	v_mfma_f32_16x16x32_bf16 v[58:61], v[154:157], v[188:191], v[58:61]
	v_mfma_f32_16x16x32_bf16 v[46:49], v[146:149], v[196:199], v[46:49]
	v_mfma_f32_16x16x32_bf16 v[42:45], v[154:157], v[196:199], v[42:45]
	v_mfma_f32_16x16x32_bf16 v[30:33], v[146:149], v[204:207], v[30:33]
	v_mfma_f32_16x16x32_bf16 v[26:29], v[154:157], v[204:207], v[26:29]
	v_mfma_f32_16x16x32_bf16 v[14:17], v[146:149], v[212:215], v[14:17]
	v_mfma_f32_16x16x32_bf16 v[10:13], v[154:157], v[212:215], v[10:13]
	v_mfma_f32_16x16x32_bf16 v[62:65], v[150:153], v[192:195], v[62:65]
	v_mfma_f32_16x16x32_bf16 v[58:61], v[158:161], v[192:195], v[58:61]
	v_mfma_f32_16x16x32_bf16 v[46:49], v[150:153], v[200:203], v[46:49]
	v_mfma_f32_16x16x32_bf16 v[42:45], v[158:161], v[200:203], v[42:45]
	v_mfma_f32_16x16x32_bf16 v[30:33], v[150:153], v[208:211], v[30:33]
	v_mfma_f32_16x16x32_bf16 v[26:29], v[158:161], v[208:211], v[26:29]
	v_mfma_f32_16x16x32_bf16 v[14:17], v[150:153], v[216:219], v[14:17]
	v_mfma_f32_16x16x32_bf16 v[10:13], v[158:161], v[216:219], v[10:13]
	v_mfma_f32_16x16x32_bf16 v[54:57], v[162:165], v[188:191], v[54:57]
	v_mfma_f32_16x16x32_bf16 v[50:53], v[170:173], v[188:191], v[50:53]
	v_mfma_f32_16x16x32_bf16 v[38:41], v[162:165], v[196:199], v[38:41]
	v_mfma_f32_16x16x32_bf16 v[34:37], v[170:173], v[196:199], v[34:37]
	v_mfma_f32_16x16x32_bf16 v[22:25], v[162:165], v[204:207], v[22:25]
	v_mfma_f32_16x16x32_bf16 v[18:21], v[170:173], v[204:207], v[18:21]
	v_mfma_f32_16x16x32_bf16 v[6:9], v[162:165], v[212:215], v[6:9]
	v_mfma_f32_16x16x32_bf16 v[2:5], v[170:173], v[212:215], v[2:5]
	v_mfma_f32_16x16x32_bf16 v[54:57], v[166:169], v[192:195], v[54:57]
	v_mfma_f32_16x16x32_bf16 v[50:53], v[174:177], v[192:195], v[50:53]
	v_mfma_f32_16x16x32_bf16 v[38:41], v[166:169], v[200:203], v[38:41]
	v_mfma_f32_16x16x32_bf16 v[34:37], v[174:177], v[200:203], v[34:37]
	v_mfma_f32_16x16x32_bf16 v[22:25], v[166:169], v[208:211], v[22:25]
	v_mfma_f32_16x16x32_bf16 v[18:21], v[174:177], v[208:211], v[18:21]
	v_mfma_f32_16x16x32_bf16 v[6:9], v[166:169], v[216:219], v[6:9]
	v_mfma_f32_16x16x32_bf16 v[2:5], v[174:177], v[216:219], v[2:5]
	s_setprio 0
	s_barrier
	s_add_i32 s41, s41, 2
	s_add_u32 s20, s20, 0x100
	s_addc_u32 s21, s21, 0
	s_add_u32 s52, s52, 0x100
	s_addc_u32 s53, s53, 0
	s_cmp_gt_u32 s41, 29
	s_cbranch_scc0 .LBB0_2130
	s_cmp_ge_u32 s74, 16
	s_cbranch_scc1 .Lwpf_d
	s_lshl_b32 s100, s74, 9
	v_add_u32_e32 v146, s100, v246
	v_lshrrev_b32_e32 v147, 2, v146
	v_and_b32_e32 v146, 3, v146
	v_lshlrev_b32_e32 v146, 7, v146
	v_lshl_add_u32 v146, v147, 14, v146
	s_add_u32 s100, s88, 0x2000000
	s_addc_u32 s101, s89, 0
	s_mov_b32 m0, 0x21000
	s_nop 0
	global_load_lds_dword v146, s[100:101]

; #define PG8_STAGE(bufoff, gbase, voff) do { _Pragma("unroll") for (int _i = 0; _i < 2; ++_i) \
;         __builtin_amdgcn_global_load_lds((const unsigned*)((const char*)(gbase) + (voff)[_i]), (LAS unsigned*)(lds + (bufoff) + ldsw + _i * 8192), 16, 0, 0); } while (0)
; #define PG8_LDA(dst, b, h) do { _Pragma("unroll") for (int m = 0; m < 4; ++m) _Pragma("unroll") for (int k = 0; k < 2; ++k) dst[m][k] = *(const LAS bf16x8*)(lds + PG8_SA(b, h) + aoff + m * 2048 + k * 1024); } while (0)
; #define PG8_LDB(dst, b, h) do { _Pragma("unroll") for (int n = 0; n < 2; ++n) _Pragma("unroll") for (int k = 0; k < 2; ++k) dst[n][k] = *(const LAS bf16x8*)(lds + PG8_SB(b, h) + boff + n * 2048 + k * 1024); } while (0)
; #define PG8_MMA(ai, bj, At, Bt) do { __builtin_amdgcn_s_setprio(1); _Pragma("unroll") for (int m = 0; m < 4; ++m) _Pragma("unroll") for (int n = 0; n < 2; ++n) _Pragma("unroll") for (int k = 0; k < 2; ++k) \
;         acc[ai][bj][m][n] = __builtin_amdgcn_mfma_f32_16x16x32_bf16(Bt[n][k], At[m][k], acc[ai][bj][m][n], 0, 0, 0); __builtin_amdgcn_s_setprio(0); } while (0)
; #define PG8_WAIT_V(n) asm volatile("s_waitcnt vmcnt(" #n ")" ::: "memory")
; #define PG8_BAR __builtin_amdgcn_s_barrier()
; template <class Epi>
; __device__ __forceinline__ void gemm_phase(LAS unsigned char* lds, const Gemm g, const StaticOrder& S, const Epi& E) {
;     ...
;         const bool has_next = S.next(ui + 1, nxt);
;         const char* nA = has_next ? PG8_UA(nxt) : cA; const char* nB = has_next ? PG8_UB(nxt) : cB;
;         for (int t = 0; t < nt; t += 2) {
;             const bool last = (t == nt - 2);
;             const char* a1 = cA + (size_t)(t + 1) * kstep;
;             const char* a2 = last ? nA : cA + (size_t)(t + 2) * kstep; const char* b2 = last ? nB : cB + (size_t)(t + 2) * kstep;
;             const char* a3 = a2 + kstep; const char* b3 = b2 + kstep;
;             PG8_LDB(B0, 0, 0); PG8_LDB(B1, 0, 1); PG8_SCHED; PG8_LDA(At, 0, 0); PG8_STAGE(PG8_SA(1, 1), a1 + hstepA, voffA);
;             PG8_WAIT_V(8); PG8_WAIT_L(0); PG8_BAR; PG8_MMA(0, 0, At, B0); PG8_MMA(0, 1, At, B1); PG8_BAR; PG8_SCHED;
;             PG8_LDA(At, 0, 1); PG8_STAGE(PG8_SB(0, 0), b2, voffB); PG8_STAGE(PG8_SB(0, 1), b2 + hstepB, voffB); PG8_STAGE(PG8_SA(0, 0), a2, voffA);
;             PG8_WAIT_V(8); PG8_WAIT_L(0); PG8_BAR; PG8_MMA(1, 0, At, B0); PG8_MMA(1, 1, At, B1); PG8_BAR; PG8_SCHED;
.LBB0_2155:
	s_add_u32 s41, s20, s14
	s_addc_u32 s44, s21, 0
	s_add_u32 s15, s41, 0x100
	s_addc_u32 s34, s44, 0
	s_and_b64 s[30:31], s[28:29], exec
	s_cselect_b32 s31, s19, s34
	s_cselect_b32 s30, s3, s15
	s_add_u32 s14, s12, s14
	s_addc_u32 s15, s13, 0
	s_add_u32 s34, s14, 0x100
	s_addc_u32 s35, s15, 0
	s_add_i32 s81, 0, 0x10000
	s_and_b64 s[14:15], s[28:29], exec
	s_cselect_b32 s35, s17, s35
	s_cselect_b32 s34, s40, s34
	s_add_i32 s29, 0, 0x14000
	s_add_u32 s68, s41, 0x10080
	s_addc_u32 s69, s44, 0
	s_add_i32 s80, s81, s63
	s_add_i32 m0, s11, 0xc000
	s_add_i32 s83, s11, 0xe000
	s_add_i32 s77, s80, 0x2000
	v_add_u32_e32 v139, s81, v1
	s_add_u32 s44, s34, 0x10000
	ds_read_b128 v[140:143], v139
	ds_read_b128 v[144:147], v139 offset:1024
	ds_read_b128 v[148:151], v139 offset:2048
	ds_read_b128 v[152:155], v139 offset:3072
	v_add_u32_e32 v139, s29, v1
	s_addc_u32 s45, s35, 0
	s_add_i32 s79, s29, s63
	ds_read_b128 v[156:159], v139
	ds_read_b128 v[160:163], v139 offset:1024
	ds_read_b128 v[164:167], v139 offset:2048
	ds_read_b128 v[168:171], v139 offset:3072
	s_add_i32 s78, s79, 0x2000
	s_add_i32 s76, 0, 0x18000
	s_add_i32 vcc_hi, 0, 0x1c000
	s_add_u32 s14, s30, 0x10000
	s_addc_u32 s15, s31, 0
	s_add_i32 vcc_lo, s76, s63
	s_add_i32 s41, vcc_lo, 0x2000
	s_add_u32 s28, s34, 0x10080
	s_addc_u32 s29, s35, 0
	s_add_i32 s82, vcc_hi, s63
	s_add_i32 s81, s82, 0x2000
	v_lshl_add_u64 v[184:185], s[68:69], 0, v[130:131]
	ds_read_b128 v[172:175], v138
	ds_read_b128 v[176:179], v138 offset:1024
	ds_read_b128 v[188:191], v138 offset:2048
	ds_read_b128 v[192:195], v138 offset:3072
	ds_read_b128 v[196:199], v138 offset:4096
	ds_read_b128 v[200:203], v138 offset:5120
	ds_read_b128 v[204:207], v138 offset:6144
	ds_read_b128 v[208:211], v138 offset:7168
	global_load_lds_dwordx4 v[184:185], off
	v_lshl_add_u64 v[184:185], s[68:69], 0, v[134:135]
	s_mov_b32 m0, s83
	s_nop 0
	global_load_lds_dwordx4 v[184:185], off
	s_waitcnt vmcnt(8)
	s_waitcnt lgkmcnt(0)
	s_barrier
	s_setprio 1
	s_waitcnt lgkmcnt(0)
	v_mfma_f32_16x16x32_bf16 v[126:129], v[140:143], v[172:175], v[126:129]
	v_mfma_f32_16x16x32_bf16 v[122:125], v[148:151], v[172:175], v[122:125]
	v_mfma_f32_16x16x32_bf16 v[118:121], v[140:143], v[188:191], v[118:121]
	v_mfma_f32_16x16x32_bf16 v[114:117], v[148:151], v[188:191], v[114:117]
	v_mfma_f32_16x16x32_bf16 v[102:105], v[140:143], v[196:199], v[102:105]
	v_mfma_f32_16x16x32_bf16 v[98:101], v[148:151], v[196:199], v[98:101]
	v_mfma_f32_16x16x32_bf16 v[86:89], v[140:143], v[204:207], v[86:89]
	v_mfma_f32_16x16x32_bf16 v[82:85], v[148:151], v[204:207], v[82:85]
	v_mfma_f32_16x16x32_bf16 v[126:129], v[144:147], v[176:179], v[126:129]
	v_mfma_f32_16x16x32_bf16 v[122:125], v[152:155], v[176:179], v[122:125]
	v_mfma_f32_16x16x32_bf16 v[118:121], v[144:147], v[192:195], v[118:121]
	v_mfma_f32_16x16x32_bf16 v[114:117], v[152:155], v[192:195], v[114:117]
	v_mfma_f32_16x16x32_bf16 v[102:105], v[144:147], v[200:203], v[102:105]
	v_mfma_f32_16x16x32_bf16 v[98:101], v[152:155], v[200:203], v[98:101]
	v_mfma_f32_16x16x32_bf16 v[86:89], v[144:147], v[208:211], v[86:89]
	v_mfma_f32_16x16x32_bf16 v[82:85], v[152:155], v[208:211], v[82:85]
	v_mfma_f32_16x16x32_bf16 v[110:113], v[156:159], v[172:175], v[110:113]
	v_mfma_f32_16x16x32_bf16 v[106:109], v[164:167], v[172:175], v[106:109]
	v_mfma_f32_16x16x32_bf16 v[94:97], v[156:159], v[188:191], v[94:97]
	v_mfma_f32_16x16x32_bf16 v[90:93], v[164:167], v[188:191], v[90:93]
	v_mfma_f32_16x16x32_bf16 v[78:81], v[156:159], v[196:199], v[78:81]
	v_mfma_f32_16x16x32_bf16 v[74:77], v[164:167], v[196:199], v[74:77]
	v_mfma_f32_16x16x32_bf16 v[70:73], v[156:159], v[204:207], v[70:73]
	v_mfma_f32_16x16x32_bf16 v[66:69], v[164:167], v[204:207], v[66:69]
	v_mfma_f32_16x16x32_bf16 v[110:113], v[160:163], v[176:179], v[110:113]
	v_mfma_f32_16x16x32_bf16 v[106:109], v[168:171], v[176:179], v[106:109]
	v_mfma_f32_16x16x32_bf16 v[94:97], v[160:163], v[192:195], v[94:97]
	v_mfma_f32_16x16x32_bf16 v[90:93], v[168:171], v[192:195], v[90:93]
	v_mfma_f32_16x16x32_bf16 v[78:81], v[160:163], v[200:203], v[78:81]
	v_mfma_f32_16x16x32_bf16 v[74:77], v[168:171], v[200:203], v[74:77]
	v_mfma_f32_16x16x32_bf16 v[70:73], v[160:163], v[208:211], v[70:73]
	v_mfma_f32_16x16x32_bf16 v[66:69], v[168:171], v[208:211], v[66:69]
	s_setprio 0
	s_barrier
	s_mov_b32 m0, s80
	v_lshl_add_u64 v[184:185], s[34:35], 0, v[132:133]
	ds_read_b128 v[172:175], v138 offset:16384
	ds_read_b128 v[176:179], v138 offset:17408
	ds_read_b128 v[188:191], v138 offset:18432
	ds_read_b128 v[192:195], v138 offset:19456
	ds_read_b128 v[196:199], v138 offset:20480
	ds_read_b128 v[200:203], v138 offset:21504
	ds_read_b128 v[204:207], v138 offset:22528
	ds_read_b128 v[208:211], v138 offset:23552
	global_load_lds_dwordx4 v[184:185], off
	v_lshl_add_u64 v[212:213], s[34:35], 0, v[136:137]
	s_mov_b32 m0, s77
	v_lshl_add_u64 v[214:215], s[44:45], 0, v[132:133]
	global_load_lds_dwordx4 v[212:213], off
	s_mov_b32 m0, s79
	v_lshl_add_u64 v[216:217], s[30:31], 0, v[134:135]
	global_load_lds_dwordx4 v[214:215], off
	v_lshl_add_u64 v[214:215], s[44:45], 0, v[136:137]
	s_mov_b32 m0, s78
	s_nop 0
	global_load_lds_dwordx4 v[214:215], off
	v_lshl_add_u64 v[214:215], s[30:31], 0, v[130:131]
	s_mov_b32 m0, s11
	s_nop 0
	global_load_lds_dwordx4 v[214:215], off
	s_mov_b32 m0, s64
	s_nop 0
	global_load_lds_dwordx4 v[216:217], off
	s_waitcnt vmcnt(8)
	s_waitcnt lgkmcnt(0)
	s_barrier
; #define PG8_STAGE(bufoff, gbase, voff) do { _Pragma("unroll") for (int _i = 0; _i < 2; ++_i) \
;         __builtin_amdgcn_global_load_lds((const unsigned*)((const char*)(gbase) + (voff)[_i]), (LAS unsigned*)(lds + (bufoff) + ldsw + _i * 8192), 16, 0, 0); } while (0)
; #define PG8_LDA(dst, b, h) do { _Pragma("unroll") for (int m = 0; m < 4; ++m) _Pragma("unroll") for (int k = 0; k < 2; ++k) dst[m][k] = *(const LAS bf16x8*)(lds + PG8_SA(b, h) + aoff + m * 2048 + k * 1024); } while (0)
; #define PG8_LDB(dst, b, h) do { _Pragma("unroll") for (int n = 0; n < 2; ++n) _Pragma("unroll") for (int k = 0; k < 2; ++k) dst[n][k] = *(const LAS bf16x8*)(lds + PG8_SB(b, h) + boff + n * 2048 + k * 1024); } while (0)
; #define PG8_MMA(ai, bj, At, Bt) do { __builtin_amdgcn_s_setprio(1); _Pragma("unroll") for (int m = 0; m < 4; ++m) _Pragma("unroll") for (int n = 0; n < 2; ++n) _Pragma("unroll") for (int k = 0; k < 2; ++k) \
;         acc[ai][bj][m][n] = __builtin_amdgcn_mfma_f32_16x16x32_bf16(Bt[n][k], At[m][k], acc[ai][bj][m][n], 0, 0, 0); __builtin_amdgcn_s_setprio(0); } while (0)
; #define PG8_WAIT_V(n) asm volatile("s_waitcnt vmcnt(" #n ")" ::: "memory")
; #define PG8_WAIT_L(n) asm volatile("s_waitcnt lgkmcnt(" #n ")" ::: "memory")
; #define PG8_BAR __builtin_amdgcn_s_barrier()
; #define PG8_SCHED __builtin_amdgcn_sched_barrier(0)
; template <class Epi>
; __device__ __forceinline__ void gemm_phase(LAS unsigned char* lds, const Gemm g, const StaticOrder& S, const Epi& E) {
;     ...
;             PG8_LDA(At, 0, 1); PG8_STAGE(PG8_SB(0, 0), b2, voffB); PG8_STAGE(PG8_SB(0, 1), b2 + hstepB, voffB); PG8_STAGE(PG8_SA(0, 0), a2, voffA);
;             PG8_WAIT_V(8); PG8_WAIT_L(0); PG8_BAR; PG8_MMA(1, 0, At, B0); PG8_MMA(1, 1, At, B1); PG8_BAR; PG8_SCHED;
;             PG8_LDB(B0, 1, 0); PG8_LDB(B1, 1, 1); PG8_SCHED; PG8_LDA(At, 1, 0); PG8_STAGE(PG8_SA(0, 1), a2 + hstepA, voffA);
;             PG8_WAIT_V(8); PG8_WAIT_L(0); PG8_BAR; PG8_MMA(0, 0, At, B0); PG8_MMA(0, 1, At, B1); PG8_BAR; PG8_SCHED;
;             PG8_LDA(At, 1, 1); PG8_STAGE(PG8_SB(1, 0), b3, voffB); PG8_STAGE(PG8_SB(1, 1), b3 + hstepB, voffB); PG8_STAGE(PG8_SA(1, 0), a3, voffA);
	s_setprio 1
	s_waitcnt lgkmcnt(0)
	v_mfma_f32_16x16x32_bf16 v[62:65], v[140:143], v[172:175], v[62:65]
	v_mfma_f32_16x16x32_bf16 v[58:61], v[148:151], v[172:175], v[58:61]
	v_mfma_f32_16x16x32_bf16 v[54:57], v[140:143], v[188:191], v[54:57]
	v_mfma_f32_16x16x32_bf16 v[50:53], v[148:151], v[188:191], v[50:53]
	v_mfma_f32_16x16x32_bf16 v[38:41], v[140:143], v[196:199], v[38:41]
	v_mfma_f32_16x16x32_bf16 v[34:37], v[148:151], v[196:199], v[34:37]
	v_mfma_f32_16x16x32_bf16 v[22:25], v[140:143], v[204:207], v[22:25]
	v_mfma_f32_16x16x32_bf16 v[18:21], v[148:151], v[204:207], v[18:21]
	v_mfma_f32_16x16x32_bf16 v[62:65], v[144:147], v[176:179], v[62:65]
	v_mfma_f32_16x16x32_bf16 v[58:61], v[152:155], v[176:179], v[58:61]
	v_mfma_f32_16x16x32_bf16 v[54:57], v[144:147], v[192:195], v[54:57]
	v_mfma_f32_16x16x32_bf16 v[50:53], v[152:155], v[192:195], v[50:53]
	v_mfma_f32_16x16x32_bf16 v[38:41], v[144:147], v[200:203], v[38:41]
	v_mfma_f32_16x16x32_bf16 v[34:37], v[152:155], v[200:203], v[34:37]
	v_mfma_f32_16x16x32_bf16 v[22:25], v[144:147], v[208:211], v[22:25]
	v_mfma_f32_16x16x32_bf16 v[18:21], v[152:155], v[208:211], v[18:21]
	v_mfma_f32_16x16x32_bf16 v[46:49], v[156:159], v[172:175], v[46:49]
	v_mfma_f32_16x16x32_bf16 v[42:45], v[164:167], v[172:175], v[42:45]
	v_mfma_f32_16x16x32_bf16 v[30:33], v[156:159], v[188:191], v[30:33]
	v_mfma_f32_16x16x32_bf16 v[26:29], v[164:167], v[188:191], v[26:29]
	v_mfma_f32_16x16x32_bf16 v[14:17], v[156:159], v[196:199], v[14:17]
	v_mfma_f32_16x16x32_bf16 v[10:13], v[164:167], v[196:199], v[10:13]
	v_mfma_f32_16x16x32_bf16 v[6:9], v[156:159], v[204:207], v[6:9]
	v_mfma_f32_16x16x32_bf16 v[2:5], v[164:167], v[204:207], v[2:5]
	v_mfma_f32_16x16x32_bf16 v[46:49], v[160:163], v[176:179], v[46:49]
	v_mfma_f32_16x16x32_bf16 v[42:45], v[168:171], v[176:179], v[42:45]
	v_mfma_f32_16x16x32_bf16 v[30:33], v[160:163], v[192:195], v[30:33]
	v_mfma_f32_16x16x32_bf16 v[26:29], v[168:171], v[192:195], v[26:29]
	v_mfma_f32_16x16x32_bf16 v[14:17], v[160:163], v[200:203], v[14:17]
	v_mfma_f32_16x16x32_bf16 v[10:13], v[168:171], v[200:203], v[10:13]
	v_mfma_f32_16x16x32_bf16 v[6:9], v[160:163], v[208:211], v[6:9]
	v_mfma_f32_16x16x32_bf16 v[2:5], v[168:171], v[208:211], v[2:5]
	s_setprio 0
	s_barrier
	v_add_u32_e32 v139, s76, v1
	ds_read_b128 v[140:143], v139
	ds_read_b128 v[144:147], v139 offset:1024
	ds_read_b128 v[148:151], v139 offset:2048
	ds_read_b128 v[152:155], v139 offset:3072
	v_add_u32_e32 v139, vcc_hi, v1
	ds_read_b128 v[156:159], v139
	ds_read_b128 v[160:163], v139 offset:1024
	ds_read_b128 v[164:167], v139 offset:2048
	ds_read_b128 v[168:171], v139 offset:3072
	s_mov_b32 m0, s65
	v_lshl_add_u64 v[218:219], s[14:15], 0, v[130:131]
	ds_read_b128 v[172:175], v138 offset:32768
	ds_read_b128 v[176:179], v138 offset:33792
	ds_read_b128 v[188:191], v138 offset:34816
	ds_read_b128 v[192:195], v138 offset:35840
	ds_read_b128 v[196:199], v138 offset:36864
	ds_read_b128 v[200:203], v138 offset:37888
	ds_read_b128 v[204:207], v138 offset:38912
	ds_read_b128 v[208:211], v138 offset:39936
	global_load_lds_dwordx4 v[218:219], off
	v_lshl_add_u64 v[218:219], s[14:15], 0, v[134:135]
	s_mov_b32 m0, s70
	s_nop 0
	global_load_lds_dwordx4 v[218:219], off
	s_waitcnt vmcnt(8)
	s_waitcnt lgkmcnt(0)
	s_barrier
	s_setprio 1
	s_waitcnt lgkmcnt(0)
	v_mfma_f32_16x16x32_bf16 v[126:129], v[140:143], v[172:175], v[126:129]
	v_mfma_f32_16x16x32_bf16 v[122:125], v[148:151], v[172:175], v[122:125]
	v_mfma_f32_16x16x32_bf16 v[118:121], v[140:143], v[188:191], v[118:121]
	v_mfma_f32_16x16x32_bf16 v[114:117], v[148:151], v[188:191], v[114:117]
	v_mfma_f32_16x16x32_bf16 v[102:105], v[140:143], v[196:199], v[102:105]
	v_mfma_f32_16x16x32_bf16 v[98:101], v[148:151], v[196:199], v[98:101]
	v_mfma_f32_16x16x32_bf16 v[86:89], v[140:143], v[204:207], v[86:89]
	v_mfma_f32_16x16x32_bf16 v[82:85], v[148:151], v[204:207], v[82:85]
	v_mfma_f32_16x16x32_bf16 v[126:129], v[144:147], v[176:179], v[126:129]
	v_mfma_f32_16x16x32_bf16 v[122:125], v[152:155], v[176:179], v[122:125]
	v_mfma_f32_16x16x32_bf16 v[118:121], v[144:147], v[192:195], v[118:121]
	v_mfma_f32_16x16x32_bf16 v[114:117], v[152:155], v[192:195], v[114:117]
	v_mfma_f32_16x16x32_bf16 v[102:105], v[144:147], v[200:203], v[102:105]
	v_mfma_f32_16x16x32_bf16 v[98:101], v[152:155], v[200:203], v[98:101]
	v_mfma_f32_16x16x32_bf16 v[86:89], v[144:147], v[208:211], v[86:89]
	v_mfma_f32_16x16x32_bf16 v[82:85], v[152:155], v[208:211], v[82:85]
	v_mfma_f32_16x16x32_bf16 v[110:113], v[156:159], v[172:175], v[110:113]
	v_mfma_f32_16x16x32_bf16 v[106:109], v[164:167], v[172:175], v[106:109]
	v_mfma_f32_16x16x32_bf16 v[94:97], v[156:159], v[188:191], v[94:97]
	v_mfma_f32_16x16x32_bf16 v[90:93], v[164:167], v[188:191], v[90:93]
	v_mfma_f32_16x16x32_bf16 v[78:81], v[156:159], v[196:199], v[78:81]
	v_mfma_f32_16x16x32_bf16 v[74:77], v[164:167], v[196:199], v[74:77]
	v_mfma_f32_16x16x32_bf16 v[70:73], v[156:159], v[204:207], v[70:73]
	v_mfma_f32_16x16x32_bf16 v[66:69], v[164:167], v[204:207], v[66:69]
	v_mfma_f32_16x16x32_bf16 v[110:113], v[160:163], v[176:179], v[110:113]
	v_mfma_f32_16x16x32_bf16 v[106:109], v[168:171], v[176:179], v[106:109]
	v_mfma_f32_16x16x32_bf16 v[94:97], v[160:163], v[192:195], v[94:97]
	v_mfma_f32_16x16x32_bf16 v[90:93], v[168:171], v[192:195], v[90:93]
	v_mfma_f32_16x16x32_bf16 v[78:81], v[160:163], v[200:203], v[78:81]
	v_mfma_f32_16x16x32_bf16 v[74:77], v[168:171], v[200:203], v[74:77]
	v_mfma_f32_16x16x32_bf16 v[70:73], v[160:163], v[208:211], v[70:73]
	v_mfma_f32_16x16x32_bf16 v[66:69], v[168:171], v[208:211], v[66:69]
	s_setprio 0
	s_barrier
; __device__ __forceinline__ int launder(int v) { asm volatile("" : "+v"(v)); return v; }
; #define PG8_STAGE(bufoff, gbase, voff) do { _Pragma("unroll") for (int _i = 0; _i < 2; ++_i) \
;         __builtin_amdgcn_global_load_lds((const unsigned*)((const char*)(gbase) + (voff)[_i]), (LAS unsigned*)(lds + (bufoff) + ldsw + _i * 8192), 16, 0, 0); } while (0)
; #define PG8_LDA(dst, b, h) do { _Pragma("unroll") for (int m = 0; m < 4; ++m) _Pragma("unroll") for (int k = 0; k < 2; ++k) dst[m][k] = *(const LAS bf16x8*)(lds + PG8_SA(b, h) + aoff + m * 2048 + k * 1024); } while (0)
; #define PG8_MMA(ai, bj, At, Bt) do { __builtin_amdgcn_s_setprio(1); _Pragma("unroll") for (int m = 0; m < 4; ++m) _Pragma("unroll") for (int n = 0; n < 2; ++n) _Pragma("unroll") for (int k = 0; k < 2; ++k) \
;         acc[ai][bj][m][n] = __builtin_amdgcn_mfma_f32_16x16x32_bf16(Bt[n][k], At[m][k], acc[ai][bj][m][n], 0, 0, 0); __builtin_amdgcn_s_setprio(0); } while (0)
; #define PG8_WAIT_V(n) asm volatile("s_waitcnt vmcnt(" #n ")" ::: "memory")
; #define PG8_WAIT_L(n) asm volatile("s_waitcnt lgkmcnt(" #n ")" ::: "memory")
; #define PG8_BAR __builtin_amdgcn_s_barrier()
; #define PG8_SCHED __builtin_amdgcn_sched_barrier(0)
; template <class Epi>
; __device__ __forceinline__ void gemm_phase(LAS unsigned char* lds, const Gemm g, const StaticOrder& S, const Epi& E) {
;     ...
;             PG8_LDA(At, 1, 1); PG8_STAGE(PG8_SB(1, 0), b3, voffB); PG8_STAGE(PG8_SB(1, 1), b3 + hstepB, voffB); PG8_STAGE(PG8_SA(1, 0), a3, voffA);
;             PG8_WAIT_V(8); PG8_WAIT_L(0); PG8_BAR; PG8_MMA(1, 0, At, B0); PG8_MMA(1, 1, At, B1); PG8_BAR; PG8_SCHED;
;         }
;         if (wr == 0) PG8_BAR;
;         { const int l2 = launder(threadIdx.x) & 63; E(acc, cur, wr, wc, l2 & 15, l2 >> 4); }
;         if (!has_next) break;
	s_mov_b32 m0, vcc_lo
	v_lshl_add_u64 v[184:185], v[184:185], 0, s[84:85]
	ds_read_b128 v[172:175], v138 offset:49152
	ds_read_b128 v[176:179], v138 offset:50176
	ds_read_b128 v[188:191], v138 offset:51200
	ds_read_b128 v[192:195], v138 offset:52224
	ds_read_b128 v[196:199], v138 offset:53248
	ds_read_b128 v[200:203], v138 offset:54272
	ds_read_b128 v[204:207], v138 offset:55296
	ds_read_b128 v[208:211], v138 offset:56320
	global_load_lds_dwordx4 v[184:185], off
	v_lshl_add_u64 v[184:185], v[212:213], 0, s[84:85]
	s_mov_b32 m0, s41
	s_nop 0
	global_load_lds_dwordx4 v[184:185], off
	v_lshl_add_u64 v[184:185], s[28:29], 0, v[132:133]
	s_mov_b32 m0, s82
	s_nop 0
	global_load_lds_dwordx4 v[184:185], off
	v_lshl_add_u64 v[184:185], s[28:29], 0, v[136:137]
	s_mov_b32 m0, s81
	s_nop 0
	global_load_lds_dwordx4 v[184:185], off
	v_lshl_add_u64 v[184:185], v[214:215], 0, s[84:85]
	s_mov_b32 m0, s86
	s_nop 0
	global_load_lds_dwordx4 v[184:185], off
	v_lshl_add_u64 v[184:185], v[216:217], 0, s[84:85]
	s_mov_b32 m0, s87
	s_nop 0
	global_load_lds_dwordx4 v[184:185], off
	s_waitcnt vmcnt(8)
	s_waitcnt lgkmcnt(0)
	s_barrier
	s_setprio 1
	s_waitcnt lgkmcnt(0)
	v_mfma_f32_16x16x32_bf16 v[62:65], v[140:143], v[172:175], v[62:65]
	v_mfma_f32_16x16x32_bf16 v[58:61], v[148:151], v[172:175], v[58:61]
	v_mfma_f32_16x16x32_bf16 v[54:57], v[140:143], v[188:191], v[54:57]
	v_mfma_f32_16x16x32_bf16 v[50:53], v[148:151], v[188:191], v[50:53]
	v_mfma_f32_16x16x32_bf16 v[38:41], v[140:143], v[196:199], v[38:41]
	v_mfma_f32_16x16x32_bf16 v[34:37], v[148:151], v[196:199], v[34:37]
	v_mfma_f32_16x16x32_bf16 v[22:25], v[140:143], v[204:207], v[22:25]
	v_mfma_f32_16x16x32_bf16 v[18:21], v[148:151], v[204:207], v[18:21]
	v_mfma_f32_16x16x32_bf16 v[62:65], v[144:147], v[176:179], v[62:65]
	v_mfma_f32_16x16x32_bf16 v[58:61], v[152:155], v[176:179], v[58:61]
	v_mfma_f32_16x16x32_bf16 v[54:57], v[144:147], v[192:195], v[54:57]
	v_mfma_f32_16x16x32_bf16 v[50:53], v[152:155], v[192:195], v[50:53]
	v_mfma_f32_16x16x32_bf16 v[38:41], v[144:147], v[200:203], v[38:41]
	v_mfma_f32_16x16x32_bf16 v[34:37], v[152:155], v[200:203], v[34:37]
	v_mfma_f32_16x16x32_bf16 v[22:25], v[144:147], v[208:211], v[22:25]
	v_mfma_f32_16x16x32_bf16 v[18:21], v[152:155], v[208:211], v[18:21]
	v_mfma_f32_16x16x32_bf16 v[46:49], v[156:159], v[172:175], v[46:49]
	v_mfma_f32_16x16x32_bf16 v[42:45], v[164:167], v[172:175], v[42:45]
	v_mfma_f32_16x16x32_bf16 v[30:33], v[156:159], v[188:191], v[30:33]
	v_mfma_f32_16x16x32_bf16 v[26:29], v[164:167], v[188:191], v[26:29]
	v_mfma_f32_16x16x32_bf16 v[14:17], v[156:159], v[196:199], v[14:17]
	v_mfma_f32_16x16x32_bf16 v[10:13], v[164:167], v[196:199], v[10:13]
	v_mfma_f32_16x16x32_bf16 v[6:9], v[156:159], v[204:207], v[6:9]
	v_mfma_f32_16x16x32_bf16 v[2:5], v[164:167], v[204:207], v[2:5]
	v_mfma_f32_16x16x32_bf16 v[46:49], v[160:163], v[176:179], v[46:49]
	v_mfma_f32_16x16x32_bf16 v[42:45], v[168:171], v[176:179], v[42:45]
	v_mfma_f32_16x16x32_bf16 v[30:33], v[160:163], v[192:195], v[30:33]
	v_mfma_f32_16x16x32_bf16 v[26:29], v[168:171], v[192:195], v[26:29]
	v_mfma_f32_16x16x32_bf16 v[14:17], v[160:163], v[200:203], v[14:17]
	v_mfma_f32_16x16x32_bf16 v[10:13], v[168:171], v[200:203], v[10:13]
	v_mfma_f32_16x16x32_bf16 v[6:9], v[160:163], v[208:211], v[6:9]
	v_mfma_f32_16x16x32_bf16 v[2:5], v[168:171], v[208:211], v[2:5]
	s_setprio 0
	s_barrier
	s_movk_i32 s14, 0x100
	s_andn2_b64 vcc, exec, s[26:27]
	s_mov_b64 s[28:29], -1
	s_mov_b64 s[26:27], 0
	s_cbranch_vccz .LBB0_2155
	v_readlane_b32 s28, v255, 28
	s_and_b64 vcc, exec, s[8:9]
	v_readlane_b32 s29, v255, 29
	s_cbranch_vccz .LBB0_2158
	s_barrier

; #define PG8_STAGE(bufoff, gbase, voff) do { _Pragma("unroll") for (int _i = 0; _i < 2; ++_i) \
;         __builtin_amdgcn_global_load_lds((const unsigned*)((const char*)(gbase) + (voff)[_i]), (LAS unsigned*)(lds + (bufoff) + ldsw + _i * 8192), 16, 0, 0); } while (0)
; #define PG8_LDA(dst, b, h) do { _Pragma("unroll") for (int m = 0; m < 4; ++m) _Pragma("unroll") for (int k = 0; k < 2; ++k) dst[m][k] = *(const LAS bf16x8*)(lds + PG8_SA(b, h) + aoff + m * 2048 + k * 1024); } while (0)
; #define PG8_LDB(dst, b, h) do { _Pragma("unroll") for (int n = 0; n < 2; ++n) _Pragma("unroll") for (int k = 0; k < 2; ++k) dst[n][k] = *(const LAS bf16x8*)(lds + PG8_SB(b, h) + boff + n * 2048 + k * 1024); } while (0)
; #define PG8_MMA(ai, bj, At, Bt) do { __builtin_amdgcn_s_setprio(1); _Pragma("unroll") for (int m = 0; m < 4; ++m) _Pragma("unroll") for (int n = 0; n < 2; ++n) _Pragma("unroll") for (int k = 0; k < 2; ++k) \
;         acc[ai][bj][m][n] = __builtin_amdgcn_mfma_f32_16x16x32_bf16(Bt[n][k], At[m][k], acc[ai][bj][m][n], 0, 0, 0); __builtin_amdgcn_s_setprio(0); } while (0)
; #define PG8_WAIT_V(n) asm volatile("s_waitcnt vmcnt(" #n ")" ::: "memory")
; #define PG8_BAR __builtin_amdgcn_s_barrier()
; template <class Epi>
; __device__ __forceinline__ void gemm_phase(LAS unsigned char* lds, const Gemm g, const StaticOrder& S, const Epi& E) {
;     ...
;         const bool has_next = S.next(ui + 1, nxt);
;         const char* nA = has_next ? PG8_UA(nxt) : cA; const char* nB = has_next ? PG8_UB(nxt) : cB;
;         for (int t = 0; t < nt; t += 2) {
;             const bool last = (t == nt - 2);
;             const char* a1 = cA + (size_t)(t + 1) * kstep;
;             const char* a2 = last ? nA : cA + (size_t)(t + 2) * kstep; const char* b2 = last ? nB : cB + (size_t)(t + 2) * kstep;
;             const char* a3 = a2 + kstep; const char* b3 = b2 + kstep;
;             PG8_LDB(B0, 0, 0); PG8_LDB(B1, 0, 1); PG8_SCHED; PG8_LDA(At, 0, 0); PG8_STAGE(PG8_SA(1, 1), a1 + hstepA, voffA);
;             PG8_WAIT_V(8); PG8_WAIT_L(0); PG8_BAR; PG8_MMA(0, 0, At, B0); PG8_MMA(0, 1, At, B1); PG8_BAR; PG8_SCHED;
;             PG8_LDA(At, 0, 1); PG8_STAGE(PG8_SB(0, 0), b2, voffB); PG8_STAGE(PG8_SB(0, 1), b2 + hstepB, voffB); PG8_STAGE(PG8_SA(0, 0), a2, voffA);
;             PG8_WAIT_V(8); PG8_WAIT_L(0); PG8_BAR; PG8_MMA(1, 0, At, B0); PG8_MMA(1, 1, At, B1); PG8_BAR; PG8_SCHED;
.LBB0_2233:
	s_add_u32 s14, s24, 0xffe00080
	s_addc_u32 s15, s25, -1
	s_add_i32 s52, 0, 0x10000
	s_cmpk_eq_i32 s41, 0x7c
	s_cselect_b32 s27, s1, s15
	s_cselect_b32 s26, s3, s14
	s_cselect_b32 s15, s9, s40
	s_cselect_b32 s14, s17, s19
	s_add_i32 s62, 0, 0x14000
	v_add_u32_e32 v142, s52, v1
	v_add_u32_e32 v167, s62, v1
	ds_read_b128 v[130:133], v142
	ds_read_b128 v[134:137], v142 offset:1024
	ds_read_b128 v[138:141], v142 offset:2048
	ds_read_b128 v[142:145], v142 offset:3072
	ds_read_b128 v[146:149], v167
	ds_read_b128 v[162:165], v167 offset:1024
	ds_read_b128 v[168:171], v167 offset:2048
	ds_read_b128 v[172:175], v167 offset:3072
	v_lshl_add_u64 v[184:185], s[24:25], 0, v[158:159]
	s_add_i32 m0, s31, 0xc000
	ds_read_b128 v[176:179], v166
	ds_read_b128 v[188:191], v166 offset:1024
	ds_read_b128 v[192:195], v166 offset:2048
	ds_read_b128 v[196:199], v166 offset:3072
	ds_read_b128 v[200:203], v166 offset:4096
	ds_read_b128 v[204:207], v166 offset:5120
	ds_read_b128 v[208:211], v166 offset:6144
	ds_read_b128 v[212:215], v166 offset:7168
	global_load_lds_dwordx4 v[184:185], off
	v_lshl_add_u64 v[184:185], s[24:25], 0, v[160:161]
	s_add_i32 m0, s31, 0xe000
	s_nop 0
	global_load_lds_dwordx4 v[184:185], off
	s_waitcnt vmcnt(8)
	s_waitcnt lgkmcnt(0)
	s_barrier
	s_setprio 1
	s_waitcnt lgkmcnt(0)
	v_mfma_f32_16x16x32_bf16 v[126:129], v[130:133], v[176:179], v[126:129]
	v_mfma_f32_16x16x32_bf16 v[122:125], v[138:141], v[176:179], v[122:125]
	v_mfma_f32_16x16x32_bf16 v[118:121], v[130:133], v[192:195], v[118:121]
	v_mfma_f32_16x16x32_bf16 v[114:117], v[138:141], v[192:195], v[114:117]
	v_mfma_f32_16x16x32_bf16 v[94:97], v[130:133], v[200:203], v[94:97]
	v_mfma_f32_16x16x32_bf16 v[90:93], v[138:141], v[200:203], v[90:93]
	v_mfma_f32_16x16x32_bf16 v[82:85], v[130:133], v[208:211], v[82:85]
	v_mfma_f32_16x16x32_bf16 v[74:77], v[138:141], v[208:211], v[74:77]
	v_mfma_f32_16x16x32_bf16 v[126:129], v[134:137], v[188:191], v[126:129]
	v_mfma_f32_16x16x32_bf16 v[122:125], v[142:145], v[188:191], v[122:125]
	v_mfma_f32_16x16x32_bf16 v[118:121], v[134:137], v[196:199], v[118:121]
	v_mfma_f32_16x16x32_bf16 v[114:117], v[142:145], v[196:199], v[114:117]
	v_mfma_f32_16x16x32_bf16 v[94:97], v[134:137], v[204:207], v[94:97]
	v_mfma_f32_16x16x32_bf16 v[90:93], v[142:145], v[204:207], v[90:93]
	v_mfma_f32_16x16x32_bf16 v[82:85], v[134:137], v[212:215], v[82:85]
	v_mfma_f32_16x16x32_bf16 v[74:77], v[142:145], v[212:215], v[74:77]
	v_mfma_f32_16x16x32_bf16 v[110:113], v[146:149], v[176:179], v[110:113]
	v_mfma_f32_16x16x32_bf16 v[106:109], v[168:171], v[176:179], v[106:109]
	v_mfma_f32_16x16x32_bf16 v[102:105], v[146:149], v[192:195], v[102:105]
	v_mfma_f32_16x16x32_bf16 v[98:101], v[168:171], v[192:195], v[98:101]
	v_mfma_f32_16x16x32_bf16 v[86:89], v[146:149], v[200:203], v[86:89]
	v_mfma_f32_16x16x32_bf16 v[78:81], v[168:171], v[200:203], v[78:81]
	v_mfma_f32_16x16x32_bf16 v[70:73], v[146:149], v[208:211], v[70:73]
	v_mfma_f32_16x16x32_bf16 v[66:69], v[168:171], v[208:211], v[66:69]
	v_mfma_f32_16x16x32_bf16 v[110:113], v[162:165], v[188:191], v[110:113]
	v_mfma_f32_16x16x32_bf16 v[106:109], v[172:175], v[188:191], v[106:109]
	v_mfma_f32_16x16x32_bf16 v[102:105], v[162:165], v[196:199], v[102:105]
	v_mfma_f32_16x16x32_bf16 v[98:101], v[172:175], v[196:199], v[98:101]
	v_mfma_f32_16x16x32_bf16 v[86:89], v[162:165], v[204:207], v[86:89]
	v_mfma_f32_16x16x32_bf16 v[78:81], v[172:175], v[204:207], v[78:81]
	v_mfma_f32_16x16x32_bf16 v[70:73], v[162:165], v[212:215], v[70:73]
	v_mfma_f32_16x16x32_bf16 v[66:69], v[172:175], v[212:215], v[66:69]
	s_setprio 0
	s_barrier
	s_add_i32 s52, s52, s30
	v_lshl_add_u64 v[184:185], s[14:15], 0, v[152:153]
	s_mov_b32 m0, s52
	ds_read_b128 v[176:179], v166 offset:16384
	ds_read_b128 v[188:191], v166 offset:17408
	ds_read_b128 v[192:195], v166 offset:18432
	ds_read_b128 v[196:199], v166 offset:19456
	ds_read_b128 v[200:203], v166 offset:20480
	ds_read_b128 v[204:207], v166 offset:21504
	ds_read_b128 v[208:211], v166 offset:22528
	ds_read_b128 v[212:215], v166 offset:23552
	global_load_lds_dwordx4 v[184:185], off
	s_add_i32 m0, s52, 0x2000
	s_add_u32 s52, s14, 0x200000
	v_lshl_add_u64 v[216:217], s[14:15], 0, v[156:157]
	s_addc_u32 s53, s15, 0
	s_add_i32 s62, s62, s30
	global_load_lds_dwordx4 v[216:217], off
	v_lshl_add_u64 v[218:219], s[52:53], 0, v[152:153]
	s_mov_b32 m0, s62
	v_lshl_add_u64 v[220:221], s[26:27], 0, v[154:155]
	global_load_lds_dwordx4 v[218:219], off
	v_lshl_add_u64 v[218:219], s[52:53], 0, v[156:157]
	s_add_i32 m0, s62, 0x2000
	s_nop 0
	global_load_lds_dwordx4 v[218:219], off
	v_lshl_add_u64 v[218:219], s[26:27], 0, v[150:151]
	s_mov_b32 m0, s31
	s_nop 0
	global_load_lds_dwordx4 v[218:219], off
	s_mov_b32 m0, s34
	s_nop 0
	global_load_lds_dwordx4 v[220:221], off
	s_waitcnt vmcnt(8)
	s_waitcnt lgkmcnt(0)
	s_barrier
; #define PG8_STAGE(bufoff, gbase, voff) do { _Pragma("unroll") for (int _i = 0; _i < 2; ++_i) \
;         __builtin_amdgcn_global_load_lds((const unsigned*)((const char*)(gbase) + (voff)[_i]), (LAS unsigned*)(lds + (bufoff) + ldsw + _i * 8192), 16, 0, 0); } while (0)
; #define PG8_LDA(dst, b, h) do { _Pragma("unroll") for (int m = 0; m < 4; ++m) _Pragma("unroll") for (int k = 0; k < 2; ++k) dst[m][k] = *(const LAS bf16x8*)(lds + PG8_SA(b, h) + aoff + m * 2048 + k * 1024); } while (0)
; #define PG8_LDB(dst, b, h) do { _Pragma("unroll") for (int n = 0; n < 2; ++n) _Pragma("unroll") for (int k = 0; k < 2; ++k) dst[n][k] = *(const LAS bf16x8*)(lds + PG8_SB(b, h) + boff + n * 2048 + k * 1024); } while (0)
; #define PG8_MMA(ai, bj, At, Bt) do { __builtin_amdgcn_s_setprio(1); _Pragma("unroll") for (int m = 0; m < 4; ++m) _Pragma("unroll") for (int n = 0; n < 2; ++n) _Pragma("unroll") for (int k = 0; k < 2; ++k) \
;         acc[ai][bj][m][n] = __builtin_amdgcn_mfma_f32_16x16x32_bf16(Bt[n][k], At[m][k], acc[ai][bj][m][n], 0, 0, 0); __builtin_amdgcn_s_setprio(0); } while (0)
; #define PG8_WAIT_V(n) asm volatile("s_waitcnt vmcnt(" #n ")" ::: "memory")
; #define PG8_WAIT_L(n) asm volatile("s_waitcnt lgkmcnt(" #n ")" ::: "memory")
; #define PG8_BAR __builtin_amdgcn_s_barrier()
; #define PG8_SCHED __builtin_amdgcn_sched_barrier(0)
; template <class Epi>
; __device__ __forceinline__ void gemm_phase(LAS unsigned char* lds, const Gemm g, const StaticOrder& S, const Epi& E) {
;     ...
;             PG8_LDA(At, 0, 1); PG8_STAGE(PG8_SB(0, 0), b2, voffB); PG8_STAGE(PG8_SB(0, 1), b2 + hstepB, voffB); PG8_STAGE(PG8_SA(0, 0), a2, voffA);
;             PG8_WAIT_V(8); PG8_WAIT_L(0); PG8_BAR; PG8_MMA(1, 0, At, B0); PG8_MMA(1, 1, At, B1); PG8_BAR; PG8_SCHED;
;             PG8_LDB(B0, 1, 0); PG8_LDB(B1, 1, 1); PG8_SCHED; PG8_LDA(At, 1, 0); PG8_STAGE(PG8_SA(0, 1), a2 + hstepA, voffA);
;             PG8_WAIT_V(8); PG8_WAIT_L(0); PG8_BAR; PG8_MMA(0, 0, At, B0); PG8_MMA(0, 1, At, B1); PG8_BAR; PG8_SCHED;
;             PG8_LDA(At, 1, 1); PG8_STAGE(PG8_SB(1, 0), b3, voffB); PG8_STAGE(PG8_SB(1, 1), b3 + hstepB, voffB); PG8_STAGE(PG8_SA(1, 0), a3, voffA);
	s_setprio 1
	s_waitcnt lgkmcnt(0)
	v_mfma_f32_16x16x32_bf16 v[62:65], v[130:133], v[176:179], v[62:65]
	v_mfma_f32_16x16x32_bf16 v[58:61], v[138:141], v[176:179], v[58:61]
	v_mfma_f32_16x16x32_bf16 v[50:53], v[130:133], v[192:195], v[50:53]
	v_mfma_f32_16x16x32_bf16 v[42:45], v[138:141], v[192:195], v[42:45]
	v_mfma_f32_16x16x32_bf16 v[30:33], v[130:133], v[200:203], v[30:33]
	v_mfma_f32_16x16x32_bf16 v[26:29], v[138:141], v[200:203], v[26:29]
	v_mfma_f32_16x16x32_bf16 v[18:21], v[130:133], v[208:211], v[18:21]
	v_mfma_f32_16x16x32_bf16 v[10:13], v[138:141], v[208:211], v[10:13]
	v_mfma_f32_16x16x32_bf16 v[62:65], v[134:137], v[188:191], v[62:65]
	v_mfma_f32_16x16x32_bf16 v[58:61], v[142:145], v[188:191], v[58:61]
	v_mfma_f32_16x16x32_bf16 v[50:53], v[134:137], v[196:199], v[50:53]
	v_mfma_f32_16x16x32_bf16 v[42:45], v[142:145], v[196:199], v[42:45]
	v_mfma_f32_16x16x32_bf16 v[30:33], v[134:137], v[204:207], v[30:33]
	v_mfma_f32_16x16x32_bf16 v[26:29], v[142:145], v[204:207], v[26:29]
	v_mfma_f32_16x16x32_bf16 v[18:21], v[134:137], v[212:215], v[18:21]
	v_mfma_f32_16x16x32_bf16 v[10:13], v[142:145], v[212:215], v[10:13]
	v_mfma_f32_16x16x32_bf16 v[54:57], v[146:149], v[176:179], v[54:57]
	v_mfma_f32_16x16x32_bf16 v[46:49], v[168:171], v[176:179], v[46:49]
	v_mfma_f32_16x16x32_bf16 v[38:41], v[146:149], v[192:195], v[38:41]
	v_mfma_f32_16x16x32_bf16 v[34:37], v[168:171], v[192:195], v[34:37]
	v_mfma_f32_16x16x32_bf16 v[22:25], v[146:149], v[200:203], v[22:25]
	v_mfma_f32_16x16x32_bf16 v[14:17], v[168:171], v[200:203], v[14:17]
	v_mfma_f32_16x16x32_bf16 v[6:9], v[146:149], v[208:211], v[6:9]
	v_mfma_f32_16x16x32_bf16 v[2:5], v[168:171], v[208:211], v[2:5]
	v_mfma_f32_16x16x32_bf16 v[54:57], v[162:165], v[188:191], v[54:57]
	v_mfma_f32_16x16x32_bf16 v[46:49], v[172:175], v[188:191], v[46:49]
	v_mfma_f32_16x16x32_bf16 v[38:41], v[162:165], v[196:199], v[38:41]
	v_mfma_f32_16x16x32_bf16 v[34:37], v[172:175], v[196:199], v[34:37]
	v_mfma_f32_16x16x32_bf16 v[22:25], v[162:165], v[204:207], v[22:25]
	v_mfma_f32_16x16x32_bf16 v[14:17], v[172:175], v[204:207], v[14:17]
	v_mfma_f32_16x16x32_bf16 v[6:9], v[162:165], v[212:215], v[6:9]
	v_mfma_f32_16x16x32_bf16 v[2:5], v[172:175], v[212:215], v[2:5]
	s_setprio 0
	s_barrier
	s_add_i32 s52, 0, 0x18000
	s_add_i32 s53, 0, 0x1c000
	v_add_u32_e32 v142, s52, v1
	v_add_u32_e32 v167, s53, v1
	ds_read_b128 v[130:133], v142
	ds_read_b128 v[134:137], v142 offset:1024
	ds_read_b128 v[138:141], v142 offset:2048
	ds_read_b128 v[142:145], v142 offset:3072
	ds_read_b128 v[146:149], v167
	ds_read_b128 v[162:165], v167 offset:1024
	ds_read_b128 v[168:171], v167 offset:2048
	ds_read_b128 v[172:175], v167 offset:3072
	s_add_u32 s26, s26, 0x200000
	s_addc_u32 s27, s27, 0
	s_mov_b32 m0, s35
	v_lshl_add_u64 v[222:223], s[26:27], 0, v[150:151]
	ds_read_b128 v[176:179], v166 offset:32768
	ds_read_b128 v[188:191], v166 offset:33792
	ds_read_b128 v[192:195], v166 offset:34816
	ds_read_b128 v[196:199], v166 offset:35840
	ds_read_b128 v[200:203], v166 offset:36864
	ds_read_b128 v[204:207], v166 offset:37888
	ds_read_b128 v[208:211], v166 offset:38912
	ds_read_b128 v[212:215], v166 offset:39936
	global_load_lds_dwordx4 v[222:223], off
	v_lshl_add_u64 v[222:223], s[26:27], 0, v[154:155]
	s_mov_b32 m0, s42
	s_nop 0
	global_load_lds_dwordx4 v[222:223], off
	s_waitcnt vmcnt(8)
	s_waitcnt lgkmcnt(0)
	s_barrier
	s_setprio 1
	s_waitcnt lgkmcnt(0)
	v_mfma_f32_16x16x32_bf16 v[126:129], v[130:133], v[176:179], v[126:129]
	v_mfma_f32_16x16x32_bf16 v[122:125], v[138:141], v[176:179], v[122:125]
	v_mfma_f32_16x16x32_bf16 v[118:121], v[130:133], v[192:195], v[118:121]
	v_mfma_f32_16x16x32_bf16 v[114:117], v[138:141], v[192:195], v[114:117]
	v_mfma_f32_16x16x32_bf16 v[94:97], v[130:133], v[200:203], v[94:97]
	v_mfma_f32_16x16x32_bf16 v[90:93], v[138:141], v[200:203], v[90:93]
	v_mfma_f32_16x16x32_bf16 v[82:85], v[130:133], v[208:211], v[82:85]
	v_mfma_f32_16x16x32_bf16 v[74:77], v[138:141], v[208:211], v[74:77]
	v_mfma_f32_16x16x32_bf16 v[126:129], v[134:137], v[188:191], v[126:129]
	v_mfma_f32_16x16x32_bf16 v[122:125], v[142:145], v[188:191], v[122:125]
	v_mfma_f32_16x16x32_bf16 v[118:121], v[134:137], v[196:199], v[118:121]
	v_mfma_f32_16x16x32_bf16 v[114:117], v[142:145], v[196:199], v[114:117]
	v_mfma_f32_16x16x32_bf16 v[94:97], v[134:137], v[204:207], v[94:97]
	v_mfma_f32_16x16x32_bf16 v[90:93], v[142:145], v[204:207], v[90:93]
	v_mfma_f32_16x16x32_bf16 v[82:85], v[134:137], v[212:215], v[82:85]
	v_mfma_f32_16x16x32_bf16 v[74:77], v[142:145], v[212:215], v[74:77]
	v_mfma_f32_16x16x32_bf16 v[110:113], v[146:149], v[176:179], v[110:113]
	v_mfma_f32_16x16x32_bf16 v[106:109], v[168:171], v[176:179], v[106:109]
	v_mfma_f32_16x16x32_bf16 v[102:105], v[146:149], v[192:195], v[102:105]
	v_mfma_f32_16x16x32_bf16 v[98:101], v[168:171], v[192:195], v[98:101]
	v_mfma_f32_16x16x32_bf16 v[86:89], v[146:149], v[200:203], v[86:89]
	v_mfma_f32_16x16x32_bf16 v[78:81], v[168:171], v[200:203], v[78:81]
	v_mfma_f32_16x16x32_bf16 v[70:73], v[146:149], v[208:211], v[70:73]
	v_mfma_f32_16x16x32_bf16 v[66:69], v[168:171], v[208:211], v[66:69]
	v_mfma_f32_16x16x32_bf16 v[110:113], v[162:165], v[188:191], v[110:113]
	v_mfma_f32_16x16x32_bf16 v[106:109], v[172:175], v[188:191], v[106:109]
	v_mfma_f32_16x16x32_bf16 v[102:105], v[162:165], v[196:199], v[102:105]
	v_mfma_f32_16x16x32_bf16 v[98:101], v[172:175], v[196:199], v[98:101]
	v_mfma_f32_16x16x32_bf16 v[86:89], v[162:165], v[204:207], v[86:89]
	v_mfma_f32_16x16x32_bf16 v[78:81], v[172:175], v[204:207], v[78:81]
	v_mfma_f32_16x16x32_bf16 v[70:73], v[162:165], v[212:215], v[70:73]
	v_mfma_f32_16x16x32_bf16 v[66:69], v[172:175], v[212:215], v[66:69]
	s_setprio 0
	s_barrier
; #define PG8_STAGE(bufoff, gbase, voff) do { _Pragma("unroll") for (int _i = 0; _i < 2; ++_i) \
;         __builtin_amdgcn_global_load_lds((const unsigned*)((const char*)(gbase) + (voff)[_i]), (LAS unsigned*)(lds + (bufoff) + ldsw + _i * 8192), 16, 0, 0); } while (0)
; #define PG8_LDA(dst, b, h) do { _Pragma("unroll") for (int m = 0; m < 4; ++m) _Pragma("unroll") for (int k = 0; k < 2; ++k) dst[m][k] = *(const LAS bf16x8*)(lds + PG8_SA(b, h) + aoff + m * 2048 + k * 1024); } while (0)
; #define PG8_MMA(ai, bj, At, Bt) do { __builtin_amdgcn_s_setprio(1); _Pragma("unroll") for (int m = 0; m < 4; ++m) _Pragma("unroll") for (int n = 0; n < 2; ++n) _Pragma("unroll") for (int k = 0; k < 2; ++k) \
;         acc[ai][bj][m][n] = __builtin_amdgcn_mfma_f32_16x16x32_bf16(Bt[n][k], At[m][k], acc[ai][bj][m][n], 0, 0, 0); __builtin_amdgcn_s_setprio(0); } while (0)
; #define PG8_WAIT_V(n) asm volatile("s_waitcnt vmcnt(" #n ")" ::: "memory")
; #define PG8_WAIT_L(n) asm volatile("s_waitcnt lgkmcnt(" #n ")" ::: "memory")
; #define PG8_BAR __builtin_amdgcn_s_barrier()
; #define PG8_SCHED __builtin_amdgcn_sched_barrier(0)
; template <class Epi>
; __device__ __forceinline__ void gemm_phase(LAS unsigned char* lds, const Gemm g, const StaticOrder& S, const Epi& E) {
;     ...
;             PG8_LDA(At, 1, 1); PG8_STAGE(PG8_SB(1, 0), b3, voffB); PG8_STAGE(PG8_SB(1, 1), b3 + hstepB, voffB); PG8_STAGE(PG8_SA(1, 0), a3, voffA);
;             PG8_WAIT_V(8); PG8_WAIT_L(0); PG8_BAR; PG8_MMA(1, 0, At, B0); PG8_MMA(1, 1, At, B1); PG8_BAR; PG8_SCHED;
;         }
	s_add_i32 s26, s52, s30
	v_lshl_add_u64 v[184:185], v[184:185], 0, s[84:85]
	s_mov_b32 m0, s26
	ds_read_b128 v[176:179], v166 offset:49152
	ds_read_b128 v[188:191], v166 offset:50176
	ds_read_b128 v[192:195], v166 offset:51200
	ds_read_b128 v[196:199], v166 offset:52224
	ds_read_b128 v[200:203], v166 offset:53248
	ds_read_b128 v[204:207], v166 offset:54272
	ds_read_b128 v[208:211], v166 offset:55296
	ds_read_b128 v[212:215], v166 offset:56320
	global_load_lds_dwordx4 v[184:185], off
	s_add_i32 m0, s26, 0x2000
	s_add_u32 s14, s14, 0x200080
	v_lshl_add_u64 v[184:185], v[216:217], 0, s[84:85]
	s_addc_u32 s15, s15, 0
	s_add_i32 s26, s53, s30
	global_load_lds_dwordx4 v[184:185], off
	v_lshl_add_u64 v[184:185], s[14:15], 0, v[152:153]
	s_mov_b32 m0, s26
	s_nop 0
	global_load_lds_dwordx4 v[184:185], off
	v_lshl_add_u64 v[184:185], s[14:15], 0, v[156:157]
	s_add_i32 m0, s26, 0x2000
	s_nop 0
	global_load_lds_dwordx4 v[184:185], off
	v_lshl_add_u64 v[184:185], v[218:219], 0, s[84:85]
	s_mov_b32 m0, s68
	s_nop 0
	global_load_lds_dwordx4 v[184:185], off
	v_lshl_add_u64 v[184:185], v[220:221], 0, s[84:85]
	s_mov_b32 m0, s69
	s_nop 0
	global_load_lds_dwordx4 v[184:185], off
	s_waitcnt vmcnt(8)
	s_waitcnt lgkmcnt(0)
	s_barrier
	s_setprio 1
	s_waitcnt lgkmcnt(0)
	v_mfma_f32_16x16x32_bf16 v[62:65], v[130:133], v[176:179], v[62:65]
	v_mfma_f32_16x16x32_bf16 v[58:61], v[138:141], v[176:179], v[58:61]
	v_mfma_f32_16x16x32_bf16 v[50:53], v[130:133], v[192:195], v[50:53]
	v_mfma_f32_16x16x32_bf16 v[42:45], v[138:141], v[192:195], v[42:45]
	v_mfma_f32_16x16x32_bf16 v[30:33], v[130:133], v[200:203], v[30:33]
	v_mfma_f32_16x16x32_bf16 v[26:29], v[138:141], v[200:203], v[26:29]
	v_mfma_f32_16x16x32_bf16 v[18:21], v[130:133], v[208:211], v[18:21]
	v_mfma_f32_16x16x32_bf16 v[10:13], v[138:141], v[208:211], v[10:13]
	v_mfma_f32_16x16x32_bf16 v[62:65], v[134:137], v[188:191], v[62:65]
	v_mfma_f32_16x16x32_bf16 v[58:61], v[142:145], v[188:191], v[58:61]
	v_mfma_f32_16x16x32_bf16 v[50:53], v[134:137], v[196:199], v[50:53]
	v_mfma_f32_16x16x32_bf16 v[42:45], v[142:145], v[196:199], v[42:45]
	v_mfma_f32_16x16x32_bf16 v[30:33], v[134:137], v[204:207], v[30:33]
	v_mfma_f32_16x16x32_bf16 v[26:29], v[142:145], v[204:207], v[26:29]
	v_mfma_f32_16x16x32_bf16 v[18:21], v[134:137], v[212:215], v[18:21]
	v_mfma_f32_16x16x32_bf16 v[10:13], v[142:145], v[212:215], v[10:13]
	v_mfma_f32_16x16x32_bf16 v[54:57], v[146:149], v[176:179], v[54:57]
	v_mfma_f32_16x16x32_bf16 v[46:49], v[168:171], v[176:179], v[46:49]
	v_mfma_f32_16x16x32_bf16 v[38:41], v[146:149], v[192:195], v[38:41]
	v_mfma_f32_16x16x32_bf16 v[34:37], v[168:171], v[192:195], v[34:37]
	v_mfma_f32_16x16x32_bf16 v[22:25], v[146:149], v[200:203], v[22:25]
	v_mfma_f32_16x16x32_bf16 v[14:17], v[168:171], v[200:203], v[14:17]
	v_mfma_f32_16x16x32_bf16 v[6:9], v[146:149], v[208:211], v[6:9]
	v_mfma_f32_16x16x32_bf16 v[2:5], v[168:171], v[208:211], v[2:5]
	v_mfma_f32_16x16x32_bf16 v[54:57], v[162:165], v[188:191], v[54:57]
	v_mfma_f32_16x16x32_bf16 v[46:49], v[172:175], v[188:191], v[46:49]
	v_mfma_f32_16x16x32_bf16 v[38:41], v[162:165], v[196:199], v[38:41]
	v_mfma_f32_16x16x32_bf16 v[34:37], v[172:175], v[196:199], v[34:37]
	v_mfma_f32_16x16x32_bf16 v[22:25], v[162:165], v[204:207], v[22:25]
	v_mfma_f32_16x16x32_bf16 v[14:17], v[172:175], v[204:207], v[14:17]
	v_mfma_f32_16x16x32_bf16 v[6:9], v[162:165], v[212:215], v[6:9]
	v_mfma_f32_16x16x32_bf16 v[2:5], v[172:175], v[212:215], v[2:5]
	s_setprio 0
	s_barrier
	s_add_i32 s41, s41, 2
	s_add_u32 s24, s24, 0x100
	s_addc_u32 s25, s25, 0
	s_add_u32 s19, s19, 0x100
	s_addc_u32 s40, s40, 0
	s_cmpk_gt_u32 s41, 0x7d
	s_cbranch_scc0 .LBB0_2233
	s_cmp_ge_u32 s74, 16
	s_cbranch_scc1 .Lwpf_e
	s_lshl_b32 s100, s74, 9
	v_add_u32_e32 v130, s100, v246
	v_lshrrev_b32_e32 v131, 2, v130
	v_and_b32_e32 v130, 3, v130
	v_lshlrev_b32_e32 v130, 7, v130
	v_lshl_add_u32 v130, v131, 12, v130
	s_add_u32 s100, s88, 0x4000000
	s_addc_u32 s101, s89, 0
	s_mov_b32 m0, 0x21000
	s_nop 0
	global_load_lds_dword v130, s[100:101]

; #define PG8_STAGE(bufoff, gbase, voff) do { _Pragma("unroll") for (int _i = 0; _i < 2; ++_i) \
;         __builtin_amdgcn_global_load_lds((const unsigned*)((const char*)(gbase) + (voff)[_i]), (LAS unsigned*)(lds + (bufoff) + ldsw + _i * 8192), 16, 0, 0); } while (0)
; #define PG8_LDA(dst, b, h) do { _Pragma("unroll") for (int m = 0; m < 4; ++m) _Pragma("unroll") for (int k = 0; k < 2; ++k) dst[m][k] = *(const LAS bf16x8*)(lds + PG8_SA(b, h) + aoff + m * 2048 + k * 1024); } while (0)
; #define PG8_LDB(dst, b, h) do { _Pragma("unroll") for (int n = 0; n < 2; ++n) _Pragma("unroll") for (int k = 0; k < 2; ++k) dst[n][k] = *(const LAS bf16x8*)(lds + PG8_SB(b, h) + boff + n * 2048 + k * 1024); } while (0)
; #define PG8_MMA(ai, bj, At, Bt) do { __builtin_amdgcn_s_setprio(1); _Pragma("unroll") for (int m = 0; m < 4; ++m) _Pragma("unroll") for (int n = 0; n < 2; ++n) _Pragma("unroll") for (int k = 0; k < 2; ++k) \
;         acc[ai][bj][m][n] = __builtin_amdgcn_mfma_f32_16x16x32_bf16(Bt[n][k], At[m][k], acc[ai][bj][m][n], 0, 0, 0); __builtin_amdgcn_s_setprio(0); } while (0)
; #define PG8_WAIT_V(n) asm volatile("s_waitcnt vmcnt(" #n ")" ::: "memory")
; #define PG8_BAR __builtin_amdgcn_s_barrier()
; template <class Epi>
; __device__ __forceinline__ void gemm_phase(LAS unsigned char* lds, const Gemm g, const StaticOrder& S, const Epi& E) {
;     ...
;         const bool has_next = S.next(ui + 1, nxt);
;         const char* nA = has_next ? PG8_UA(nxt) : cA; const char* nB = has_next ? PG8_UB(nxt) : cB;
;         for (int t = 0; t < nt; t += 2) {
;             const bool last = (t == nt - 2);
;             const char* a1 = cA + (size_t)(t + 1) * kstep;
;             const char* a2 = last ? nA : cA + (size_t)(t + 2) * kstep; const char* b2 = last ? nB : cB + (size_t)(t + 2) * kstep;
;             const char* a3 = a2 + kstep; const char* b3 = b2 + kstep;
;             PG8_LDB(B0, 0, 0); PG8_LDB(B1, 0, 1); PG8_SCHED; PG8_LDA(At, 0, 0); PG8_STAGE(PG8_SA(1, 1), a1 + hstepA, voffA);
;             PG8_WAIT_V(8); PG8_WAIT_L(0); PG8_BAR; PG8_MMA(0, 0, At, B0); PG8_MMA(0, 1, At, B1); PG8_BAR; PG8_SCHED;
;             PG8_LDA(At, 0, 1); PG8_STAGE(PG8_SB(0, 0), b2, voffB); PG8_STAGE(PG8_SB(0, 1), b2 + hstepB, voffB); PG8_STAGE(PG8_SA(0, 0), a2, voffA);
;             PG8_WAIT_V(8); PG8_WAIT_L(0); PG8_BAR; PG8_MMA(1, 0, At, B0); PG8_MMA(1, 1, At, B1); PG8_BAR; PG8_SCHED;
.LBB0_2332:
	s_add_u32 s14, s24, 0xfff80080
	s_addc_u32 s15, s25, -1
	s_add_i32 s41, 0, 0x10000
	s_cmp_eq_u32 s40, 28
	s_cselect_b32 s27, s1, s15
	s_cselect_b32 s26, s3, s14
	s_cselect_b32 s15, s9, s33
	s_cselect_b32 s14, s17, s19
	s_add_i32 s62, 0, 0x14000
	v_add_u32_e32 v142, s41, v1
	v_add_u32_e32 v170, s62, v1
	ds_read_b128 v[130:133], v142
	ds_read_b128 v[134:137], v142 offset:1024
	ds_read_b128 v[138:141], v142 offset:2048
	ds_read_b128 v[142:145], v142 offset:3072
	ds_read_b128 v[146:149], v170
	ds_read_b128 v[150:153], v170 offset:1024
	ds_read_b128 v[166:169], v170 offset:2048
	ds_read_b128 v[170:173], v170 offset:3072
	v_lshl_add_u64 v[178:179], s[24:25], 0, v[162:163]
	s_add_i32 m0, s35, 0xc000
	ds_read_b128 v[174:177], v181
	ds_read_b128 v[188:191], v181 offset:1024
	ds_read_b128 v[192:195], v181 offset:2048
	ds_read_b128 v[196:199], v181 offset:3072
	ds_read_b128 v[200:203], v181 offset:4096
	ds_read_b128 v[204:207], v181 offset:5120
	ds_read_b128 v[208:211], v181 offset:6144
	ds_read_b128 v[212:215], v181 offset:7168
	global_load_lds_dwordx4 v[178:179], off
	v_lshl_add_u64 v[178:179], s[24:25], 0, v[164:165]
	s_add_i32 m0, s35, 0xe000
	s_nop 0
	global_load_lds_dwordx4 v[178:179], off
	s_waitcnt vmcnt(8)
	s_waitcnt lgkmcnt(0)
	s_barrier
	s_setprio 1
	s_waitcnt lgkmcnt(0)
	v_mfma_f32_16x16x32_bf16 v[126:129], v[130:133], v[174:177], v[126:129]
	v_mfma_f32_16x16x32_bf16 v[122:125], v[138:141], v[174:177], v[122:125]
	v_mfma_f32_16x16x32_bf16 v[118:121], v[130:133], v[192:195], v[118:121]
	v_mfma_f32_16x16x32_bf16 v[114:117], v[138:141], v[192:195], v[114:117]
	v_mfma_f32_16x16x32_bf16 v[102:105], v[130:133], v[200:203], v[102:105]
	v_mfma_f32_16x16x32_bf16 v[98:101], v[138:141], v[200:203], v[98:101]
	v_mfma_f32_16x16x32_bf16 v[86:89], v[130:133], v[208:211], v[86:89]
	v_mfma_f32_16x16x32_bf16 v[82:85], v[138:141], v[208:211], v[82:85]
	v_mfma_f32_16x16x32_bf16 v[126:129], v[134:137], v[188:191], v[126:129]
	v_mfma_f32_16x16x32_bf16 v[122:125], v[142:145], v[188:191], v[122:125]
	v_mfma_f32_16x16x32_bf16 v[118:121], v[134:137], v[196:199], v[118:121]
	v_mfma_f32_16x16x32_bf16 v[114:117], v[142:145], v[196:199], v[114:117]
	v_mfma_f32_16x16x32_bf16 v[102:105], v[134:137], v[204:207], v[102:105]
	v_mfma_f32_16x16x32_bf16 v[98:101], v[142:145], v[204:207], v[98:101]
	v_mfma_f32_16x16x32_bf16 v[86:89], v[134:137], v[212:215], v[86:89]
	v_mfma_f32_16x16x32_bf16 v[82:85], v[142:145], v[212:215], v[82:85]
	v_mfma_f32_16x16x32_bf16 v[110:113], v[146:149], v[174:177], v[110:113]
	v_mfma_f32_16x16x32_bf16 v[106:109], v[166:169], v[174:177], v[106:109]
	v_mfma_f32_16x16x32_bf16 v[94:97], v[146:149], v[192:195], v[94:97]
	v_mfma_f32_16x16x32_bf16 v[90:93], v[166:169], v[192:195], v[90:93]
	v_mfma_f32_16x16x32_bf16 v[78:81], v[146:149], v[200:203], v[78:81]
	v_mfma_f32_16x16x32_bf16 v[74:77], v[166:169], v[200:203], v[74:77]
	v_mfma_f32_16x16x32_bf16 v[70:73], v[146:149], v[208:211], v[70:73]
	v_mfma_f32_16x16x32_bf16 v[66:69], v[166:169], v[208:211], v[66:69]
	v_mfma_f32_16x16x32_bf16 v[110:113], v[150:153], v[188:191], v[110:113]
	v_mfma_f32_16x16x32_bf16 v[106:109], v[170:173], v[188:191], v[106:109]
	v_mfma_f32_16x16x32_bf16 v[94:97], v[150:153], v[196:199], v[94:97]
	v_mfma_f32_16x16x32_bf16 v[90:93], v[170:173], v[196:199], v[90:93]
	v_mfma_f32_16x16x32_bf16 v[78:81], v[150:153], v[204:207], v[78:81]
	v_mfma_f32_16x16x32_bf16 v[74:77], v[170:173], v[204:207], v[74:77]
	v_mfma_f32_16x16x32_bf16 v[70:73], v[150:153], v[212:215], v[70:73]
	v_mfma_f32_16x16x32_bf16 v[66:69], v[170:173], v[212:215], v[66:69]
	s_setprio 0
	s_barrier
	s_add_i32 s41, s41, s34
	v_lshl_add_u64 v[178:179], s[14:15], 0, v[156:157]
	s_mov_b32 m0, s41
	ds_read_b128 v[174:177], v181 offset:16384
	ds_read_b128 v[188:191], v181 offset:17408
	ds_read_b128 v[192:195], v181 offset:18432
	ds_read_b128 v[196:199], v181 offset:19456
	ds_read_b128 v[200:203], v181 offset:20480
	ds_read_b128 v[204:207], v181 offset:21504
	ds_read_b128 v[208:211], v181 offset:22528
	ds_read_b128 v[212:215], v181 offset:23552
	global_load_lds_dwordx4 v[178:179], off
	s_add_i32 m0, s41, 0x2000
	s_add_u32 s52, s14, 0x80000
	v_lshl_add_u64 v[184:185], s[14:15], 0, v[160:161]
	s_addc_u32 s53, s15, 0
	s_add_i32 s41, s62, s34
	global_load_lds_dwordx4 v[184:185], off
	v_lshl_add_u64 v[216:217], s[52:53], 0, v[156:157]
	s_mov_b32 m0, s41
	v_lshl_add_u64 v[218:219], s[26:27], 0, v[158:159]
	global_load_lds_dwordx4 v[216:217], off
	v_lshl_add_u64 v[216:217], s[52:53], 0, v[160:161]
	s_add_i32 m0, s41, 0x2000
	s_nop 0
	global_load_lds_dwordx4 v[216:217], off
	v_lshl_add_u64 v[216:217], s[26:27], 0, v[154:155]
	s_mov_b32 m0, s35
	s_nop 0
	global_load_lds_dwordx4 v[216:217], off
	s_mov_b32 m0, s42
	s_nop 0
	global_load_lds_dwordx4 v[218:219], off
	s_waitcnt vmcnt(8)
	s_waitcnt lgkmcnt(0)
	s_barrier
; #define PG8_STAGE(bufoff, gbase, voff) do { _Pragma("unroll") for (int _i = 0; _i < 2; ++_i) \
;         __builtin_amdgcn_global_load_lds((const unsigned*)((const char*)(gbase) + (voff)[_i]), (LAS unsigned*)(lds + (bufoff) + ldsw + _i * 8192), 16, 0, 0); } while (0)
; #define PG8_LDA(dst, b, h) do { _Pragma("unroll") for (int m = 0; m < 4; ++m) _Pragma("unroll") for (int k = 0; k < 2; ++k) dst[m][k] = *(const LAS bf16x8*)(lds + PG8_SA(b, h) + aoff + m * 2048 + k * 1024); } while (0)
; #define PG8_LDB(dst, b, h) do { _Pragma("unroll") for (int n = 0; n < 2; ++n) _Pragma("unroll") for (int k = 0; k < 2; ++k) dst[n][k] = *(const LAS bf16x8*)(lds + PG8_SB(b, h) + boff + n * 2048 + k * 1024); } while (0)
; #define PG8_MMA(ai, bj, At, Bt) do { __builtin_amdgcn_s_setprio(1); _Pragma("unroll") for (int m = 0; m < 4; ++m) _Pragma("unroll") for (int n = 0; n < 2; ++n) _Pragma("unroll") for (int k = 0; k < 2; ++k) \
;         acc[ai][bj][m][n] = __builtin_amdgcn_mfma_f32_16x16x32_bf16(Bt[n][k], At[m][k], acc[ai][bj][m][n], 0, 0, 0); __builtin_amdgcn_s_setprio(0); } while (0)
; #define PG8_WAIT_V(n) asm volatile("s_waitcnt vmcnt(" #n ")" ::: "memory")
; #define PG8_WAIT_L(n) asm volatile("s_waitcnt lgkmcnt(" #n ")" ::: "memory")
; #define PG8_BAR __builtin_amdgcn_s_barrier()
; #define PG8_SCHED __builtin_amdgcn_sched_barrier(0)
; template <class Epi>
; __device__ __forceinline__ void gemm_phase(LAS unsigned char* lds, const Gemm g, const StaticOrder& S, const Epi& E) {
;     ...
;             PG8_LDA(At, 0, 1); PG8_STAGE(PG8_SB(0, 0), b2, voffB); PG8_STAGE(PG8_SB(0, 1), b2 + hstepB, voffB); PG8_STAGE(PG8_SA(0, 0), a2, voffA);
;             PG8_WAIT_V(8); PG8_WAIT_L(0); PG8_BAR; PG8_MMA(1, 0, At, B0); PG8_MMA(1, 1, At, B1); PG8_BAR; PG8_SCHED;
;             PG8_LDB(B0, 1, 0); PG8_LDB(B1, 1, 1); PG8_SCHED; PG8_LDA(At, 1, 0); PG8_STAGE(PG8_SA(0, 1), a2 + hstepA, voffA);
;             PG8_WAIT_V(8); PG8_WAIT_L(0); PG8_BAR; PG8_MMA(0, 0, At, B0); PG8_MMA(0, 1, At, B1); PG8_BAR; PG8_SCHED;
;             PG8_LDA(At, 1, 1); PG8_STAGE(PG8_SB(1, 0), b3, voffB); PG8_STAGE(PG8_SB(1, 1), b3 + hstepB, voffB); PG8_STAGE(PG8_SA(1, 0), a3, voffA);
	s_setprio 1
	s_waitcnt lgkmcnt(0)
	v_mfma_f32_16x16x32_bf16 v[62:65], v[130:133], v[174:177], v[62:65]
	v_mfma_f32_16x16x32_bf16 v[58:61], v[138:141], v[174:177], v[58:61]
	v_mfma_f32_16x16x32_bf16 v[54:57], v[130:133], v[192:195], v[54:57]
	v_mfma_f32_16x16x32_bf16 v[50:53], v[138:141], v[192:195], v[50:53]
	v_mfma_f32_16x16x32_bf16 v[46:49], v[130:133], v[200:203], v[46:49]
	v_mfma_f32_16x16x32_bf16 v[38:41], v[138:141], v[200:203], v[38:41]
	v_mfma_f32_16x16x32_bf16 v[30:33], v[130:133], v[208:211], v[30:33]
	v_mfma_f32_16x16x32_bf16 v[22:25], v[138:141], v[208:211], v[22:25]
	v_mfma_f32_16x16x32_bf16 v[62:65], v[134:137], v[188:191], v[62:65]
	v_mfma_f32_16x16x32_bf16 v[58:61], v[142:145], v[188:191], v[58:61]
	v_mfma_f32_16x16x32_bf16 v[54:57], v[134:137], v[196:199], v[54:57]
	v_mfma_f32_16x16x32_bf16 v[50:53], v[142:145], v[196:199], v[50:53]
	v_mfma_f32_16x16x32_bf16 v[46:49], v[134:137], v[204:207], v[46:49]
	v_mfma_f32_16x16x32_bf16 v[38:41], v[142:145], v[204:207], v[38:41]
	v_mfma_f32_16x16x32_bf16 v[30:33], v[134:137], v[212:215], v[30:33]
	v_mfma_f32_16x16x32_bf16 v[22:25], v[142:145], v[212:215], v[22:25]
	v_mfma_f32_16x16x32_bf16 v[42:45], v[146:149], v[174:177], v[42:45]
	v_mfma_f32_16x16x32_bf16 v[34:37], v[166:169], v[174:177], v[34:37]
	v_mfma_f32_16x16x32_bf16 v[26:29], v[146:149], v[192:195], v[26:29]
	v_mfma_f32_16x16x32_bf16 v[18:21], v[166:169], v[192:195], v[18:21]
	v_mfma_f32_16x16x32_bf16 v[14:17], v[146:149], v[200:203], v[14:17]
	v_mfma_f32_16x16x32_bf16 v[10:13], v[166:169], v[200:203], v[10:13]
	v_mfma_f32_16x16x32_bf16 v[6:9], v[146:149], v[208:211], v[6:9]
	v_mfma_f32_16x16x32_bf16 v[2:5], v[166:169], v[208:211], v[2:5]
	v_mfma_f32_16x16x32_bf16 v[42:45], v[150:153], v[188:191], v[42:45]
	v_mfma_f32_16x16x32_bf16 v[34:37], v[170:173], v[188:191], v[34:37]
	v_mfma_f32_16x16x32_bf16 v[26:29], v[150:153], v[196:199], v[26:29]
	v_mfma_f32_16x16x32_bf16 v[18:21], v[170:173], v[196:199], v[18:21]
	v_mfma_f32_16x16x32_bf16 v[14:17], v[150:153], v[204:207], v[14:17]
	v_mfma_f32_16x16x32_bf16 v[10:13], v[170:173], v[204:207], v[10:13]
	v_mfma_f32_16x16x32_bf16 v[6:9], v[150:153], v[212:215], v[6:9]
	v_mfma_f32_16x16x32_bf16 v[2:5], v[170:173], v[212:215], v[2:5]
	s_setprio 0
	s_barrier
	s_add_i32 s41, 0, 0x18000
	s_add_i32 s52, 0, 0x1c000
	v_add_u32_e32 v142, s41, v1
	v_add_u32_e32 v170, s52, v1
	ds_read_b128 v[130:133], v142
	ds_read_b128 v[134:137], v142 offset:1024
	ds_read_b128 v[138:141], v142 offset:2048
	ds_read_b128 v[142:145], v142 offset:3072
	ds_read_b128 v[146:149], v170
	ds_read_b128 v[150:153], v170 offset:1024
	ds_read_b128 v[166:169], v170 offset:2048
	ds_read_b128 v[170:173], v170 offset:3072
	s_add_u32 s26, s26, 0x80000
	s_addc_u32 s27, s27, 0
	s_mov_b32 m0, s44
	v_lshl_add_u64 v[220:221], s[26:27], 0, v[154:155]
	ds_read_b128 v[174:177], v181 offset:32768
	ds_read_b128 v[188:191], v181 offset:33792
	ds_read_b128 v[192:195], v181 offset:34816
	ds_read_b128 v[196:199], v181 offset:35840
	ds_read_b128 v[200:203], v181 offset:36864
	ds_read_b128 v[204:207], v181 offset:37888
	ds_read_b128 v[208:211], v181 offset:38912
	ds_read_b128 v[212:215], v181 offset:39936
	global_load_lds_dwordx4 v[220:221], off
	v_lshl_add_u64 v[220:221], s[26:27], 0, v[158:159]
	s_mov_b32 m0, s45
	s_nop 0
	global_load_lds_dwordx4 v[220:221], off
	s_waitcnt vmcnt(8)
	s_waitcnt lgkmcnt(0)
	s_barrier
	s_setprio 1
	s_waitcnt lgkmcnt(0)
	v_mfma_f32_16x16x32_bf16 v[126:129], v[130:133], v[174:177], v[126:129]
	v_mfma_f32_16x16x32_bf16 v[122:125], v[138:141], v[174:177], v[122:125]
	v_mfma_f32_16x16x32_bf16 v[118:121], v[130:133], v[192:195], v[118:121]
	v_mfma_f32_16x16x32_bf16 v[114:117], v[138:141], v[192:195], v[114:117]
	v_mfma_f32_16x16x32_bf16 v[102:105], v[130:133], v[200:203], v[102:105]
	v_mfma_f32_16x16x32_bf16 v[98:101], v[138:141], v[200:203], v[98:101]
	v_mfma_f32_16x16x32_bf16 v[86:89], v[130:133], v[208:211], v[86:89]
	v_mfma_f32_16x16x32_bf16 v[82:85], v[138:141], v[208:211], v[82:85]
	v_mfma_f32_16x16x32_bf16 v[126:129], v[134:137], v[188:191], v[126:129]
	v_mfma_f32_16x16x32_bf16 v[122:125], v[142:145], v[188:191], v[122:125]
	v_mfma_f32_16x16x32_bf16 v[118:121], v[134:137], v[196:199], v[118:121]
	v_mfma_f32_16x16x32_bf16 v[114:117], v[142:145], v[196:199], v[114:117]
	v_mfma_f32_16x16x32_bf16 v[102:105], v[134:137], v[204:207], v[102:105]
	v_mfma_f32_16x16x32_bf16 v[98:101], v[142:145], v[204:207], v[98:101]
	v_mfma_f32_16x16x32_bf16 v[86:89], v[134:137], v[212:215], v[86:89]
	v_mfma_f32_16x16x32_bf16 v[82:85], v[142:145], v[212:215], v[82:85]
	v_mfma_f32_16x16x32_bf16 v[110:113], v[146:149], v[174:177], v[110:113]
	v_mfma_f32_16x16x32_bf16 v[106:109], v[166:169], v[174:177], v[106:109]
	v_mfma_f32_16x16x32_bf16 v[94:97], v[146:149], v[192:195], v[94:97]
	v_mfma_f32_16x16x32_bf16 v[90:93], v[166:169], v[192:195], v[90:93]
	v_mfma_f32_16x16x32_bf16 v[78:81], v[146:149], v[200:203], v[78:81]
	v_mfma_f32_16x16x32_bf16 v[74:77], v[166:169], v[200:203], v[74:77]
	v_mfma_f32_16x16x32_bf16 v[70:73], v[146:149], v[208:211], v[70:73]
	v_mfma_f32_16x16x32_bf16 v[66:69], v[166:169], v[208:211], v[66:69]
	v_mfma_f32_16x16x32_bf16 v[110:113], v[150:153], v[188:191], v[110:113]
	v_mfma_f32_16x16x32_bf16 v[106:109], v[170:173], v[188:191], v[106:109]
	v_mfma_f32_16x16x32_bf16 v[94:97], v[150:153], v[196:199], v[94:97]
	v_mfma_f32_16x16x32_bf16 v[90:93], v[170:173], v[196:199], v[90:93]
	v_mfma_f32_16x16x32_bf16 v[78:81], v[150:153], v[204:207], v[78:81]
	v_mfma_f32_16x16x32_bf16 v[74:77], v[170:173], v[204:207], v[74:77]
	v_mfma_f32_16x16x32_bf16 v[70:73], v[150:153], v[212:215], v[70:73]
	v_mfma_f32_16x16x32_bf16 v[66:69], v[170:173], v[212:215], v[66:69]
	s_setprio 0
	s_barrier
; #define PG8_STAGE(bufoff, gbase, voff) do { _Pragma("unroll") for (int _i = 0; _i < 2; ++_i) \
;         __builtin_amdgcn_global_load_lds((const unsigned*)((const char*)(gbase) + (voff)[_i]), (LAS unsigned*)(lds + (bufoff) + ldsw + _i * 8192), 16, 0, 0); } while (0)
; #define PG8_LDA(dst, b, h) do { _Pragma("unroll") for (int m = 0; m < 4; ++m) _Pragma("unroll") for (int k = 0; k < 2; ++k) dst[m][k] = *(const LAS bf16x8*)(lds + PG8_SA(b, h) + aoff + m * 2048 + k * 1024); } while (0)
; #define PG8_MMA(ai, bj, At, Bt) do { __builtin_amdgcn_s_setprio(1); _Pragma("unroll") for (int m = 0; m < 4; ++m) _Pragma("unroll") for (int n = 0; n < 2; ++n) _Pragma("unroll") for (int k = 0; k < 2; ++k) \
;         acc[ai][bj][m][n] = __builtin_amdgcn_mfma_f32_16x16x32_bf16(Bt[n][k], At[m][k], acc[ai][bj][m][n], 0, 0, 0); __builtin_amdgcn_s_setprio(0); } while (0)
; #define PG8_WAIT_V(n) asm volatile("s_waitcnt vmcnt(" #n ")" ::: "memory")
; #define PG8_WAIT_L(n) asm volatile("s_waitcnt lgkmcnt(" #n ")" ::: "memory")
; #define PG8_BAR __builtin_amdgcn_s_barrier()
; #define PG8_SCHED __builtin_amdgcn_sched_barrier(0)
; template <class Epi>
; __device__ __forceinline__ void gemm_phase(LAS unsigned char* lds, const Gemm g, const StaticOrder& S, const Epi& E) {
;     ...
;             PG8_LDA(At, 1, 1); PG8_STAGE(PG8_SB(1, 0), b3, voffB); PG8_STAGE(PG8_SB(1, 1), b3 + hstepB, voffB); PG8_STAGE(PG8_SA(1, 0), a3, voffA);
;             PG8_WAIT_V(8); PG8_WAIT_L(0); PG8_BAR; PG8_MMA(1, 0, At, B0); PG8_MMA(1, 1, At, B1); PG8_BAR; PG8_SCHED;
;         }
	s_add_i32 s26, s41, s34
	v_lshl_add_u64 v[178:179], v[178:179], 0, s[84:85]
	s_mov_b32 m0, s26
	ds_read_b128 v[174:177], v181 offset:49152
	ds_read_b128 v[188:191], v181 offset:50176
	ds_read_b128 v[192:195], v181 offset:51200
	ds_read_b128 v[196:199], v181 offset:52224
	ds_read_b128 v[200:203], v181 offset:53248
	ds_read_b128 v[204:207], v181 offset:54272
	ds_read_b128 v[208:211], v181 offset:55296
	ds_read_b128 v[212:215], v181 offset:56320
	global_load_lds_dwordx4 v[178:179], off
	s_add_i32 m0, s26, 0x2000
	s_add_u32 s14, s14, 0x80080
	v_lshl_add_u64 v[178:179], v[184:185], 0, s[84:85]
	s_addc_u32 s15, s15, 0
	s_add_i32 s26, s52, s34
	global_load_lds_dwordx4 v[178:179], off
	v_lshl_add_u64 v[178:179], s[14:15], 0, v[156:157]
	s_mov_b32 m0, s26
	s_nop 0
	global_load_lds_dwordx4 v[178:179], off
	v_lshl_add_u64 v[178:179], s[14:15], 0, v[160:161]
	s_add_i32 m0, s26, 0x2000
	s_nop 0
	global_load_lds_dwordx4 v[178:179], off
	v_lshl_add_u64 v[178:179], v[216:217], 0, s[84:85]
	s_mov_b32 m0, s86
	s_nop 0
	global_load_lds_dwordx4 v[178:179], off
	v_lshl_add_u64 v[178:179], v[218:219], 0, s[84:85]
	s_mov_b32 m0, s87
	s_nop 0
	global_load_lds_dwordx4 v[178:179], off
	s_waitcnt vmcnt(8)
	s_waitcnt lgkmcnt(0)
	s_barrier
	s_setprio 1
	s_waitcnt lgkmcnt(0)
	v_mfma_f32_16x16x32_bf16 v[62:65], v[130:133], v[174:177], v[62:65]
	v_mfma_f32_16x16x32_bf16 v[58:61], v[138:141], v[174:177], v[58:61]
	v_mfma_f32_16x16x32_bf16 v[54:57], v[130:133], v[192:195], v[54:57]
	v_mfma_f32_16x16x32_bf16 v[50:53], v[138:141], v[192:195], v[50:53]
	v_mfma_f32_16x16x32_bf16 v[46:49], v[130:133], v[200:203], v[46:49]
	v_mfma_f32_16x16x32_bf16 v[38:41], v[138:141], v[200:203], v[38:41]
	v_mfma_f32_16x16x32_bf16 v[30:33], v[130:133], v[208:211], v[30:33]
	v_mfma_f32_16x16x32_bf16 v[22:25], v[138:141], v[208:211], v[22:25]
	v_mfma_f32_16x16x32_bf16 v[62:65], v[134:137], v[188:191], v[62:65]
	v_mfma_f32_16x16x32_bf16 v[58:61], v[142:145], v[188:191], v[58:61]
	v_mfma_f32_16x16x32_bf16 v[54:57], v[134:137], v[196:199], v[54:57]
	v_mfma_f32_16x16x32_bf16 v[50:53], v[142:145], v[196:199], v[50:53]
	v_mfma_f32_16x16x32_bf16 v[46:49], v[134:137], v[204:207], v[46:49]
	v_mfma_f32_16x16x32_bf16 v[38:41], v[142:145], v[204:207], v[38:41]
	v_mfma_f32_16x16x32_bf16 v[30:33], v[134:137], v[212:215], v[30:33]
	v_mfma_f32_16x16x32_bf16 v[22:25], v[142:145], v[212:215], v[22:25]
	v_mfma_f32_16x16x32_bf16 v[42:45], v[146:149], v[174:177], v[42:45]
	v_mfma_f32_16x16x32_bf16 v[34:37], v[166:169], v[174:177], v[34:37]
	v_mfma_f32_16x16x32_bf16 v[26:29], v[146:149], v[192:195], v[26:29]
	v_mfma_f32_16x16x32_bf16 v[18:21], v[166:169], v[192:195], v[18:21]
	v_mfma_f32_16x16x32_bf16 v[14:17], v[146:149], v[200:203], v[14:17]
	v_mfma_f32_16x16x32_bf16 v[10:13], v[166:169], v[200:203], v[10:13]
	v_mfma_f32_16x16x32_bf16 v[6:9], v[146:149], v[208:211], v[6:9]
	v_mfma_f32_16x16x32_bf16 v[2:5], v[166:169], v[208:211], v[2:5]
	v_mfma_f32_16x16x32_bf16 v[42:45], v[150:153], v[188:191], v[42:45]
	v_mfma_f32_16x16x32_bf16 v[34:37], v[170:173], v[188:191], v[34:37]
	v_mfma_f32_16x16x32_bf16 v[26:29], v[150:153], v[196:199], v[26:29]
	v_mfma_f32_16x16x32_bf16 v[18:21], v[170:173], v[196:199], v[18:21]
	v_mfma_f32_16x16x32_bf16 v[14:17], v[150:153], v[204:207], v[14:17]
	v_mfma_f32_16x16x32_bf16 v[10:13], v[170:173], v[204:207], v[10:13]
	v_mfma_f32_16x16x32_bf16 v[6:9], v[150:153], v[212:215], v[6:9]
	v_mfma_f32_16x16x32_bf16 v[2:5], v[170:173], v[212:215], v[2:5]
	s_setprio 0
	s_barrier
	s_add_i32 s40, s40, 2
	s_add_u32 s24, s24, 0x100
	s_addc_u32 s25, s25, 0
	s_add_u32 s19, s19, 0x100
	s_addc_u32 s33, s33, 0
	s_cmp_gt_u32 s40, 29
	s_cbranch_scc0 .LBB0_2332
	s_cmp_ge_u32 s74, 16
	s_cbranch_scc1 .Lwpf_f
	s_lshl_b32 s100, s74, 9
	v_add_u32_e32 v130, s100, v246
	v_lshrrev_b32_e32 v131, 2, v130
	v_and_b32_e32 v130, 3, v130
	v_lshlrev_b32_e32 v130, 7, v130
	v_lshl_add_u32 v130, v131, 12, v130
	v_readlane_b32 s100, v255, 42
	s_nop 3
	s_mov_b32 s101, 0x16900000
	s_cmp_eq_u32 s100, 1
	s_cselect_b32 s101, 0x15100000, s101
	s_cmp_eq_u32 s100, 0
	s_cselect_b32 s101, 0x13700000, s101
	s_add_u32 s100, s38, s101
	s_addc_u32 s101, s39, 0
	s_mov_b32 m0, 0x21000
	s_nop 0
	global_load_lds_dword v130, s[100:101]

; #define PG8_STAGE(bufoff, gbase, voff) do { _Pragma("unroll") for (int _i = 0; _i < 2; ++_i) \
;         __builtin_amdgcn_global_load_lds((const unsigned*)((const char*)(gbase) + (voff)[_i]), (LAS unsigned*)(lds + (bufoff) + ldsw + _i * 8192), 16, 0, 0); } while (0)
; #define PG8_LDA(dst, b, h) do { _Pragma("unroll") for (int m = 0; m < 4; ++m) _Pragma("unroll") for (int k = 0; k < 2; ++k) dst[m][k] = *(const LAS bf16x8*)(lds + PG8_SA(b, h) + aoff + m * 2048 + k * 1024); } while (0)
; #define PG8_LDB(dst, b, h) do { _Pragma("unroll") for (int n = 0; n < 2; ++n) _Pragma("unroll") for (int k = 0; k < 2; ++k) dst[n][k] = *(const LAS bf16x8*)(lds + PG8_SB(b, h) + boff + n * 2048 + k * 1024); } while (0)
; #define PG8_MMA(ai, bj, At, Bt) do { __builtin_amdgcn_s_setprio(1); _Pragma("unroll") for (int m = 0; m < 4; ++m) _Pragma("unroll") for (int n = 0; n < 2; ++n) _Pragma("unroll") for (int k = 0; k < 2; ++k) \
;         acc[ai][bj][m][n] = __builtin_amdgcn_mfma_f32_16x16x32_bf16(Bt[n][k], At[m][k], acc[ai][bj][m][n], 0, 0, 0); __builtin_amdgcn_s_setprio(0); } while (0)
; #define PG8_WAIT_V(n) asm volatile("s_waitcnt vmcnt(" #n ")" ::: "memory")
; #define PG8_BAR __builtin_amdgcn_s_barrier()
; template <class Epi>
; __device__ __forceinline__ void gemm_phase(LAS unsigned char* lds, const Gemm g, const StaticOrder& S, const Epi& E) {
;     ...
;         const bool has_next = S.next(ui + 1, nxt);
;         const char* nA = has_next ? PG8_UA(nxt) : cA; const char* nB = has_next ? PG8_UB(nxt) : cB;
;         for (int t = 0; t < nt; t += 2) {
;             const bool last = (t == nt - 2);
;             const char* a1 = cA + (size_t)(t + 1) * kstep;
;             const char* a2 = last ? nA : cA + (size_t)(t + 2) * kstep; const char* b2 = last ? nB : cB + (size_t)(t + 2) * kstep;
;             const char* a3 = a2 + kstep; const char* b3 = b2 + kstep;
;             PG8_LDB(B0, 0, 0); PG8_LDB(B1, 0, 1); PG8_SCHED; PG8_LDA(At, 0, 0); PG8_STAGE(PG8_SA(1, 1), a1 + hstepA, voffA);
;             PG8_WAIT_V(8); PG8_WAIT_L(0); PG8_BAR; PG8_MMA(0, 0, At, B0); PG8_MMA(0, 1, At, B1); PG8_BAR; PG8_SCHED;
;             PG8_LDA(At, 0, 1); PG8_STAGE(PG8_SB(0, 0), b2, voffB); PG8_STAGE(PG8_SB(0, 1), b2 + hstepB, voffB); PG8_STAGE(PG8_SA(0, 0), a2, voffA);
;             PG8_WAIT_V(8); PG8_WAIT_L(0); PG8_BAR; PG8_MMA(1, 0, At, B0); PG8_MMA(1, 1, At, B1); PG8_BAR; PG8_SCHED;
.LBB0_2376:
	s_add_u32 s14, s22, 0xfff80080
	s_addc_u32 s15, s23, -1
	s_add_i32 s53, 0, 0x10000
	s_cmp_eq_u32 s41, 28
	s_cselect_b32 s25, s3, s15
	s_cselect_b32 s24, s9, s14
	s_cselect_b32 s15, s13, s52
	s_cselect_b32 s14, s17, s40
	s_add_i32 s64, 0, 0x14000
	v_add_u32_e32 v142, s53, v1
	v_add_u32_e32 v170, s64, v1
	ds_read_b128 v[130:133], v142
	ds_read_b128 v[134:137], v142 offset:1024
	ds_read_b128 v[138:141], v142 offset:2048
	ds_read_b128 v[142:145], v142 offset:3072
	ds_read_b128 v[146:149], v170
	ds_read_b128 v[150:153], v170 offset:1024
	ds_read_b128 v[166:169], v170 offset:2048
	ds_read_b128 v[170:173], v170 offset:3072
	v_lshl_add_u64 v[178:179], s[22:23], 0, v[162:163]
	s_add_i32 m0, s30, 0xc000
	ds_read_b128 v[174:177], v181
	ds_read_b128 v[188:191], v181 offset:1024
	ds_read_b128 v[192:195], v181 offset:2048
	ds_read_b128 v[196:199], v181 offset:3072
	ds_read_b128 v[200:203], v181 offset:4096
	ds_read_b128 v[204:207], v181 offset:5120
	ds_read_b128 v[208:211], v181 offset:6144
	ds_read_b128 v[212:215], v181 offset:7168
	global_load_lds_dwordx4 v[178:179], off
	v_lshl_add_u64 v[178:179], s[22:23], 0, v[164:165]
	s_add_i32 m0, s30, 0xe000
	s_nop 0
	global_load_lds_dwordx4 v[178:179], off
	s_waitcnt vmcnt(8)
	s_waitcnt lgkmcnt(0)
	s_barrier
	s_setprio 1
	s_waitcnt lgkmcnt(0)
	v_mfma_f32_16x16x32_bf16 v[126:129], v[130:133], v[174:177], v[126:129]
	v_mfma_f32_16x16x32_bf16 v[122:125], v[138:141], v[174:177], v[122:125]
	v_mfma_f32_16x16x32_bf16 v[118:121], v[130:133], v[192:195], v[118:121]
	v_mfma_f32_16x16x32_bf16 v[114:117], v[138:141], v[192:195], v[114:117]
	v_mfma_f32_16x16x32_bf16 v[102:105], v[130:133], v[200:203], v[102:105]
	v_mfma_f32_16x16x32_bf16 v[98:101], v[138:141], v[200:203], v[98:101]
	v_mfma_f32_16x16x32_bf16 v[86:89], v[130:133], v[208:211], v[86:89]
	v_mfma_f32_16x16x32_bf16 v[82:85], v[138:141], v[208:211], v[82:85]
	v_mfma_f32_16x16x32_bf16 v[126:129], v[134:137], v[188:191], v[126:129]
	v_mfma_f32_16x16x32_bf16 v[122:125], v[142:145], v[188:191], v[122:125]
	v_mfma_f32_16x16x32_bf16 v[118:121], v[134:137], v[196:199], v[118:121]
	v_mfma_f32_16x16x32_bf16 v[114:117], v[142:145], v[196:199], v[114:117]
	v_mfma_f32_16x16x32_bf16 v[102:105], v[134:137], v[204:207], v[102:105]
	v_mfma_f32_16x16x32_bf16 v[98:101], v[142:145], v[204:207], v[98:101]
	v_mfma_f32_16x16x32_bf16 v[86:89], v[134:137], v[212:215], v[86:89]
	v_mfma_f32_16x16x32_bf16 v[82:85], v[142:145], v[212:215], v[82:85]
	v_mfma_f32_16x16x32_bf16 v[110:113], v[146:149], v[174:177], v[110:113]
	v_mfma_f32_16x16x32_bf16 v[106:109], v[166:169], v[174:177], v[106:109]
	v_mfma_f32_16x16x32_bf16 v[94:97], v[146:149], v[192:195], v[94:97]
	v_mfma_f32_16x16x32_bf16 v[90:93], v[166:169], v[192:195], v[90:93]
	v_mfma_f32_16x16x32_bf16 v[78:81], v[146:149], v[200:203], v[78:81]
	v_mfma_f32_16x16x32_bf16 v[74:77], v[166:169], v[200:203], v[74:77]
	v_mfma_f32_16x16x32_bf16 v[70:73], v[146:149], v[208:211], v[70:73]
	v_mfma_f32_16x16x32_bf16 v[66:69], v[166:169], v[208:211], v[66:69]
	v_mfma_f32_16x16x32_bf16 v[110:113], v[150:153], v[188:191], v[110:113]
	v_mfma_f32_16x16x32_bf16 v[106:109], v[170:173], v[188:191], v[106:109]
	v_mfma_f32_16x16x32_bf16 v[94:97], v[150:153], v[196:199], v[94:97]
	v_mfma_f32_16x16x32_bf16 v[90:93], v[170:173], v[196:199], v[90:93]
	v_mfma_f32_16x16x32_bf16 v[78:81], v[150:153], v[204:207], v[78:81]
	v_mfma_f32_16x16x32_bf16 v[74:77], v[170:173], v[204:207], v[74:77]
	v_mfma_f32_16x16x32_bf16 v[70:73], v[150:153], v[212:215], v[70:73]
	v_mfma_f32_16x16x32_bf16 v[66:69], v[170:173], v[212:215], v[66:69]
	s_setprio 0
	s_barrier
	s_add_i32 s53, s53, s27
	v_lshl_add_u64 v[178:179], s[14:15], 0, v[156:157]
	s_mov_b32 m0, s53
	ds_read_b128 v[174:177], v181 offset:16384
	ds_read_b128 v[188:191], v181 offset:17408
	ds_read_b128 v[192:195], v181 offset:18432
	ds_read_b128 v[196:199], v181 offset:19456
	ds_read_b128 v[200:203], v181 offset:20480
	ds_read_b128 v[204:207], v181 offset:21504
	ds_read_b128 v[208:211], v181 offset:22528
	ds_read_b128 v[212:215], v181 offset:23552
	global_load_lds_dwordx4 v[178:179], off
	s_add_i32 m0, s53, 0x2000
	s_add_u32 s62, s14, 0x80000
	v_lshl_add_u64 v[184:185], s[14:15], 0, v[160:161]
	s_addc_u32 s63, s15, 0
	s_add_i32 s53, s64, s27
	global_load_lds_dwordx4 v[184:185], off
	v_lshl_add_u64 v[186:187], s[62:63], 0, v[156:157]
	s_mov_b32 m0, s53
	v_lshl_add_u64 v[216:217], s[24:25], 0, v[158:159]
	global_load_lds_dwordx4 v[186:187], off
	v_lshl_add_u64 v[186:187], s[62:63], 0, v[160:161]
	s_add_i32 m0, s53, 0x2000
	s_nop 0
	global_load_lds_dwordx4 v[186:187], off
	v_lshl_add_u64 v[186:187], s[24:25], 0, v[154:155]
	s_mov_b32 m0, s30
	s_nop 0
	global_load_lds_dwordx4 v[186:187], off
	s_mov_b32 m0, s31
	s_nop 0
	global_load_lds_dwordx4 v[216:217], off
	s_waitcnt vmcnt(8)
	s_waitcnt lgkmcnt(0)
	s_barrier
; #define PG8_STAGE(bufoff, gbase, voff) do { _Pragma("unroll") for (int _i = 0; _i < 2; ++_i) \
;         __builtin_amdgcn_global_load_lds((const unsigned*)((const char*)(gbase) + (voff)[_i]), (LAS unsigned*)(lds + (bufoff) + ldsw + _i * 8192), 16, 0, 0); } while (0)
; #define PG8_LDA(dst, b, h) do { _Pragma("unroll") for (int m = 0; m < 4; ++m) _Pragma("unroll") for (int k = 0; k < 2; ++k) dst[m][k] = *(const LAS bf16x8*)(lds + PG8_SA(b, h) + aoff + m * 2048 + k * 1024); } while (0)
; #define PG8_LDB(dst, b, h) do { _Pragma("unroll") for (int n = 0; n < 2; ++n) _Pragma("unroll") for (int k = 0; k < 2; ++k) dst[n][k] = *(const LAS bf16x8*)(lds + PG8_SB(b, h) + boff + n * 2048 + k * 1024); } while (0)
; #define PG8_MMA(ai, bj, At, Bt) do { __builtin_amdgcn_s_setprio(1); _Pragma("unroll") for (int m = 0; m < 4; ++m) _Pragma("unroll") for (int n = 0; n < 2; ++n) _Pragma("unroll") for (int k = 0; k < 2; ++k) \
;         acc[ai][bj][m][n] = __builtin_amdgcn_mfma_f32_16x16x32_bf16(Bt[n][k], At[m][k], acc[ai][bj][m][n], 0, 0, 0); __builtin_amdgcn_s_setprio(0); } while (0)
; #define PG8_WAIT_V(n) asm volatile("s_waitcnt vmcnt(" #n ")" ::: "memory")
; #define PG8_WAIT_L(n) asm volatile("s_waitcnt lgkmcnt(" #n ")" ::: "memory")
; #define PG8_BAR __builtin_amdgcn_s_barrier()
; #define PG8_SCHED __builtin_amdgcn_sched_barrier(0)
; template <class Epi>
; __device__ __forceinline__ void gemm_phase(LAS unsigned char* lds, const Gemm g, const StaticOrder& S, const Epi& E) {
;     ...
;             PG8_LDA(At, 0, 1); PG8_STAGE(PG8_SB(0, 0), b2, voffB); PG8_STAGE(PG8_SB(0, 1), b2 + hstepB, voffB); PG8_STAGE(PG8_SA(0, 0), a2, voffA);
;             PG8_WAIT_V(8); PG8_WAIT_L(0); PG8_BAR; PG8_MMA(1, 0, At, B0); PG8_MMA(1, 1, At, B1); PG8_BAR; PG8_SCHED;
;             PG8_LDB(B0, 1, 0); PG8_LDB(B1, 1, 1); PG8_SCHED; PG8_LDA(At, 1, 0); PG8_STAGE(PG8_SA(0, 1), a2 + hstepA, voffA);
;             PG8_WAIT_V(8); PG8_WAIT_L(0); PG8_BAR; PG8_MMA(0, 0, At, B0); PG8_MMA(0, 1, At, B1); PG8_BAR; PG8_SCHED;
;             PG8_LDA(At, 1, 1); PG8_STAGE(PG8_SB(1, 0), b3, voffB); PG8_STAGE(PG8_SB(1, 1), b3 + hstepB, voffB); PG8_STAGE(PG8_SA(1, 0), a3, voffA);
	s_setprio 1
	s_waitcnt lgkmcnt(0)
	v_mfma_f32_16x16x32_bf16 v[62:65], v[130:133], v[174:177], v[62:65]
	v_mfma_f32_16x16x32_bf16 v[58:61], v[138:141], v[174:177], v[58:61]
	v_mfma_f32_16x16x32_bf16 v[54:57], v[130:133], v[192:195], v[54:57]
	v_mfma_f32_16x16x32_bf16 v[50:53], v[138:141], v[192:195], v[50:53]
	v_mfma_f32_16x16x32_bf16 v[46:49], v[130:133], v[200:203], v[46:49]
	v_mfma_f32_16x16x32_bf16 v[38:41], v[138:141], v[200:203], v[38:41]
	v_mfma_f32_16x16x32_bf16 v[30:33], v[130:133], v[208:211], v[30:33]
	v_mfma_f32_16x16x32_bf16 v[22:25], v[138:141], v[208:211], v[22:25]
	v_mfma_f32_16x16x32_bf16 v[62:65], v[134:137], v[188:191], v[62:65]
	v_mfma_f32_16x16x32_bf16 v[58:61], v[142:145], v[188:191], v[58:61]
	v_mfma_f32_16x16x32_bf16 v[54:57], v[134:137], v[196:199], v[54:57]
	v_mfma_f32_16x16x32_bf16 v[50:53], v[142:145], v[196:199], v[50:53]
	v_mfma_f32_16x16x32_bf16 v[46:49], v[134:137], v[204:207], v[46:49]
	v_mfma_f32_16x16x32_bf16 v[38:41], v[142:145], v[204:207], v[38:41]
	v_mfma_f32_16x16x32_bf16 v[30:33], v[134:137], v[212:215], v[30:33]
	v_mfma_f32_16x16x32_bf16 v[22:25], v[142:145], v[212:215], v[22:25]
	v_mfma_f32_16x16x32_bf16 v[42:45], v[146:149], v[174:177], v[42:45]
	v_mfma_f32_16x16x32_bf16 v[34:37], v[166:169], v[174:177], v[34:37]
	v_mfma_f32_16x16x32_bf16 v[26:29], v[146:149], v[192:195], v[26:29]
	v_mfma_f32_16x16x32_bf16 v[18:21], v[166:169], v[192:195], v[18:21]
	v_mfma_f32_16x16x32_bf16 v[14:17], v[146:149], v[200:203], v[14:17]
	v_mfma_f32_16x16x32_bf16 v[10:13], v[166:169], v[200:203], v[10:13]
	v_mfma_f32_16x16x32_bf16 v[6:9], v[146:149], v[208:211], v[6:9]
	v_mfma_f32_16x16x32_bf16 v[2:5], v[166:169], v[208:211], v[2:5]
	v_mfma_f32_16x16x32_bf16 v[42:45], v[150:153], v[188:191], v[42:45]
	v_mfma_f32_16x16x32_bf16 v[34:37], v[170:173], v[188:191], v[34:37]
	v_mfma_f32_16x16x32_bf16 v[26:29], v[150:153], v[196:199], v[26:29]
	v_mfma_f32_16x16x32_bf16 v[18:21], v[170:173], v[196:199], v[18:21]
	v_mfma_f32_16x16x32_bf16 v[14:17], v[150:153], v[204:207], v[14:17]
	v_mfma_f32_16x16x32_bf16 v[10:13], v[170:173], v[204:207], v[10:13]
	v_mfma_f32_16x16x32_bf16 v[6:9], v[150:153], v[212:215], v[6:9]
	v_mfma_f32_16x16x32_bf16 v[2:5], v[170:173], v[212:215], v[2:5]
	s_setprio 0
	s_barrier
	s_add_i32 s53, 0, 0x18000
	s_add_i32 s62, 0, 0x1c000
	v_add_u32_e32 v142, s53, v1
	v_add_u32_e32 v170, s62, v1
	ds_read_b128 v[130:133], v142
	ds_read_b128 v[134:137], v142 offset:1024
	ds_read_b128 v[138:141], v142 offset:2048
	ds_read_b128 v[142:145], v142 offset:3072
	ds_read_b128 v[146:149], v170
	ds_read_b128 v[150:153], v170 offset:1024
	ds_read_b128 v[166:169], v170 offset:2048
	ds_read_b128 v[170:173], v170 offset:3072
	s_add_u32 s24, s24, 0x80000
	s_addc_u32 s25, s25, 0
	s_mov_b32 m0, s34
	v_lshl_add_u64 v[218:219], s[24:25], 0, v[154:155]
	ds_read_b128 v[174:177], v181 offset:32768
	ds_read_b128 v[188:191], v181 offset:33792
	ds_read_b128 v[192:195], v181 offset:34816
	ds_read_b128 v[196:199], v181 offset:35840
	ds_read_b128 v[200:203], v181 offset:36864
	ds_read_b128 v[204:207], v181 offset:37888
	ds_read_b128 v[208:211], v181 offset:38912
	ds_read_b128 v[212:215], v181 offset:39936
	global_load_lds_dwordx4 v[218:219], off
	v_lshl_add_u64 v[218:219], s[24:25], 0, v[158:159]
	s_mov_b32 m0, s35
	s_nop 0
	global_load_lds_dwordx4 v[218:219], off
	s_waitcnt vmcnt(8)
	s_waitcnt lgkmcnt(0)
	s_barrier
	s_setprio 1
	s_waitcnt lgkmcnt(0)
	v_mfma_f32_16x16x32_bf16 v[126:129], v[130:133], v[174:177], v[126:129]
	v_mfma_f32_16x16x32_bf16 v[122:125], v[138:141], v[174:177], v[122:125]
	v_mfma_f32_16x16x32_bf16 v[118:121], v[130:133], v[192:195], v[118:121]
	v_mfma_f32_16x16x32_bf16 v[114:117], v[138:141], v[192:195], v[114:117]
	v_mfma_f32_16x16x32_bf16 v[102:105], v[130:133], v[200:203], v[102:105]
	v_mfma_f32_16x16x32_bf16 v[98:101], v[138:141], v[200:203], v[98:101]
	v_mfma_f32_16x16x32_bf16 v[86:89], v[130:133], v[208:211], v[86:89]
	v_mfma_f32_16x16x32_bf16 v[82:85], v[138:141], v[208:211], v[82:85]
	v_mfma_f32_16x16x32_bf16 v[126:129], v[134:137], v[188:191], v[126:129]
	v_mfma_f32_16x16x32_bf16 v[122:125], v[142:145], v[188:191], v[122:125]
	v_mfma_f32_16x16x32_bf16 v[118:121], v[134:137], v[196:199], v[118:121]
	v_mfma_f32_16x16x32_bf16 v[114:117], v[142:145], v[196:199], v[114:117]
	v_mfma_f32_16x16x32_bf16 v[102:105], v[134:137], v[204:207], v[102:105]
	v_mfma_f32_16x16x32_bf16 v[98:101], v[142:145], v[204:207], v[98:101]
	v_mfma_f32_16x16x32_bf16 v[86:89], v[134:137], v[212:215], v[86:89]
	v_mfma_f32_16x16x32_bf16 v[82:85], v[142:145], v[212:215], v[82:85]
	v_mfma_f32_16x16x32_bf16 v[110:113], v[146:149], v[174:177], v[110:113]
	v_mfma_f32_16x16x32_bf16 v[106:109], v[166:169], v[174:177], v[106:109]
	v_mfma_f32_16x16x32_bf16 v[94:97], v[146:149], v[192:195], v[94:97]
	v_mfma_f32_16x16x32_bf16 v[90:93], v[166:169], v[192:195], v[90:93]
	v_mfma_f32_16x16x32_bf16 v[78:81], v[146:149], v[200:203], v[78:81]
	v_mfma_f32_16x16x32_bf16 v[74:77], v[166:169], v[200:203], v[74:77]
	v_mfma_f32_16x16x32_bf16 v[70:73], v[146:149], v[208:211], v[70:73]
	v_mfma_f32_16x16x32_bf16 v[66:69], v[166:169], v[208:211], v[66:69]
	v_mfma_f32_16x16x32_bf16 v[110:113], v[150:153], v[188:191], v[110:113]
	v_mfma_f32_16x16x32_bf16 v[106:109], v[170:173], v[188:191], v[106:109]
	v_mfma_f32_16x16x32_bf16 v[94:97], v[150:153], v[196:199], v[94:97]
	v_mfma_f32_16x16x32_bf16 v[90:93], v[170:173], v[196:199], v[90:93]
	v_mfma_f32_16x16x32_bf16 v[78:81], v[150:153], v[204:207], v[78:81]
	v_mfma_f32_16x16x32_bf16 v[74:77], v[170:173], v[204:207], v[74:77]
	v_mfma_f32_16x16x32_bf16 v[70:73], v[150:153], v[212:215], v[70:73]
	v_mfma_f32_16x16x32_bf16 v[66:69], v[170:173], v[212:215], v[66:69]
	s_setprio 0
	s_barrier
; __device__ __forceinline__ int launder(int v) { asm volatile("" : "+v"(v)); return v; }
; #define PG8_STAGE(bufoff, gbase, voff) do { _Pragma("unroll") for (int _i = 0; _i < 2; ++_i) \
;         __builtin_amdgcn_global_load_lds((const unsigned*)((const char*)(gbase) + (voff)[_i]), (LAS unsigned*)(lds + (bufoff) + ldsw + _i * 8192), 16, 0, 0); } while (0)
; #define PG8_LDA(dst, b, h) do { _Pragma("unroll") for (int m = 0; m < 4; ++m) _Pragma("unroll") for (int k = 0; k < 2; ++k) dst[m][k] = *(const LAS bf16x8*)(lds + PG8_SA(b, h) + aoff + m * 2048 + k * 1024); } while (0)
; #define PG8_MMA(ai, bj, At, Bt) do { __builtin_amdgcn_s_setprio(1); _Pragma("unroll") for (int m = 0; m < 4; ++m) _Pragma("unroll") for (int n = 0; n < 2; ++n) _Pragma("unroll") for (int k = 0; k < 2; ++k) \
;         acc[ai][bj][m][n] = __builtin_amdgcn_mfma_f32_16x16x32_bf16(Bt[n][k], At[m][k], acc[ai][bj][m][n], 0, 0, 0); __builtin_amdgcn_s_setprio(0); } while (0)
; #define PG8_WAIT_V(n) asm volatile("s_waitcnt vmcnt(" #n ")" ::: "memory")
; #define PG8_WAIT_L(n) asm volatile("s_waitcnt lgkmcnt(" #n ")" ::: "memory")
; #define PG8_BAR __builtin_amdgcn_s_barrier()
; #define PG8_SCHED __builtin_amdgcn_sched_barrier(0)
; template <class Epi>
; __device__ __forceinline__ void gemm_phase(LAS unsigned char* lds, const Gemm g, const StaticOrder& S, const Epi& E) {
;     ...
;             PG8_LDA(At, 1, 1); PG8_STAGE(PG8_SB(1, 0), b3, voffB); PG8_STAGE(PG8_SB(1, 1), b3 + hstepB, voffB); PG8_STAGE(PG8_SA(1, 0), a3, voffA);
;             PG8_WAIT_V(8); PG8_WAIT_L(0); PG8_BAR; PG8_MMA(1, 0, At, B0); PG8_MMA(1, 1, At, B1); PG8_BAR; PG8_SCHED;
;         }
;         if (wr == 0) PG8_BAR;
;         { const int l2 = launder(threadIdx.x) & 63; E(acc, cur, wr, wc, l2 & 15, l2 >> 4); }
	s_add_i32 s24, s53, s27
	v_lshl_add_u64 v[178:179], v[178:179], 0, s[84:85]
	s_mov_b32 m0, s24
	ds_read_b128 v[174:177], v181 offset:49152
	ds_read_b128 v[188:191], v181 offset:50176
	ds_read_b128 v[192:195], v181 offset:51200
	ds_read_b128 v[196:199], v181 offset:52224
	ds_read_b128 v[200:203], v181 offset:53248
	ds_read_b128 v[204:207], v181 offset:54272
	ds_read_b128 v[208:211], v181 offset:55296
	ds_read_b128 v[212:215], v181 offset:56320
	global_load_lds_dwordx4 v[178:179], off
	s_add_i32 m0, s24, 0x2000
	s_add_u32 s14, s14, 0x80080
	v_lshl_add_u64 v[178:179], v[184:185], 0, s[84:85]
	s_addc_u32 s15, s15, 0
	s_add_i32 s24, s62, s27
	global_load_lds_dwordx4 v[178:179], off
	v_lshl_add_u64 v[178:179], s[14:15], 0, v[156:157]
	s_mov_b32 m0, s24
	s_nop 0
	global_load_lds_dwordx4 v[178:179], off
	v_lshl_add_u64 v[178:179], s[14:15], 0, v[160:161]
	s_add_i32 m0, s24, 0x2000
	s_nop 0
	global_load_lds_dwordx4 v[178:179], off
	v_lshl_add_u64 v[178:179], v[186:187], 0, s[84:85]
	s_mov_b32 m0, s45
	s_nop 0
	global_load_lds_dwordx4 v[178:179], off
	v_lshl_add_u64 v[178:179], v[216:217], 0, s[84:85]
	s_mov_b32 m0, s68
	s_nop 0
	global_load_lds_dwordx4 v[178:179], off
	s_waitcnt vmcnt(8)
	s_waitcnt lgkmcnt(0)
	s_barrier
	s_setprio 1
	s_waitcnt lgkmcnt(0)
	v_mfma_f32_16x16x32_bf16 v[62:65], v[130:133], v[174:177], v[62:65]
	v_mfma_f32_16x16x32_bf16 v[58:61], v[138:141], v[174:177], v[58:61]
	v_mfma_f32_16x16x32_bf16 v[54:57], v[130:133], v[192:195], v[54:57]
	v_mfma_f32_16x16x32_bf16 v[50:53], v[138:141], v[192:195], v[50:53]
	v_mfma_f32_16x16x32_bf16 v[46:49], v[130:133], v[200:203], v[46:49]
	v_mfma_f32_16x16x32_bf16 v[38:41], v[138:141], v[200:203], v[38:41]
	v_mfma_f32_16x16x32_bf16 v[30:33], v[130:133], v[208:211], v[30:33]
	v_mfma_f32_16x16x32_bf16 v[22:25], v[138:141], v[208:211], v[22:25]
	v_mfma_f32_16x16x32_bf16 v[62:65], v[134:137], v[188:191], v[62:65]
	v_mfma_f32_16x16x32_bf16 v[58:61], v[142:145], v[188:191], v[58:61]
	v_mfma_f32_16x16x32_bf16 v[54:57], v[134:137], v[196:199], v[54:57]
	v_mfma_f32_16x16x32_bf16 v[50:53], v[142:145], v[196:199], v[50:53]
	v_mfma_f32_16x16x32_bf16 v[46:49], v[134:137], v[204:207], v[46:49]
	v_mfma_f32_16x16x32_bf16 v[38:41], v[142:145], v[204:207], v[38:41]
	v_mfma_f32_16x16x32_bf16 v[30:33], v[134:137], v[212:215], v[30:33]
	v_mfma_f32_16x16x32_bf16 v[22:25], v[142:145], v[212:215], v[22:25]
	v_mfma_f32_16x16x32_bf16 v[42:45], v[146:149], v[174:177], v[42:45]
	v_mfma_f32_16x16x32_bf16 v[34:37], v[166:169], v[174:177], v[34:37]
	v_mfma_f32_16x16x32_bf16 v[26:29], v[146:149], v[192:195], v[26:29]
	v_mfma_f32_16x16x32_bf16 v[18:21], v[166:169], v[192:195], v[18:21]
	v_mfma_f32_16x16x32_bf16 v[14:17], v[146:149], v[200:203], v[14:17]
	v_mfma_f32_16x16x32_bf16 v[10:13], v[166:169], v[200:203], v[10:13]
	v_mfma_f32_16x16x32_bf16 v[6:9], v[146:149], v[208:211], v[6:9]
	v_mfma_f32_16x16x32_bf16 v[2:5], v[166:169], v[208:211], v[2:5]
	v_mfma_f32_16x16x32_bf16 v[42:45], v[150:153], v[188:191], v[42:45]
	v_mfma_f32_16x16x32_bf16 v[34:37], v[170:173], v[188:191], v[34:37]
	v_mfma_f32_16x16x32_bf16 v[26:29], v[150:153], v[196:199], v[26:29]
	v_mfma_f32_16x16x32_bf16 v[18:21], v[170:173], v[196:199], v[18:21]
	v_mfma_f32_16x16x32_bf16 v[14:17], v[150:153], v[204:207], v[14:17]
	v_mfma_f32_16x16x32_bf16 v[10:13], v[170:173], v[204:207], v[10:13]
	v_mfma_f32_16x16x32_bf16 v[6:9], v[150:153], v[212:215], v[6:9]
	v_mfma_f32_16x16x32_bf16 v[2:5], v[170:173], v[212:215], v[2:5]
	s_setprio 0
	s_barrier
	s_add_i32 s41, s41, 2
	s_add_u32 s22, s22, 0x100
	s_addc_u32 s23, s23, 0
	s_add_u32 s40, s40, 0x100
	s_addc_u32 s52, s52, 0
	s_cmp_gt_u32 s41, 29
	s_cbranch_scc0 .LBB0_2376
	v_mov_b64_e32 v[250:251], 0xff
	v_mov_b64_e32 v[252:253], 0x100
	v_mov_b32_e32 v183, 0x7f800000
	s_and_b64 vcc, exec, s[10:11]
	s_cbranch_vccz .LBB0_2379
	s_barrier
